# V-side pipelined + PQ GEMM core v3 (BK64 LDS-DMA single image) + GLA warm-up covers two chunks per wait
# speedup vs baseline: 1.1286x; 1.0177x over previous
.LBB0_1462:
	s_andn2_b64 vcc, exec, s[0:1]
	s_cbranch_vccnz .LBB0_1375
	s_ashr_i32 s19, s23, 3
	s_lshl_b32 s8, s19, 1
	v_readlane_b32 s2, v255, 19
	s_or_b32 s8, s8, s2
	s_waitcnt vmcnt(8)
	v_mov_b32_e32 v50, v179
	s_and_b32 s13, s23, 1
	s_ashr_i32 s9, s8, 31
	s_lshl_b64 s[8:9], s[8:9], 3
	v_ashrrev_i32_e32 v46, 6, v50
	s_lshl_b32 s20, s13, 2
	v_and_b32_e32 v52, 15, v50
	s_bfe_u32 s10, s23, 0x20001
	s_or_b32 s8, s8, s20
	s_waitcnt vmcnt(1)
	v_lshlrev_b32_e32 v2, 5, v46
	v_readlane_b32 s40, v252, 8
	s_or_b32 s8, s8, s10
	v_lshlrev_b32_e32 v0, 2, v52
	v_readlane_b32 s44, v252, 12
	v_readlane_b32 s45, v252, 13
	v_ashrrev_i32_e32 v3, 31, v2
	v_bfe_u32 v38, v50, 4, 2
	v_lshl_add_u64 v[4:5], s[44:45], 0, v[0:1]
	v_lshlrev_b64 v[34:35], 2, v[2:3]
	s_lshl_b64 s[8:9], s[8:9], 15
	v_lshl_add_u64 v[22:23], v[4:5], 0, v[34:35]
	v_lshl_or_b32 v24, v38, 11, s8
	v_mov_b32_e32 v25, s9
	v_lshl_add_u64 v[30:31], v[22:23], 0, v[24:25]
	v_add_co_u32_e32 v10, vcc, s68, v30
	s_movk_i32 s2, 0x4000
	s_nop 0
	v_addc_co_u32_e32 v11, vcc, 0, v31, vcc
	s_waitcnt vmcnt(0)
	v_or_b32_e32 v6, 0x2000, v24
	v_mov_b32_e32 v7, s9
	v_add_co_u32_e32 v18, vcc, s2, v30
	s_mov_b64 s[0:1], 0
	v_lshl_add_u64 v[14:15], v[22:23], 0, v[6:7]
	v_addc_co_u32_e32 v19, vcc, 0, v31, vcc
	global_load_dword v26, v[30:31], off
	global_load_dword v27, v[30:31], off offset:512
	global_load_dword v28, v[30:31], off offset:1024
	global_load_dword v29, v[30:31], off offset:1536
	global_load_dword v5, v[30:31], off offset:1600
	global_load_dword v4, v[30:31], off offset:1088
	global_load_dword v3, v[30:31], off offset:576
	global_load_dword v2, v[30:31], off offset:64
	global_load_dword v6, v[14:15], off
	global_load_dword v7, v[10:11], off offset:512
	global_load_dword v8, v[10:11], off offset:1024
	global_load_dword v9, v[10:11], off offset:1536
	global_load_dword v13, v[10:11], off offset:1600
	global_load_dword v12, v[10:11], off offset:1088
	s_nop 0
	global_load_dword v11, v[10:11], off offset:576
	s_nop 0
	global_load_dword v10, v[14:15], off offset:64
	v_or_b32_e32 v14, 0x4000, v24
	v_mov_b32_e32 v15, s9
	v_or_b32_e32 v24, 0x6000, v24
	v_add_co_u32_e32 v30, vcc, s29, v30
	v_lshl_add_u64 v[32:33], v[22:23], 0, v[14:15]
	v_lshl_add_u64 v[36:37], v[22:23], 0, v[24:25]
	v_addc_co_u32_e32 v31, vcc, 0, v31, vcc
	global_load_dword v14, v[32:33], off
	global_load_dword v15, v[18:19], off offset:512
	global_load_dword v16, v[18:19], off offset:1024
	global_load_dword v17, v[18:19], off offset:1536
	global_load_dword v21, v[18:19], off offset:1600
	global_load_dword v20, v[18:19], off offset:1088
	s_nop 0
	global_load_dword v19, v[18:19], off offset:576
	s_nop 0
	global_load_dword v18, v[32:33], off offset:64
	global_load_dword v22, v[36:37], off
	global_load_dword v23, v[30:31], off offset:512
	global_load_dword v24, v[30:31], off offset:1024
	global_load_dword v25, v[30:31], off offset:1536
	s_nop 0
	global_load_dword v33, v[30:31], off offset:1600
	global_load_dword v32, v[30:31], off offset:1088
	s_nop 0
	global_load_dword v31, v[30:31], off offset:576
	s_nop 0
	global_load_dword v30, v[36:37], off offset:64
	s_lshl_b32 s8, s19, 12
	s_add_i32 s28, s8, 0x2000
	s_add_u32 s20, s90, s0
	s_addc_u32 s21, s91, s1
	s_ashr_i32 s23, s28, 6
	s_mul_i32 s0, s13, 0x3000000
	v_readlane_b32 s41, v252, 9
	s_add_u32 s40, s20, s0
	s_addc_u32 s41, s21, 0
	s_cmp_eq_u32 s13, 0
	s_cselect_b64 s[34:35], -1, 0
	s_add_u32 s8, s20, 0x2993d700
	s_addc_u32 s9, s21, 0
	s_add_u32 s0, s20, 0x2b13d700
	s_addc_u32 s1, s21, 0
	s_add_u32 s44, s20, 0x2c9fd700
	v_readlane_b32 s46, v252, 14
	s_addc_u32 s45, s21, 0
	v_readlane_b32 s47, v252, 15
	s_add_u32 s46, s20, 0x2c93d700
	v_and_b32_e32 v37, 63, v50
	s_addc_u32 s47, s21, 0
	v_or_b32_e32 v60, s28, v52
	s_lshl_b32 s28, s10, 9
	s_add_u32 s40, s40, s28
	v_lshlrev_b32_e32 v47, 7, v37
	v_lshlrev_b32_e32 v53, 11, v46
	v_and_b32_e32 v0, 48, v50
	s_addc_u32 s41, s41, 0
	v_add_u32_e32 v48, v53, v47
	v_lshlrev_b32_e32 v36, 2, v38
	v_lshl_add_u64 v[42:43], s[46:47], 0, v[0:1]
	v_lshl_add_u64 v[38:39], s[0:1], 0, v[0:1]
	v_lshl_add_u64 v[40:41], s[44:45], 0, v[0:1]
	v_lshl_add_u64 v[58:59], s[40:41], 0, v[0:1]
	v_lshlrev_b32_e32 v0, 12, v46
	s_movk_i32 s2, 0xf000
	v_add_u32_e32 v46, 0xfffff800, v48
	v_add3_u32 v44, v47, v0, s2
	v_ashrrev_i32_e32 v47, 31, v46
	v_ashrrev_i32_e32 v45, 31, v44
	v_lshl_add_u64 v[46:47], s[0:1], 0, v[46:47]
	v_cmp_gt_u32_e32 vcc, 64, v50
	v_cmp_gt_u32_e64 s[0:1], 2, v37
	v_lshlrev_b32_e32 v0, 7, v50
	v_lshl_or_b32 v56, v52, 6, v53
	v_readlane_b32 s42, v252, 10
	v_readlane_b32 s43, v252, 11
	v_lshl_add_u64 v[44:45], s[44:45], 0, v[44:45]
	v_ashrrev_i32_e32 v49, 31, v48
	s_and_b64 s[44:45], vcc, s[0:1]
	v_lshl_add_u64 v[50:51], s[46:47], 0, v[0:1]
	v_ashrrev_i32_e32 v57, 31, v56
	v_lshlrev_b32_e32 v0, 7, v52
	v_lshl_add_u64 v[34:35], v[58:59], 0, v[34:35]
	s_mov_b64 s[0:1], 0x2e1fd700
	s_mov_b32 s38, 63
	s_mov_b32 s19, 2
	v_cmp_lt_u32_e64 s[40:41], 15, v37
	v_cmp_lt_u32_e64 s[42:43], 31, v37
	v_lshl_add_u64 v[48:49], s[8:9], 0, v[48:49]
	v_lshl_add_u64 v[52:53], s[8:9], 0, v[0:1]
	v_lshl_add_u64 v[54:55], v[38:39], 0, v[0:1]
	v_lshl_add_u64 v[56:57], v[56:57], 1, v[40:41]
	v_lshl_add_u64 v[58:59], v[34:35], 0, s[0:1]
	v_mov_b32_e32 v61, 0
	v_lshlrev_b32_e32 v0, 1, v36
	v_readlane_b32 s48, v252, 16
	v_readlane_b32 s49, v252, 17
	v_readlane_b32 s50, v252, 18
	v_readlane_b32 s51, v252, 19
	v_readlane_b32 s52, v252, 20
	v_readlane_b32 s53, v252, 21
	v_readlane_b32 s54, v252, 22
	v_readlane_b32 s55, v252, 23
	s_and_b64 s[0:1], s[34:35], exec
	s_cselect_b32 s1, -1, 1
	s_mul_i32 s0, s1, 0x10000
	s_mul_i32 s8, s1, 0x800
	s_ashr_i32 s1, s1, 31
	v_mov_b32_e32 v154, s0
	v_mov_b32_e32 v157, s8
	v_mov_b32_e32 v155, s1
	v_cndmask_b32_e64 v154, v154, v157, s[44:45]

.LBB0_1470:
	s_andn2_saveexec_b64 s[46:47], s[46:47]
	s_ashr_i32 s9, s8, 31
	s_lshl_b64 s[48:49], s[8:9], 13
	v_lshl_add_u64 v[36:37], v[48:49], 0, s[48:49]
	v_mov_b64_e32 v[34:35], s[8:9]
	s_or_b64 exec, exec, s[46:47]
	s_add_i32 s1, s19, -2
	s_and_b64 s[8:9], s[34:35], exec
	s_cselect_b32 s1, s1, s38
	s_add_i32 s8, s1, s23
	s_lshl_b32 s8, s8, 2
	s_or_b32 s48, s8, s10
	s_lshl_b32 s8, s48, 1
	s_or_b32 s46, s8, s13
	v_lshlrev_b64 v[38:39], 8, v[34:35]
	s_ashr_i32 s47, s46, 31
	v_lshl_add_u64 v[38:39], v[50:51], 0, v[38:39]
	v_cndmask_b32_e64 v37, v37, v39, s[44:45]
	v_cndmask_b32_e64 v36, v36, v38, s[44:45]
	s_lshl_b64 s[8:9], s[46:47], 13
	v_add_co_u32_e32 v152, vcc, v36, v154
	s_nop 1
	v_addc_co_u32_e32 v153, vcc, v37, v155, vcc
	flat_load_dword v62, v[152:153] sc0 sc1
	v_add_co_u32_e32 v152, vcc, v152, v154
	s_nop 1
	v_addc_co_u32_e32 v153, vcc, v153, v155, vcc
	flat_load_dword v156, v[152:153] sc0 sc1
	s_waitcnt vmcnt(0)
	v_lshl_add_u64 v[36:37], v[52:53], 0, s[8:9]
	v_lshl_add_u64 v[40:41], v[36:37], 0, v[0:1]
	global_load_dwordx2 v[36:37], v[40:41], off
	global_load_dwordx2 v[38:39], v[40:41], off offset:32
	global_load_dwordx2 v[64:65], v[40:41], off offset:2048
	global_load_dwordx2 v[66:67], v[40:41], off offset:2080
	v_add_co_u32_e32 v126, vcc, s14, v40
	s_ashr_i32 s49, s48, 31
	s_nop 0
	v_addc_co_u32_e32 v127, vcc, 0, v41, vcc
	global_load_dwordx2 v[68:69], v[126:127], off
	global_load_dwordx2 v[70:71], v[126:127], off offset:32
	global_load_dwordx2 v[80:81], v[40:41], off offset:64
	global_load_dwordx2 v[82:83], v[40:41], off offset:96
	global_load_dwordx2 v[88:89], v[40:41], off offset:2112
	global_load_dwordx2 v[90:91], v[40:41], off offset:2144
	global_load_dwordx2 v[96:97], v[126:127], off offset:2048
	global_load_dwordx2 v[98:99], v[126:127], off offset:2080
	s_lshl_b64 s[48:49], s[48:49], 14
	s_lshl_b64 s[46:47], s[46:47], 8
	v_lshl_add_u64 v[140:141], v[56:57], 0, s[48:49]
	v_lshl_add_u64 v[148:149], v[42:43], 0, s[46:47]
	v_lshl_add_u64 v[40:41], v[54:55], 0, s[8:9]
	global_load_dwordx4 v[100:103], v[148:149], off
	global_load_dwordx4 v[104:107], v[40:41], off
	global_load_dwordx2 v[108:109], v[126:127], off offset:64
	global_load_dwordx2 v[110:111], v[126:127], off offset:96
	global_load_dwordx4 v[116:119], v[140:141], off
	global_load_dwordx2 v[124:125], v[126:127], off offset:2112
	s_nop 0
	global_load_dwordx2 v[126:127], v[126:127], off offset:2144
	v_cvt_pk_bf16_f32 v72, v26, v27
	v_cvt_pk_bf16_f32 v73, v28, v29
	v_cvt_pk_bf16_f32 v74, v6, v7
	v_cvt_pk_bf16_f32 v75, v8, v9
	v_cvt_pk_bf16_f32 v76, v2, v3
	v_cvt_pk_bf16_f32 v77, v4, v5
	v_cvt_pk_bf16_f32 v78, v10, v11
	v_cvt_pk_bf16_f32 v79, v12, v13
	v_cvt_pk_bf16_f32 v120, v14, v15
	v_cvt_pk_bf16_f32 v121, v16, v17
	v_cvt_pk_bf16_f32 v122, v22, v23
	v_cvt_pk_bf16_f32 v123, v24, v25
	v_cvt_pk_bf16_f32 v136, v18, v19
	v_cvt_pk_bf16_f32 v137, v20, v21
	v_cvt_pk_bf16_f32 v138, v30, v31
	v_cvt_pk_bf16_f32 v139, v32, v33
	global_load_dwordx4 v[128:131], v[140:141], off offset:64
	global_load_dwordx4 v[132:135], v[40:41], off offset:64
	s_cmp_lt_u32 s50, 63
	s_mov_b64 s[8:9], -1
	s_waitcnt vmcnt(0)
	v_mfma_f32_16x16x32_bf16 v[84:87], v[72:75], v[36:39], 0
	v_mul_f32_e64 v28, v28, v102
	v_mul_f32_e64 v29, v29, v103
	v_mfma_f32_16x16x32_bf16 v[36:39], v[76:79], v[36:39], 0
	v_mul_f32_e64 v26, v26, v100
	v_mul_f32_e64 v27, v27, v101
	v_pk_mul_f32 v[4:5], v[4:5], v[102:103]
	v_pk_mul_f32 v[2:3], v[2:3], v[100:101]
	v_mfma_f32_16x16x32_bf16 v[92:95], v[72:75], v[64:67], 0
	v_mfma_f32_16x16x32_bf16 v[64:67], v[76:79], v[64:67], 0
	v_mfma_f32_16x16x32_bf16 v[112:115], v[72:75], v[68:71], 0
	v_mfma_f32_16x16x32_bf16 v[68:71], v[76:79], v[68:71], 0
	v_mfma_f32_16x16x32_bf16 v[72:75], v[72:75], v[96:99], 0
	v_mfma_f32_16x16x32_bf16 v[76:79], v[76:79], v[96:99], 0
	global_load_dwordx4 v[96:99], v[148:149], off offset:64
	s_waitcnt vmcnt(0)
	v_pk_mul_f32 v[8:9], v[8:9], v[98:99]
	v_mfma_f32_16x16x32_bf16 v[84:87], v[120:123], v[80:83], v[84:87]
	v_mul_f32_e64 v6, v6, v96
	v_mul_f32_e64 v7, v7, v97
	v_pk_mul_f32 v[12:13], v[12:13], v[98:99]
	v_pk_mul_f32 v[10:11], v[10:11], v[96:97]
	v_mfma_f32_16x16x32_bf16 v[36:39], v[136:139], v[80:83], v[36:39]
	v_mfma_f32_16x16x32_bf16 v[80:83], v[120:123], v[88:91], v[92:95]
	s_nop 2
	global_load_dwordx4 v[92:95], v[140:141], off offset:2048
	s_nop 0
	global_load_dwordx4 v[140:143], v[140:141], off offset:2112
	s_nop 0
	global_load_dwordx4 v[144:147], v[40:41], off offset:2112
	v_mfma_f32_16x16x32_bf16 v[64:67], v[136:139], v[88:91], v[64:67]
	global_load_dwordx4 v[88:91], v[40:41], off offset:2048
	v_add_co_u32_e32 v40, vcc, s14, v40
	v_mfma_f32_16x16x32_bf16 v[112:115], v[120:123], v[108:111], v[112:115]
	s_nop 0
	v_addc_co_u32_e32 v41, vcc, 0, v41, vcc
	v_mfma_f32_16x16x32_bf16 v[68:71], v[136:139], v[108:111], v[68:71]
	v_mfma_f32_16x16x32_bf16 v[72:75], v[120:123], v[124:127], v[72:75]
	global_load_dwordx4 v[108:111], v[40:41], off
	global_load_dwordx4 v[120:123], v[148:149], off offset:128
	s_waitcnt vmcnt(0)
	v_pk_mul_f32 v[16:17], v[16:17], v[122:123]
	v_mfma_f32_16x16x32_bf16 v[76:79], v[136:139], v[124:127], v[76:79]
	global_load_dwordx4 v[124:127], v[40:41], off offset:64
	global_load_dwordx4 v[136:139], v[148:149], off offset:192
	global_load_dwordx4 v[100:103], v[40:41], off offset:2112
	v_pk_mul_f32 v[14:15], v[14:15], v[120:121]
	global_load_dwordx4 v[148:151], v[40:41], off offset:2048
	v_lshl_add_u32 v40, s1, 6, v60
	v_ashrrev_i32_e32 v41, 31, v40
	v_mfma_f32_16x16x32_bf16 v[26:29], v[104:107], v[116:119], v[26:29]
	v_mul_f32_e64 v20, v20, v122
	v_mul_f32_e64 v21, v21, v123
	v_pk_mul_f32 v[18:19], v[18:19], v[120:121]
	s_waitcnt vmcnt(0)
	v_pk_mul_f32 v[24:25], v[24:25], v[138:139]
	v_mfma_f32_16x16x32_bf16 v[2:5], v[104:107], v[92:95], v[2:5]
	v_lshlrev_b64 v[104:105], 11, v[40:41]
	v_lshl_add_u64 v[104:105], v[58:59], 0, v[104:105]
	global_store_dwordx4 v[104:105], v[36:39], off offset:64
	v_pk_mul_f32 v[22:23], v[22:23], v[136:137]
	v_pk_mul_f32 v[32:33], v[32:33], v[138:139]
	v_or_b32_e32 v36, 16, v40
	v_ashrrev_i32_e32 v37, 31, v36
	v_lshlrev_b64 v[36:37], 11, v[36:37]
	v_lshl_add_u64 v[36:37], v[58:59], 0, v[36:37]
	v_pk_mul_f32 v[30:31], v[30:31], v[136:137]
	v_mfma_f32_16x16x32_bf16 v[6:9], v[88:91], v[116:119], v[6:9]
	global_store_dwordx4 v[104:105], v[84:87], off
	global_store_dwordx4 v[36:37], v[80:83], off
	global_store_dwordx4 v[36:37], v[64:67], off offset:64
	v_or_b32_e32 v36, 32, v40
	v_mfma_f32_16x16x32_bf16 v[10:13], v[88:91], v[92:95], v[10:13]
	v_ashrrev_i32_e32 v37, 31, v36
	v_lshlrev_b64 v[36:37], 11, v[36:37]
	v_lshl_add_u64 v[36:37], v[58:59], 0, v[36:37]
	v_mfma_f32_16x16x32_bf16 v[14:17], v[108:111], v[116:119], v[14:17]
	global_store_dwordx4 v[36:37], v[112:115], off
	global_store_dwordx4 v[36:37], v[68:71], off offset:64
	v_or_b32_e32 v36, 48, v40
	v_mfma_f32_16x16x32_bf16 v[18:21], v[108:111], v[92:95], v[18:21]
	v_ashrrev_i32_e32 v37, 31, v36
	v_lshlrev_b64 v[36:37], 11, v[36:37]
	v_lshl_add_u64 v[36:37], v[58:59], 0, v[36:37]
	v_mfma_f32_16x16x32_bf16 v[22:25], v[148:151], v[116:119], v[22:25]
	global_store_dwordx4 v[36:37], v[72:75], off
	global_store_dwordx4 v[36:37], v[76:79], off offset:64
	v_mfma_f32_16x16x32_bf16 v[30:33], v[148:151], v[92:95], v[30:33]
	v_mfma_f32_16x16x32_bf16 v[26:29], v[132:135], v[128:131], v[26:29]
	v_mfma_f32_16x16x32_bf16 v[2:5], v[132:135], v[140:143], v[2:5]
	v_mfma_f32_16x16x32_bf16 v[6:9], v[144:147], v[128:131], v[6:9]
	v_mfma_f32_16x16x32_bf16 v[10:13], v[144:147], v[140:143], v[10:13]
	v_mfma_f32_16x16x32_bf16 v[14:17], v[124:127], v[128:131], v[14:17]
	v_mfma_f32_16x16x32_bf16 v[18:21], v[124:127], v[140:143], v[18:21]
	v_mfma_f32_16x16x32_bf16 v[22:25], v[100:103], v[128:131], v[22:25]
	v_mfma_f32_16x16x32_bf16 v[30:33], v[100:103], v[140:143], v[30:33]
	s_cbranch_scc1 .LBB0_1474
	s_add_i32 s52, s38, -2
	s_mov_b64 s[8:9], 0

.LBB0_1481:
	s_andn2_saveexec_b64 s[46:47], s[46:47]
	s_ashr_i32 s9, s8, 31
	s_lshl_b64 s[48:49], s[8:9], 13
	v_lshl_add_u64 v[36:37], v[48:49], 0, s[48:49]
	v_mov_b64_e32 v[38:39], s[8:9]
	s_or_b64 exec, exec, s[46:47]
	v_lshlrev_b64 v[38:39], 8, v[38:39]
	v_lshl_add_u64 v[38:39], v[50:51], 0, v[38:39]
	v_cndmask_b32_e64 v37, v37, v39, s[44:45]
	v_cndmask_b32_e64 v36, v36, v38, s[44:45]
	v_mov_b32_e32 v63, 0

.LBB0_1810:
	s_lshr_b32 s10, s9, 1
	s_and_b32 s10, s10, 0x78
	s_or_b32 s10, s10, s67
	s_waitcnt vmcnt(0)
	s_lshl_b32 s13, s10, 8
	s_lshl_b32 s6, s9, 7
	s_and_b32 s10, s6, 0x780
	s_and_b32 s7, s6, 0x7800
	s_and_b32 s19, s8, 0x780
	s_or_b32 s22, s75, s7
	s_mov_b32 s23, 0
	s_mov_b64 s[6:7], s[86:87]
	s_lshr_b32 s21, s13, 21
	s_lshl_b32 s20, s13, 11
	s_add_u32 s50, s70, s20
	s_addc_u32 s51, s71, s21
	s_add_u32 s52, s50, 0x8000
	s_addc_u32 s53, s51, 0
	s_add_u32 s54, s52, 0x8000
	s_addc_u32 s55, s53, 0
	s_add_u32 s56, s54, 0x8000
	s_addc_u32 s57, s55, 0
	s_lshr_b32 s21, s10, 21
	s_lshl_b32 s20, s10, 11
	s_add_u32 s58, s0, s20
	s_addc_u32 s59, s1, s21
	s_add_u32 s60, s58, 0x8000
	s_addc_u32 s61, s59, 0
	v_lshrrev_b32_e32 v246, 6, v179
	s_nop 0
	v_readfirstlane_b32 s63, v246
	v_and_b32_e32 v247, 63, v179
	v_lshrrev_b32_e32 v248, 3, v247
	v_and_b32_e32 v249, 7, v247
	v_lshrrev_b32_e32 v246, 1, v248
	v_lshrrev_b32_e32 v247, 2, v248
	v_xor_b32_e32 v0, v246, v247
	v_xor_b32_e32 v42, 5, v0
	v_xor_b32_e32 v0, v0, v249
	v_lshlrev_b32_e32 v0, 4, v0
	v_mov_b32_e32 v43, v0
	v_xor_b32_e32 v42, v42, v249
	v_lshlrev_b32_e32 v42, 4, v42
	v_mov_b32_e32 v114, v42
	s_lshl_b32 s81, s63, 6
	v_add_u32_e32 v246, s81, v248
	v_lshl_add_u32 v0, v246, 11, v0
	v_add_u32_e32 v246, 8, v246
	v_lshl_add_u32 v42, v246, 11, v42
	s_lshl_b32 s81, s63, 5
	v_add_u32_e32 v246, s81, v248
	v_lshl_add_u32 v43, v246, 11, v43
	v_add_u32_e32 v246, 8, v246
	v_lshl_add_u32 v114, v246, 11, v114
	v_and_b32_e32 v246, 15, v179
	v_bfe_u32 v247, v179, 4, 2
	v_lshrrev_b32_e32 v248, 1, v246
	v_add_u32_e32 v249, 4, v246
	v_bfe_u32 v249, v249, 3, 1
	v_xor_b32_e32 v248, v248, v249
	v_xor_b32_e32 v247, v247, v248
	v_lshlrev_b32_e32 v247, 4, v247
	v_lshl_add_u32 v122, v246, 7, v247
	s_lshl_b32 s81, s63, 13
	v_add_u32_e32 v115, s81, v122
	v_add_u32_e32 v122, 32768, v122
	v_xor_b32_e32 v116, 64, v115
	v_xor_b32_e32 v124, 64, v122
	s_lshl_b32 s46, s63, 13
	s_lshl_b32 s47, s63, 12
	s_add_u32 s47, s47, 32768
	v_mov_b32_e32 v174, 0
	v_mov_b32_e32 v175, 0
	v_mov_b32_e32 v176, 0
	v_mov_b32_e32 v177, 0
	v_mov_b32_e32 v170, 0
	v_mov_b32_e32 v171, 0
	v_mov_b32_e32 v172, 0
	v_mov_b32_e32 v173, 0
	v_mov_b32_e32 v166, 0
	v_mov_b32_e32 v167, 0
	v_mov_b32_e32 v168, 0
	v_mov_b32_e32 v169, 0
	v_mov_b32_e32 v162, 0
	v_mov_b32_e32 v163, 0
	v_mov_b32_e32 v164, 0
	v_mov_b32_e32 v165, 0
	v_mov_b32_e32 v158, 0
	v_mov_b32_e32 v159, 0
	v_mov_b32_e32 v160, 0
	v_mov_b32_e32 v161, 0
	v_mov_b32_e32 v154, 0
	v_mov_b32_e32 v155, 0
	v_mov_b32_e32 v156, 0
	v_mov_b32_e32 v157, 0
	v_mov_b32_e32 v150, 0
	v_mov_b32_e32 v151, 0
	v_mov_b32_e32 v152, 0
	v_mov_b32_e32 v153, 0
	v_mov_b32_e32 v138, 0
	v_mov_b32_e32 v139, 0
	v_mov_b32_e32 v140, 0
	v_mov_b32_e32 v141, 0
	v_mov_b32_e32 v134, 0
	v_mov_b32_e32 v135, 0
	v_mov_b32_e32 v136, 0
	v_mov_b32_e32 v137, 0
	v_mov_b32_e32 v130, 0
	v_mov_b32_e32 v131, 0
	v_mov_b32_e32 v132, 0
	v_mov_b32_e32 v133, 0
	v_mov_b32_e32 v126, 0
	v_mov_b32_e32 v127, 0
	v_mov_b32_e32 v128, 0
	v_mov_b32_e32 v129, 0
	v_mov_b32_e32 v118, 0
	v_mov_b32_e32 v119, 0
	v_mov_b32_e32 v120, 0
	v_mov_b32_e32 v121, 0
	v_mov_b32_e32 v110, 0
	v_mov_b32_e32 v111, 0
	v_mov_b32_e32 v112, 0
	v_mov_b32_e32 v113, 0
	v_mov_b32_e32 v106, 0
	v_mov_b32_e32 v107, 0
	v_mov_b32_e32 v108, 0
	v_mov_b32_e32 v109, 0
	v_mov_b32_e32 v102, 0
	v_mov_b32_e32 v103, 0
	v_mov_b32_e32 v104, 0
	v_mov_b32_e32 v105, 0
	v_mov_b32_e32 v98, 0
	v_mov_b32_e32 v99, 0
	v_mov_b32_e32 v100, 0
	v_mov_b32_e32 v101, 0
	v_mov_b32_e32 v86, 0
	v_mov_b32_e32 v87, 0
	v_mov_b32_e32 v88, 0
	v_mov_b32_e32 v89, 0
	v_mov_b32_e32 v82, 0
	v_mov_b32_e32 v83, 0
	v_mov_b32_e32 v84, 0
	v_mov_b32_e32 v85, 0
	v_mov_b32_e32 v78, 0
	v_mov_b32_e32 v79, 0
	v_mov_b32_e32 v80, 0
	v_mov_b32_e32 v81, 0
	v_mov_b32_e32 v74, 0
	v_mov_b32_e32 v75, 0
	v_mov_b32_e32 v76, 0
	v_mov_b32_e32 v77, 0
	v_mov_b32_e32 v70, 0
	v_mov_b32_e32 v71, 0
	v_mov_b32_e32 v72, 0
	v_mov_b32_e32 v73, 0
	v_mov_b32_e32 v58, 0
	v_mov_b32_e32 v59, 0
	v_mov_b32_e32 v60, 0
	v_mov_b32_e32 v61, 0
	v_mov_b32_e32 v54, 0
	v_mov_b32_e32 v55, 0
	v_mov_b32_e32 v56, 0
	v_mov_b32_e32 v57, 0
	v_mov_b32_e32 v50, 0
	v_mov_b32_e32 v51, 0
	v_mov_b32_e32 v52, 0
	v_mov_b32_e32 v53, 0
	v_mov_b32_e32 v46, 0
	v_mov_b32_e32 v47, 0
	v_mov_b32_e32 v48, 0
	v_mov_b32_e32 v49, 0
	v_mov_b32_e32 v34, 0
	v_mov_b32_e32 v35, 0
	v_mov_b32_e32 v36, 0
	v_mov_b32_e32 v37, 0
	v_mov_b32_e32 v30, 0
	v_mov_b32_e32 v31, 0
	v_mov_b32_e32 v32, 0
	v_mov_b32_e32 v33, 0
	v_mov_b32_e32 v26, 0
	v_mov_b32_e32 v27, 0
	v_mov_b32_e32 v28, 0
	v_mov_b32_e32 v29, 0
	v_mov_b32_e32 v22, 0
	v_mov_b32_e32 v23, 0
	v_mov_b32_e32 v24, 0
	v_mov_b32_e32 v25, 0
	v_mov_b32_e32 v18, 0
	v_mov_b32_e32 v19, 0
	v_mov_b32_e32 v20, 0
	v_mov_b32_e32 v21, 0
	v_mov_b32_e32 v6, 0
	v_mov_b32_e32 v7, 0
	v_mov_b32_e32 v8, 0
	v_mov_b32_e32 v9, 0
	v_mov_b32_e32 v2, 0
	v_mov_b32_e32 v3, 0
	v_mov_b32_e32 v4, 0
	v_mov_b32_e32 v5, 0
	s_barrier
	s_mov_b32 m0, s46
	s_nop 0
	global_load_lds_dwordx4 v0, s[50:51]
	s_add_u32 m0, s46, 1024
	s_nop 0
	global_load_lds_dwordx4 v42, s[50:51]
	s_add_u32 m0, s46, 2048
	s_nop 0
	global_load_lds_dwordx4 v0, s[52:53]
	s_add_u32 m0, s46, 3072
	s_nop 0
	global_load_lds_dwordx4 v42, s[52:53]
	s_add_u32 m0, s46, 4096
	s_nop 0
	global_load_lds_dwordx4 v0, s[54:55]
	s_add_u32 m0, s46, 5120
	s_nop 0
	global_load_lds_dwordx4 v42, s[54:55]
	s_add_u32 m0, s46, 6144
	s_nop 0
	global_load_lds_dwordx4 v0, s[56:57]
	s_add_u32 m0, s46, 7168
	s_nop 0
	global_load_lds_dwordx4 v42, s[56:57]
	s_mov_b32 m0, s47
	s_nop 0
	global_load_lds_dwordx4 v43, s[58:59]
	s_add_u32 m0, s47, 1024
	s_nop 0
	global_load_lds_dwordx4 v114, s[58:59]
	s_add_u32 m0, s47, 2048
	s_nop 0
	global_load_lds_dwordx4 v43, s[60:61]
	s_add_u32 m0, s47, 3072
	s_nop 0
	global_load_lds_dwordx4 v114, s[60:61]
	s_add_u32 s50, s50, 0x80
	s_addc_u32 s51, s51, 0
	s_add_u32 s52, s52, 0x80
	s_addc_u32 s53, s53, 0
	s_add_u32 s54, s54, 0x80
	s_addc_u32 s55, s55, 0
	s_add_u32 s56, s56, 0x80
	s_addc_u32 s57, s57, 0
	s_add_u32 s58, s58, 0x80
	s_addc_u32 s59, s59, 0
	s_add_u32 s60, s60, 0x80
	s_addc_u32 s61, s61, 0
	s_mov_b32 s49, 15
.Lg3_pq_loop:
	s_waitcnt vmcnt(0)
	s_barrier
	ds_read_b128 v[216:219], v115
	ds_read_b128 v[226:229], v115 offset:2048
	ds_read_b128 v[230:233], v115 offset:4096
	ds_read_b128 v[234:237], v115 offset:6144
	ds_read_b128 v[10:13], v122
	ds_read_b128 v[14:17], v122 offset:2048
	ds_read_b128 v[38:41], v122 offset:4096
	ds_read_b128 v[62:65], v122 offset:6144
	ds_read_b128 v[66:69], v122 offset:8192
	ds_read_b128 v[90:93], v122 offset:10240
	ds_read_b128 v[94:97], v122 offset:12288
	ds_read_b128 v[142:145], v122 offset:14336
	s_waitcnt lgkmcnt(7)
	v_mfma_f32_16x16x32_bf16 v[174:177], v[10:13], v[216:219], v[174:177]
	v_mfma_f32_16x16x32_bf16 v[134:137], v[10:13], v[226:229], v[134:137]
	v_mfma_f32_16x16x32_bf16 v[86:89], v[10:13], v[230:233], v[86:89]
	v_mfma_f32_16x16x32_bf16 v[46:49], v[10:13], v[234:237], v[46:49]
	ds_read_b128 v[146:149], v124
	ds_read_b128 v[180:183], v124 offset:2048
	ds_read_b128 v[184:187], v124 offset:4096
	ds_read_b128 v[188:191], v124 offset:6144
	ds_read_b128 v[192:195], v124 offset:8192
	ds_read_b128 v[196:199], v124 offset:10240
	ds_read_b128 v[200:203], v124 offset:12288
	ds_read_b128 v[204:207], v124 offset:14336
	ds_read_b128 v[238:241], v116
	ds_read_b128 v[242:245], v116 offset:2048
	ds_read_b128 v[246:249], v116 offset:4096
	ds_read_b128 v[10:13], v116 offset:6144
	s_waitcnt lgkmcnt(0)
	s_barrier
	s_mov_b32 m0, s46
	s_nop 0
	global_load_lds_dwordx4 v0, s[50:51]
	s_add_u32 m0, s46, 1024
	s_nop 0
	global_load_lds_dwordx4 v42, s[50:51]
	s_add_u32 m0, s46, 2048
	s_nop 0
	global_load_lds_dwordx4 v0, s[52:53]
	s_add_u32 m0, s46, 3072
	s_nop 0
	global_load_lds_dwordx4 v42, s[52:53]
	s_add_u32 m0, s46, 4096
	s_nop 0
	global_load_lds_dwordx4 v0, s[54:55]
	s_add_u32 m0, s46, 5120
	s_nop 0
	global_load_lds_dwordx4 v42, s[54:55]
	s_add_u32 m0, s46, 6144
	s_nop 0
	global_load_lds_dwordx4 v0, s[56:57]
	s_add_u32 m0, s46, 7168
	s_nop 0
	global_load_lds_dwordx4 v42, s[56:57]
	s_mov_b32 m0, s47
	s_nop 0
	global_load_lds_dwordx4 v43, s[58:59]
	s_add_u32 m0, s47, 1024
	s_nop 0
	global_load_lds_dwordx4 v114, s[58:59]
	s_add_u32 m0, s47, 2048
	s_nop 0
	global_load_lds_dwordx4 v43, s[60:61]
	s_add_u32 m0, s47, 3072
	s_nop 0
	global_load_lds_dwordx4 v114, s[60:61]
	s_add_u32 s50, s50, 0x80
	s_addc_u32 s51, s51, 0
	s_add_u32 s52, s52, 0x80
	s_addc_u32 s53, s53, 0
	s_add_u32 s54, s54, 0x80
	s_addc_u32 s55, s55, 0
	s_add_u32 s56, s56, 0x80
	s_addc_u32 s57, s57, 0
	s_add_u32 s58, s58, 0x80
	s_addc_u32 s59, s59, 0
	s_add_u32 s60, s60, 0x80
	s_addc_u32 s61, s61, 0
	v_mfma_f32_16x16x32_bf16 v[170:173], v[14:17], v[216:219], v[170:173]
	v_mfma_f32_16x16x32_bf16 v[130:133], v[14:17], v[226:229], v[130:133]
	v_mfma_f32_16x16x32_bf16 v[82:85], v[14:17], v[230:233], v[82:85]
	v_mfma_f32_16x16x32_bf16 v[34:37], v[14:17], v[234:237], v[34:37]
	v_mfma_f32_16x16x32_bf16 v[166:169], v[38:41], v[216:219], v[166:169]
	v_mfma_f32_16x16x32_bf16 v[126:129], v[38:41], v[226:229], v[126:129]
	v_mfma_f32_16x16x32_bf16 v[78:81], v[38:41], v[230:233], v[78:81]
	v_mfma_f32_16x16x32_bf16 v[30:33], v[38:41], v[234:237], v[30:33]
	v_mfma_f32_16x16x32_bf16 v[162:165], v[62:65], v[216:219], v[162:165]
	v_mfma_f32_16x16x32_bf16 v[118:121], v[62:65], v[226:229], v[118:121]
	v_mfma_f32_16x16x32_bf16 v[74:77], v[62:65], v[230:233], v[74:77]
	v_mfma_f32_16x16x32_bf16 v[26:29], v[62:65], v[234:237], v[26:29]
	v_mfma_f32_16x16x32_bf16 v[158:161], v[66:69], v[216:219], v[158:161]
	v_mfma_f32_16x16x32_bf16 v[110:113], v[66:69], v[226:229], v[110:113]
	v_mfma_f32_16x16x32_bf16 v[70:73], v[66:69], v[230:233], v[70:73]
	v_mfma_f32_16x16x32_bf16 v[22:25], v[66:69], v[234:237], v[22:25]
	v_mfma_f32_16x16x32_bf16 v[154:157], v[90:93], v[216:219], v[154:157]
	v_mfma_f32_16x16x32_bf16 v[106:109], v[90:93], v[226:229], v[106:109]
	v_mfma_f32_16x16x32_bf16 v[58:61], v[90:93], v[230:233], v[58:61]
	v_mfma_f32_16x16x32_bf16 v[18:21], v[90:93], v[234:237], v[18:21]
	v_mfma_f32_16x16x32_bf16 v[150:153], v[94:97], v[216:219], v[150:153]
	v_mfma_f32_16x16x32_bf16 v[102:105], v[94:97], v[226:229], v[102:105]
	v_mfma_f32_16x16x32_bf16 v[54:57], v[94:97], v[230:233], v[54:57]
	v_mfma_f32_16x16x32_bf16 v[6:9], v[94:97], v[234:237], v[6:9]
	v_mfma_f32_16x16x32_bf16 v[138:141], v[142:145], v[216:219], v[138:141]
	v_mfma_f32_16x16x32_bf16 v[98:101], v[142:145], v[226:229], v[98:101]
	v_mfma_f32_16x16x32_bf16 v[50:53], v[142:145], v[230:233], v[50:53]
	v_mfma_f32_16x16x32_bf16 v[2:5], v[142:145], v[234:237], v[2:5]
	v_mfma_f32_16x16x32_bf16 v[174:177], v[146:149], v[238:241], v[174:177]
	v_mfma_f32_16x16x32_bf16 v[134:137], v[146:149], v[242:245], v[134:137]
	v_mfma_f32_16x16x32_bf16 v[86:89], v[146:149], v[246:249], v[86:89]
	v_mfma_f32_16x16x32_bf16 v[46:49], v[146:149], v[10:13], v[46:49]
	v_mfma_f32_16x16x32_bf16 v[170:173], v[180:183], v[238:241], v[170:173]
	v_mfma_f32_16x16x32_bf16 v[130:133], v[180:183], v[242:245], v[130:133]
	v_mfma_f32_16x16x32_bf16 v[82:85], v[180:183], v[246:249], v[82:85]
	v_mfma_f32_16x16x32_bf16 v[34:37], v[180:183], v[10:13], v[34:37]
	v_mfma_f32_16x16x32_bf16 v[166:169], v[184:187], v[238:241], v[166:169]
	v_mfma_f32_16x16x32_bf16 v[126:129], v[184:187], v[242:245], v[126:129]
	v_mfma_f32_16x16x32_bf16 v[78:81], v[184:187], v[246:249], v[78:81]
	v_mfma_f32_16x16x32_bf16 v[30:33], v[184:187], v[10:13], v[30:33]
	v_mfma_f32_16x16x32_bf16 v[162:165], v[188:191], v[238:241], v[162:165]
	v_mfma_f32_16x16x32_bf16 v[118:121], v[188:191], v[242:245], v[118:121]
	v_mfma_f32_16x16x32_bf16 v[74:77], v[188:191], v[246:249], v[74:77]
	v_mfma_f32_16x16x32_bf16 v[26:29], v[188:191], v[10:13], v[26:29]
	v_mfma_f32_16x16x32_bf16 v[158:161], v[192:195], v[238:241], v[158:161]
	v_mfma_f32_16x16x32_bf16 v[110:113], v[192:195], v[242:245], v[110:113]
	v_mfma_f32_16x16x32_bf16 v[70:73], v[192:195], v[246:249], v[70:73]
	v_mfma_f32_16x16x32_bf16 v[22:25], v[192:195], v[10:13], v[22:25]
	v_mfma_f32_16x16x32_bf16 v[154:157], v[196:199], v[238:241], v[154:157]
	v_mfma_f32_16x16x32_bf16 v[106:109], v[196:199], v[242:245], v[106:109]
	v_mfma_f32_16x16x32_bf16 v[58:61], v[196:199], v[246:249], v[58:61]
	v_mfma_f32_16x16x32_bf16 v[18:21], v[196:199], v[10:13], v[18:21]
	v_mfma_f32_16x16x32_bf16 v[150:153], v[200:203], v[238:241], v[150:153]
	v_mfma_f32_16x16x32_bf16 v[102:105], v[200:203], v[242:245], v[102:105]
	v_mfma_f32_16x16x32_bf16 v[54:57], v[200:203], v[246:249], v[54:57]
	v_mfma_f32_16x16x32_bf16 v[6:9], v[200:203], v[10:13], v[6:9]
	v_mfma_f32_16x16x32_bf16 v[138:141], v[204:207], v[238:241], v[138:141]
	v_mfma_f32_16x16x32_bf16 v[98:101], v[204:207], v[242:245], v[98:101]
	v_mfma_f32_16x16x32_bf16 v[50:53], v[204:207], v[246:249], v[50:53]
	v_mfma_f32_16x16x32_bf16 v[2:5], v[204:207], v[10:13], v[2:5]
	s_sub_u32 s49, s49, 1
	s_cmp_lg_u32 s49, 0
	s_cbranch_scc1 .Lg3_pq_loop
	s_waitcnt vmcnt(0)
	s_barrier
	ds_read_b128 v[216:219], v115
	ds_read_b128 v[226:229], v115 offset:2048
	ds_read_b128 v[230:233], v115 offset:4096
	ds_read_b128 v[234:237], v115 offset:6144
	ds_read_b128 v[10:13], v122
	ds_read_b128 v[14:17], v122 offset:2048
	ds_read_b128 v[38:41], v122 offset:4096
	ds_read_b128 v[62:65], v122 offset:6144
	ds_read_b128 v[66:69], v122 offset:8192
	ds_read_b128 v[90:93], v122 offset:10240
	ds_read_b128 v[94:97], v122 offset:12288
	ds_read_b128 v[142:145], v122 offset:14336
	s_waitcnt lgkmcnt(7)
	v_mfma_f32_16x16x32_bf16 v[174:177], v[10:13], v[216:219], v[174:177]
	v_mfma_f32_16x16x32_bf16 v[134:137], v[10:13], v[226:229], v[134:137]
	v_mfma_f32_16x16x32_bf16 v[86:89], v[10:13], v[230:233], v[86:89]
	v_mfma_f32_16x16x32_bf16 v[46:49], v[10:13], v[234:237], v[46:49]
	ds_read_b128 v[146:149], v124
	ds_read_b128 v[180:183], v124 offset:2048
	ds_read_b128 v[184:187], v124 offset:4096
	ds_read_b128 v[188:191], v124 offset:6144
	ds_read_b128 v[192:195], v124 offset:8192
	ds_read_b128 v[196:199], v124 offset:10240
	ds_read_b128 v[200:203], v124 offset:12288
	ds_read_b128 v[204:207], v124 offset:14336
	ds_read_b128 v[238:241], v116
	ds_read_b128 v[242:245], v116 offset:2048
	ds_read_b128 v[246:249], v116 offset:4096
	ds_read_b128 v[10:13], v116 offset:6144
	s_waitcnt lgkmcnt(0)
	s_barrier
	v_mfma_f32_16x16x32_bf16 v[170:173], v[14:17], v[216:219], v[170:173]
	v_mfma_f32_16x16x32_bf16 v[130:133], v[14:17], v[226:229], v[130:133]
	v_mfma_f32_16x16x32_bf16 v[82:85], v[14:17], v[230:233], v[82:85]
	v_mfma_f32_16x16x32_bf16 v[34:37], v[14:17], v[234:237], v[34:37]
	v_mfma_f32_16x16x32_bf16 v[166:169], v[38:41], v[216:219], v[166:169]
	v_mfma_f32_16x16x32_bf16 v[126:129], v[38:41], v[226:229], v[126:129]
	v_mfma_f32_16x16x32_bf16 v[78:81], v[38:41], v[230:233], v[78:81]
	v_mfma_f32_16x16x32_bf16 v[30:33], v[38:41], v[234:237], v[30:33]
	v_mfma_f32_16x16x32_bf16 v[162:165], v[62:65], v[216:219], v[162:165]
	v_mfma_f32_16x16x32_bf16 v[118:121], v[62:65], v[226:229], v[118:121]
	v_mfma_f32_16x16x32_bf16 v[74:77], v[62:65], v[230:233], v[74:77]
	v_mfma_f32_16x16x32_bf16 v[26:29], v[62:65], v[234:237], v[26:29]
	v_mfma_f32_16x16x32_bf16 v[158:161], v[66:69], v[216:219], v[158:161]
	v_mfma_f32_16x16x32_bf16 v[110:113], v[66:69], v[226:229], v[110:113]
	v_mfma_f32_16x16x32_bf16 v[70:73], v[66:69], v[230:233], v[70:73]
	v_mfma_f32_16x16x32_bf16 v[22:25], v[66:69], v[234:237], v[22:25]
	v_mfma_f32_16x16x32_bf16 v[154:157], v[90:93], v[216:219], v[154:157]
	v_mfma_f32_16x16x32_bf16 v[106:109], v[90:93], v[226:229], v[106:109]
	v_mfma_f32_16x16x32_bf16 v[58:61], v[90:93], v[230:233], v[58:61]
	v_mfma_f32_16x16x32_bf16 v[18:21], v[90:93], v[234:237], v[18:21]
	v_mfma_f32_16x16x32_bf16 v[150:153], v[94:97], v[216:219], v[150:153]
	v_mfma_f32_16x16x32_bf16 v[102:105], v[94:97], v[226:229], v[102:105]
	v_mfma_f32_16x16x32_bf16 v[54:57], v[94:97], v[230:233], v[54:57]
	v_mfma_f32_16x16x32_bf16 v[6:9], v[94:97], v[234:237], v[6:9]
	v_mfma_f32_16x16x32_bf16 v[138:141], v[142:145], v[216:219], v[138:141]
	v_mfma_f32_16x16x32_bf16 v[98:101], v[142:145], v[226:229], v[98:101]
	v_mfma_f32_16x16x32_bf16 v[50:53], v[142:145], v[230:233], v[50:53]
	v_mfma_f32_16x16x32_bf16 v[2:5], v[142:145], v[234:237], v[2:5]
	v_mfma_f32_16x16x32_bf16 v[174:177], v[146:149], v[238:241], v[174:177]
	v_mfma_f32_16x16x32_bf16 v[134:137], v[146:149], v[242:245], v[134:137]
	v_mfma_f32_16x16x32_bf16 v[86:89], v[146:149], v[246:249], v[86:89]
	v_mfma_f32_16x16x32_bf16 v[46:49], v[146:149], v[10:13], v[46:49]
	v_mfma_f32_16x16x32_bf16 v[170:173], v[180:183], v[238:241], v[170:173]
	v_mfma_f32_16x16x32_bf16 v[130:133], v[180:183], v[242:245], v[130:133]
	v_mfma_f32_16x16x32_bf16 v[82:85], v[180:183], v[246:249], v[82:85]
	v_mfma_f32_16x16x32_bf16 v[34:37], v[180:183], v[10:13], v[34:37]
	v_mfma_f32_16x16x32_bf16 v[166:169], v[184:187], v[238:241], v[166:169]
	v_mfma_f32_16x16x32_bf16 v[126:129], v[184:187], v[242:245], v[126:129]
	v_mfma_f32_16x16x32_bf16 v[78:81], v[184:187], v[246:249], v[78:81]
	v_mfma_f32_16x16x32_bf16 v[30:33], v[184:187], v[10:13], v[30:33]
	v_mfma_f32_16x16x32_bf16 v[162:165], v[188:191], v[238:241], v[162:165]
	v_mfma_f32_16x16x32_bf16 v[118:121], v[188:191], v[242:245], v[118:121]
	v_mfma_f32_16x16x32_bf16 v[74:77], v[188:191], v[246:249], v[74:77]
	v_mfma_f32_16x16x32_bf16 v[26:29], v[188:191], v[10:13], v[26:29]
	v_mfma_f32_16x16x32_bf16 v[158:161], v[192:195], v[238:241], v[158:161]
	v_mfma_f32_16x16x32_bf16 v[110:113], v[192:195], v[242:245], v[110:113]
	v_mfma_f32_16x16x32_bf16 v[70:73], v[192:195], v[246:249], v[70:73]
	v_mfma_f32_16x16x32_bf16 v[22:25], v[192:195], v[10:13], v[22:25]
	v_mfma_f32_16x16x32_bf16 v[154:157], v[196:199], v[238:241], v[154:157]
	v_mfma_f32_16x16x32_bf16 v[106:109], v[196:199], v[242:245], v[106:109]
	v_mfma_f32_16x16x32_bf16 v[58:61], v[196:199], v[246:249], v[58:61]
	v_mfma_f32_16x16x32_bf16 v[18:21], v[196:199], v[10:13], v[18:21]
	v_mfma_f32_16x16x32_bf16 v[150:153], v[200:203], v[238:241], v[150:153]
	v_mfma_f32_16x16x32_bf16 v[102:105], v[200:203], v[242:245], v[102:105]
	v_mfma_f32_16x16x32_bf16 v[54:57], v[200:203], v[246:249], v[54:57]
	v_mfma_f32_16x16x32_bf16 v[6:9], v[200:203], v[10:13], v[6:9]
	v_mfma_f32_16x16x32_bf16 v[138:141], v[204:207], v[238:241], v[138:141]
	v_mfma_f32_16x16x32_bf16 v[98:101], v[204:207], v[242:245], v[98:101]
	v_mfma_f32_16x16x32_bf16 v[50:53], v[204:207], v[246:249], v[50:53]
	v_mfma_f32_16x16x32_bf16 v[2:5], v[204:207], v[10:13], v[2:5]
	s_branch .LBB0_1809

.Lu_cloop:
	s_waitcnt vmcnt(16)
	ds_write_b128 v168, v[2:5]
	ds_write_b128 v168, v[6:9] offset:1024
	s_waitcnt lgkmcnt(2)
	v_lshl_add_u32 v174, v150, 10, v166
	global_load_dwordx4 v[2:5], v174, s[50:51]
	v_lshl_add_u32 v175, v151, 10, v167
	global_load_dwordx4 v[6:9], v175, s[50:51]
	ds_read_b128 v[180:183], v169
	ds_read_b128 v[184:187], v170
	s_waitcnt vmcnt(16)
	ds_write_b128 v168, v[10:13]
	ds_write_b128 v168, v[14:17] offset:1024
	v_lshl_add_u32 v176, v152, 10, v166
	global_load_dwordx4 v[10:13], v176, s[50:51]
	v_lshl_add_u32 v177, v153, 10, v167
	global_load_dwordx4 v[14:17], v177, s[50:51]
	ds_read_b128 v[188:191], v169
	ds_read_b128 v[192:195], v170
	s_waitcnt lgkmcnt(4)
	v_mfma_f32_16x16x32_fp8_fp8 v[196:199], v[180:181], v[134:135], 0
	v_mfma_f32_16x16x32_fp8_fp8 v[196:199], v[182:183], v[136:137], v[196:199]
	v_mfma_f32_16x16x32_fp8_fp8 v[196:199], v[184:185], v[138:139], v[196:199]
	v_mfma_f32_16x16x32_fp8_fp8 v[196:199], v[186:187], v[140:141], v[196:199]
	s_waitcnt vmcnt(16)
	ds_write_b128 v168, v[18:21]
	ds_write_b128 v168, v[22:25] offset:1024
	v_lshl_add_u32 v174, v154, 10, v166
	global_load_dwordx4 v[18:21], v174, s[50:51]
	v_lshl_add_u32 v175, v155, 10, v167
	global_load_dwordx4 v[22:25], v175, s[50:51]
	ds_read_b128 v[180:183], v169
	ds_read_b128 v[184:187], v170
	s_waitcnt lgkmcnt(4)
	v_mfma_f32_16x16x32_fp8_fp8 v[200:203], v[188:189], v[134:135], 0
	v_mfma_f32_16x16x32_fp8_fp8 v[200:203], v[190:191], v[136:137], v[200:203]
	v_mfma_f32_16x16x32_fp8_fp8 v[200:203], v[192:193], v[138:139], v[200:203]
	v_mfma_f32_16x16x32_fp8_fp8 v[200:203], v[194:195], v[140:141], v[200:203]
	v_cndmask_b32_e64 v226, v196, v198, s[54:55]
	v_cndmask_b32_e64 v227, v197, v199, s[54:55]
	s_waitcnt vmcnt(16)
	ds_write_b128 v168, v[26:29]
	ds_write_b128 v168, v[30:33] offset:1024
	v_lshl_add_u32 v176, v156, 10, v166
	global_load_dwordx4 v[26:29], v176, s[50:51]
	v_lshl_add_u32 v177, v157, 10, v167
	global_load_dwordx4 v[30:33], v177, s[50:51]
	ds_read_b128 v[188:191], v169
	ds_read_b128 v[192:195], v170
	s_waitcnt lgkmcnt(4)
	v_mfma_f32_16x16x32_fp8_fp8 v[204:207], v[180:181], v[134:135], 0
	v_mfma_f32_16x16x32_fp8_fp8 v[204:207], v[182:183], v[136:137], v[204:207]
	v_mfma_f32_16x16x32_fp8_fp8 v[204:207], v[184:185], v[138:139], v[204:207]
	v_mfma_f32_16x16x32_fp8_fp8 v[204:207], v[186:187], v[140:141], v[204:207]
	v_cndmask_b32_e64 v228, v200, v202, s[54:55]
	v_cndmask_b32_e64 v229, v201, v203, s[54:55]
	v_cndmask_b32_e64 v230, v226, v228, s[56:57]
	v_cndmask_b32_e64 v231, v227, v229, s[56:57]
	s_waitcnt vmcnt(16)
	ds_write_b128 v168, v[34:37]
	ds_write_b128 v168, v[38:41] offset:1024
	v_lshl_add_u32 v174, v158, 10, v166
	global_load_dwordx4 v[34:37], v174, s[50:51]
	v_lshl_add_u32 v175, v159, 10, v167
	global_load_dwordx4 v[38:41], v175, s[50:51]
	ds_read_b128 v[180:183], v169
	ds_read_b128 v[184:187], v170
	s_waitcnt lgkmcnt(4)
	v_mfma_f32_16x16x32_fp8_fp8 v[216:219], v[188:189], v[134:135], 0
	v_mfma_f32_16x16x32_fp8_fp8 v[216:219], v[190:191], v[136:137], v[216:219]
	v_mfma_f32_16x16x32_fp8_fp8 v[216:219], v[192:193], v[138:139], v[216:219]
	v_mfma_f32_16x16x32_fp8_fp8 v[216:219], v[194:195], v[140:141], v[216:219]
	v_cndmask_b32_e64 v226, v204, v206, s[54:55]
	v_cndmask_b32_e64 v227, v205, v207, s[54:55]
	s_waitcnt vmcnt(16)
	ds_write_b128 v168, v[42:45]
	ds_write_b128 v168, v[46:49] offset:1024
	v_lshl_add_u32 v176, v160, 10, v166
	global_load_dwordx4 v[42:45], v176, s[50:51]
	v_lshl_add_u32 v177, v161, 10, v167
	global_load_dwordx4 v[46:49], v177, s[50:51]
	ds_read_b128 v[188:191], v169
	ds_read_b128 v[192:195], v170
	s_waitcnt lgkmcnt(4)
	v_mfma_f32_16x16x32_fp8_fp8 v[196:199], v[180:181], v[134:135], 0
	v_mfma_f32_16x16x32_fp8_fp8 v[196:199], v[182:183], v[136:137], v[196:199]
	v_mfma_f32_16x16x32_fp8_fp8 v[196:199], v[184:185], v[138:139], v[196:199]
	v_mfma_f32_16x16x32_fp8_fp8 v[196:199], v[186:187], v[140:141], v[196:199]
	v_cndmask_b32_e64 v228, v216, v218, s[54:55]
	v_cndmask_b32_e64 v229, v217, v219, s[54:55]
	v_cndmask_b32_e64 v232, v226, v228, s[56:57]
	v_cndmask_b32_e64 v233, v227, v229, s[56:57]
	s_waitcnt vmcnt(16)
	ds_write_b128 v168, v[50:53]
	ds_write_b128 v168, v[54:57] offset:1024
	v_lshl_add_u32 v174, v162, 10, v166
	global_load_dwordx4 v[50:53], v174, s[50:51]
	v_lshl_add_u32 v175, v163, 10, v167
	global_load_dwordx4 v[54:57], v175, s[50:51]
	ds_read_b128 v[180:183], v169
	ds_read_b128 v[184:187], v170
	s_waitcnt lgkmcnt(4)
	v_mfma_f32_16x16x32_fp8_fp8 v[200:203], v[188:189], v[134:135], 0
	v_mfma_f32_16x16x32_fp8_fp8 v[200:203], v[190:191], v[136:137], v[200:203]
	v_mfma_f32_16x16x32_fp8_fp8 v[200:203], v[192:193], v[138:139], v[200:203]
	v_mfma_f32_16x16x32_fp8_fp8 v[200:203], v[194:195], v[140:141], v[200:203]
	v_cndmask_b32_e64 v226, v196, v198, s[54:55]
	v_cndmask_b32_e64 v227, v197, v199, s[54:55]
	s_waitcnt vmcnt(16)
	ds_write_b128 v168, v[58:61]
	ds_write_b128 v168, v[62:65] offset:1024
	v_lshl_add_u32 v176, v164, 10, v166
	global_load_dwordx4 v[58:61], v176, s[50:51]
	v_lshl_add_u32 v177, v165, 10, v167
	global_load_dwordx4 v[62:65], v177, s[50:51]
	ds_read_b128 v[188:191], v169
	ds_read_b128 v[192:195], v170
	s_waitcnt lgkmcnt(4)
	v_mfma_f32_16x16x32_fp8_fp8 v[204:207], v[180:181], v[134:135], 0
	v_mfma_f32_16x16x32_fp8_fp8 v[204:207], v[182:183], v[136:137], v[204:207]
	v_mfma_f32_16x16x32_fp8_fp8 v[204:207], v[184:185], v[138:139], v[204:207]
	v_mfma_f32_16x16x32_fp8_fp8 v[204:207], v[186:187], v[140:141], v[204:207]
	v_cndmask_b32_e64 v228, v200, v202, s[54:55]
	v_cndmask_b32_e64 v229, v201, v203, s[54:55]
	v_cndmask_b32_e64 v234, v226, v228, s[56:57]
	v_cndmask_b32_e64 v235, v227, v229, s[56:57]
	s_waitcnt lgkmcnt(0)
	v_mfma_f32_16x16x32_fp8_fp8 v[216:219], v[188:189], v[134:135], 0
	v_mfma_f32_16x16x32_fp8_fp8 v[216:219], v[190:191], v[136:137], v[216:219]
	v_mfma_f32_16x16x32_fp8_fp8 v[216:219], v[192:193], v[138:139], v[216:219]
	v_mfma_f32_16x16x32_fp8_fp8 v[216:219], v[194:195], v[140:141], v[216:219]
	v_add_u32_e32 v0, 1024, v172
	ds_read2_b32 v[150:151], v0 offset0:0 offset1:8
	ds_read2_b32 v[152:153], v0 offset0:16 offset1:24
	ds_read2_b32 v[154:155], v0 offset0:32 offset1:40
	ds_read2_b32 v[156:157], v0 offset0:48 offset1:56
	ds_read2_b32 v[158:159], v0 offset0:64 offset1:72
	ds_read2_b32 v[160:161], v0 offset0:80 offset1:88
	ds_read2_b32 v[162:163], v0 offset0:96 offset1:104
	ds_read2_b32 v[164:165], v0 offset0:112 offset1:120
	v_add_u32_e32 v171, s80, v171
	global_load_dwordx4 v[134:137], v171, s[52:53]
	global_load_dwordx4 v[138:141], v171, s[52:53] offset:16
	v_cndmask_b32_e64 v226, v204, v206, s[54:55]
	v_cndmask_b32_e64 v227, v205, v207, s[54:55]
	v_cndmask_b32_e64 v228, v216, v218, s[54:55]
	v_cndmask_b32_e64 v229, v217, v219, s[54:55]
	v_cndmask_b32_e64 v236, v226, v228, s[56:57]
	v_cndmask_b32_e64 v237, v227, v229, s[56:57]
	v_cndmask_b32_e64 v226, v230, v232, s[58:59]
	v_cndmask_b32_e64 v228, v234, v236, s[58:59]
	v_cndmask_b32_e64 v227, v231, v233, s[58:59]
	v_cndmask_b32_e64 v229, v235, v237, s[58:59]
	v_cndmask_b32_e64 v226, v226, v228, s[60:61]
	v_cndmask_b32_e64 v227, v227, v229, s[60:61]
	v_add_f32_e32 v242, v242, v226
	v_add_f32_e32 v243, v243, v227
	s_waitcnt vmcnt(16)
	ds_write_b128 v168, v[2:5]
	ds_write_b128 v168, v[6:9] offset:1024
	s_waitcnt lgkmcnt(2)
	v_lshl_add_u32 v174, v150, 10, v166
	global_load_dwordx4 v[2:5], v174, s[50:51]
	v_lshl_add_u32 v175, v151, 10, v167
	global_load_dwordx4 v[6:9], v175, s[50:51]
	ds_read_b128 v[180:183], v169
	ds_read_b128 v[184:187], v170
	s_waitcnt vmcnt(16)
	ds_write_b128 v168, v[10:13]
	ds_write_b128 v168, v[14:17] offset:1024
	v_lshl_add_u32 v176, v152, 10, v166
	global_load_dwordx4 v[10:13], v176, s[50:51]
	v_lshl_add_u32 v177, v153, 10, v167
	global_load_dwordx4 v[14:17], v177, s[50:51]
	ds_read_b128 v[188:191], v169
	ds_read_b128 v[192:195], v170
	s_waitcnt lgkmcnt(4)
	v_mfma_f32_16x16x32_fp8_fp8 v[196:199], v[180:181], v[142:143], 0
	v_mfma_f32_16x16x32_fp8_fp8 v[196:199], v[182:183], v[144:145], v[196:199]
	v_mfma_f32_16x16x32_fp8_fp8 v[196:199], v[184:185], v[146:147], v[196:199]
	v_mfma_f32_16x16x32_fp8_fp8 v[196:199], v[186:187], v[148:149], v[196:199]
	s_waitcnt vmcnt(16)
	ds_write_b128 v168, v[18:21]
	ds_write_b128 v168, v[22:25] offset:1024
	v_lshl_add_u32 v174, v154, 10, v166
	global_load_dwordx4 v[18:21], v174, s[50:51]
	v_lshl_add_u32 v175, v155, 10, v167
	global_load_dwordx4 v[22:25], v175, s[50:51]
	ds_read_b128 v[180:183], v169
	ds_read_b128 v[184:187], v170
	s_waitcnt lgkmcnt(4)
	v_mfma_f32_16x16x32_fp8_fp8 v[200:203], v[188:189], v[142:143], 0
	v_mfma_f32_16x16x32_fp8_fp8 v[200:203], v[190:191], v[144:145], v[200:203]
	v_mfma_f32_16x16x32_fp8_fp8 v[200:203], v[192:193], v[146:147], v[200:203]
	v_mfma_f32_16x16x32_fp8_fp8 v[200:203], v[194:195], v[148:149], v[200:203]
	v_cndmask_b32_e64 v226, v196, v198, s[54:55]
	v_cndmask_b32_e64 v227, v197, v199, s[54:55]
	s_waitcnt vmcnt(16)
	ds_write_b128 v168, v[26:29]
	ds_write_b128 v168, v[30:33] offset:1024
	v_lshl_add_u32 v176, v156, 10, v166
	global_load_dwordx4 v[26:29], v176, s[50:51]
	v_lshl_add_u32 v177, v157, 10, v167
	global_load_dwordx4 v[30:33], v177, s[50:51]
	ds_read_b128 v[188:191], v169
	ds_read_b128 v[192:195], v170
	s_waitcnt lgkmcnt(4)
	v_mfma_f32_16x16x32_fp8_fp8 v[204:207], v[180:181], v[142:143], 0
	v_mfma_f32_16x16x32_fp8_fp8 v[204:207], v[182:183], v[144:145], v[204:207]
	v_mfma_f32_16x16x32_fp8_fp8 v[204:207], v[184:185], v[146:147], v[204:207]
	v_mfma_f32_16x16x32_fp8_fp8 v[204:207], v[186:187], v[148:149], v[204:207]
	v_cndmask_b32_e64 v228, v200, v202, s[54:55]
	v_cndmask_b32_e64 v229, v201, v203, s[54:55]
	v_cndmask_b32_e64 v230, v226, v228, s[56:57]
	v_cndmask_b32_e64 v231, v227, v229, s[56:57]
	s_waitcnt vmcnt(16)
	ds_write_b128 v168, v[34:37]
	ds_write_b128 v168, v[38:41] offset:1024
	v_lshl_add_u32 v174, v158, 10, v166
	global_load_dwordx4 v[34:37], v174, s[50:51]
	v_lshl_add_u32 v175, v159, 10, v167
	global_load_dwordx4 v[38:41], v175, s[50:51]
	ds_read_b128 v[180:183], v169
	ds_read_b128 v[184:187], v170
	s_waitcnt lgkmcnt(4)
	v_mfma_f32_16x16x32_fp8_fp8 v[216:219], v[188:189], v[142:143], 0
	v_mfma_f32_16x16x32_fp8_fp8 v[216:219], v[190:191], v[144:145], v[216:219]
	v_mfma_f32_16x16x32_fp8_fp8 v[216:219], v[192:193], v[146:147], v[216:219]
	v_mfma_f32_16x16x32_fp8_fp8 v[216:219], v[194:195], v[148:149], v[216:219]
	v_cndmask_b32_e64 v226, v204, v206, s[54:55]
	v_cndmask_b32_e64 v227, v205, v207, s[54:55]
	s_waitcnt vmcnt(16)
	ds_write_b128 v168, v[42:45]
	ds_write_b128 v168, v[46:49] offset:1024
	v_lshl_add_u32 v176, v160, 10, v166
	global_load_dwordx4 v[42:45], v176, s[50:51]
	v_lshl_add_u32 v177, v161, 10, v167
	global_load_dwordx4 v[46:49], v177, s[50:51]
	ds_read_b128 v[188:191], v169
	ds_read_b128 v[192:195], v170
	s_waitcnt lgkmcnt(4)
	v_mfma_f32_16x16x32_fp8_fp8 v[196:199], v[180:181], v[142:143], 0
	v_mfma_f32_16x16x32_fp8_fp8 v[196:199], v[182:183], v[144:145], v[196:199]
	v_mfma_f32_16x16x32_fp8_fp8 v[196:199], v[184:185], v[146:147], v[196:199]
	v_mfma_f32_16x16x32_fp8_fp8 v[196:199], v[186:187], v[148:149], v[196:199]
	v_cndmask_b32_e64 v228, v216, v218, s[54:55]
	v_cndmask_b32_e64 v229, v217, v219, s[54:55]
	v_cndmask_b32_e64 v232, v226, v228, s[56:57]
	v_cndmask_b32_e64 v233, v227, v229, s[56:57]
	s_waitcnt vmcnt(16)
	ds_write_b128 v168, v[50:53]
	ds_write_b128 v168, v[54:57] offset:1024
	v_lshl_add_u32 v174, v162, 10, v166
	global_load_dwordx4 v[50:53], v174, s[50:51]
	v_lshl_add_u32 v175, v163, 10, v167
	global_load_dwordx4 v[54:57], v175, s[50:51]
	ds_read_b128 v[180:183], v169
	ds_read_b128 v[184:187], v170
	s_waitcnt lgkmcnt(4)
	v_mfma_f32_16x16x32_fp8_fp8 v[200:203], v[188:189], v[142:143], 0
	v_mfma_f32_16x16x32_fp8_fp8 v[200:203], v[190:191], v[144:145], v[200:203]
	v_mfma_f32_16x16x32_fp8_fp8 v[200:203], v[192:193], v[146:147], v[200:203]
	v_mfma_f32_16x16x32_fp8_fp8 v[200:203], v[194:195], v[148:149], v[200:203]
	v_cndmask_b32_e64 v226, v196, v198, s[54:55]
	v_cndmask_b32_e64 v227, v197, v199, s[54:55]
	s_waitcnt vmcnt(16)
	ds_write_b128 v168, v[58:61]
	ds_write_b128 v168, v[62:65] offset:1024
	v_lshl_add_u32 v176, v164, 10, v166
	global_load_dwordx4 v[58:61], v176, s[50:51]
	v_lshl_add_u32 v177, v165, 10, v167
	global_load_dwordx4 v[62:65], v177, s[50:51]
	ds_read_b128 v[188:191], v169
	ds_read_b128 v[192:195], v170
	s_waitcnt lgkmcnt(4)
	v_mfma_f32_16x16x32_fp8_fp8 v[204:207], v[180:181], v[142:143], 0
	v_mfma_f32_16x16x32_fp8_fp8 v[204:207], v[182:183], v[144:145], v[204:207]
	v_mfma_f32_16x16x32_fp8_fp8 v[204:207], v[184:185], v[146:147], v[204:207]
	v_mfma_f32_16x16x32_fp8_fp8 v[204:207], v[186:187], v[148:149], v[204:207]
	v_cndmask_b32_e64 v228, v200, v202, s[54:55]
	v_cndmask_b32_e64 v229, v201, v203, s[54:55]
	v_cndmask_b32_e64 v234, v226, v228, s[56:57]
	v_cndmask_b32_e64 v235, v227, v229, s[56:57]
	s_waitcnt lgkmcnt(0)
	v_mfma_f32_16x16x32_fp8_fp8 v[216:219], v[188:189], v[142:143], 0
	v_mfma_f32_16x16x32_fp8_fp8 v[216:219], v[190:191], v[144:145], v[216:219]
	v_mfma_f32_16x16x32_fp8_fp8 v[216:219], v[192:193], v[146:147], v[216:219]
	v_mfma_f32_16x16x32_fp8_fp8 v[216:219], v[194:195], v[148:149], v[216:219]
	v_add_u32_e32 v0, 1536, v172
	ds_read2_b32 v[150:151], v0 offset0:0 offset1:8
	ds_read2_b32 v[152:153], v0 offset0:16 offset1:24
	ds_read2_b32 v[154:155], v0 offset0:32 offset1:40
	ds_read2_b32 v[156:157], v0 offset0:48 offset1:56
	ds_read2_b32 v[158:159], v0 offset0:64 offset1:72
	ds_read2_b32 v[160:161], v0 offset0:80 offset1:88
	ds_read2_b32 v[162:163], v0 offset0:96 offset1:104
	ds_read2_b32 v[164:165], v0 offset0:112 offset1:120
	v_add_u32_e32 v171, s80, v171
	global_load_dwordx4 v[142:145], v171, s[52:53]
	global_load_dwordx4 v[146:149], v171, s[52:53] offset:16
	v_cndmask_b32_e64 v226, v204, v206, s[54:55]
	v_cndmask_b32_e64 v227, v205, v207, s[54:55]
	v_cndmask_b32_e64 v228, v216, v218, s[54:55]
	v_cndmask_b32_e64 v229, v217, v219, s[54:55]
	v_cndmask_b32_e64 v236, v226, v228, s[56:57]
	v_cndmask_b32_e64 v237, v227, v229, s[56:57]
	v_cndmask_b32_e64 v226, v230, v232, s[58:59]
	v_cndmask_b32_e64 v228, v234, v236, s[58:59]
	v_cndmask_b32_e64 v227, v231, v233, s[58:59]
	v_cndmask_b32_e64 v229, v235, v237, s[58:59]
	v_cndmask_b32_e64 v226, v226, v228, s[60:61]
	v_cndmask_b32_e64 v227, v227, v229, s[60:61]
	v_add_f32_e32 v244, v244, v226
	v_add_f32_e32 v245, v245, v227
	s_waitcnt vmcnt(16)
	ds_write_b128 v168, v[2:5]
	ds_write_b128 v168, v[6:9] offset:1024
	s_waitcnt lgkmcnt(2)
	v_lshl_add_u32 v174, v150, 10, v166
	global_load_dwordx4 v[2:5], v174, s[50:51]
	v_lshl_add_u32 v175, v151, 10, v167
	global_load_dwordx4 v[6:9], v175, s[50:51]
	ds_read_b128 v[180:183], v169
	ds_read_b128 v[184:187], v170
	s_waitcnt vmcnt(16)
	ds_write_b128 v168, v[10:13]
	ds_write_b128 v168, v[14:17] offset:1024
	v_lshl_add_u32 v176, v152, 10, v166
	global_load_dwordx4 v[10:13], v176, s[50:51]
	v_lshl_add_u32 v177, v153, 10, v167
	global_load_dwordx4 v[14:17], v177, s[50:51]
	ds_read_b128 v[188:191], v169
	ds_read_b128 v[192:195], v170
	s_waitcnt lgkmcnt(4)
	v_mfma_f32_16x16x32_fp8_fp8 v[196:199], v[180:181], v[134:135], 0
	v_mfma_f32_16x16x32_fp8_fp8 v[196:199], v[182:183], v[136:137], v[196:199]
	v_mfma_f32_16x16x32_fp8_fp8 v[196:199], v[184:185], v[138:139], v[196:199]
	v_mfma_f32_16x16x32_fp8_fp8 v[196:199], v[186:187], v[140:141], v[196:199]
	s_waitcnt vmcnt(16)
	ds_write_b128 v168, v[18:21]
	ds_write_b128 v168, v[22:25] offset:1024
	v_lshl_add_u32 v174, v154, 10, v166
	global_load_dwordx4 v[18:21], v174, s[50:51]
	v_lshl_add_u32 v175, v155, 10, v167
	global_load_dwordx4 v[22:25], v175, s[50:51]
	ds_read_b128 v[180:183], v169
	ds_read_b128 v[184:187], v170
	s_waitcnt lgkmcnt(4)
	v_mfma_f32_16x16x32_fp8_fp8 v[200:203], v[188:189], v[134:135], 0
	v_mfma_f32_16x16x32_fp8_fp8 v[200:203], v[190:191], v[136:137], v[200:203]
	v_mfma_f32_16x16x32_fp8_fp8 v[200:203], v[192:193], v[138:139], v[200:203]
	v_mfma_f32_16x16x32_fp8_fp8 v[200:203], v[194:195], v[140:141], v[200:203]
	v_cndmask_b32_e64 v226, v196, v198, s[54:55]
	v_cndmask_b32_e64 v227, v197, v199, s[54:55]
	s_waitcnt vmcnt(16)
	ds_write_b128 v168, v[26:29]
	ds_write_b128 v168, v[30:33] offset:1024
	v_lshl_add_u32 v176, v156, 10, v166
	global_load_dwordx4 v[26:29], v176, s[50:51]
	v_lshl_add_u32 v177, v157, 10, v167
	global_load_dwordx4 v[30:33], v177, s[50:51]
	ds_read_b128 v[188:191], v169
	ds_read_b128 v[192:195], v170
	s_waitcnt lgkmcnt(4)
	v_mfma_f32_16x16x32_fp8_fp8 v[204:207], v[180:181], v[134:135], 0
	v_mfma_f32_16x16x32_fp8_fp8 v[204:207], v[182:183], v[136:137], v[204:207]
	v_mfma_f32_16x16x32_fp8_fp8 v[204:207], v[184:185], v[138:139], v[204:207]
	v_mfma_f32_16x16x32_fp8_fp8 v[204:207], v[186:187], v[140:141], v[204:207]
	v_cndmask_b32_e64 v228, v200, v202, s[54:55]
	v_cndmask_b32_e64 v229, v201, v203, s[54:55]
	v_cndmask_b32_e64 v230, v226, v228, s[56:57]
	v_cndmask_b32_e64 v231, v227, v229, s[56:57]
	s_waitcnt vmcnt(16)
	ds_write_b128 v168, v[34:37]
	ds_write_b128 v168, v[38:41] offset:1024
	v_lshl_add_u32 v174, v158, 10, v166
	global_load_dwordx4 v[34:37], v174, s[50:51]
	v_lshl_add_u32 v175, v159, 10, v167
	global_load_dwordx4 v[38:41], v175, s[50:51]
	ds_read_b128 v[180:183], v169
	ds_read_b128 v[184:187], v170
	s_waitcnt lgkmcnt(4)
	v_mfma_f32_16x16x32_fp8_fp8 v[216:219], v[188:189], v[134:135], 0
	v_mfma_f32_16x16x32_fp8_fp8 v[216:219], v[190:191], v[136:137], v[216:219]
	v_mfma_f32_16x16x32_fp8_fp8 v[216:219], v[192:193], v[138:139], v[216:219]
	v_mfma_f32_16x16x32_fp8_fp8 v[216:219], v[194:195], v[140:141], v[216:219]
	v_cndmask_b32_e64 v226, v204, v206, s[54:55]
	v_cndmask_b32_e64 v227, v205, v207, s[54:55]
	s_waitcnt vmcnt(16)
	ds_write_b128 v168, v[42:45]
	ds_write_b128 v168, v[46:49] offset:1024
	v_lshl_add_u32 v176, v160, 10, v166
	global_load_dwordx4 v[42:45], v176, s[50:51]
	v_lshl_add_u32 v177, v161, 10, v167
	global_load_dwordx4 v[46:49], v177, s[50:51]
	ds_read_b128 v[188:191], v169
	ds_read_b128 v[192:195], v170
	s_waitcnt lgkmcnt(4)
	v_mfma_f32_16x16x32_fp8_fp8 v[196:199], v[180:181], v[134:135], 0
	v_mfma_f32_16x16x32_fp8_fp8 v[196:199], v[182:183], v[136:137], v[196:199]
	v_mfma_f32_16x16x32_fp8_fp8 v[196:199], v[184:185], v[138:139], v[196:199]
	v_mfma_f32_16x16x32_fp8_fp8 v[196:199], v[186:187], v[140:141], v[196:199]
	v_cndmask_b32_e64 v228, v216, v218, s[54:55]
	v_cndmask_b32_e64 v229, v217, v219, s[54:55]
	v_cndmask_b32_e64 v232, v226, v228, s[56:57]
	v_cndmask_b32_e64 v233, v227, v229, s[56:57]
	s_waitcnt vmcnt(16)
	ds_write_b128 v168, v[50:53]
	ds_write_b128 v168, v[54:57] offset:1024
	v_lshl_add_u32 v174, v162, 10, v166
	global_load_dwordx4 v[50:53], v174, s[50:51]
	v_lshl_add_u32 v175, v163, 10, v167
	global_load_dwordx4 v[54:57], v175, s[50:51]
	ds_read_b128 v[180:183], v169
	ds_read_b128 v[184:187], v170
	s_waitcnt lgkmcnt(4)
	v_mfma_f32_16x16x32_fp8_fp8 v[200:203], v[188:189], v[134:135], 0
	v_mfma_f32_16x16x32_fp8_fp8 v[200:203], v[190:191], v[136:137], v[200:203]
	v_mfma_f32_16x16x32_fp8_fp8 v[200:203], v[192:193], v[138:139], v[200:203]
	v_mfma_f32_16x16x32_fp8_fp8 v[200:203], v[194:195], v[140:141], v[200:203]
	v_cndmask_b32_e64 v226, v196, v198, s[54:55]
	v_cndmask_b32_e64 v227, v197, v199, s[54:55]
	s_waitcnt vmcnt(16)
	ds_write_b128 v168, v[58:61]
	ds_write_b128 v168, v[62:65] offset:1024
	v_lshl_add_u32 v176, v164, 10, v166
	global_load_dwordx4 v[58:61], v176, s[50:51]
	v_lshl_add_u32 v177, v165, 10, v167
	global_load_dwordx4 v[62:65], v177, s[50:51]
	ds_read_b128 v[188:191], v169
	ds_read_b128 v[192:195], v170
	s_waitcnt lgkmcnt(4)
	v_mfma_f32_16x16x32_fp8_fp8 v[204:207], v[180:181], v[134:135], 0
	v_mfma_f32_16x16x32_fp8_fp8 v[204:207], v[182:183], v[136:137], v[204:207]
	v_mfma_f32_16x16x32_fp8_fp8 v[204:207], v[184:185], v[138:139], v[204:207]
	v_mfma_f32_16x16x32_fp8_fp8 v[204:207], v[186:187], v[140:141], v[204:207]
	v_cndmask_b32_e64 v228, v200, v202, s[54:55]
	v_cndmask_b32_e64 v229, v201, v203, s[54:55]
	v_cndmask_b32_e64 v234, v226, v228, s[56:57]
	v_cndmask_b32_e64 v235, v227, v229, s[56:57]
	s_waitcnt lgkmcnt(0)
	v_mfma_f32_16x16x32_fp8_fp8 v[216:219], v[188:189], v[134:135], 0
	v_mfma_f32_16x16x32_fp8_fp8 v[216:219], v[190:191], v[136:137], v[216:219]
	v_mfma_f32_16x16x32_fp8_fp8 v[216:219], v[192:193], v[138:139], v[216:219]
	v_mfma_f32_16x16x32_fp8_fp8 v[216:219], v[194:195], v[140:141], v[216:219]
	v_add_u32_e32 v0, 2048, v172
	ds_read2_b32 v[150:151], v0 offset0:0 offset1:8
	ds_read2_b32 v[152:153], v0 offset0:16 offset1:24
	ds_read2_b32 v[154:155], v0 offset0:32 offset1:40
	ds_read2_b32 v[156:157], v0 offset0:48 offset1:56
	ds_read2_b32 v[158:159], v0 offset0:64 offset1:72
	ds_read2_b32 v[160:161], v0 offset0:80 offset1:88
	ds_read2_b32 v[162:163], v0 offset0:96 offset1:104
	ds_read2_b32 v[164:165], v0 offset0:112 offset1:120
	v_add_u32_e32 v171, s80, v171
	global_load_dwordx4 v[134:137], v171, s[52:53]
	global_load_dwordx4 v[138:141], v171, s[52:53] offset:16
	v_cndmask_b32_e64 v226, v204, v206, s[54:55]
	v_cndmask_b32_e64 v227, v205, v207, s[54:55]
	v_cndmask_b32_e64 v228, v216, v218, s[54:55]
	v_cndmask_b32_e64 v229, v217, v219, s[54:55]
	v_cndmask_b32_e64 v236, v226, v228, s[56:57]
	v_cndmask_b32_e64 v237, v227, v229, s[56:57]
	v_cndmask_b32_e64 v226, v230, v232, s[58:59]
	v_cndmask_b32_e64 v228, v234, v236, s[58:59]
	v_cndmask_b32_e64 v227, v231, v233, s[58:59]
	v_cndmask_b32_e64 v229, v235, v237, s[58:59]
	v_cndmask_b32_e64 v226, v226, v228, s[60:61]
	v_cndmask_b32_e64 v227, v227, v229, s[60:61]
	v_add_f32_e32 v246, v246, v226
	v_add_f32_e32 v247, v247, v227
	s_waitcnt vmcnt(16)
	ds_write_b128 v168, v[2:5]
	ds_write_b128 v168, v[6:9] offset:1024
	s_waitcnt lgkmcnt(2)
	v_lshl_add_u32 v174, v150, 10, v166
	global_load_dwordx4 v[2:5], v174, s[50:51]
	v_lshl_add_u32 v175, v151, 10, v167
	global_load_dwordx4 v[6:9], v175, s[50:51]
	ds_read_b128 v[180:183], v169
	ds_read_b128 v[184:187], v170
	s_waitcnt vmcnt(16)
	ds_write_b128 v168, v[10:13]
	ds_write_b128 v168, v[14:17] offset:1024
	v_lshl_add_u32 v176, v152, 10, v166
	global_load_dwordx4 v[10:13], v176, s[50:51]
	v_lshl_add_u32 v177, v153, 10, v167
	global_load_dwordx4 v[14:17], v177, s[50:51]
	ds_read_b128 v[188:191], v169
	ds_read_b128 v[192:195], v170
	s_waitcnt lgkmcnt(4)
	v_mfma_f32_16x16x32_fp8_fp8 v[196:199], v[180:181], v[142:143], 0
	v_mfma_f32_16x16x32_fp8_fp8 v[196:199], v[182:183], v[144:145], v[196:199]
	v_mfma_f32_16x16x32_fp8_fp8 v[196:199], v[184:185], v[146:147], v[196:199]
	v_mfma_f32_16x16x32_fp8_fp8 v[196:199], v[186:187], v[148:149], v[196:199]
	s_waitcnt vmcnt(16)
	ds_write_b128 v168, v[18:21]
	ds_write_b128 v168, v[22:25] offset:1024
	v_lshl_add_u32 v174, v154, 10, v166
	global_load_dwordx4 v[18:21], v174, s[50:51]
	v_lshl_add_u32 v175, v155, 10, v167
	global_load_dwordx4 v[22:25], v175, s[50:51]
	ds_read_b128 v[180:183], v169
	ds_read_b128 v[184:187], v170
	s_waitcnt lgkmcnt(4)
	v_mfma_f32_16x16x32_fp8_fp8 v[200:203], v[188:189], v[142:143], 0
	v_mfma_f32_16x16x32_fp8_fp8 v[200:203], v[190:191], v[144:145], v[200:203]
	v_mfma_f32_16x16x32_fp8_fp8 v[200:203], v[192:193], v[146:147], v[200:203]
	v_mfma_f32_16x16x32_fp8_fp8 v[200:203], v[194:195], v[148:149], v[200:203]
	v_cndmask_b32_e64 v226, v196, v198, s[54:55]
	v_cndmask_b32_e64 v227, v197, v199, s[54:55]
	s_waitcnt vmcnt(16)
	ds_write_b128 v168, v[26:29]
	ds_write_b128 v168, v[30:33] offset:1024
	v_lshl_add_u32 v176, v156, 10, v166
	global_load_dwordx4 v[26:29], v176, s[50:51]
	v_lshl_add_u32 v177, v157, 10, v167
	global_load_dwordx4 v[30:33], v177, s[50:51]
	ds_read_b128 v[188:191], v169
	ds_read_b128 v[192:195], v170
	s_waitcnt lgkmcnt(4)
	v_mfma_f32_16x16x32_fp8_fp8 v[204:207], v[180:181], v[142:143], 0
	v_mfma_f32_16x16x32_fp8_fp8 v[204:207], v[182:183], v[144:145], v[204:207]
	v_mfma_f32_16x16x32_fp8_fp8 v[204:207], v[184:185], v[146:147], v[204:207]
	v_mfma_f32_16x16x32_fp8_fp8 v[204:207], v[186:187], v[148:149], v[204:207]
	v_cndmask_b32_e64 v228, v200, v202, s[54:55]
	v_cndmask_b32_e64 v229, v201, v203, s[54:55]
	v_cndmask_b32_e64 v230, v226, v228, s[56:57]
	v_cndmask_b32_e64 v231, v227, v229, s[56:57]
	s_waitcnt vmcnt(16)
	ds_write_b128 v168, v[34:37]
	ds_write_b128 v168, v[38:41] offset:1024
	v_lshl_add_u32 v174, v158, 10, v166
	global_load_dwordx4 v[34:37], v174, s[50:51]
	v_lshl_add_u32 v175, v159, 10, v167
	global_load_dwordx4 v[38:41], v175, s[50:51]
	ds_read_b128 v[180:183], v169
	ds_read_b128 v[184:187], v170
	s_waitcnt lgkmcnt(4)
	v_mfma_f32_16x16x32_fp8_fp8 v[216:219], v[188:189], v[142:143], 0
	v_mfma_f32_16x16x32_fp8_fp8 v[216:219], v[190:191], v[144:145], v[216:219]
	v_mfma_f32_16x16x32_fp8_fp8 v[216:219], v[192:193], v[146:147], v[216:219]
	v_mfma_f32_16x16x32_fp8_fp8 v[216:219], v[194:195], v[148:149], v[216:219]
	v_cndmask_b32_e64 v226, v204, v206, s[54:55]
	v_cndmask_b32_e64 v227, v205, v207, s[54:55]
	s_waitcnt vmcnt(16)
	ds_write_b128 v168, v[42:45]
	ds_write_b128 v168, v[46:49] offset:1024
	v_lshl_add_u32 v176, v160, 10, v166
	global_load_dwordx4 v[42:45], v176, s[50:51]
	v_lshl_add_u32 v177, v161, 10, v167
	global_load_dwordx4 v[46:49], v177, s[50:51]
	ds_read_b128 v[188:191], v169
	ds_read_b128 v[192:195], v170
	s_waitcnt lgkmcnt(4)
	v_mfma_f32_16x16x32_fp8_fp8 v[196:199], v[180:181], v[142:143], 0
	v_mfma_f32_16x16x32_fp8_fp8 v[196:199], v[182:183], v[144:145], v[196:199]
	v_mfma_f32_16x16x32_fp8_fp8 v[196:199], v[184:185], v[146:147], v[196:199]
	v_mfma_f32_16x16x32_fp8_fp8 v[196:199], v[186:187], v[148:149], v[196:199]
	v_cndmask_b32_e64 v228, v216, v218, s[54:55]
	v_cndmask_b32_e64 v229, v217, v219, s[54:55]
	v_cndmask_b32_e64 v232, v226, v228, s[56:57]
	v_cndmask_b32_e64 v233, v227, v229, s[56:57]
	s_waitcnt vmcnt(16)
	ds_write_b128 v168, v[50:53]
	ds_write_b128 v168, v[54:57] offset:1024
	v_lshl_add_u32 v174, v162, 10, v166
	global_load_dwordx4 v[50:53], v174, s[50:51]
	v_lshl_add_u32 v175, v163, 10, v167
	global_load_dwordx4 v[54:57], v175, s[50:51]
	ds_read_b128 v[180:183], v169
	ds_read_b128 v[184:187], v170
	s_waitcnt lgkmcnt(4)
	v_mfma_f32_16x16x32_fp8_fp8 v[200:203], v[188:189], v[142:143], 0
	v_mfma_f32_16x16x32_fp8_fp8 v[200:203], v[190:191], v[144:145], v[200:203]
	v_mfma_f32_16x16x32_fp8_fp8 v[200:203], v[192:193], v[146:147], v[200:203]
	v_mfma_f32_16x16x32_fp8_fp8 v[200:203], v[194:195], v[148:149], v[200:203]
	v_cndmask_b32_e64 v226, v196, v198, s[54:55]
	v_cndmask_b32_e64 v227, v197, v199, s[54:55]
	s_waitcnt vmcnt(16)
	ds_write_b128 v168, v[58:61]
	ds_write_b128 v168, v[62:65] offset:1024
	v_lshl_add_u32 v176, v164, 10, v166
	global_load_dwordx4 v[58:61], v176, s[50:51]
	v_lshl_add_u32 v177, v165, 10, v167
	global_load_dwordx4 v[62:65], v177, s[50:51]
	ds_read_b128 v[188:191], v169
	ds_read_b128 v[192:195], v170
	s_waitcnt lgkmcnt(4)
	v_mfma_f32_16x16x32_fp8_fp8 v[204:207], v[180:181], v[142:143], 0
	v_mfma_f32_16x16x32_fp8_fp8 v[204:207], v[182:183], v[144:145], v[204:207]
	v_mfma_f32_16x16x32_fp8_fp8 v[204:207], v[184:185], v[146:147], v[204:207]
	v_mfma_f32_16x16x32_fp8_fp8 v[204:207], v[186:187], v[148:149], v[204:207]
	v_cndmask_b32_e64 v228, v200, v202, s[54:55]
	v_cndmask_b32_e64 v229, v201, v203, s[54:55]
	v_cndmask_b32_e64 v234, v226, v228, s[56:57]
	v_cndmask_b32_e64 v235, v227, v229, s[56:57]
	s_waitcnt lgkmcnt(0)
	v_mfma_f32_16x16x32_fp8_fp8 v[216:219], v[188:189], v[142:143], 0
	v_mfma_f32_16x16x32_fp8_fp8 v[216:219], v[190:191], v[144:145], v[216:219]
	v_mfma_f32_16x16x32_fp8_fp8 v[216:219], v[192:193], v[146:147], v[216:219]
	v_mfma_f32_16x16x32_fp8_fp8 v[216:219], v[194:195], v[148:149], v[216:219]
	v_add_u32_e32 v0, 2560, v172
	ds_read2_b32 v[150:151], v0 offset0:0 offset1:8
	ds_read2_b32 v[152:153], v0 offset0:16 offset1:24
	ds_read2_b32 v[154:155], v0 offset0:32 offset1:40
	ds_read2_b32 v[156:157], v0 offset0:48 offset1:56
	ds_read2_b32 v[158:159], v0 offset0:64 offset1:72
	ds_read2_b32 v[160:161], v0 offset0:80 offset1:88
	ds_read2_b32 v[162:163], v0 offset0:96 offset1:104
	ds_read2_b32 v[164:165], v0 offset0:112 offset1:120
	v_add_u32_e32 v171, s80, v171
	global_load_dwordx4 v[142:145], v171, s[52:53]
	global_load_dwordx4 v[146:149], v171, s[52:53] offset:16
	v_cndmask_b32_e64 v226, v204, v206, s[54:55]
	v_cndmask_b32_e64 v227, v205, v207, s[54:55]
	v_cndmask_b32_e64 v228, v216, v218, s[54:55]
	v_cndmask_b32_e64 v229, v217, v219, s[54:55]
	v_cndmask_b32_e64 v236, v226, v228, s[56:57]
	v_cndmask_b32_e64 v237, v227, v229, s[56:57]
	v_cndmask_b32_e64 v226, v230, v232, s[58:59]
	v_cndmask_b32_e64 v228, v234, v236, s[58:59]
	v_cndmask_b32_e64 v227, v231, v233, s[58:59]
	v_cndmask_b32_e64 v229, v235, v237, s[58:59]
	v_cndmask_b32_e64 v226, v226, v228, s[60:61]
	v_cndmask_b32_e64 v227, v227, v229, s[60:61]
	v_add_f32_e32 v248, v248, v226
	v_add_f32_e32 v249, v249, v227
	s_waitcnt vmcnt(16)
	ds_write_b128 v168, v[2:5]
	ds_write_b128 v168, v[6:9] offset:1024
	s_waitcnt lgkmcnt(2)
	v_lshl_add_u32 v174, v150, 10, v166
	global_load_dwordx4 v[2:5], v174, s[50:51]
	v_lshl_add_u32 v175, v151, 10, v167
	global_load_dwordx4 v[6:9], v175, s[50:51]
	ds_read_b128 v[180:183], v169
	ds_read_b128 v[184:187], v170
	s_waitcnt vmcnt(16)
	ds_write_b128 v168, v[10:13]
	ds_write_b128 v168, v[14:17] offset:1024
	v_lshl_add_u32 v176, v152, 10, v166
	global_load_dwordx4 v[10:13], v176, s[50:51]
	v_lshl_add_u32 v177, v153, 10, v167
	global_load_dwordx4 v[14:17], v177, s[50:51]
	ds_read_b128 v[188:191], v169
	ds_read_b128 v[192:195], v170
	s_waitcnt lgkmcnt(4)
	v_mfma_f32_16x16x32_fp8_fp8 v[196:199], v[180:181], v[134:135], 0
	v_mfma_f32_16x16x32_fp8_fp8 v[196:199], v[182:183], v[136:137], v[196:199]
	v_mfma_f32_16x16x32_fp8_fp8 v[196:199], v[184:185], v[138:139], v[196:199]
	v_mfma_f32_16x16x32_fp8_fp8 v[196:199], v[186:187], v[140:141], v[196:199]
	s_waitcnt vmcnt(16)
	ds_write_b128 v168, v[18:21]
	ds_write_b128 v168, v[22:25] offset:1024
	v_lshl_add_u32 v174, v154, 10, v166
	global_load_dwordx4 v[18:21], v174, s[50:51]
	v_lshl_add_u32 v175, v155, 10, v167
	global_load_dwordx4 v[22:25], v175, s[50:51]
	ds_read_b128 v[180:183], v169
	ds_read_b128 v[184:187], v170
	s_waitcnt lgkmcnt(4)
	v_mfma_f32_16x16x32_fp8_fp8 v[200:203], v[188:189], v[134:135], 0
	v_mfma_f32_16x16x32_fp8_fp8 v[200:203], v[190:191], v[136:137], v[200:203]
	v_mfma_f32_16x16x32_fp8_fp8 v[200:203], v[192:193], v[138:139], v[200:203]
	v_mfma_f32_16x16x32_fp8_fp8 v[200:203], v[194:195], v[140:141], v[200:203]
	v_cndmask_b32_e64 v226, v196, v198, s[54:55]
	v_cndmask_b32_e64 v227, v197, v199, s[54:55]
	s_waitcnt vmcnt(16)
	ds_write_b128 v168, v[26:29]
	ds_write_b128 v168, v[30:33] offset:1024
	v_lshl_add_u32 v176, v156, 10, v166
	global_load_dwordx4 v[26:29], v176, s[50:51]
	v_lshl_add_u32 v177, v157, 10, v167
	global_load_dwordx4 v[30:33], v177, s[50:51]
	ds_read_b128 v[188:191], v169
	ds_read_b128 v[192:195], v170
	s_waitcnt lgkmcnt(4)
	v_mfma_f32_16x16x32_fp8_fp8 v[204:207], v[180:181], v[134:135], 0
	v_mfma_f32_16x16x32_fp8_fp8 v[204:207], v[182:183], v[136:137], v[204:207]
	v_mfma_f32_16x16x32_fp8_fp8 v[204:207], v[184:185], v[138:139], v[204:207]
	v_mfma_f32_16x16x32_fp8_fp8 v[204:207], v[186:187], v[140:141], v[204:207]
	v_cndmask_b32_e64 v228, v200, v202, s[54:55]
	v_cndmask_b32_e64 v229, v201, v203, s[54:55]
	v_cndmask_b32_e64 v230, v226, v228, s[56:57]
	v_cndmask_b32_e64 v231, v227, v229, s[56:57]
	s_waitcnt vmcnt(16)
	ds_write_b128 v168, v[34:37]
	ds_write_b128 v168, v[38:41] offset:1024
	v_lshl_add_u32 v174, v158, 10, v166
	global_load_dwordx4 v[34:37], v174, s[50:51]
	v_lshl_add_u32 v175, v159, 10, v167
	global_load_dwordx4 v[38:41], v175, s[50:51]
	ds_read_b128 v[180:183], v169
	ds_read_b128 v[184:187], v170
	s_waitcnt lgkmcnt(4)
	v_mfma_f32_16x16x32_fp8_fp8 v[216:219], v[188:189], v[134:135], 0
	v_mfma_f32_16x16x32_fp8_fp8 v[216:219], v[190:191], v[136:137], v[216:219]
	v_mfma_f32_16x16x32_fp8_fp8 v[216:219], v[192:193], v[138:139], v[216:219]
	v_mfma_f32_16x16x32_fp8_fp8 v[216:219], v[194:195], v[140:141], v[216:219]
	v_cndmask_b32_e64 v226, v204, v206, s[54:55]
	v_cndmask_b32_e64 v227, v205, v207, s[54:55]
	s_waitcnt vmcnt(16)
	ds_write_b128 v168, v[42:45]
	ds_write_b128 v168, v[46:49] offset:1024
	v_lshl_add_u32 v176, v160, 10, v166
	global_load_dwordx4 v[42:45], v176, s[50:51]
	v_lshl_add_u32 v177, v161, 10, v167
	global_load_dwordx4 v[46:49], v177, s[50:51]
	ds_read_b128 v[188:191], v169
	ds_read_b128 v[192:195], v170
	s_waitcnt lgkmcnt(4)
	v_mfma_f32_16x16x32_fp8_fp8 v[196:199], v[180:181], v[134:135], 0
	v_mfma_f32_16x16x32_fp8_fp8 v[196:199], v[182:183], v[136:137], v[196:199]
	v_mfma_f32_16x16x32_fp8_fp8 v[196:199], v[184:185], v[138:139], v[196:199]
	v_mfma_f32_16x16x32_fp8_fp8 v[196:199], v[186:187], v[140:141], v[196:199]
	v_cndmask_b32_e64 v228, v216, v218, s[54:55]
	v_cndmask_b32_e64 v229, v217, v219, s[54:55]
	v_cndmask_b32_e64 v232, v226, v228, s[56:57]
	v_cndmask_b32_e64 v233, v227, v229, s[56:57]
	s_waitcnt vmcnt(16)
	ds_write_b128 v168, v[50:53]
	ds_write_b128 v168, v[54:57] offset:1024
	v_lshl_add_u32 v174, v162, 10, v166
	global_load_dwordx4 v[50:53], v174, s[50:51]
	v_lshl_add_u32 v175, v163, 10, v167
	global_load_dwordx4 v[54:57], v175, s[50:51]
	ds_read_b128 v[180:183], v169
	ds_read_b128 v[184:187], v170
	s_waitcnt lgkmcnt(4)
	v_mfma_f32_16x16x32_fp8_fp8 v[200:203], v[188:189], v[134:135], 0
	v_mfma_f32_16x16x32_fp8_fp8 v[200:203], v[190:191], v[136:137], v[200:203]
	v_mfma_f32_16x16x32_fp8_fp8 v[200:203], v[192:193], v[138:139], v[200:203]
	v_mfma_f32_16x16x32_fp8_fp8 v[200:203], v[194:195], v[140:141], v[200:203]
	v_cndmask_b32_e64 v226, v196, v198, s[54:55]
	v_cndmask_b32_e64 v227, v197, v199, s[54:55]
	s_waitcnt vmcnt(16)
	ds_write_b128 v168, v[58:61]
	ds_write_b128 v168, v[62:65] offset:1024
	v_lshl_add_u32 v176, v164, 10, v166
	global_load_dwordx4 v[58:61], v176, s[50:51]
	v_lshl_add_u32 v177, v165, 10, v167
	global_load_dwordx4 v[62:65], v177, s[50:51]
	ds_read_b128 v[188:191], v169
	ds_read_b128 v[192:195], v170
	s_waitcnt lgkmcnt(4)
	v_mfma_f32_16x16x32_fp8_fp8 v[204:207], v[180:181], v[134:135], 0
	v_mfma_f32_16x16x32_fp8_fp8 v[204:207], v[182:183], v[136:137], v[204:207]
	v_mfma_f32_16x16x32_fp8_fp8 v[204:207], v[184:185], v[138:139], v[204:207]
	v_mfma_f32_16x16x32_fp8_fp8 v[204:207], v[186:187], v[140:141], v[204:207]
	v_cndmask_b32_e64 v228, v200, v202, s[54:55]
	v_cndmask_b32_e64 v229, v201, v203, s[54:55]
	v_cndmask_b32_e64 v234, v226, v228, s[56:57]
	v_cndmask_b32_e64 v235, v227, v229, s[56:57]
	s_waitcnt lgkmcnt(0)
	v_mfma_f32_16x16x32_fp8_fp8 v[216:219], v[188:189], v[134:135], 0
	v_mfma_f32_16x16x32_fp8_fp8 v[216:219], v[190:191], v[136:137], v[216:219]
	v_mfma_f32_16x16x32_fp8_fp8 v[216:219], v[192:193], v[138:139], v[216:219]
	v_mfma_f32_16x16x32_fp8_fp8 v[216:219], v[194:195], v[140:141], v[216:219]
	v_add_u32_e32 v0, 3072, v172
	ds_read2_b32 v[150:151], v0 offset0:0 offset1:8
	ds_read2_b32 v[152:153], v0 offset0:16 offset1:24
	ds_read2_b32 v[154:155], v0 offset0:32 offset1:40
	ds_read2_b32 v[156:157], v0 offset0:48 offset1:56
	ds_read2_b32 v[158:159], v0 offset0:64 offset1:72
	ds_read2_b32 v[160:161], v0 offset0:80 offset1:88
	ds_read2_b32 v[162:163], v0 offset0:96 offset1:104
	ds_read2_b32 v[164:165], v0 offset0:112 offset1:120
	v_add_u32_e32 v171, s80, v171
	global_load_dwordx4 v[134:137], v171, s[52:53]
	global_load_dwordx4 v[138:141], v171, s[52:53] offset:16
	v_cndmask_b32_e64 v226, v204, v206, s[54:55]
	v_cndmask_b32_e64 v227, v205, v207, s[54:55]
	v_cndmask_b32_e64 v228, v216, v218, s[54:55]
	v_cndmask_b32_e64 v229, v217, v219, s[54:55]
	v_cndmask_b32_e64 v236, v226, v228, s[56:57]
	v_cndmask_b32_e64 v237, v227, v229, s[56:57]
	v_cndmask_b32_e64 v226, v230, v232, s[58:59]
	v_cndmask_b32_e64 v228, v234, v236, s[58:59]
	v_cndmask_b32_e64 v227, v231, v233, s[58:59]
	v_cndmask_b32_e64 v229, v235, v237, s[58:59]
	v_cndmask_b32_e64 v226, v226, v228, s[60:61]
	v_cndmask_b32_e64 v227, v227, v229, s[60:61]
	v_add_f32_e32 v238, v238, v226
	v_add_f32_e32 v239, v239, v227
	s_waitcnt vmcnt(16)
	ds_write_b128 v168, v[2:5]
	ds_write_b128 v168, v[6:9] offset:1024
	s_waitcnt lgkmcnt(2)
	v_lshl_add_u32 v174, v150, 10, v166
	global_load_dwordx4 v[2:5], v174, s[50:51]
	v_lshl_add_u32 v175, v151, 10, v167
	global_load_dwordx4 v[6:9], v175, s[50:51]
	ds_read_b128 v[180:183], v169
	ds_read_b128 v[184:187], v170
	s_waitcnt vmcnt(16)
	ds_write_b128 v168, v[10:13]
	ds_write_b128 v168, v[14:17] offset:1024
	v_lshl_add_u32 v176, v152, 10, v166
	global_load_dwordx4 v[10:13], v176, s[50:51]
	v_lshl_add_u32 v177, v153, 10, v167
	global_load_dwordx4 v[14:17], v177, s[50:51]
	ds_read_b128 v[188:191], v169
	ds_read_b128 v[192:195], v170
	s_waitcnt lgkmcnt(4)
	v_mfma_f32_16x16x32_fp8_fp8 v[196:199], v[180:181], v[142:143], 0
	v_mfma_f32_16x16x32_fp8_fp8 v[196:199], v[182:183], v[144:145], v[196:199]
	v_mfma_f32_16x16x32_fp8_fp8 v[196:199], v[184:185], v[146:147], v[196:199]
	v_mfma_f32_16x16x32_fp8_fp8 v[196:199], v[186:187], v[148:149], v[196:199]
	s_waitcnt vmcnt(16)
	ds_write_b128 v168, v[18:21]
	ds_write_b128 v168, v[22:25] offset:1024
	v_lshl_add_u32 v174, v154, 10, v166
	global_load_dwordx4 v[18:21], v174, s[50:51]
	v_lshl_add_u32 v175, v155, 10, v167
	global_load_dwordx4 v[22:25], v175, s[50:51]
	ds_read_b128 v[180:183], v169
	ds_read_b128 v[184:187], v170
	s_waitcnt lgkmcnt(4)
	v_mfma_f32_16x16x32_fp8_fp8 v[200:203], v[188:189], v[142:143], 0
	v_mfma_f32_16x16x32_fp8_fp8 v[200:203], v[190:191], v[144:145], v[200:203]
	v_mfma_f32_16x16x32_fp8_fp8 v[200:203], v[192:193], v[146:147], v[200:203]
	v_mfma_f32_16x16x32_fp8_fp8 v[200:203], v[194:195], v[148:149], v[200:203]
	v_cndmask_b32_e64 v226, v196, v198, s[54:55]
	v_cndmask_b32_e64 v227, v197, v199, s[54:55]
	s_waitcnt vmcnt(16)
	ds_write_b128 v168, v[26:29]
	ds_write_b128 v168, v[30:33] offset:1024
	v_lshl_add_u32 v176, v156, 10, v166
	global_load_dwordx4 v[26:29], v176, s[50:51]
	v_lshl_add_u32 v177, v157, 10, v167
	global_load_dwordx4 v[30:33], v177, s[50:51]
	ds_read_b128 v[188:191], v169
	ds_read_b128 v[192:195], v170
	s_waitcnt lgkmcnt(4)
	v_mfma_f32_16x16x32_fp8_fp8 v[204:207], v[180:181], v[142:143], 0
	v_mfma_f32_16x16x32_fp8_fp8 v[204:207], v[182:183], v[144:145], v[204:207]
	v_mfma_f32_16x16x32_fp8_fp8 v[204:207], v[184:185], v[146:147], v[204:207]
	v_mfma_f32_16x16x32_fp8_fp8 v[204:207], v[186:187], v[148:149], v[204:207]
	v_cndmask_b32_e64 v228, v200, v202, s[54:55]
	v_cndmask_b32_e64 v229, v201, v203, s[54:55]
	v_cndmask_b32_e64 v230, v226, v228, s[56:57]
	v_cndmask_b32_e64 v231, v227, v229, s[56:57]
	s_waitcnt vmcnt(16)
	ds_write_b128 v168, v[34:37]
	ds_write_b128 v168, v[38:41] offset:1024
	v_lshl_add_u32 v174, v158, 10, v166
	global_load_dwordx4 v[34:37], v174, s[50:51]
	v_lshl_add_u32 v175, v159, 10, v167
	global_load_dwordx4 v[38:41], v175, s[50:51]
	ds_read_b128 v[180:183], v169
	ds_read_b128 v[184:187], v170
	s_waitcnt lgkmcnt(4)
	v_mfma_f32_16x16x32_fp8_fp8 v[216:219], v[188:189], v[142:143], 0
	v_mfma_f32_16x16x32_fp8_fp8 v[216:219], v[190:191], v[144:145], v[216:219]
	v_mfma_f32_16x16x32_fp8_fp8 v[216:219], v[192:193], v[146:147], v[216:219]
	v_mfma_f32_16x16x32_fp8_fp8 v[216:219], v[194:195], v[148:149], v[216:219]
	v_cndmask_b32_e64 v226, v204, v206, s[54:55]
	v_cndmask_b32_e64 v227, v205, v207, s[54:55]
	s_waitcnt vmcnt(16)
	ds_write_b128 v168, v[42:45]
	ds_write_b128 v168, v[46:49] offset:1024
	v_lshl_add_u32 v176, v160, 10, v166
	global_load_dwordx4 v[42:45], v176, s[50:51]
	v_lshl_add_u32 v177, v161, 10, v167
	global_load_dwordx4 v[46:49], v177, s[50:51]
	ds_read_b128 v[188:191], v169
	ds_read_b128 v[192:195], v170
	s_waitcnt lgkmcnt(4)
	v_mfma_f32_16x16x32_fp8_fp8 v[196:199], v[180:181], v[142:143], 0
	v_mfma_f32_16x16x32_fp8_fp8 v[196:199], v[182:183], v[144:145], v[196:199]
	v_mfma_f32_16x16x32_fp8_fp8 v[196:199], v[184:185], v[146:147], v[196:199]
	v_mfma_f32_16x16x32_fp8_fp8 v[196:199], v[186:187], v[148:149], v[196:199]
	v_cndmask_b32_e64 v228, v216, v218, s[54:55]
	v_cndmask_b32_e64 v229, v217, v219, s[54:55]
	v_cndmask_b32_e64 v232, v226, v228, s[56:57]
	v_cndmask_b32_e64 v233, v227, v229, s[56:57]
	s_waitcnt vmcnt(16)
	ds_write_b128 v168, v[50:53]
	ds_write_b128 v168, v[54:57] offset:1024
	v_lshl_add_u32 v174, v162, 10, v166
	global_load_dwordx4 v[50:53], v174, s[50:51]
	v_lshl_add_u32 v175, v163, 10, v167
	global_load_dwordx4 v[54:57], v175, s[50:51]
	ds_read_b128 v[180:183], v169
	ds_read_b128 v[184:187], v170
	s_waitcnt lgkmcnt(4)
	v_mfma_f32_16x16x32_fp8_fp8 v[200:203], v[188:189], v[142:143], 0
	v_mfma_f32_16x16x32_fp8_fp8 v[200:203], v[190:191], v[144:145], v[200:203]
	v_mfma_f32_16x16x32_fp8_fp8 v[200:203], v[192:193], v[146:147], v[200:203]
	v_mfma_f32_16x16x32_fp8_fp8 v[200:203], v[194:195], v[148:149], v[200:203]
	v_cndmask_b32_e64 v226, v196, v198, s[54:55]
	v_cndmask_b32_e64 v227, v197, v199, s[54:55]
	s_waitcnt vmcnt(16)
	ds_write_b128 v168, v[58:61]
	ds_write_b128 v168, v[62:65] offset:1024
	v_lshl_add_u32 v176, v164, 10, v166
	global_load_dwordx4 v[58:61], v176, s[50:51]
	v_lshl_add_u32 v177, v165, 10, v167
	global_load_dwordx4 v[62:65], v177, s[50:51]
	ds_read_b128 v[188:191], v169
	ds_read_b128 v[192:195], v170
	s_waitcnt lgkmcnt(4)
	v_mfma_f32_16x16x32_fp8_fp8 v[204:207], v[180:181], v[142:143], 0
	v_mfma_f32_16x16x32_fp8_fp8 v[204:207], v[182:183], v[144:145], v[204:207]
	v_mfma_f32_16x16x32_fp8_fp8 v[204:207], v[184:185], v[146:147], v[204:207]
	v_mfma_f32_16x16x32_fp8_fp8 v[204:207], v[186:187], v[148:149], v[204:207]
	v_cndmask_b32_e64 v228, v200, v202, s[54:55]
	v_cndmask_b32_e64 v229, v201, v203, s[54:55]
	v_cndmask_b32_e64 v234, v226, v228, s[56:57]
	v_cndmask_b32_e64 v235, v227, v229, s[56:57]
	s_waitcnt lgkmcnt(0)
	v_mfma_f32_16x16x32_fp8_fp8 v[216:219], v[188:189], v[142:143], 0
	v_mfma_f32_16x16x32_fp8_fp8 v[216:219], v[190:191], v[144:145], v[216:219]
	v_mfma_f32_16x16x32_fp8_fp8 v[216:219], v[192:193], v[146:147], v[216:219]
	v_mfma_f32_16x16x32_fp8_fp8 v[216:219], v[194:195], v[148:149], v[216:219]
	v_add_u32_e32 v0, 3584, v172
	ds_read2_b32 v[150:151], v0 offset0:0 offset1:8
	ds_read2_b32 v[152:153], v0 offset0:16 offset1:24
	ds_read2_b32 v[154:155], v0 offset0:32 offset1:40
	ds_read2_b32 v[156:157], v0 offset0:48 offset1:56
	ds_read2_b32 v[158:159], v0 offset0:64 offset1:72
	ds_read2_b32 v[160:161], v0 offset0:80 offset1:88
	ds_read2_b32 v[162:163], v0 offset0:96 offset1:104
	ds_read2_b32 v[164:165], v0 offset0:112 offset1:120
	v_add_u32_e32 v171, s80, v171
	global_load_dwordx4 v[142:145], v171, s[52:53]
	global_load_dwordx4 v[146:149], v171, s[52:53] offset:16
	v_cndmask_b32_e64 v226, v204, v206, s[54:55]
	v_cndmask_b32_e64 v227, v205, v207, s[54:55]
	v_cndmask_b32_e64 v228, v216, v218, s[54:55]
	v_cndmask_b32_e64 v229, v217, v219, s[54:55]
	v_cndmask_b32_e64 v236, v226, v228, s[56:57]
	v_cndmask_b32_e64 v237, v227, v229, s[56:57]
	v_cndmask_b32_e64 v226, v230, v232, s[58:59]
	v_cndmask_b32_e64 v228, v234, v236, s[58:59]
	v_cndmask_b32_e64 v227, v231, v233, s[58:59]
	v_cndmask_b32_e64 v229, v235, v237, s[58:59]
	v_cndmask_b32_e64 v226, v226, v228, s[60:61]
	v_cndmask_b32_e64 v227, v227, v229, s[60:61]
	v_add_f32_e32 v240, v240, v226
	v_add_f32_e32 v241, v241, v227
	s_waitcnt vmcnt(16)
	ds_write_b128 v168, v[2:5]
	ds_write_b128 v168, v[6:9] offset:1024
	s_waitcnt lgkmcnt(2)
	v_lshl_add_u32 v174, v150, 10, v166
	global_load_dwordx4 v[2:5], v174, s[50:51]
	v_lshl_add_u32 v175, v151, 10, v167
	global_load_dwordx4 v[6:9], v175, s[50:51]
	ds_read_b128 v[180:183], v169
	ds_read_b128 v[184:187], v170
	s_waitcnt vmcnt(16)
	ds_write_b128 v168, v[10:13]
	ds_write_b128 v168, v[14:17] offset:1024
	v_lshl_add_u32 v176, v152, 10, v166
	global_load_dwordx4 v[10:13], v176, s[50:51]
	v_lshl_add_u32 v177, v153, 10, v167
	global_load_dwordx4 v[14:17], v177, s[50:51]
	ds_read_b128 v[188:191], v169
	ds_read_b128 v[192:195], v170
	s_waitcnt lgkmcnt(4)
	v_mfma_f32_16x16x32_fp8_fp8 v[196:199], v[180:181], v[134:135], 0
	v_mfma_f32_16x16x32_fp8_fp8 v[196:199], v[182:183], v[136:137], v[196:199]
	v_mfma_f32_16x16x32_fp8_fp8 v[196:199], v[184:185], v[138:139], v[196:199]
	v_mfma_f32_16x16x32_fp8_fp8 v[196:199], v[186:187], v[140:141], v[196:199]
	s_waitcnt vmcnt(16)
	ds_write_b128 v168, v[18:21]
	ds_write_b128 v168, v[22:25] offset:1024
	v_lshl_add_u32 v174, v154, 10, v166
	global_load_dwordx4 v[18:21], v174, s[50:51]
	v_lshl_add_u32 v175, v155, 10, v167
	global_load_dwordx4 v[22:25], v175, s[50:51]
	ds_read_b128 v[180:183], v169
	ds_read_b128 v[184:187], v170
	s_waitcnt lgkmcnt(4)
	v_mfma_f32_16x16x32_fp8_fp8 v[200:203], v[188:189], v[134:135], 0
	v_mfma_f32_16x16x32_fp8_fp8 v[200:203], v[190:191], v[136:137], v[200:203]
	v_mfma_f32_16x16x32_fp8_fp8 v[200:203], v[192:193], v[138:139], v[200:203]
	v_mfma_f32_16x16x32_fp8_fp8 v[200:203], v[194:195], v[140:141], v[200:203]
	v_cndmask_b32_e64 v226, v196, v198, s[54:55]
	v_cndmask_b32_e64 v227, v197, v199, s[54:55]
	s_waitcnt vmcnt(16)
	ds_write_b128 v168, v[26:29]
	ds_write_b128 v168, v[30:33] offset:1024
	v_lshl_add_u32 v176, v156, 10, v166
	global_load_dwordx4 v[26:29], v176, s[50:51]
	v_lshl_add_u32 v177, v157, 10, v167
	global_load_dwordx4 v[30:33], v177, s[50:51]
	ds_read_b128 v[188:191], v169
	ds_read_b128 v[192:195], v170
	s_waitcnt lgkmcnt(4)
	v_mfma_f32_16x16x32_fp8_fp8 v[204:207], v[180:181], v[134:135], 0
	v_mfma_f32_16x16x32_fp8_fp8 v[204:207], v[182:183], v[136:137], v[204:207]
	v_mfma_f32_16x16x32_fp8_fp8 v[204:207], v[184:185], v[138:139], v[204:207]
	v_mfma_f32_16x16x32_fp8_fp8 v[204:207], v[186:187], v[140:141], v[204:207]
	v_cndmask_b32_e64 v228, v200, v202, s[54:55]
	v_cndmask_b32_e64 v229, v201, v203, s[54:55]
	v_cndmask_b32_e64 v230, v226, v228, s[56:57]
	v_cndmask_b32_e64 v231, v227, v229, s[56:57]
	s_waitcnt vmcnt(16)
	ds_write_b128 v168, v[34:37]
	ds_write_b128 v168, v[38:41] offset:1024
	v_lshl_add_u32 v174, v158, 10, v166
	global_load_dwordx4 v[34:37], v174, s[50:51]
	v_lshl_add_u32 v175, v159, 10, v167
	global_load_dwordx4 v[38:41], v175, s[50:51]
	ds_read_b128 v[180:183], v169
	ds_read_b128 v[184:187], v170
	s_waitcnt lgkmcnt(4)
	v_mfma_f32_16x16x32_fp8_fp8 v[216:219], v[188:189], v[134:135], 0
	v_mfma_f32_16x16x32_fp8_fp8 v[216:219], v[190:191], v[136:137], v[216:219]
	v_mfma_f32_16x16x32_fp8_fp8 v[216:219], v[192:193], v[138:139], v[216:219]
	v_mfma_f32_16x16x32_fp8_fp8 v[216:219], v[194:195], v[140:141], v[216:219]
	v_cndmask_b32_e64 v226, v204, v206, s[54:55]
	v_cndmask_b32_e64 v227, v205, v207, s[54:55]
	s_waitcnt vmcnt(16)
	ds_write_b128 v168, v[42:45]
	ds_write_b128 v168, v[46:49] offset:1024
	v_lshl_add_u32 v176, v160, 10, v166
	global_load_dwordx4 v[42:45], v176, s[50:51]
	v_lshl_add_u32 v177, v161, 10, v167
	global_load_dwordx4 v[46:49], v177, s[50:51]
	ds_read_b128 v[188:191], v169
	ds_read_b128 v[192:195], v170
	s_waitcnt lgkmcnt(4)
	v_mfma_f32_16x16x32_fp8_fp8 v[196:199], v[180:181], v[134:135], 0
	v_mfma_f32_16x16x32_fp8_fp8 v[196:199], v[182:183], v[136:137], v[196:199]
	v_mfma_f32_16x16x32_fp8_fp8 v[196:199], v[184:185], v[138:139], v[196:199]
	v_mfma_f32_16x16x32_fp8_fp8 v[196:199], v[186:187], v[140:141], v[196:199]
	v_cndmask_b32_e64 v228, v216, v218, s[54:55]
	v_cndmask_b32_e64 v229, v217, v219, s[54:55]
	v_cndmask_b32_e64 v232, v226, v228, s[56:57]
	v_cndmask_b32_e64 v233, v227, v229, s[56:57]
	s_waitcnt vmcnt(16)
	ds_write_b128 v168, v[50:53]
	ds_write_b128 v168, v[54:57] offset:1024
	v_lshl_add_u32 v174, v162, 10, v166
	global_load_dwordx4 v[50:53], v174, s[50:51]
	v_lshl_add_u32 v175, v163, 10, v167
	global_load_dwordx4 v[54:57], v175, s[50:51]
	ds_read_b128 v[180:183], v169
	ds_read_b128 v[184:187], v170
	s_waitcnt lgkmcnt(4)
	v_mfma_f32_16x16x32_fp8_fp8 v[200:203], v[188:189], v[134:135], 0
	v_mfma_f32_16x16x32_fp8_fp8 v[200:203], v[190:191], v[136:137], v[200:203]
	v_mfma_f32_16x16x32_fp8_fp8 v[200:203], v[192:193], v[138:139], v[200:203]
	v_mfma_f32_16x16x32_fp8_fp8 v[200:203], v[194:195], v[140:141], v[200:203]
	v_cndmask_b32_e64 v226, v196, v198, s[54:55]
	v_cndmask_b32_e64 v227, v197, v199, s[54:55]
	s_waitcnt vmcnt(16)
	ds_write_b128 v168, v[58:61]
	ds_write_b128 v168, v[62:65] offset:1024
	v_lshl_add_u32 v176, v164, 10, v166
	global_load_dwordx4 v[58:61], v176, s[50:51]
	v_lshl_add_u32 v177, v165, 10, v167
	global_load_dwordx4 v[62:65], v177, s[50:51]
	ds_read_b128 v[188:191], v169
	ds_read_b128 v[192:195], v170
	s_waitcnt lgkmcnt(4)
	v_mfma_f32_16x16x32_fp8_fp8 v[204:207], v[180:181], v[134:135], 0
	v_mfma_f32_16x16x32_fp8_fp8 v[204:207], v[182:183], v[136:137], v[204:207]
	v_mfma_f32_16x16x32_fp8_fp8 v[204:207], v[184:185], v[138:139], v[204:207]
	v_mfma_f32_16x16x32_fp8_fp8 v[204:207], v[186:187], v[140:141], v[204:207]
	v_cndmask_b32_e64 v228, v200, v202, s[54:55]
	v_cndmask_b32_e64 v229, v201, v203, s[54:55]
	v_cndmask_b32_e64 v234, v226, v228, s[56:57]
	v_cndmask_b32_e64 v235, v227, v229, s[56:57]
	s_waitcnt lgkmcnt(0)
	v_mfma_f32_16x16x32_fp8_fp8 v[216:219], v[188:189], v[134:135], 0
	v_mfma_f32_16x16x32_fp8_fp8 v[216:219], v[190:191], v[136:137], v[216:219]
	v_mfma_f32_16x16x32_fp8_fp8 v[216:219], v[192:193], v[138:139], v[216:219]
	v_mfma_f32_16x16x32_fp8_fp8 v[216:219], v[194:195], v[140:141], v[216:219]
	v_add_u32_e32 v0, 4096, v172
	ds_read2_b32 v[150:151], v0 offset0:0 offset1:8
	ds_read2_b32 v[152:153], v0 offset0:16 offset1:24
	ds_read2_b32 v[154:155], v0 offset0:32 offset1:40
	ds_read2_b32 v[156:157], v0 offset0:48 offset1:56
	ds_read2_b32 v[158:159], v0 offset0:64 offset1:72
	ds_read2_b32 v[160:161], v0 offset0:80 offset1:88
	ds_read2_b32 v[162:163], v0 offset0:96 offset1:104
	ds_read2_b32 v[164:165], v0 offset0:112 offset1:120
	v_add_u32_e32 v171, s80, v171
	global_load_dwordx4 v[134:137], v171, s[52:53]
	global_load_dwordx4 v[138:141], v171, s[52:53] offset:16
	v_cndmask_b32_e64 v226, v204, v206, s[54:55]
	v_cndmask_b32_e64 v227, v205, v207, s[54:55]
	v_cndmask_b32_e64 v228, v216, v218, s[54:55]
	v_cndmask_b32_e64 v229, v217, v219, s[54:55]
	v_cndmask_b32_e64 v236, v226, v228, s[56:57]
	v_cndmask_b32_e64 v237, v227, v229, s[56:57]
	v_cndmask_b32_e64 v226, v230, v232, s[58:59]
	v_cndmask_b32_e64 v228, v234, v236, s[58:59]
	v_cndmask_b32_e64 v227, v231, v233, s[58:59]
	v_cndmask_b32_e64 v229, v235, v237, s[58:59]
	v_cndmask_b32_e64 v226, v226, v228, s[60:61]
	v_cndmask_b32_e64 v227, v227, v229, s[60:61]
	v_add_f32_e32 v94, v94, v226
	v_add_f32_e32 v95, v95, v227
	s_waitcnt vmcnt(16)
	ds_write_b128 v168, v[2:5]
	ds_write_b128 v168, v[6:9] offset:1024
	s_waitcnt lgkmcnt(2)
	v_lshl_add_u32 v174, v150, 10, v166
	global_load_dwordx4 v[2:5], v174, s[50:51]
	v_lshl_add_u32 v175, v151, 10, v167
	global_load_dwordx4 v[6:9], v175, s[50:51]
	ds_read_b128 v[180:183], v169
	ds_read_b128 v[184:187], v170
	s_waitcnt vmcnt(16)
	ds_write_b128 v168, v[10:13]
	ds_write_b128 v168, v[14:17] offset:1024
	v_lshl_add_u32 v176, v152, 10, v166
	global_load_dwordx4 v[10:13], v176, s[50:51]
	v_lshl_add_u32 v177, v153, 10, v167
	global_load_dwordx4 v[14:17], v177, s[50:51]
	ds_read_b128 v[188:191], v169
	ds_read_b128 v[192:195], v170
	s_waitcnt lgkmcnt(4)
	v_mfma_f32_16x16x32_fp8_fp8 v[196:199], v[180:181], v[142:143], 0
	v_mfma_f32_16x16x32_fp8_fp8 v[196:199], v[182:183], v[144:145], v[196:199]
	v_mfma_f32_16x16x32_fp8_fp8 v[196:199], v[184:185], v[146:147], v[196:199]
	v_mfma_f32_16x16x32_fp8_fp8 v[196:199], v[186:187], v[148:149], v[196:199]
	s_waitcnt vmcnt(16)
	ds_write_b128 v168, v[18:21]
	ds_write_b128 v168, v[22:25] offset:1024
	v_lshl_add_u32 v174, v154, 10, v166
	global_load_dwordx4 v[18:21], v174, s[50:51]
	v_lshl_add_u32 v175, v155, 10, v167
	global_load_dwordx4 v[22:25], v175, s[50:51]
	ds_read_b128 v[180:183], v169
	ds_read_b128 v[184:187], v170
	s_waitcnt lgkmcnt(4)
	v_mfma_f32_16x16x32_fp8_fp8 v[200:203], v[188:189], v[142:143], 0
	v_mfma_f32_16x16x32_fp8_fp8 v[200:203], v[190:191], v[144:145], v[200:203]
	v_mfma_f32_16x16x32_fp8_fp8 v[200:203], v[192:193], v[146:147], v[200:203]
	v_mfma_f32_16x16x32_fp8_fp8 v[200:203], v[194:195], v[148:149], v[200:203]
	v_cndmask_b32_e64 v226, v196, v198, s[54:55]
	v_cndmask_b32_e64 v227, v197, v199, s[54:55]
	s_waitcnt vmcnt(16)
	ds_write_b128 v168, v[26:29]
	ds_write_b128 v168, v[30:33] offset:1024
	v_lshl_add_u32 v176, v156, 10, v166
	global_load_dwordx4 v[26:29], v176, s[50:51]
	v_lshl_add_u32 v177, v157, 10, v167
	global_load_dwordx4 v[30:33], v177, s[50:51]
	ds_read_b128 v[188:191], v169
	ds_read_b128 v[192:195], v170
	s_waitcnt lgkmcnt(4)
	v_mfma_f32_16x16x32_fp8_fp8 v[204:207], v[180:181], v[142:143], 0
	v_mfma_f32_16x16x32_fp8_fp8 v[204:207], v[182:183], v[144:145], v[204:207]
	v_mfma_f32_16x16x32_fp8_fp8 v[204:207], v[184:185], v[146:147], v[204:207]
	v_mfma_f32_16x16x32_fp8_fp8 v[204:207], v[186:187], v[148:149], v[204:207]
	v_cndmask_b32_e64 v228, v200, v202, s[54:55]
	v_cndmask_b32_e64 v229, v201, v203, s[54:55]
	v_cndmask_b32_e64 v230, v226, v228, s[56:57]
	v_cndmask_b32_e64 v231, v227, v229, s[56:57]
	s_waitcnt vmcnt(16)
	ds_write_b128 v168, v[34:37]
	ds_write_b128 v168, v[38:41] offset:1024
	v_lshl_add_u32 v174, v158, 10, v166
	global_load_dwordx4 v[34:37], v174, s[50:51]
	v_lshl_add_u32 v175, v159, 10, v167
	global_load_dwordx4 v[38:41], v175, s[50:51]
	ds_read_b128 v[180:183], v169
	ds_read_b128 v[184:187], v170
	s_waitcnt lgkmcnt(4)
	v_mfma_f32_16x16x32_fp8_fp8 v[216:219], v[188:189], v[142:143], 0
	v_mfma_f32_16x16x32_fp8_fp8 v[216:219], v[190:191], v[144:145], v[216:219]
	v_mfma_f32_16x16x32_fp8_fp8 v[216:219], v[192:193], v[146:147], v[216:219]
	v_mfma_f32_16x16x32_fp8_fp8 v[216:219], v[194:195], v[148:149], v[216:219]
	v_cndmask_b32_e64 v226, v204, v206, s[54:55]
	v_cndmask_b32_e64 v227, v205, v207, s[54:55]
	s_waitcnt vmcnt(16)
	ds_write_b128 v168, v[42:45]
	ds_write_b128 v168, v[46:49] offset:1024
	v_lshl_add_u32 v176, v160, 10, v166
	global_load_dwordx4 v[42:45], v176, s[50:51]
	v_lshl_add_u32 v177, v161, 10, v167
	global_load_dwordx4 v[46:49], v177, s[50:51]
	ds_read_b128 v[188:191], v169
	ds_read_b128 v[192:195], v170
	s_waitcnt lgkmcnt(4)
	v_mfma_f32_16x16x32_fp8_fp8 v[196:199], v[180:181], v[142:143], 0
	v_mfma_f32_16x16x32_fp8_fp8 v[196:199], v[182:183], v[144:145], v[196:199]
	v_mfma_f32_16x16x32_fp8_fp8 v[196:199], v[184:185], v[146:147], v[196:199]
	v_mfma_f32_16x16x32_fp8_fp8 v[196:199], v[186:187], v[148:149], v[196:199]
	v_cndmask_b32_e64 v228, v216, v218, s[54:55]
	v_cndmask_b32_e64 v229, v217, v219, s[54:55]
	v_cndmask_b32_e64 v232, v226, v228, s[56:57]
	v_cndmask_b32_e64 v233, v227, v229, s[56:57]
	s_waitcnt vmcnt(16)
	ds_write_b128 v168, v[50:53]
	ds_write_b128 v168, v[54:57] offset:1024
	v_lshl_add_u32 v174, v162, 10, v166
	global_load_dwordx4 v[50:53], v174, s[50:51]
	v_lshl_add_u32 v175, v163, 10, v167
	global_load_dwordx4 v[54:57], v175, s[50:51]
	ds_read_b128 v[180:183], v169
	ds_read_b128 v[184:187], v170
	s_waitcnt lgkmcnt(4)
	v_mfma_f32_16x16x32_fp8_fp8 v[200:203], v[188:189], v[142:143], 0
	v_mfma_f32_16x16x32_fp8_fp8 v[200:203], v[190:191], v[144:145], v[200:203]
	v_mfma_f32_16x16x32_fp8_fp8 v[200:203], v[192:193], v[146:147], v[200:203]
	v_mfma_f32_16x16x32_fp8_fp8 v[200:203], v[194:195], v[148:149], v[200:203]
	v_cndmask_b32_e64 v226, v196, v198, s[54:55]
	v_cndmask_b32_e64 v227, v197, v199, s[54:55]
	s_waitcnt vmcnt(16)
	ds_write_b128 v168, v[58:61]
	ds_write_b128 v168, v[62:65] offset:1024
	v_lshl_add_u32 v176, v164, 10, v166
	global_load_dwordx4 v[58:61], v176, s[50:51]
	v_lshl_add_u32 v177, v165, 10, v167
	global_load_dwordx4 v[62:65], v177, s[50:51]
	ds_read_b128 v[188:191], v169
	ds_read_b128 v[192:195], v170
	s_waitcnt lgkmcnt(4)
	v_mfma_f32_16x16x32_fp8_fp8 v[204:207], v[180:181], v[142:143], 0
	v_mfma_f32_16x16x32_fp8_fp8 v[204:207], v[182:183], v[144:145], v[204:207]
	v_mfma_f32_16x16x32_fp8_fp8 v[204:207], v[184:185], v[146:147], v[204:207]
	v_mfma_f32_16x16x32_fp8_fp8 v[204:207], v[186:187], v[148:149], v[204:207]
	v_cndmask_b32_e64 v228, v200, v202, s[54:55]
	v_cndmask_b32_e64 v229, v201, v203, s[54:55]
	v_cndmask_b32_e64 v234, v226, v228, s[56:57]
	v_cndmask_b32_e64 v235, v227, v229, s[56:57]
	s_waitcnt lgkmcnt(0)
	v_mfma_f32_16x16x32_fp8_fp8 v[216:219], v[188:189], v[142:143], 0
	v_mfma_f32_16x16x32_fp8_fp8 v[216:219], v[190:191], v[144:145], v[216:219]
	v_mfma_f32_16x16x32_fp8_fp8 v[216:219], v[192:193], v[146:147], v[216:219]
	v_mfma_f32_16x16x32_fp8_fp8 v[216:219], v[194:195], v[148:149], v[216:219]
	v_add_u32_e32 v0, 4608, v172
	ds_read2_b32 v[150:151], v0 offset0:0 offset1:8
	ds_read2_b32 v[152:153], v0 offset0:16 offset1:24
	ds_read2_b32 v[154:155], v0 offset0:32 offset1:40
	ds_read2_b32 v[156:157], v0 offset0:48 offset1:56
	ds_read2_b32 v[158:159], v0 offset0:64 offset1:72
	ds_read2_b32 v[160:161], v0 offset0:80 offset1:88
	ds_read2_b32 v[162:163], v0 offset0:96 offset1:104
	ds_read2_b32 v[164:165], v0 offset0:112 offset1:120
	v_add_u32_e32 v171, s80, v171
	global_load_dwordx4 v[142:145], v171, s[52:53]
	global_load_dwordx4 v[146:149], v171, s[52:53] offset:16
	v_cndmask_b32_e64 v226, v204, v206, s[54:55]
	v_cndmask_b32_e64 v227, v205, v207, s[54:55]
	v_cndmask_b32_e64 v228, v216, v218, s[54:55]
	v_cndmask_b32_e64 v229, v217, v219, s[54:55]
	v_cndmask_b32_e64 v236, v226, v228, s[56:57]
	v_cndmask_b32_e64 v237, v227, v229, s[56:57]
	v_cndmask_b32_e64 v226, v230, v232, s[58:59]
	v_cndmask_b32_e64 v228, v234, v236, s[58:59]
	v_cndmask_b32_e64 v227, v231, v233, s[58:59]
	v_cndmask_b32_e64 v229, v235, v237, s[58:59]
	v_cndmask_b32_e64 v226, v226, v228, s[60:61]
	v_cndmask_b32_e64 v227, v227, v229, s[60:61]
	v_add_f32_e32 v96, v96, v226
	v_add_f32_e32 v97, v97, v227
	s_waitcnt vmcnt(16)
	ds_write_b128 v168, v[2:5]
	ds_write_b128 v168, v[6:9] offset:1024
	s_waitcnt lgkmcnt(2)
	v_lshl_add_u32 v174, v150, 10, v166
	global_load_dwordx4 v[2:5], v174, s[50:51]
	v_lshl_add_u32 v175, v151, 10, v167
	global_load_dwordx4 v[6:9], v175, s[50:51]
	ds_read_b128 v[180:183], v169
	ds_read_b128 v[184:187], v170
	s_waitcnt vmcnt(16)
	ds_write_b128 v168, v[10:13]
	ds_write_b128 v168, v[14:17] offset:1024
	v_lshl_add_u32 v176, v152, 10, v166
	global_load_dwordx4 v[10:13], v176, s[50:51]
	v_lshl_add_u32 v177, v153, 10, v167
	global_load_dwordx4 v[14:17], v177, s[50:51]
	ds_read_b128 v[188:191], v169
	ds_read_b128 v[192:195], v170
	s_waitcnt lgkmcnt(4)
	v_mfma_f32_16x16x32_fp8_fp8 v[196:199], v[180:181], v[134:135], 0
	v_mfma_f32_16x16x32_fp8_fp8 v[196:199], v[182:183], v[136:137], v[196:199]
	v_mfma_f32_16x16x32_fp8_fp8 v[196:199], v[184:185], v[138:139], v[196:199]
	v_mfma_f32_16x16x32_fp8_fp8 v[196:199], v[186:187], v[140:141], v[196:199]
	s_waitcnt vmcnt(16)
	ds_write_b128 v168, v[18:21]
	ds_write_b128 v168, v[22:25] offset:1024
	v_lshl_add_u32 v174, v154, 10, v166
	global_load_dwordx4 v[18:21], v174, s[50:51]
	v_lshl_add_u32 v175, v155, 10, v167
	global_load_dwordx4 v[22:25], v175, s[50:51]
	ds_read_b128 v[180:183], v169
	ds_read_b128 v[184:187], v170
	s_waitcnt lgkmcnt(4)
	v_mfma_f32_16x16x32_fp8_fp8 v[200:203], v[188:189], v[134:135], 0
	v_mfma_f32_16x16x32_fp8_fp8 v[200:203], v[190:191], v[136:137], v[200:203]
	v_mfma_f32_16x16x32_fp8_fp8 v[200:203], v[192:193], v[138:139], v[200:203]
	v_mfma_f32_16x16x32_fp8_fp8 v[200:203], v[194:195], v[140:141], v[200:203]
	v_cndmask_b32_e64 v226, v196, v198, s[54:55]
	v_cndmask_b32_e64 v227, v197, v199, s[54:55]
	s_waitcnt vmcnt(16)
	ds_write_b128 v168, v[26:29]
	ds_write_b128 v168, v[30:33] offset:1024
	v_lshl_add_u32 v176, v156, 10, v166
	global_load_dwordx4 v[26:29], v176, s[50:51]
	v_lshl_add_u32 v177, v157, 10, v167
	global_load_dwordx4 v[30:33], v177, s[50:51]
	ds_read_b128 v[188:191], v169
	ds_read_b128 v[192:195], v170
	s_waitcnt lgkmcnt(4)
	v_mfma_f32_16x16x32_fp8_fp8 v[204:207], v[180:181], v[134:135], 0
	v_mfma_f32_16x16x32_fp8_fp8 v[204:207], v[182:183], v[136:137], v[204:207]
	v_mfma_f32_16x16x32_fp8_fp8 v[204:207], v[184:185], v[138:139], v[204:207]
	v_mfma_f32_16x16x32_fp8_fp8 v[204:207], v[186:187], v[140:141], v[204:207]
	v_cndmask_b32_e64 v228, v200, v202, s[54:55]
	v_cndmask_b32_e64 v229, v201, v203, s[54:55]
	v_cndmask_b32_e64 v230, v226, v228, s[56:57]
	v_cndmask_b32_e64 v231, v227, v229, s[56:57]
	s_waitcnt vmcnt(16)
	ds_write_b128 v168, v[34:37]
	ds_write_b128 v168, v[38:41] offset:1024
	v_lshl_add_u32 v174, v158, 10, v166
	global_load_dwordx4 v[34:37], v174, s[50:51]
	v_lshl_add_u32 v175, v159, 10, v167
	global_load_dwordx4 v[38:41], v175, s[50:51]
	ds_read_b128 v[180:183], v169
	ds_read_b128 v[184:187], v170
	s_waitcnt lgkmcnt(4)
	v_mfma_f32_16x16x32_fp8_fp8 v[216:219], v[188:189], v[134:135], 0
	v_mfma_f32_16x16x32_fp8_fp8 v[216:219], v[190:191], v[136:137], v[216:219]
	v_mfma_f32_16x16x32_fp8_fp8 v[216:219], v[192:193], v[138:139], v[216:219]
	v_mfma_f32_16x16x32_fp8_fp8 v[216:219], v[194:195], v[140:141], v[216:219]
	v_cndmask_b32_e64 v226, v204, v206, s[54:55]
	v_cndmask_b32_e64 v227, v205, v207, s[54:55]
	s_waitcnt vmcnt(16)
	ds_write_b128 v168, v[42:45]
	ds_write_b128 v168, v[46:49] offset:1024
	v_lshl_add_u32 v176, v160, 10, v166
	global_load_dwordx4 v[42:45], v176, s[50:51]
	v_lshl_add_u32 v177, v161, 10, v167
	global_load_dwordx4 v[46:49], v177, s[50:51]
	ds_read_b128 v[188:191], v169
	ds_read_b128 v[192:195], v170
	s_waitcnt lgkmcnt(4)
	v_mfma_f32_16x16x32_fp8_fp8 v[196:199], v[180:181], v[134:135], 0
	v_mfma_f32_16x16x32_fp8_fp8 v[196:199], v[182:183], v[136:137], v[196:199]
	v_mfma_f32_16x16x32_fp8_fp8 v[196:199], v[184:185], v[138:139], v[196:199]
	v_mfma_f32_16x16x32_fp8_fp8 v[196:199], v[186:187], v[140:141], v[196:199]
	v_cndmask_b32_e64 v228, v216, v218, s[54:55]
	v_cndmask_b32_e64 v229, v217, v219, s[54:55]
	v_cndmask_b32_e64 v232, v226, v228, s[56:57]
	v_cndmask_b32_e64 v233, v227, v229, s[56:57]
	s_waitcnt vmcnt(16)
	ds_write_b128 v168, v[50:53]
	ds_write_b128 v168, v[54:57] offset:1024
	v_lshl_add_u32 v174, v162, 10, v166
	global_load_dwordx4 v[50:53], v174, s[50:51]
	v_lshl_add_u32 v175, v163, 10, v167
	global_load_dwordx4 v[54:57], v175, s[50:51]
	ds_read_b128 v[180:183], v169
	ds_read_b128 v[184:187], v170
	s_waitcnt lgkmcnt(4)
	v_mfma_f32_16x16x32_fp8_fp8 v[200:203], v[188:189], v[134:135], 0
	v_mfma_f32_16x16x32_fp8_fp8 v[200:203], v[190:191], v[136:137], v[200:203]
	v_mfma_f32_16x16x32_fp8_fp8 v[200:203], v[192:193], v[138:139], v[200:203]
	v_mfma_f32_16x16x32_fp8_fp8 v[200:203], v[194:195], v[140:141], v[200:203]
	v_cndmask_b32_e64 v226, v196, v198, s[54:55]
	v_cndmask_b32_e64 v227, v197, v199, s[54:55]
	s_waitcnt vmcnt(16)
	ds_write_b128 v168, v[58:61]
	ds_write_b128 v168, v[62:65] offset:1024
	v_lshl_add_u32 v176, v164, 10, v166
	global_load_dwordx4 v[58:61], v176, s[50:51]
	v_lshl_add_u32 v177, v165, 10, v167
	global_load_dwordx4 v[62:65], v177, s[50:51]
	ds_read_b128 v[188:191], v169
	ds_read_b128 v[192:195], v170
	s_waitcnt lgkmcnt(4)
	v_mfma_f32_16x16x32_fp8_fp8 v[204:207], v[180:181], v[134:135], 0
	v_mfma_f32_16x16x32_fp8_fp8 v[204:207], v[182:183], v[136:137], v[204:207]
	v_mfma_f32_16x16x32_fp8_fp8 v[204:207], v[184:185], v[138:139], v[204:207]
	v_mfma_f32_16x16x32_fp8_fp8 v[204:207], v[186:187], v[140:141], v[204:207]
	v_cndmask_b32_e64 v228, v200, v202, s[54:55]
	v_cndmask_b32_e64 v229, v201, v203, s[54:55]
	v_cndmask_b32_e64 v234, v226, v228, s[56:57]
	v_cndmask_b32_e64 v235, v227, v229, s[56:57]
	s_waitcnt lgkmcnt(0)
	v_mfma_f32_16x16x32_fp8_fp8 v[216:219], v[188:189], v[134:135], 0
	v_mfma_f32_16x16x32_fp8_fp8 v[216:219], v[190:191], v[136:137], v[216:219]
	v_mfma_f32_16x16x32_fp8_fp8 v[216:219], v[192:193], v[138:139], v[216:219]
	v_mfma_f32_16x16x32_fp8_fp8 v[216:219], v[194:195], v[140:141], v[216:219]
	v_add_u32_e32 v0, 5120, v172
	ds_read2_b32 v[150:151], v0 offset0:0 offset1:8
	ds_read2_b32 v[152:153], v0 offset0:16 offset1:24
	ds_read2_b32 v[154:155], v0 offset0:32 offset1:40
	ds_read2_b32 v[156:157], v0 offset0:48 offset1:56
	ds_read2_b32 v[158:159], v0 offset0:64 offset1:72
	ds_read2_b32 v[160:161], v0 offset0:80 offset1:88
	ds_read2_b32 v[162:163], v0 offset0:96 offset1:104
	ds_read2_b32 v[164:165], v0 offset0:112 offset1:120
	v_add_u32_e32 v171, s80, v171
	global_load_dwordx4 v[134:137], v171, s[52:53]
	global_load_dwordx4 v[138:141], v171, s[52:53] offset:16
	v_cndmask_b32_e64 v226, v204, v206, s[54:55]
	v_cndmask_b32_e64 v227, v205, v207, s[54:55]
	v_cndmask_b32_e64 v228, v216, v218, s[54:55]
	v_cndmask_b32_e64 v229, v217, v219, s[54:55]
	v_cndmask_b32_e64 v236, v226, v228, s[56:57]
	v_cndmask_b32_e64 v237, v227, v229, s[56:57]
	v_cndmask_b32_e64 v226, v230, v232, s[58:59]
	v_cndmask_b32_e64 v228, v234, v236, s[58:59]
	v_cndmask_b32_e64 v227, v231, v233, s[58:59]
	v_cndmask_b32_e64 v229, v235, v237, s[58:59]
	v_cndmask_b32_e64 v226, v226, v228, s[60:61]
	v_cndmask_b32_e64 v227, v227, v229, s[60:61]
	v_add_f32_e32 v98, v98, v226
	v_add_f32_e32 v99, v99, v227
	s_waitcnt vmcnt(16)
	ds_write_b128 v168, v[2:5]
	ds_write_b128 v168, v[6:9] offset:1024
	s_waitcnt lgkmcnt(2)
	v_lshl_add_u32 v174, v150, 10, v166
	global_load_dwordx4 v[2:5], v174, s[50:51]
	v_lshl_add_u32 v175, v151, 10, v167
	global_load_dwordx4 v[6:9], v175, s[50:51]
	ds_read_b128 v[180:183], v169
	ds_read_b128 v[184:187], v170
	s_waitcnt vmcnt(16)
	ds_write_b128 v168, v[10:13]
	ds_write_b128 v168, v[14:17] offset:1024
	v_lshl_add_u32 v176, v152, 10, v166
	global_load_dwordx4 v[10:13], v176, s[50:51]
	v_lshl_add_u32 v177, v153, 10, v167
	global_load_dwordx4 v[14:17], v177, s[50:51]
	ds_read_b128 v[188:191], v169
	ds_read_b128 v[192:195], v170
	s_waitcnt lgkmcnt(4)
	v_mfma_f32_16x16x32_fp8_fp8 v[196:199], v[180:181], v[142:143], 0
	v_mfma_f32_16x16x32_fp8_fp8 v[196:199], v[182:183], v[144:145], v[196:199]
	v_mfma_f32_16x16x32_fp8_fp8 v[196:199], v[184:185], v[146:147], v[196:199]
	v_mfma_f32_16x16x32_fp8_fp8 v[196:199], v[186:187], v[148:149], v[196:199]
	s_waitcnt vmcnt(16)
	ds_write_b128 v168, v[18:21]
	ds_write_b128 v168, v[22:25] offset:1024
	v_lshl_add_u32 v174, v154, 10, v166
	global_load_dwordx4 v[18:21], v174, s[50:51]
	v_lshl_add_u32 v175, v155, 10, v167
	global_load_dwordx4 v[22:25], v175, s[50:51]
	ds_read_b128 v[180:183], v169
	ds_read_b128 v[184:187], v170
	s_waitcnt lgkmcnt(4)
	v_mfma_f32_16x16x32_fp8_fp8 v[200:203], v[188:189], v[142:143], 0
	v_mfma_f32_16x16x32_fp8_fp8 v[200:203], v[190:191], v[144:145], v[200:203]
	v_mfma_f32_16x16x32_fp8_fp8 v[200:203], v[192:193], v[146:147], v[200:203]
	v_mfma_f32_16x16x32_fp8_fp8 v[200:203], v[194:195], v[148:149], v[200:203]
	v_cndmask_b32_e64 v226, v196, v198, s[54:55]
	v_cndmask_b32_e64 v227, v197, v199, s[54:55]
	s_waitcnt vmcnt(16)
	ds_write_b128 v168, v[26:29]
	ds_write_b128 v168, v[30:33] offset:1024
	v_lshl_add_u32 v176, v156, 10, v166
	global_load_dwordx4 v[26:29], v176, s[50:51]
	v_lshl_add_u32 v177, v157, 10, v167
	global_load_dwordx4 v[30:33], v177, s[50:51]
	ds_read_b128 v[188:191], v169
	ds_read_b128 v[192:195], v170
	s_waitcnt lgkmcnt(4)
	v_mfma_f32_16x16x32_fp8_fp8 v[204:207], v[180:181], v[142:143], 0
	v_mfma_f32_16x16x32_fp8_fp8 v[204:207], v[182:183], v[144:145], v[204:207]
	v_mfma_f32_16x16x32_fp8_fp8 v[204:207], v[184:185], v[146:147], v[204:207]
	v_mfma_f32_16x16x32_fp8_fp8 v[204:207], v[186:187], v[148:149], v[204:207]
	v_cndmask_b32_e64 v228, v200, v202, s[54:55]
	v_cndmask_b32_e64 v229, v201, v203, s[54:55]
	v_cndmask_b32_e64 v230, v226, v228, s[56:57]
	v_cndmask_b32_e64 v231, v227, v229, s[56:57]
	s_waitcnt vmcnt(16)
	ds_write_b128 v168, v[34:37]
	ds_write_b128 v168, v[38:41] offset:1024
	v_lshl_add_u32 v174, v158, 10, v166
	global_load_dwordx4 v[34:37], v174, s[50:51]
	v_lshl_add_u32 v175, v159, 10, v167
	global_load_dwordx4 v[38:41], v175, s[50:51]
	ds_read_b128 v[180:183], v169
	ds_read_b128 v[184:187], v170
	s_waitcnt lgkmcnt(4)
	v_mfma_f32_16x16x32_fp8_fp8 v[216:219], v[188:189], v[142:143], 0
	v_mfma_f32_16x16x32_fp8_fp8 v[216:219], v[190:191], v[144:145], v[216:219]
	v_mfma_f32_16x16x32_fp8_fp8 v[216:219], v[192:193], v[146:147], v[216:219]
	v_mfma_f32_16x16x32_fp8_fp8 v[216:219], v[194:195], v[148:149], v[216:219]
	v_cndmask_b32_e64 v226, v204, v206, s[54:55]
	v_cndmask_b32_e64 v227, v205, v207, s[54:55]
	s_waitcnt vmcnt(16)
	ds_write_b128 v168, v[42:45]
	ds_write_b128 v168, v[46:49] offset:1024
	v_lshl_add_u32 v176, v160, 10, v166
	global_load_dwordx4 v[42:45], v176, s[50:51]
	v_lshl_add_u32 v177, v161, 10, v167
	global_load_dwordx4 v[46:49], v177, s[50:51]
	ds_read_b128 v[188:191], v169
	ds_read_b128 v[192:195], v170
	s_waitcnt lgkmcnt(4)
	v_mfma_f32_16x16x32_fp8_fp8 v[196:199], v[180:181], v[142:143], 0
	v_mfma_f32_16x16x32_fp8_fp8 v[196:199], v[182:183], v[144:145], v[196:199]
	v_mfma_f32_16x16x32_fp8_fp8 v[196:199], v[184:185], v[146:147], v[196:199]
	v_mfma_f32_16x16x32_fp8_fp8 v[196:199], v[186:187], v[148:149], v[196:199]
	v_cndmask_b32_e64 v228, v216, v218, s[54:55]
	v_cndmask_b32_e64 v229, v217, v219, s[54:55]
	v_cndmask_b32_e64 v232, v226, v228, s[56:57]
	v_cndmask_b32_e64 v233, v227, v229, s[56:57]
	s_waitcnt vmcnt(16)
	ds_write_b128 v168, v[50:53]
	ds_write_b128 v168, v[54:57] offset:1024
	v_lshl_add_u32 v174, v162, 10, v166
	global_load_dwordx4 v[50:53], v174, s[50:51]
	v_lshl_add_u32 v175, v163, 10, v167
	global_load_dwordx4 v[54:57], v175, s[50:51]
	ds_read_b128 v[180:183], v169
	ds_read_b128 v[184:187], v170
	s_waitcnt lgkmcnt(4)
	v_mfma_f32_16x16x32_fp8_fp8 v[200:203], v[188:189], v[142:143], 0
	v_mfma_f32_16x16x32_fp8_fp8 v[200:203], v[190:191], v[144:145], v[200:203]
	v_mfma_f32_16x16x32_fp8_fp8 v[200:203], v[192:193], v[146:147], v[200:203]
	v_mfma_f32_16x16x32_fp8_fp8 v[200:203], v[194:195], v[148:149], v[200:203]
	v_cndmask_b32_e64 v226, v196, v198, s[54:55]
	v_cndmask_b32_e64 v227, v197, v199, s[54:55]
	s_waitcnt vmcnt(16)
	ds_write_b128 v168, v[58:61]
	ds_write_b128 v168, v[62:65] offset:1024
	v_lshl_add_u32 v176, v164, 10, v166
	global_load_dwordx4 v[58:61], v176, s[50:51]
	v_lshl_add_u32 v177, v165, 10, v167
	global_load_dwordx4 v[62:65], v177, s[50:51]
	ds_read_b128 v[188:191], v169
	ds_read_b128 v[192:195], v170
	s_waitcnt lgkmcnt(4)
	v_mfma_f32_16x16x32_fp8_fp8 v[204:207], v[180:181], v[142:143], 0
	v_mfma_f32_16x16x32_fp8_fp8 v[204:207], v[182:183], v[144:145], v[204:207]
	v_mfma_f32_16x16x32_fp8_fp8 v[204:207], v[184:185], v[146:147], v[204:207]
	v_mfma_f32_16x16x32_fp8_fp8 v[204:207], v[186:187], v[148:149], v[204:207]
	v_cndmask_b32_e64 v228, v200, v202, s[54:55]
	v_cndmask_b32_e64 v229, v201, v203, s[54:55]
	v_cndmask_b32_e64 v234, v226, v228, s[56:57]
	v_cndmask_b32_e64 v235, v227, v229, s[56:57]
	s_waitcnt lgkmcnt(0)
	v_mfma_f32_16x16x32_fp8_fp8 v[216:219], v[188:189], v[142:143], 0
	v_mfma_f32_16x16x32_fp8_fp8 v[216:219], v[190:191], v[144:145], v[216:219]
	v_mfma_f32_16x16x32_fp8_fp8 v[216:219], v[192:193], v[146:147], v[216:219]
	v_mfma_f32_16x16x32_fp8_fp8 v[216:219], v[194:195], v[148:149], v[216:219]
	v_add_u32_e32 v0, 5632, v172
	ds_read2_b32 v[150:151], v0 offset0:0 offset1:8
	ds_read2_b32 v[152:153], v0 offset0:16 offset1:24
	ds_read2_b32 v[154:155], v0 offset0:32 offset1:40
	ds_read2_b32 v[156:157], v0 offset0:48 offset1:56
	ds_read2_b32 v[158:159], v0 offset0:64 offset1:72
	ds_read2_b32 v[160:161], v0 offset0:80 offset1:88
	ds_read2_b32 v[162:163], v0 offset0:96 offset1:104
	ds_read2_b32 v[164:165], v0 offset0:112 offset1:120
	v_add_u32_e32 v171, s80, v171
	global_load_dwordx4 v[142:145], v171, s[52:53]
	global_load_dwordx4 v[146:149], v171, s[52:53] offset:16
	v_cndmask_b32_e64 v226, v204, v206, s[54:55]
	v_cndmask_b32_e64 v227, v205, v207, s[54:55]
	v_cndmask_b32_e64 v228, v216, v218, s[54:55]
	v_cndmask_b32_e64 v229, v217, v219, s[54:55]
	v_cndmask_b32_e64 v236, v226, v228, s[56:57]
	v_cndmask_b32_e64 v237, v227, v229, s[56:57]
	v_cndmask_b32_e64 v226, v230, v232, s[58:59]
	v_cndmask_b32_e64 v228, v234, v236, s[58:59]
	v_cndmask_b32_e64 v227, v231, v233, s[58:59]
	v_cndmask_b32_e64 v229, v235, v237, s[58:59]
	v_cndmask_b32_e64 v226, v226, v228, s[60:61]
	v_cndmask_b32_e64 v227, v227, v229, s[60:61]
	v_add_f32_e32 v100, v100, v226
	v_add_f32_e32 v101, v101, v227
	s_waitcnt vmcnt(16)
	ds_write_b128 v168, v[2:5]
	ds_write_b128 v168, v[6:9] offset:1024
	s_waitcnt lgkmcnt(2)
	v_lshl_add_u32 v174, v150, 10, v166
	global_load_dwordx4 v[2:5], v174, s[50:51]
	v_lshl_add_u32 v175, v151, 10, v167
	global_load_dwordx4 v[6:9], v175, s[50:51]
	ds_read_b128 v[180:183], v169
	ds_read_b128 v[184:187], v170
	s_waitcnt vmcnt(16)
	ds_write_b128 v168, v[10:13]
	ds_write_b128 v168, v[14:17] offset:1024
	v_lshl_add_u32 v176, v152, 10, v166
	global_load_dwordx4 v[10:13], v176, s[50:51]
	v_lshl_add_u32 v177, v153, 10, v167
	global_load_dwordx4 v[14:17], v177, s[50:51]
	ds_read_b128 v[188:191], v169
	ds_read_b128 v[192:195], v170
	s_waitcnt lgkmcnt(4)
	v_mfma_f32_16x16x32_fp8_fp8 v[196:199], v[180:181], v[134:135], 0
	v_mfma_f32_16x16x32_fp8_fp8 v[196:199], v[182:183], v[136:137], v[196:199]
	v_mfma_f32_16x16x32_fp8_fp8 v[196:199], v[184:185], v[138:139], v[196:199]
	v_mfma_f32_16x16x32_fp8_fp8 v[196:199], v[186:187], v[140:141], v[196:199]
	s_waitcnt vmcnt(16)
	ds_write_b128 v168, v[18:21]
	ds_write_b128 v168, v[22:25] offset:1024
	v_lshl_add_u32 v174, v154, 10, v166
	global_load_dwordx4 v[18:21], v174, s[50:51]
	v_lshl_add_u32 v175, v155, 10, v167
	global_load_dwordx4 v[22:25], v175, s[50:51]
	ds_read_b128 v[180:183], v169
	ds_read_b128 v[184:187], v170
	s_waitcnt lgkmcnt(4)
	v_mfma_f32_16x16x32_fp8_fp8 v[200:203], v[188:189], v[134:135], 0
	v_mfma_f32_16x16x32_fp8_fp8 v[200:203], v[190:191], v[136:137], v[200:203]
	v_mfma_f32_16x16x32_fp8_fp8 v[200:203], v[192:193], v[138:139], v[200:203]
	v_mfma_f32_16x16x32_fp8_fp8 v[200:203], v[194:195], v[140:141], v[200:203]
	v_cndmask_b32_e64 v226, v196, v198, s[54:55]
	v_cndmask_b32_e64 v227, v197, v199, s[54:55]
	s_waitcnt vmcnt(16)
	ds_write_b128 v168, v[26:29]
	ds_write_b128 v168, v[30:33] offset:1024
	v_lshl_add_u32 v176, v156, 10, v166
	global_load_dwordx4 v[26:29], v176, s[50:51]
	v_lshl_add_u32 v177, v157, 10, v167
	global_load_dwordx4 v[30:33], v177, s[50:51]
	ds_read_b128 v[188:191], v169
	ds_read_b128 v[192:195], v170
	s_waitcnt lgkmcnt(4)
	v_mfma_f32_16x16x32_fp8_fp8 v[204:207], v[180:181], v[134:135], 0
	v_mfma_f32_16x16x32_fp8_fp8 v[204:207], v[182:183], v[136:137], v[204:207]
	v_mfma_f32_16x16x32_fp8_fp8 v[204:207], v[184:185], v[138:139], v[204:207]
	v_mfma_f32_16x16x32_fp8_fp8 v[204:207], v[186:187], v[140:141], v[204:207]
	v_cndmask_b32_e64 v228, v200, v202, s[54:55]
	v_cndmask_b32_e64 v229, v201, v203, s[54:55]
	v_cndmask_b32_e64 v230, v226, v228, s[56:57]
	v_cndmask_b32_e64 v231, v227, v229, s[56:57]
	s_waitcnt vmcnt(16)
	ds_write_b128 v168, v[34:37]
	ds_write_b128 v168, v[38:41] offset:1024
	v_lshl_add_u32 v174, v158, 10, v166
	global_load_dwordx4 v[34:37], v174, s[50:51]
	v_lshl_add_u32 v175, v159, 10, v167
	global_load_dwordx4 v[38:41], v175, s[50:51]
	ds_read_b128 v[180:183], v169
	ds_read_b128 v[184:187], v170
	s_waitcnt lgkmcnt(4)
	v_mfma_f32_16x16x32_fp8_fp8 v[216:219], v[188:189], v[134:135], 0
	v_mfma_f32_16x16x32_fp8_fp8 v[216:219], v[190:191], v[136:137], v[216:219]
	v_mfma_f32_16x16x32_fp8_fp8 v[216:219], v[192:193], v[138:139], v[216:219]
	v_mfma_f32_16x16x32_fp8_fp8 v[216:219], v[194:195], v[140:141], v[216:219]
	v_cndmask_b32_e64 v226, v204, v206, s[54:55]
	v_cndmask_b32_e64 v227, v205, v207, s[54:55]
	s_waitcnt vmcnt(16)
	ds_write_b128 v168, v[42:45]
	ds_write_b128 v168, v[46:49] offset:1024
	v_lshl_add_u32 v176, v160, 10, v166
	global_load_dwordx4 v[42:45], v176, s[50:51]
	v_lshl_add_u32 v177, v161, 10, v167
	global_load_dwordx4 v[46:49], v177, s[50:51]
	ds_read_b128 v[188:191], v169
	ds_read_b128 v[192:195], v170
	s_waitcnt lgkmcnt(4)
	v_mfma_f32_16x16x32_fp8_fp8 v[196:199], v[180:181], v[134:135], 0
	v_mfma_f32_16x16x32_fp8_fp8 v[196:199], v[182:183], v[136:137], v[196:199]
	v_mfma_f32_16x16x32_fp8_fp8 v[196:199], v[184:185], v[138:139], v[196:199]
	v_mfma_f32_16x16x32_fp8_fp8 v[196:199], v[186:187], v[140:141], v[196:199]
	v_cndmask_b32_e64 v228, v216, v218, s[54:55]
	v_cndmask_b32_e64 v229, v217, v219, s[54:55]
	v_cndmask_b32_e64 v232, v226, v228, s[56:57]
	v_cndmask_b32_e64 v233, v227, v229, s[56:57]
	s_waitcnt vmcnt(16)
	ds_write_b128 v168, v[50:53]
	ds_write_b128 v168, v[54:57] offset:1024
	v_lshl_add_u32 v174, v162, 10, v166
	global_load_dwordx4 v[50:53], v174, s[50:51]
	v_lshl_add_u32 v175, v163, 10, v167
	global_load_dwordx4 v[54:57], v175, s[50:51]
	ds_read_b128 v[180:183], v169
	ds_read_b128 v[184:187], v170
	s_waitcnt lgkmcnt(4)
	v_mfma_f32_16x16x32_fp8_fp8 v[200:203], v[188:189], v[134:135], 0
	v_mfma_f32_16x16x32_fp8_fp8 v[200:203], v[190:191], v[136:137], v[200:203]
	v_mfma_f32_16x16x32_fp8_fp8 v[200:203], v[192:193], v[138:139], v[200:203]
	v_mfma_f32_16x16x32_fp8_fp8 v[200:203], v[194:195], v[140:141], v[200:203]
	v_cndmask_b32_e64 v226, v196, v198, s[54:55]
	v_cndmask_b32_e64 v227, v197, v199, s[54:55]
	s_waitcnt vmcnt(16)
	ds_write_b128 v168, v[58:61]
	ds_write_b128 v168, v[62:65] offset:1024
	v_lshl_add_u32 v176, v164, 10, v166
	global_load_dwordx4 v[58:61], v176, s[50:51]
	v_lshl_add_u32 v177, v165, 10, v167
	global_load_dwordx4 v[62:65], v177, s[50:51]
	ds_read_b128 v[188:191], v169
	ds_read_b128 v[192:195], v170
	s_waitcnt lgkmcnt(4)
	v_mfma_f32_16x16x32_fp8_fp8 v[204:207], v[180:181], v[134:135], 0
	v_mfma_f32_16x16x32_fp8_fp8 v[204:207], v[182:183], v[136:137], v[204:207]
	v_mfma_f32_16x16x32_fp8_fp8 v[204:207], v[184:185], v[138:139], v[204:207]
	v_mfma_f32_16x16x32_fp8_fp8 v[204:207], v[186:187], v[140:141], v[204:207]
	v_cndmask_b32_e64 v228, v200, v202, s[54:55]
	v_cndmask_b32_e64 v229, v201, v203, s[54:55]
	v_cndmask_b32_e64 v234, v226, v228, s[56:57]
	v_cndmask_b32_e64 v235, v227, v229, s[56:57]
	s_waitcnt lgkmcnt(0)
	v_mfma_f32_16x16x32_fp8_fp8 v[216:219], v[188:189], v[134:135], 0
	v_mfma_f32_16x16x32_fp8_fp8 v[216:219], v[190:191], v[136:137], v[216:219]
	v_mfma_f32_16x16x32_fp8_fp8 v[216:219], v[192:193], v[138:139], v[216:219]
	v_mfma_f32_16x16x32_fp8_fp8 v[216:219], v[194:195], v[140:141], v[216:219]
	v_add_u32_e32 v0, 0, v172
	ds_read2_b32 v[150:151], v0 offset0:0 offset1:8
	ds_read2_b32 v[152:153], v0 offset0:16 offset1:24
	ds_read2_b32 v[154:155], v0 offset0:32 offset1:40
	ds_read2_b32 v[156:157], v0 offset0:48 offset1:56
	ds_read2_b32 v[158:159], v0 offset0:64 offset1:72
	ds_read2_b32 v[160:161], v0 offset0:80 offset1:88
	ds_read2_b32 v[162:163], v0 offset0:96 offset1:104
	ds_read2_b32 v[164:165], v0 offset0:112 offset1:120
	v_add_u32_e32 v171, s81, v171
	global_load_dwordx4 v[134:137], v171, s[52:53]
	global_load_dwordx4 v[138:141], v171, s[52:53] offset:16
	v_cndmask_b32_e64 v226, v204, v206, s[54:55]
	v_cndmask_b32_e64 v227, v205, v207, s[54:55]
	v_cndmask_b32_e64 v228, v216, v218, s[54:55]
	v_cndmask_b32_e64 v229, v217, v219, s[54:55]
	v_cndmask_b32_e64 v236, v226, v228, s[56:57]
	v_cndmask_b32_e64 v237, v227, v229, s[56:57]
	v_cndmask_b32_e64 v226, v230, v232, s[58:59]
	v_cndmask_b32_e64 v228, v234, v236, s[58:59]
	v_cndmask_b32_e64 v227, v231, v233, s[58:59]
	v_cndmask_b32_e64 v229, v235, v237, s[58:59]
	v_cndmask_b32_e64 v226, v226, v228, s[60:61]
	v_cndmask_b32_e64 v227, v227, v229, s[60:61]
	v_add_f32_e32 v66, v66, v226
	v_add_f32_e32 v67, v67, v227
	v_add_u32_e32 v166, 0x80, v166
	v_add_u32_e32 v167, 0x80, v167
	s_waitcnt vmcnt(16)
	ds_write_b128 v168, v[2:5]
	ds_write_b128 v168, v[6:9] offset:1024
	s_waitcnt lgkmcnt(2)
	v_lshl_add_u32 v174, v150, 10, v166
	global_load_dwordx4 v[2:5], v174, s[50:51]
	v_lshl_add_u32 v175, v151, 10, v167
	global_load_dwordx4 v[6:9], v175, s[50:51]
	ds_read_b128 v[180:183], v169
	ds_read_b128 v[184:187], v170
	s_waitcnt vmcnt(16)
	ds_write_b128 v168, v[10:13]
	ds_write_b128 v168, v[14:17] offset:1024
	v_lshl_add_u32 v176, v152, 10, v166
	global_load_dwordx4 v[10:13], v176, s[50:51]
	v_lshl_add_u32 v177, v153, 10, v167
	global_load_dwordx4 v[14:17], v177, s[50:51]
	ds_read_b128 v[188:191], v169
	ds_read_b128 v[192:195], v170
	s_waitcnt lgkmcnt(4)
	v_mfma_f32_16x16x32_fp8_fp8 v[196:199], v[180:181], v[142:143], 0
	v_mfma_f32_16x16x32_fp8_fp8 v[196:199], v[182:183], v[144:145], v[196:199]
	v_mfma_f32_16x16x32_fp8_fp8 v[196:199], v[184:185], v[146:147], v[196:199]
	v_mfma_f32_16x16x32_fp8_fp8 v[196:199], v[186:187], v[148:149], v[196:199]
	s_waitcnt vmcnt(16)
	ds_write_b128 v168, v[18:21]
	ds_write_b128 v168, v[22:25] offset:1024
	v_lshl_add_u32 v174, v154, 10, v166
	global_load_dwordx4 v[18:21], v174, s[50:51]
	v_lshl_add_u32 v175, v155, 10, v167
	global_load_dwordx4 v[22:25], v175, s[50:51]
	ds_read_b128 v[180:183], v169
	ds_read_b128 v[184:187], v170
	s_waitcnt lgkmcnt(4)
	v_mfma_f32_16x16x32_fp8_fp8 v[200:203], v[188:189], v[142:143], 0
	v_mfma_f32_16x16x32_fp8_fp8 v[200:203], v[190:191], v[144:145], v[200:203]
	v_mfma_f32_16x16x32_fp8_fp8 v[200:203], v[192:193], v[146:147], v[200:203]
	v_mfma_f32_16x16x32_fp8_fp8 v[200:203], v[194:195], v[148:149], v[200:203]
	v_cndmask_b32_e64 v226, v196, v198, s[54:55]
	v_cndmask_b32_e64 v227, v197, v199, s[54:55]
	s_waitcnt vmcnt(16)
	ds_write_b128 v168, v[26:29]
	ds_write_b128 v168, v[30:33] offset:1024
	v_lshl_add_u32 v176, v156, 10, v166
	global_load_dwordx4 v[26:29], v176, s[50:51]
	v_lshl_add_u32 v177, v157, 10, v167
	global_load_dwordx4 v[30:33], v177, s[50:51]
	ds_read_b128 v[188:191], v169
	ds_read_b128 v[192:195], v170
	s_waitcnt lgkmcnt(4)
	v_mfma_f32_16x16x32_fp8_fp8 v[204:207], v[180:181], v[142:143], 0
	v_mfma_f32_16x16x32_fp8_fp8 v[204:207], v[182:183], v[144:145], v[204:207]
	v_mfma_f32_16x16x32_fp8_fp8 v[204:207], v[184:185], v[146:147], v[204:207]
	v_mfma_f32_16x16x32_fp8_fp8 v[204:207], v[186:187], v[148:149], v[204:207]
	v_cndmask_b32_e64 v228, v200, v202, s[54:55]
	v_cndmask_b32_e64 v229, v201, v203, s[54:55]
	v_cndmask_b32_e64 v230, v226, v228, s[56:57]
	v_cndmask_b32_e64 v231, v227, v229, s[56:57]
	s_waitcnt vmcnt(16)
	ds_write_b128 v168, v[34:37]
	ds_write_b128 v168, v[38:41] offset:1024
	v_lshl_add_u32 v174, v158, 10, v166
	global_load_dwordx4 v[34:37], v174, s[50:51]
	v_lshl_add_u32 v175, v159, 10, v167
	global_load_dwordx4 v[38:41], v175, s[50:51]
	ds_read_b128 v[180:183], v169
	ds_read_b128 v[184:187], v170
	s_waitcnt lgkmcnt(4)
	v_mfma_f32_16x16x32_fp8_fp8 v[216:219], v[188:189], v[142:143], 0
	v_mfma_f32_16x16x32_fp8_fp8 v[216:219], v[190:191], v[144:145], v[216:219]
	v_mfma_f32_16x16x32_fp8_fp8 v[216:219], v[192:193], v[146:147], v[216:219]
	v_mfma_f32_16x16x32_fp8_fp8 v[216:219], v[194:195], v[148:149], v[216:219]
	v_cndmask_b32_e64 v226, v204, v206, s[54:55]
	v_cndmask_b32_e64 v227, v205, v207, s[54:55]
	s_waitcnt vmcnt(16)
	ds_write_b128 v168, v[42:45]
	ds_write_b128 v168, v[46:49] offset:1024
	v_lshl_add_u32 v176, v160, 10, v166
	global_load_dwordx4 v[42:45], v176, s[50:51]
	v_lshl_add_u32 v177, v161, 10, v167
	global_load_dwordx4 v[46:49], v177, s[50:51]
	ds_read_b128 v[188:191], v169
	ds_read_b128 v[192:195], v170
	s_waitcnt lgkmcnt(4)
	v_mfma_f32_16x16x32_fp8_fp8 v[196:199], v[180:181], v[142:143], 0
	v_mfma_f32_16x16x32_fp8_fp8 v[196:199], v[182:183], v[144:145], v[196:199]
	v_mfma_f32_16x16x32_fp8_fp8 v[196:199], v[184:185], v[146:147], v[196:199]
	v_mfma_f32_16x16x32_fp8_fp8 v[196:199], v[186:187], v[148:149], v[196:199]
	v_cndmask_b32_e64 v228, v216, v218, s[54:55]
	v_cndmask_b32_e64 v229, v217, v219, s[54:55]
	v_cndmask_b32_e64 v232, v226, v228, s[56:57]
	v_cndmask_b32_e64 v233, v227, v229, s[56:57]
	s_waitcnt vmcnt(16)
	ds_write_b128 v168, v[50:53]
	ds_write_b128 v168, v[54:57] offset:1024
	v_lshl_add_u32 v174, v162, 10, v166
	global_load_dwordx4 v[50:53], v174, s[50:51]
	v_lshl_add_u32 v175, v163, 10, v167
	global_load_dwordx4 v[54:57], v175, s[50:51]
	ds_read_b128 v[180:183], v169
	ds_read_b128 v[184:187], v170
	s_waitcnt lgkmcnt(4)
	v_mfma_f32_16x16x32_fp8_fp8 v[200:203], v[188:189], v[142:143], 0
	v_mfma_f32_16x16x32_fp8_fp8 v[200:203], v[190:191], v[144:145], v[200:203]
	v_mfma_f32_16x16x32_fp8_fp8 v[200:203], v[192:193], v[146:147], v[200:203]
	v_mfma_f32_16x16x32_fp8_fp8 v[200:203], v[194:195], v[148:149], v[200:203]
	v_cndmask_b32_e64 v226, v196, v198, s[54:55]
	v_cndmask_b32_e64 v227, v197, v199, s[54:55]
	s_waitcnt vmcnt(16)
	ds_write_b128 v168, v[58:61]
	ds_write_b128 v168, v[62:65] offset:1024
	v_lshl_add_u32 v176, v164, 10, v166
	global_load_dwordx4 v[58:61], v176, s[50:51]
	v_lshl_add_u32 v177, v165, 10, v167
	global_load_dwordx4 v[62:65], v177, s[50:51]
	ds_read_b128 v[188:191], v169
	ds_read_b128 v[192:195], v170
	s_waitcnt lgkmcnt(4)
	v_mfma_f32_16x16x32_fp8_fp8 v[204:207], v[180:181], v[142:143], 0
	v_mfma_f32_16x16x32_fp8_fp8 v[204:207], v[182:183], v[144:145], v[204:207]
	v_mfma_f32_16x16x32_fp8_fp8 v[204:207], v[184:185], v[146:147], v[204:207]
	v_mfma_f32_16x16x32_fp8_fp8 v[204:207], v[186:187], v[148:149], v[204:207]
	v_cndmask_b32_e64 v228, v200, v202, s[54:55]
	v_cndmask_b32_e64 v229, v201, v203, s[54:55]
	v_cndmask_b32_e64 v234, v226, v228, s[56:57]
	v_cndmask_b32_e64 v235, v227, v229, s[56:57]
	s_waitcnt lgkmcnt(0)
	v_mfma_f32_16x16x32_fp8_fp8 v[216:219], v[188:189], v[142:143], 0
	v_mfma_f32_16x16x32_fp8_fp8 v[216:219], v[190:191], v[144:145], v[216:219]
	v_mfma_f32_16x16x32_fp8_fp8 v[216:219], v[192:193], v[146:147], v[216:219]
	v_mfma_f32_16x16x32_fp8_fp8 v[216:219], v[194:195], v[148:149], v[216:219]
	v_add_u32_e32 v0, 512, v172
	ds_read2_b32 v[150:151], v0 offset0:0 offset1:8
	ds_read2_b32 v[152:153], v0 offset0:16 offset1:24
	ds_read2_b32 v[154:155], v0 offset0:32 offset1:40
	ds_read2_b32 v[156:157], v0 offset0:48 offset1:56
	ds_read2_b32 v[158:159], v0 offset0:64 offset1:72
	ds_read2_b32 v[160:161], v0 offset0:80 offset1:88
	ds_read2_b32 v[162:163], v0 offset0:96 offset1:104
	ds_read2_b32 v[164:165], v0 offset0:112 offset1:120
	v_add_u32_e32 v171, s80, v171
	global_load_dwordx4 v[142:145], v171, s[52:53]
	global_load_dwordx4 v[146:149], v171, s[52:53] offset:16
	v_cndmask_b32_e64 v226, v204, v206, s[54:55]
	v_cndmask_b32_e64 v227, v205, v207, s[54:55]
	v_cndmask_b32_e64 v228, v216, v218, s[54:55]
	v_cndmask_b32_e64 v229, v217, v219, s[54:55]
	v_cndmask_b32_e64 v236, v226, v228, s[56:57]
	v_cndmask_b32_e64 v237, v227, v229, s[56:57]
	v_cndmask_b32_e64 v226, v230, v232, s[58:59]
	v_cndmask_b32_e64 v228, v234, v236, s[58:59]
	v_cndmask_b32_e64 v227, v231, v233, s[58:59]
	v_cndmask_b32_e64 v229, v235, v237, s[58:59]
	v_cndmask_b32_e64 v226, v226, v228, s[60:61]
	v_cndmask_b32_e64 v227, v227, v229, s[60:61]
	v_add_f32_e32 v68, v68, v226
	v_add_f32_e32 v69, v69, v227
	s_add_i32 s49, s49, 1
	s_cmp_lt_u32 s49, 8
	s_cbranch_scc1 .Lu_cloop
	s_waitcnt vmcnt(0)
	v_lshrrev_b32_e32 v202, 1, v209
	v_lshlrev_b32_e32 v202, 4, v202
	v_lshl_add_u32 v202, v103, 2, v202
	v_and_b32_e32 v203, 1, v209
	v_lshl_add_u32 v202, v203, 1, v202
	v_lshlrev_b32_e32 v196, 2, v202
	v_lshrrev_b32_e32 v203, 6, v179
	v_mul_u32_u24_e32 v203, 0x3000, v203
	v_add_u32_e32 v198, v203, v196
	v_lshl_add_u32 v197, v202, 3, v203
	ds_read_b64 v[2:3], v198 offset:0
	ds_read_b64 v[4:5], v198 offset:512
	ds_read_b64 v[6:7], v198 offset:1024
	ds_read_b64 v[8:9], v198 offset:1536
	ds_read_b64 v[10:11], v198 offset:2048
	ds_read_b64 v[12:13], v198 offset:2560
	ds_read_b64 v[14:15], v198 offset:3072
	ds_read_b64 v[16:17], v198 offset:3584
	ds_read_b64 v[18:19], v198 offset:4096
	ds_read_b64 v[20:21], v198 offset:4608
	ds_read_b64 v[22:23], v198 offset:5120
	ds_read_b64 v[24:25], v198 offset:5632
	v_readfirstlane_b32 s20, v78
	v_readfirstlane_b32 s21, v79
	s_mov_b32 s8, 0x378e98ab
	s_mov_b32 s9, 0x3b7cd369
	s_mov_b32 s13, 0xbcc618b2
	s_mov_b32 s32, 0x3dda74e4
	s_mov_b32 s38, 0x3f228afd
	s_mov_b32 s49, 0x3e03c728
	s_mov_b32 s50, 0x42ce8ed0
	s_mov_b32 s51, 0xc2b17218
	v_mov_b32_e32 v199, v70
	s_waitcnt lgkmcnt(0)
	v_lshlrev_b32_e32 v202, 2, v199
	global_load_dword v26, v202, s[42:43]
	v_lshl_add_u32 v203, v199, 9, v196
	global_load_dwordx2 v[28:29], v203, s[20:21]
	v_lshlrev_b32_e32 v200, 2, v2
	v_lshlrev_b32_e32 v201, 2, v3
	global_load_dword v30, v200, s[6:7]
	global_load_dword v31, v201, s[6:7]
	global_load_dword v32, v200, s[22:23]
	global_load_dword v33, v201, s[22:23]
	v_add_u32_e32 v199, s30, v199
	v_lshlrev_b32_e32 v202, 2, v199
	global_load_dword v34, v202, s[42:43]
	v_lshl_add_u32 v203, v199, 9, v196
	global_load_dwordx2 v[36:37], v203, s[20:21]
	v_lshlrev_b32_e32 v200, 2, v4
	v_lshlrev_b32_e32 v201, 2, v5
	global_load_dword v38, v200, s[6:7]
	global_load_dword v39, v201, s[6:7]
	global_load_dword v40, v200, s[22:23]
	global_load_dword v41, v201, s[22:23]
	v_add_u32_e32 v199, s30, v199
	v_lshlrev_b32_e32 v202, 2, v199
	global_load_dword v42, v202, s[42:43]
	v_lshl_add_u32 v203, v199, 9, v196
	global_load_dwordx2 v[44:45], v203, s[20:21]
	v_lshlrev_b32_e32 v200, 2, v6
	v_lshlrev_b32_e32 v201, 2, v7
	global_load_dword v46, v200, s[6:7]
	global_load_dword v47, v201, s[6:7]
	global_load_dword v48, v200, s[22:23]
	global_load_dword v49, v201, s[22:23]
	v_add_u32_e32 v199, s30, v199
	v_lshlrev_b32_e32 v202, 2, v199
	global_load_dword v50, v202, s[42:43]
	v_lshl_add_u32 v203, v199, 9, v196
	global_load_dwordx2 v[52:53], v203, s[20:21]
	v_lshlrev_b32_e32 v200, 2, v8
	v_lshlrev_b32_e32 v201, 2, v9
	global_load_dword v54, v200, s[6:7]
	global_load_dword v55, v201, s[6:7]
	global_load_dword v56, v200, s[22:23]
	global_load_dword v57, v201, s[22:23]
	v_add_u32_e32 v199, s30, v199
	v_lshlrev_b32_e32 v202, 2, v199
	global_load_dword v58, v202, s[42:43]
	v_lshl_add_u32 v203, v199, 9, v196
	global_load_dwordx2 v[60:61], v203, s[20:21]
	v_lshlrev_b32_e32 v200, 2, v10
	v_lshlrev_b32_e32 v201, 2, v11
	global_load_dword v62, v200, s[6:7]
	global_load_dword v63, v201, s[6:7]
	global_load_dword v64, v200, s[22:23]
	global_load_dword v65, v201, s[22:23]
	v_add_u32_e32 v199, s30, v199
	v_lshlrev_b32_e32 v202, 2, v199
	global_load_dword v134, v202, s[42:43]
	v_lshl_add_u32 v203, v199, 9, v196
	global_load_dwordx2 v[136:137], v203, s[20:21]
	v_lshlrev_b32_e32 v200, 2, v12
	v_lshlrev_b32_e32 v201, 2, v13
	global_load_dword v138, v200, s[6:7]
	global_load_dword v139, v201, s[6:7]
	global_load_dword v140, v200, s[22:23]
	global_load_dword v141, v201, s[22:23]
	v_add_u32_e32 v199, s30, v199
	v_lshlrev_b32_e32 v202, 2, v199
	global_load_dword v142, v202, s[42:43]
	v_lshl_add_u32 v203, v199, 9, v196
	global_load_dwordx2 v[144:145], v203, s[20:21]
	v_lshlrev_b32_e32 v200, 2, v14
	v_lshlrev_b32_e32 v201, 2, v15
	global_load_dword v146, v200, s[6:7]
	global_load_dword v147, v201, s[6:7]
	global_load_dword v148, v200, s[22:23]
	global_load_dword v149, v201, s[22:23]
	v_add_u32_e32 v199, s30, v199
	v_lshlrev_b32_e32 v202, 2, v199
	global_load_dword v150, v202, s[42:43]
	v_lshl_add_u32 v203, v199, 9, v196
	global_load_dwordx2 v[152:153], v203, s[20:21]
	v_lshlrev_b32_e32 v200, 2, v16
	v_lshlrev_b32_e32 v201, 2, v17
	global_load_dword v154, v200, s[6:7]
	global_load_dword v155, v201, s[6:7]
	global_load_dword v156, v200, s[22:23]
	global_load_dword v157, v201, s[22:23]
	v_add_u32_e32 v199, s30, v199
	s_waitcnt vmcnt(42)
	v_lshlrev_b32_e32 v204, 10, v2
	v_lshlrev_b32_e32 v205, 10, v3
	v_mul_f32_e32 v229, v242, v26
	v_mul_f32_e32 v229, v229, v30
	v_mul_f32_e32 v216, 0x3f3504f3, v229
	v_fma_f32 v217, |v216|, s8, v223
	v_fma_f32 v217, |v216|, v217, s9
	v_fma_f32 v217, |v216|, v217, s13
	v_fma_f32 v217, |v216|, v217, s32
	v_fma_f32 v217, |v216|, v217, s38
	v_fma_f32 v217, |v216|, v217, s49
	v_fma_f32 v217, |v216|, v217, |v216|
	v_mul_f32_e32 v218, 0xbfb8aa3b, v217
	v_fma_f32 v219, v217, s27, -v218
	v_rndne_f32_e32 v226, v218
	v_fmac_f32_e32 v219, 0xb2a5705f, v217
	v_sub_f32_e32 v218, v218, v226
	v_add_f32_e32 v218, v218, v219
	v_cvt_i32_f32_e32 v219, v226
	v_exp_f32_e32 v218, v218
	v_cmp_nlt_f32_e32 vcc, s50, v217
	v_mul_f32_e32 v227, v216, v216
	v_ldexp_f32 v218, v218, v219
	v_fmamk_f32 v228, v227, 0xba1345e1, v212
	v_cndmask_b32_e32 v218, 0, v218, vcc
	v_cmp_ngt_f32_e32 vcc, s51, v217
	v_fmaak_f32 v228, v227, v228, 0xbcdac9b8
	v_fmaak_f32 v228, v227, v228, 0x3de703be
	v_cndmask_b32_e32 v217, v224, v218, vcc
	v_fmaak_f32 v228, v227, v228, 0xbec09330
	v_sub_f32_e32 v217, 1.0, v217
	v_fmaak_f32 v227, v227, v228, 0x3e0375d0
	v_cmp_nlt_f32_e64 vcc, |v216|, 1.0
	v_fma_f32 v227, |v216|, v227, |v216|
	v_mul_f32_e32 v229, 0.5, v229
	v_cndmask_b32_e32 v217, v227, v217, vcc
	v_bfi_b32 v217, s78, v217, v216
	v_add_f32_e32 v217, 1.0, v217
	v_mul_f32_e32 v229, v229, v217
	v_mul_f32_e32 v229, v28, v229
	v_mul_f32_e32 v206, v32, v229
	v_mul_f32_e32 v229, v243, v26
	v_mul_f32_e32 v229, v229, v31
	v_mul_f32_e32 v216, 0x3f3504f3, v229
	v_fma_f32 v217, |v216|, s8, v223
	v_fma_f32 v217, |v216|, v217, s9
	v_fma_f32 v217, |v216|, v217, s13
	v_fma_f32 v217, |v216|, v217, s32
	v_fma_f32 v217, |v216|, v217, s38
	v_fma_f32 v217, |v216|, v217, s49
	v_fma_f32 v217, |v216|, v217, |v216|
	v_mul_f32_e32 v218, 0xbfb8aa3b, v217
	v_fma_f32 v219, v217, s27, -v218
	v_rndne_f32_e32 v226, v218
	v_fmac_f32_e32 v219, 0xb2a5705f, v217
	v_sub_f32_e32 v218, v218, v226
	v_add_f32_e32 v218, v218, v219
	v_cvt_i32_f32_e32 v219, v226
	v_exp_f32_e32 v218, v218
	v_cmp_nlt_f32_e32 vcc, s50, v217
	v_mul_f32_e32 v227, v216, v216
	v_ldexp_f32 v218, v218, v219
	v_fmamk_f32 v228, v227, 0xba1345e1, v212
	v_cndmask_b32_e32 v218, 0, v218, vcc
	v_cmp_ngt_f32_e32 vcc, s51, v217
	v_fmaak_f32 v228, v227, v228, 0xbcdac9b8
	v_fmaak_f32 v228, v227, v228, 0x3de703be
	v_cndmask_b32_e32 v217, v224, v218, vcc
	v_fmaak_f32 v228, v227, v228, 0xbec09330
	v_sub_f32_e32 v217, 1.0, v217
	v_fmaak_f32 v227, v227, v228, 0x3e0375d0
	v_cmp_nlt_f32_e64 vcc, |v216|, 1.0
	v_fma_f32 v227, |v216|, v227, |v216|
	v_mul_f32_e32 v229, 0.5, v229
	v_cndmask_b32_e32 v217, v227, v217, vcc
	v_bfi_b32 v217, s78, v217, v216
	v_add_f32_e32 v217, 1.0, v217
	v_mul_f32_e32 v229, v229, v217
	v_mul_f32_e32 v229, v29, v229
	v_mul_f32_e32 v207, v33, v229
	ds_write_b64 v198, v[204:205] offset:0
	ds_write_b64 v198, v[206:207] offset:6144
	v_lshlrev_b32_e32 v202, 2, v199
	global_load_dword v158, v202, s[42:43]
	v_lshl_add_u32 v203, v199, 9, v196
	global_load_dwordx2 v[160:161], v203, s[20:21]
	v_lshlrev_b32_e32 v200, 2, v18
	v_lshlrev_b32_e32 v201, 2, v19
	global_load_dword v162, v200, s[6:7]
	global_load_dword v163, v201, s[6:7]
	global_load_dword v164, v200, s[22:23]
	global_load_dword v165, v201, s[22:23]
	v_add_u32_e32 v199, s30, v199
	s_waitcnt vmcnt(42)
	v_lshlrev_b32_e32 v204, 10, v4
	v_lshlrev_b32_e32 v205, 10, v5
	v_mul_f32_e32 v229, v244, v34
	v_mul_f32_e32 v229, v229, v38
	v_mul_f32_e32 v216, 0x3f3504f3, v229
	v_fma_f32 v217, |v216|, s8, v223
	v_fma_f32 v217, |v216|, v217, s9
	v_fma_f32 v217, |v216|, v217, s13
	v_fma_f32 v217, |v216|, v217, s32
	v_fma_f32 v217, |v216|, v217, s38
	v_fma_f32 v217, |v216|, v217, s49
	v_fma_f32 v217, |v216|, v217, |v216|
	v_mul_f32_e32 v218, 0xbfb8aa3b, v217
	v_fma_f32 v219, v217, s27, -v218
	v_rndne_f32_e32 v226, v218
	v_fmac_f32_e32 v219, 0xb2a5705f, v217
	v_sub_f32_e32 v218, v218, v226
	v_add_f32_e32 v218, v218, v219
	v_cvt_i32_f32_e32 v219, v226
	v_exp_f32_e32 v218, v218
	v_cmp_nlt_f32_e32 vcc, s50, v217
	v_mul_f32_e32 v227, v216, v216
	v_ldexp_f32 v218, v218, v219
	v_fmamk_f32 v228, v227, 0xba1345e1, v212
	v_cndmask_b32_e32 v218, 0, v218, vcc
	v_cmp_ngt_f32_e32 vcc, s51, v217
	v_fmaak_f32 v228, v227, v228, 0xbcdac9b8
	v_fmaak_f32 v228, v227, v228, 0x3de703be
	v_cndmask_b32_e32 v217, v224, v218, vcc
	v_fmaak_f32 v228, v227, v228, 0xbec09330
	v_sub_f32_e32 v217, 1.0, v217
	v_fmaak_f32 v227, v227, v228, 0x3e0375d0
	v_cmp_nlt_f32_e64 vcc, |v216|, 1.0
	v_fma_f32 v227, |v216|, v227, |v216|
	v_mul_f32_e32 v229, 0.5, v229
	v_cndmask_b32_e32 v217, v227, v217, vcc
	v_bfi_b32 v217, s78, v217, v216
	v_add_f32_e32 v217, 1.0, v217
	v_mul_f32_e32 v229, v229, v217
	v_mul_f32_e32 v229, v36, v229
	v_mul_f32_e32 v206, v40, v229
	v_mul_f32_e32 v229, v245, v34
	v_mul_f32_e32 v229, v229, v39
	v_mul_f32_e32 v216, 0x3f3504f3, v229
	v_fma_f32 v217, |v216|, s8, v223
	v_fma_f32 v217, |v216|, v217, s9
	v_fma_f32 v217, |v216|, v217, s13
	v_fma_f32 v217, |v216|, v217, s32
	v_fma_f32 v217, |v216|, v217, s38
	v_fma_f32 v217, |v216|, v217, s49
	v_fma_f32 v217, |v216|, v217, |v216|
	v_mul_f32_e32 v218, 0xbfb8aa3b, v217
	v_fma_f32 v219, v217, s27, -v218
	v_rndne_f32_e32 v226, v218
	v_fmac_f32_e32 v219, 0xb2a5705f, v217
	v_sub_f32_e32 v218, v218, v226
	v_add_f32_e32 v218, v218, v219
	v_cvt_i32_f32_e32 v219, v226
	v_exp_f32_e32 v218, v218
	v_cmp_nlt_f32_e32 vcc, s50, v217
	v_mul_f32_e32 v227, v216, v216
	v_ldexp_f32 v218, v218, v219
	v_fmamk_f32 v228, v227, 0xba1345e1, v212
	v_cndmask_b32_e32 v218, 0, v218, vcc
	v_cmp_ngt_f32_e32 vcc, s51, v217
	v_fmaak_f32 v228, v227, v228, 0xbcdac9b8
	v_fmaak_f32 v228, v227, v228, 0x3de703be
	v_cndmask_b32_e32 v217, v224, v218, vcc
	v_fmaak_f32 v228, v227, v228, 0xbec09330
	v_sub_f32_e32 v217, 1.0, v217
	v_fmaak_f32 v227, v227, v228, 0x3e0375d0
	v_cmp_nlt_f32_e64 vcc, |v216|, 1.0
	v_fma_f32 v227, |v216|, v227, |v216|
	v_mul_f32_e32 v229, 0.5, v229
	v_cndmask_b32_e32 v217, v227, v217, vcc
	v_bfi_b32 v217, s78, v217, v216
	v_add_f32_e32 v217, 1.0, v217
	v_mul_f32_e32 v229, v229, v217
	v_mul_f32_e32 v229, v37, v229
	v_mul_f32_e32 v207, v41, v229
	ds_write_b64 v198, v[204:205] offset:512
	ds_write_b64 v198, v[206:207] offset:6656
	v_lshlrev_b32_e32 v202, 2, v199
	global_load_dword v166, v202, s[42:43]
	v_lshl_add_u32 v203, v199, 9, v196
	global_load_dwordx2 v[168:169], v203, s[20:21]
	v_lshlrev_b32_e32 v200, 2, v20
	v_lshlrev_b32_e32 v201, 2, v21
	global_load_dword v170, v200, s[6:7]
	global_load_dword v171, v201, s[6:7]
	global_load_dword v172, v200, s[22:23]
	global_load_dword v173, v201, s[22:23]
	v_add_u32_e32 v199, s30, v199
	s_waitcnt vmcnt(42)
	v_lshlrev_b32_e32 v204, 10, v6
	v_lshlrev_b32_e32 v205, 10, v7
	v_mul_f32_e32 v229, v246, v42
	v_mul_f32_e32 v229, v229, v46
	v_mul_f32_e32 v216, 0x3f3504f3, v229
	v_fma_f32 v217, |v216|, s8, v223
	v_fma_f32 v217, |v216|, v217, s9
	v_fma_f32 v217, |v216|, v217, s13
	v_fma_f32 v217, |v216|, v217, s32
	v_fma_f32 v217, |v216|, v217, s38
	v_fma_f32 v217, |v216|, v217, s49
	v_fma_f32 v217, |v216|, v217, |v216|
	v_mul_f32_e32 v218, 0xbfb8aa3b, v217
	v_fma_f32 v219, v217, s27, -v218
	v_rndne_f32_e32 v226, v218
	v_fmac_f32_e32 v219, 0xb2a5705f, v217
	v_sub_f32_e32 v218, v218, v226
	v_add_f32_e32 v218, v218, v219
	v_cvt_i32_f32_e32 v219, v226
	v_exp_f32_e32 v218, v218
	v_cmp_nlt_f32_e32 vcc, s50, v217
	v_mul_f32_e32 v227, v216, v216
	v_ldexp_f32 v218, v218, v219
	v_fmamk_f32 v228, v227, 0xba1345e1, v212
	v_cndmask_b32_e32 v218, 0, v218, vcc
	v_cmp_ngt_f32_e32 vcc, s51, v217
	v_fmaak_f32 v228, v227, v228, 0xbcdac9b8
	v_fmaak_f32 v228, v227, v228, 0x3de703be
	v_cndmask_b32_e32 v217, v224, v218, vcc
	v_fmaak_f32 v228, v227, v228, 0xbec09330
	v_sub_f32_e32 v217, 1.0, v217
	v_fmaak_f32 v227, v227, v228, 0x3e0375d0
	v_cmp_nlt_f32_e64 vcc, |v216|, 1.0
	v_fma_f32 v227, |v216|, v227, |v216|
	v_mul_f32_e32 v229, 0.5, v229
	v_cndmask_b32_e32 v217, v227, v217, vcc
	v_bfi_b32 v217, s78, v217, v216
	v_add_f32_e32 v217, 1.0, v217
	v_mul_f32_e32 v229, v229, v217
	v_mul_f32_e32 v229, v44, v229
	v_mul_f32_e32 v206, v48, v229
	v_mul_f32_e32 v229, v247, v42
	v_mul_f32_e32 v229, v229, v47
	v_mul_f32_e32 v216, 0x3f3504f3, v229
	v_fma_f32 v217, |v216|, s8, v223
	v_fma_f32 v217, |v216|, v217, s9
	v_fma_f32 v217, |v216|, v217, s13
	v_fma_f32 v217, |v216|, v217, s32
	v_fma_f32 v217, |v216|, v217, s38
	v_fma_f32 v217, |v216|, v217, s49
	v_fma_f32 v217, |v216|, v217, |v216|
	v_mul_f32_e32 v218, 0xbfb8aa3b, v217
	v_fma_f32 v219, v217, s27, -v218
	v_rndne_f32_e32 v226, v218
	v_fmac_f32_e32 v219, 0xb2a5705f, v217
	v_sub_f32_e32 v218, v218, v226
	v_add_f32_e32 v218, v218, v219
	v_cvt_i32_f32_e32 v219, v226
	v_exp_f32_e32 v218, v218
	v_cmp_nlt_f32_e32 vcc, s50, v217
	v_mul_f32_e32 v227, v216, v216
	v_ldexp_f32 v218, v218, v219
	v_fmamk_f32 v228, v227, 0xba1345e1, v212
	v_cndmask_b32_e32 v218, 0, v218, vcc
	v_cmp_ngt_f32_e32 vcc, s51, v217
	v_fmaak_f32 v228, v227, v228, 0xbcdac9b8
	v_fmaak_f32 v228, v227, v228, 0x3de703be
	v_cndmask_b32_e32 v217, v224, v218, vcc
	v_fmaak_f32 v228, v227, v228, 0xbec09330
	v_sub_f32_e32 v217, 1.0, v217
	v_fmaak_f32 v227, v227, v228, 0x3e0375d0
	v_cmp_nlt_f32_e64 vcc, |v216|, 1.0
	v_fma_f32 v227, |v216|, v227, |v216|
	v_mul_f32_e32 v229, 0.5, v229
	v_cndmask_b32_e32 v217, v227, v217, vcc
	v_bfi_b32 v217, s78, v217, v216
	v_add_f32_e32 v217, 1.0, v217
	v_mul_f32_e32 v229, v229, v217
	v_mul_f32_e32 v229, v45, v229
	v_mul_f32_e32 v207, v49, v229
	ds_write_b64 v198, v[204:205] offset:1024
	ds_write_b64 v198, v[206:207] offset:7168
	v_lshlrev_b32_e32 v202, 2, v199
	global_load_dword v180, v202, s[42:43]
	v_lshl_add_u32 v203, v199, 9, v196
	global_load_dwordx2 v[182:183], v203, s[20:21]
	v_lshlrev_b32_e32 v200, 2, v22
	v_lshlrev_b32_e32 v201, 2, v23
	global_load_dword v184, v200, s[6:7]
	global_load_dword v185, v201, s[6:7]
	global_load_dword v186, v200, s[22:23]
	global_load_dword v187, v201, s[22:23]
	v_add_u32_e32 v199, s30, v199
	s_waitcnt vmcnt(42)
	v_lshlrev_b32_e32 v204, 10, v8
	v_lshlrev_b32_e32 v205, 10, v9
	v_mul_f32_e32 v229, v248, v50
	v_mul_f32_e32 v229, v229, v54
	v_mul_f32_e32 v216, 0x3f3504f3, v229
	v_fma_f32 v217, |v216|, s8, v223
	v_fma_f32 v217, |v216|, v217, s9
	v_fma_f32 v217, |v216|, v217, s13
	v_fma_f32 v217, |v216|, v217, s32
	v_fma_f32 v217, |v216|, v217, s38
	v_fma_f32 v217, |v216|, v217, s49
	v_fma_f32 v217, |v216|, v217, |v216|
	v_mul_f32_e32 v218, 0xbfb8aa3b, v217
	v_fma_f32 v219, v217, s27, -v218
	v_rndne_f32_e32 v226, v218
	v_fmac_f32_e32 v219, 0xb2a5705f, v217
	v_sub_f32_e32 v218, v218, v226
	v_add_f32_e32 v218, v218, v219
	v_cvt_i32_f32_e32 v219, v226
	v_exp_f32_e32 v218, v218
	v_cmp_nlt_f32_e32 vcc, s50, v217
	v_mul_f32_e32 v227, v216, v216
	v_ldexp_f32 v218, v218, v219
	v_fmamk_f32 v228, v227, 0xba1345e1, v212
	v_cndmask_b32_e32 v218, 0, v218, vcc
	v_cmp_ngt_f32_e32 vcc, s51, v217
	v_fmaak_f32 v228, v227, v228, 0xbcdac9b8
	v_fmaak_f32 v228, v227, v228, 0x3de703be
	v_cndmask_b32_e32 v217, v224, v218, vcc
	v_fmaak_f32 v228, v227, v228, 0xbec09330
	v_sub_f32_e32 v217, 1.0, v217
	v_fmaak_f32 v227, v227, v228, 0x3e0375d0
	v_cmp_nlt_f32_e64 vcc, |v216|, 1.0
	v_fma_f32 v227, |v216|, v227, |v216|
	v_mul_f32_e32 v229, 0.5, v229
	v_cndmask_b32_e32 v217, v227, v217, vcc
	v_bfi_b32 v217, s78, v217, v216
	v_add_f32_e32 v217, 1.0, v217
	v_mul_f32_e32 v229, v229, v217
	v_mul_f32_e32 v229, v52, v229
	v_mul_f32_e32 v206, v56, v229
	v_mul_f32_e32 v229, v249, v50
	v_mul_f32_e32 v229, v229, v55
	v_mul_f32_e32 v216, 0x3f3504f3, v229
	v_fma_f32 v217, |v216|, s8, v223
	v_fma_f32 v217, |v216|, v217, s9
	v_fma_f32 v217, |v216|, v217, s13
	v_fma_f32 v217, |v216|, v217, s32
	v_fma_f32 v217, |v216|, v217, s38
	v_fma_f32 v217, |v216|, v217, s49
	v_fma_f32 v217, |v216|, v217, |v216|
	v_mul_f32_e32 v218, 0xbfb8aa3b, v217
	v_fma_f32 v219, v217, s27, -v218
	v_rndne_f32_e32 v226, v218
	v_fmac_f32_e32 v219, 0xb2a5705f, v217
	v_sub_f32_e32 v218, v218, v226
	v_add_f32_e32 v218, v218, v219
	v_cvt_i32_f32_e32 v219, v226
	v_exp_f32_e32 v218, v218
	v_cmp_nlt_f32_e32 vcc, s50, v217
	v_mul_f32_e32 v227, v216, v216
	v_ldexp_f32 v218, v218, v219
	v_fmamk_f32 v228, v227, 0xba1345e1, v212
	v_cndmask_b32_e32 v218, 0, v218, vcc
	v_cmp_ngt_f32_e32 vcc, s51, v217
	v_fmaak_f32 v228, v227, v228, 0xbcdac9b8
	v_fmaak_f32 v228, v227, v228, 0x3de703be
	v_cndmask_b32_e32 v217, v224, v218, vcc
	v_fmaak_f32 v228, v227, v228, 0xbec09330
	v_sub_f32_e32 v217, 1.0, v217
	v_fmaak_f32 v227, v227, v228, 0x3e0375d0
	v_cmp_nlt_f32_e64 vcc, |v216|, 1.0
	v_fma_f32 v227, |v216|, v227, |v216|
	v_mul_f32_e32 v229, 0.5, v229
	v_cndmask_b32_e32 v217, v227, v217, vcc
	v_bfi_b32 v217, s78, v217, v216
	v_add_f32_e32 v217, 1.0, v217
	v_mul_f32_e32 v229, v229, v217
	v_mul_f32_e32 v229, v53, v229
	v_mul_f32_e32 v207, v57, v229
	ds_write_b64 v198, v[204:205] offset:1536
	ds_write_b64 v198, v[206:207] offset:7680
	v_lshlrev_b32_e32 v202, 2, v199
	global_load_dword v188, v202, s[42:43]
	v_lshl_add_u32 v203, v199, 9, v196
	global_load_dwordx2 v[190:191], v203, s[20:21]
	v_lshlrev_b32_e32 v200, 2, v24
	v_lshlrev_b32_e32 v201, 2, v25
	global_load_dword v192, v200, s[6:7]
	global_load_dword v193, v201, s[6:7]
	global_load_dword v194, v200, s[22:23]
	global_load_dword v195, v201, s[22:23]
	v_add_u32_e32 v199, s30, v199
	s_waitcnt vmcnt(42)
	v_lshlrev_b32_e32 v204, 10, v10
	v_lshlrev_b32_e32 v205, 10, v11
	v_mul_f32_e32 v229, v238, v58
	v_mul_f32_e32 v229, v229, v62
	v_mul_f32_e32 v216, 0x3f3504f3, v229
	v_fma_f32 v217, |v216|, s8, v223
	v_fma_f32 v217, |v216|, v217, s9
	v_fma_f32 v217, |v216|, v217, s13
	v_fma_f32 v217, |v216|, v217, s32
	v_fma_f32 v217, |v216|, v217, s38
	v_fma_f32 v217, |v216|, v217, s49
	v_fma_f32 v217, |v216|, v217, |v216|
	v_mul_f32_e32 v218, 0xbfb8aa3b, v217
	v_fma_f32 v219, v217, s27, -v218
	v_rndne_f32_e32 v226, v218
	v_fmac_f32_e32 v219, 0xb2a5705f, v217
	v_sub_f32_e32 v218, v218, v226
	v_add_f32_e32 v218, v218, v219
	v_cvt_i32_f32_e32 v219, v226
	v_exp_f32_e32 v218, v218
	v_cmp_nlt_f32_e32 vcc, s50, v217
	v_mul_f32_e32 v227, v216, v216
	v_ldexp_f32 v218, v218, v219
	v_fmamk_f32 v228, v227, 0xba1345e1, v212
	v_cndmask_b32_e32 v218, 0, v218, vcc
	v_cmp_ngt_f32_e32 vcc, s51, v217
	v_fmaak_f32 v228, v227, v228, 0xbcdac9b8
	v_fmaak_f32 v228, v227, v228, 0x3de703be
	v_cndmask_b32_e32 v217, v224, v218, vcc
	v_fmaak_f32 v228, v227, v228, 0xbec09330
	v_sub_f32_e32 v217, 1.0, v217
	v_fmaak_f32 v227, v227, v228, 0x3e0375d0
	v_cmp_nlt_f32_e64 vcc, |v216|, 1.0
	v_fma_f32 v227, |v216|, v227, |v216|
	v_mul_f32_e32 v229, 0.5, v229
	v_cndmask_b32_e32 v217, v227, v217, vcc
	v_bfi_b32 v217, s78, v217, v216
	v_add_f32_e32 v217, 1.0, v217
	v_mul_f32_e32 v229, v229, v217
	v_mul_f32_e32 v229, v60, v229
	v_mul_f32_e32 v206, v64, v229
	v_mul_f32_e32 v229, v239, v58
	v_mul_f32_e32 v229, v229, v63
	v_mul_f32_e32 v216, 0x3f3504f3, v229
	v_fma_f32 v217, |v216|, s8, v223
	v_fma_f32 v217, |v216|, v217, s9
	v_fma_f32 v217, |v216|, v217, s13
	v_fma_f32 v217, |v216|, v217, s32
	v_fma_f32 v217, |v216|, v217, s38
	v_fma_f32 v217, |v216|, v217, s49
	v_fma_f32 v217, |v216|, v217, |v216|
	v_mul_f32_e32 v218, 0xbfb8aa3b, v217
	v_fma_f32 v219, v217, s27, -v218
	v_rndne_f32_e32 v226, v218
	v_fmac_f32_e32 v219, 0xb2a5705f, v217
	v_sub_f32_e32 v218, v218, v226
	v_add_f32_e32 v218, v218, v219
	v_cvt_i32_f32_e32 v219, v226
	v_exp_f32_e32 v218, v218
	v_cmp_nlt_f32_e32 vcc, s50, v217
	v_mul_f32_e32 v227, v216, v216
	v_ldexp_f32 v218, v218, v219
	v_fmamk_f32 v228, v227, 0xba1345e1, v212
	v_cndmask_b32_e32 v218, 0, v218, vcc
	v_cmp_ngt_f32_e32 vcc, s51, v217
	v_fmaak_f32 v228, v227, v228, 0xbcdac9b8
	v_fmaak_f32 v228, v227, v228, 0x3de703be
	v_cndmask_b32_e32 v217, v224, v218, vcc
	v_fmaak_f32 v228, v227, v228, 0xbec09330
	v_sub_f32_e32 v217, 1.0, v217
	v_fmaak_f32 v227, v227, v228, 0x3e0375d0
	v_cmp_nlt_f32_e64 vcc, |v216|, 1.0
	v_fma_f32 v227, |v216|, v227, |v216|
	v_mul_f32_e32 v229, 0.5, v229
	v_cndmask_b32_e32 v217, v227, v217, vcc
	v_bfi_b32 v217, s78, v217, v216
	v_add_f32_e32 v217, 1.0, v217
	v_mul_f32_e32 v229, v229, v217
	v_mul_f32_e32 v229, v61, v229
	v_mul_f32_e32 v207, v65, v229
	ds_write_b64 v198, v[204:205] offset:2048
	ds_write_b64 v198, v[206:207] offset:8192
	s_waitcnt vmcnt(36)
	v_lshlrev_b32_e32 v204, 10, v12
	v_lshlrev_b32_e32 v205, 10, v13
	v_mul_f32_e32 v229, v240, v134
	v_mul_f32_e32 v229, v229, v138
	v_mul_f32_e32 v216, 0x3f3504f3, v229
	v_fma_f32 v217, |v216|, s8, v223
	v_fma_f32 v217, |v216|, v217, s9
	v_fma_f32 v217, |v216|, v217, s13
	v_fma_f32 v217, |v216|, v217, s32
	v_fma_f32 v217, |v216|, v217, s38
	v_fma_f32 v217, |v216|, v217, s49
	v_fma_f32 v217, |v216|, v217, |v216|
	v_mul_f32_e32 v218, 0xbfb8aa3b, v217
	v_fma_f32 v219, v217, s27, -v218
	v_rndne_f32_e32 v226, v218
	v_fmac_f32_e32 v219, 0xb2a5705f, v217
	v_sub_f32_e32 v218, v218, v226
	v_add_f32_e32 v218, v218, v219
	v_cvt_i32_f32_e32 v219, v226
	v_exp_f32_e32 v218, v218
	v_cmp_nlt_f32_e32 vcc, s50, v217
	v_mul_f32_e32 v227, v216, v216
	v_ldexp_f32 v218, v218, v219
	v_fmamk_f32 v228, v227, 0xba1345e1, v212
	v_cndmask_b32_e32 v218, 0, v218, vcc
	v_cmp_ngt_f32_e32 vcc, s51, v217
	v_fmaak_f32 v228, v227, v228, 0xbcdac9b8
	v_fmaak_f32 v228, v227, v228, 0x3de703be
	v_cndmask_b32_e32 v217, v224, v218, vcc
	v_fmaak_f32 v228, v227, v228, 0xbec09330
	v_sub_f32_e32 v217, 1.0, v217
	v_fmaak_f32 v227, v227, v228, 0x3e0375d0
	v_cmp_nlt_f32_e64 vcc, |v216|, 1.0
	v_fma_f32 v227, |v216|, v227, |v216|
	v_mul_f32_e32 v229, 0.5, v229
	v_cndmask_b32_e32 v217, v227, v217, vcc
	v_bfi_b32 v217, s78, v217, v216
	v_add_f32_e32 v217, 1.0, v217
	v_mul_f32_e32 v229, v229, v217
	v_mul_f32_e32 v229, v136, v229
	v_mul_f32_e32 v206, v140, v229
	v_mul_f32_e32 v229, v241, v134
	v_mul_f32_e32 v229, v229, v139
	v_mul_f32_e32 v216, 0x3f3504f3, v229
	v_fma_f32 v217, |v216|, s8, v223
	v_fma_f32 v217, |v216|, v217, s9
	v_fma_f32 v217, |v216|, v217, s13
	v_fma_f32 v217, |v216|, v217, s32
	v_fma_f32 v217, |v216|, v217, s38
	v_fma_f32 v217, |v216|, v217, s49
	v_fma_f32 v217, |v216|, v217, |v216|
	v_mul_f32_e32 v218, 0xbfb8aa3b, v217
	v_fma_f32 v219, v217, s27, -v218
	v_rndne_f32_e32 v226, v218
	v_fmac_f32_e32 v219, 0xb2a5705f, v217
	v_sub_f32_e32 v218, v218, v226
	v_add_f32_e32 v218, v218, v219
	v_cvt_i32_f32_e32 v219, v226
	v_exp_f32_e32 v218, v218
	v_cmp_nlt_f32_e32 vcc, s50, v217
	v_mul_f32_e32 v227, v216, v216
	v_ldexp_f32 v218, v218, v219
	v_fmamk_f32 v228, v227, 0xba1345e1, v212
	v_cndmask_b32_e32 v218, 0, v218, vcc
	v_cmp_ngt_f32_e32 vcc, s51, v217
	v_fmaak_f32 v228, v227, v228, 0xbcdac9b8
	v_fmaak_f32 v228, v227, v228, 0x3de703be
	v_cndmask_b32_e32 v217, v224, v218, vcc
	v_fmaak_f32 v228, v227, v228, 0xbec09330
	v_sub_f32_e32 v217, 1.0, v217
	v_fmaak_f32 v227, v227, v228, 0x3e0375d0
	v_cmp_nlt_f32_e64 vcc, |v216|, 1.0
	v_fma_f32 v227, |v216|, v227, |v216|
	v_mul_f32_e32 v229, 0.5, v229
	v_cndmask_b32_e32 v217, v227, v217, vcc
	v_bfi_b32 v217, s78, v217, v216
	v_add_f32_e32 v217, 1.0, v217
	v_mul_f32_e32 v229, v229, v217
	v_mul_f32_e32 v229, v137, v229
	v_mul_f32_e32 v207, v141, v229
	ds_write_b64 v198, v[204:205] offset:2560
	ds_write_b64 v198, v[206:207] offset:8704
	s_waitcnt vmcnt(30)
	v_lshlrev_b32_e32 v204, 10, v14
	v_lshlrev_b32_e32 v205, 10, v15
	v_mul_f32_e32 v229, v94, v142
	v_mul_f32_e32 v229, v229, v146
	v_mul_f32_e32 v216, 0x3f3504f3, v229
	v_fma_f32 v217, |v216|, s8, v223
	v_fma_f32 v217, |v216|, v217, s9
	v_fma_f32 v217, |v216|, v217, s13
	v_fma_f32 v217, |v216|, v217, s32
	v_fma_f32 v217, |v216|, v217, s38
	v_fma_f32 v217, |v216|, v217, s49
	v_fma_f32 v217, |v216|, v217, |v216|
	v_mul_f32_e32 v218, 0xbfb8aa3b, v217
	v_fma_f32 v219, v217, s27, -v218
	v_rndne_f32_e32 v226, v218
	v_fmac_f32_e32 v219, 0xb2a5705f, v217
	v_sub_f32_e32 v218, v218, v226
	v_add_f32_e32 v218, v218, v219
	v_cvt_i32_f32_e32 v219, v226
	v_exp_f32_e32 v218, v218
	v_cmp_nlt_f32_e32 vcc, s50, v217
	v_mul_f32_e32 v227, v216, v216
	v_ldexp_f32 v218, v218, v219
	v_fmamk_f32 v228, v227, 0xba1345e1, v212
	v_cndmask_b32_e32 v218, 0, v218, vcc
	v_cmp_ngt_f32_e32 vcc, s51, v217
	v_fmaak_f32 v228, v227, v228, 0xbcdac9b8
	v_fmaak_f32 v228, v227, v228, 0x3de703be
	v_cndmask_b32_e32 v217, v224, v218, vcc
	v_fmaak_f32 v228, v227, v228, 0xbec09330
	v_sub_f32_e32 v217, 1.0, v217
	v_fmaak_f32 v227, v227, v228, 0x3e0375d0
	v_cmp_nlt_f32_e64 vcc, |v216|, 1.0
	v_fma_f32 v227, |v216|, v227, |v216|
	v_mul_f32_e32 v229, 0.5, v229
	v_cndmask_b32_e32 v217, v227, v217, vcc
	v_bfi_b32 v217, s78, v217, v216
	v_add_f32_e32 v217, 1.0, v217
	v_mul_f32_e32 v229, v229, v217
	v_mul_f32_e32 v229, v144, v229
	v_mul_f32_e32 v206, v148, v229
	v_mul_f32_e32 v229, v95, v142
	v_mul_f32_e32 v229, v229, v147
	v_mul_f32_e32 v216, 0x3f3504f3, v229
	v_fma_f32 v217, |v216|, s8, v223
	v_fma_f32 v217, |v216|, v217, s9
	v_fma_f32 v217, |v216|, v217, s13
	v_fma_f32 v217, |v216|, v217, s32
	v_fma_f32 v217, |v216|, v217, s38
	v_fma_f32 v217, |v216|, v217, s49
	v_fma_f32 v217, |v216|, v217, |v216|
	v_mul_f32_e32 v218, 0xbfb8aa3b, v217
	v_fma_f32 v219, v217, s27, -v218
	v_rndne_f32_e32 v226, v218
	v_fmac_f32_e32 v219, 0xb2a5705f, v217
	v_sub_f32_e32 v218, v218, v226
	v_add_f32_e32 v218, v218, v219
	v_cvt_i32_f32_e32 v219, v226
	v_exp_f32_e32 v218, v218
	v_cmp_nlt_f32_e32 vcc, s50, v217
	v_mul_f32_e32 v227, v216, v216
	v_ldexp_f32 v218, v218, v219
	v_fmamk_f32 v228, v227, 0xba1345e1, v212
	v_cndmask_b32_e32 v218, 0, v218, vcc
	v_cmp_ngt_f32_e32 vcc, s51, v217
	v_fmaak_f32 v228, v227, v228, 0xbcdac9b8
	v_fmaak_f32 v228, v227, v228, 0x3de703be
	v_cndmask_b32_e32 v217, v224, v218, vcc
	v_fmaak_f32 v228, v227, v228, 0xbec09330
	v_sub_f32_e32 v217, 1.0, v217
	v_fmaak_f32 v227, v227, v228, 0x3e0375d0
	v_cmp_nlt_f32_e64 vcc, |v216|, 1.0
	v_fma_f32 v227, |v216|, v227, |v216|
	v_mul_f32_e32 v229, 0.5, v229
	v_cndmask_b32_e32 v217, v227, v217, vcc
	v_bfi_b32 v217, s78, v217, v216
	v_add_f32_e32 v217, 1.0, v217
	v_mul_f32_e32 v229, v229, v217
	v_mul_f32_e32 v229, v145, v229
	v_mul_f32_e32 v207, v149, v229
	ds_write_b64 v198, v[204:205] offset:3072
	ds_write_b64 v198, v[206:207] offset:9216
	s_waitcnt vmcnt(24)
	v_lshlrev_b32_e32 v204, 10, v16
	v_lshlrev_b32_e32 v205, 10, v17
	v_mul_f32_e32 v229, v96, v150
	v_mul_f32_e32 v229, v229, v154
	v_mul_f32_e32 v216, 0x3f3504f3, v229
	v_fma_f32 v217, |v216|, s8, v223
	v_fma_f32 v217, |v216|, v217, s9
	v_fma_f32 v217, |v216|, v217, s13
	v_fma_f32 v217, |v216|, v217, s32
	v_fma_f32 v217, |v216|, v217, s38
	v_fma_f32 v217, |v216|, v217, s49
	v_fma_f32 v217, |v216|, v217, |v216|
	v_mul_f32_e32 v218, 0xbfb8aa3b, v217
	v_fma_f32 v219, v217, s27, -v218
	v_rndne_f32_e32 v226, v218
	v_fmac_f32_e32 v219, 0xb2a5705f, v217
	v_sub_f32_e32 v218, v218, v226
	v_add_f32_e32 v218, v218, v219
	v_cvt_i32_f32_e32 v219, v226
	v_exp_f32_e32 v218, v218
	v_cmp_nlt_f32_e32 vcc, s50, v217
	v_mul_f32_e32 v227, v216, v216
	v_ldexp_f32 v218, v218, v219
	v_fmamk_f32 v228, v227, 0xba1345e1, v212
	v_cndmask_b32_e32 v218, 0, v218, vcc
	v_cmp_ngt_f32_e32 vcc, s51, v217
	v_fmaak_f32 v228, v227, v228, 0xbcdac9b8
	v_fmaak_f32 v228, v227, v228, 0x3de703be
	v_cndmask_b32_e32 v217, v224, v218, vcc
	v_fmaak_f32 v228, v227, v228, 0xbec09330
	v_sub_f32_e32 v217, 1.0, v217
	v_fmaak_f32 v227, v227, v228, 0x3e0375d0
	v_cmp_nlt_f32_e64 vcc, |v216|, 1.0
	v_fma_f32 v227, |v216|, v227, |v216|
	v_mul_f32_e32 v229, 0.5, v229
	v_cndmask_b32_e32 v217, v227, v217, vcc
	v_bfi_b32 v217, s78, v217, v216
	v_add_f32_e32 v217, 1.0, v217
	v_mul_f32_e32 v229, v229, v217
	v_mul_f32_e32 v229, v152, v229
	v_mul_f32_e32 v206, v156, v229
	v_mul_f32_e32 v229, v97, v150
	v_mul_f32_e32 v229, v229, v155
	v_mul_f32_e32 v216, 0x3f3504f3, v229
	v_fma_f32 v217, |v216|, s8, v223
	v_fma_f32 v217, |v216|, v217, s9
	v_fma_f32 v217, |v216|, v217, s13
	v_fma_f32 v217, |v216|, v217, s32
	v_fma_f32 v217, |v216|, v217, s38
	v_fma_f32 v217, |v216|, v217, s49
	v_fma_f32 v217, |v216|, v217, |v216|
	v_mul_f32_e32 v218, 0xbfb8aa3b, v217
	v_fma_f32 v219, v217, s27, -v218
	v_rndne_f32_e32 v226, v218
	v_fmac_f32_e32 v219, 0xb2a5705f, v217
	v_sub_f32_e32 v218, v218, v226
	v_add_f32_e32 v218, v218, v219
	v_cvt_i32_f32_e32 v219, v226
	v_exp_f32_e32 v218, v218
	v_cmp_nlt_f32_e32 vcc, s50, v217
	v_mul_f32_e32 v227, v216, v216
	v_ldexp_f32 v218, v218, v219
	v_fmamk_f32 v228, v227, 0xba1345e1, v212
	v_cndmask_b32_e32 v218, 0, v218, vcc
	v_cmp_ngt_f32_e32 vcc, s51, v217
	v_fmaak_f32 v228, v227, v228, 0xbcdac9b8
	v_fmaak_f32 v228, v227, v228, 0x3de703be
	v_cndmask_b32_e32 v217, v224, v218, vcc
	v_fmaak_f32 v228, v227, v228, 0xbec09330
	v_sub_f32_e32 v217, 1.0, v217
	v_fmaak_f32 v227, v227, v228, 0x3e0375d0
	v_cmp_nlt_f32_e64 vcc, |v216|, 1.0
	v_fma_f32 v227, |v216|, v227, |v216|
	v_mul_f32_e32 v229, 0.5, v229
	v_cndmask_b32_e32 v217, v227, v217, vcc
	v_bfi_b32 v217, s78, v217, v216
	v_add_f32_e32 v217, 1.0, v217
	v_mul_f32_e32 v229, v229, v217
	v_mul_f32_e32 v229, v153, v229
	v_mul_f32_e32 v207, v157, v229
	ds_write_b64 v198, v[204:205] offset:3584
	ds_write_b64 v198, v[206:207] offset:9728
	s_waitcnt vmcnt(18)
	v_lshlrev_b32_e32 v204, 10, v18
	v_lshlrev_b32_e32 v205, 10, v19
	v_mul_f32_e32 v229, v98, v158
	v_mul_f32_e32 v229, v229, v162
	v_mul_f32_e32 v216, 0x3f3504f3, v229
	v_fma_f32 v217, |v216|, s8, v223
	v_fma_f32 v217, |v216|, v217, s9
	v_fma_f32 v217, |v216|, v217, s13
	v_fma_f32 v217, |v216|, v217, s32
	v_fma_f32 v217, |v216|, v217, s38
	v_fma_f32 v217, |v216|, v217, s49
	v_fma_f32 v217, |v216|, v217, |v216|
	v_mul_f32_e32 v218, 0xbfb8aa3b, v217
	v_fma_f32 v219, v217, s27, -v218
	v_rndne_f32_e32 v226, v218
	v_fmac_f32_e32 v219, 0xb2a5705f, v217
	v_sub_f32_e32 v218, v218, v226
	v_add_f32_e32 v218, v218, v219
	v_cvt_i32_f32_e32 v219, v226
	v_exp_f32_e32 v218, v218
	v_cmp_nlt_f32_e32 vcc, s50, v217
	v_mul_f32_e32 v227, v216, v216
	v_ldexp_f32 v218, v218, v219
	v_fmamk_f32 v228, v227, 0xba1345e1, v212
	v_cndmask_b32_e32 v218, 0, v218, vcc
	v_cmp_ngt_f32_e32 vcc, s51, v217
	v_fmaak_f32 v228, v227, v228, 0xbcdac9b8
	v_fmaak_f32 v228, v227, v228, 0x3de703be
	v_cndmask_b32_e32 v217, v224, v218, vcc
	v_fmaak_f32 v228, v227, v228, 0xbec09330
	v_sub_f32_e32 v217, 1.0, v217
	v_fmaak_f32 v227, v227, v228, 0x3e0375d0
	v_cmp_nlt_f32_e64 vcc, |v216|, 1.0
	v_fma_f32 v227, |v216|, v227, |v216|
	v_mul_f32_e32 v229, 0.5, v229
	v_cndmask_b32_e32 v217, v227, v217, vcc
	v_bfi_b32 v217, s78, v217, v216
	v_add_f32_e32 v217, 1.0, v217
	v_mul_f32_e32 v229, v229, v217
	v_mul_f32_e32 v229, v160, v229
	v_mul_f32_e32 v206, v164, v229
	v_mul_f32_e32 v229, v99, v158
	v_mul_f32_e32 v229, v229, v163
	v_mul_f32_e32 v216, 0x3f3504f3, v229
	v_fma_f32 v217, |v216|, s8, v223
	v_fma_f32 v217, |v216|, v217, s9
	v_fma_f32 v217, |v216|, v217, s13
	v_fma_f32 v217, |v216|, v217, s32
	v_fma_f32 v217, |v216|, v217, s38
	v_fma_f32 v217, |v216|, v217, s49
	v_fma_f32 v217, |v216|, v217, |v216|
	v_mul_f32_e32 v218, 0xbfb8aa3b, v217
	v_fma_f32 v219, v217, s27, -v218
	v_rndne_f32_e32 v226, v218
	v_fmac_f32_e32 v219, 0xb2a5705f, v217
	v_sub_f32_e32 v218, v218, v226
	v_add_f32_e32 v218, v218, v219
	v_cvt_i32_f32_e32 v219, v226
	v_exp_f32_e32 v218, v218
	v_cmp_nlt_f32_e32 vcc, s50, v217
	v_mul_f32_e32 v227, v216, v216
	v_ldexp_f32 v218, v218, v219
	v_fmamk_f32 v228, v227, 0xba1345e1, v212
	v_cndmask_b32_e32 v218, 0, v218, vcc
	v_cmp_ngt_f32_e32 vcc, s51, v217
	v_fmaak_f32 v228, v227, v228, 0xbcdac9b8
	v_fmaak_f32 v228, v227, v228, 0x3de703be
	v_cndmask_b32_e32 v217, v224, v218, vcc
	v_fmaak_f32 v228, v227, v228, 0xbec09330
	v_sub_f32_e32 v217, 1.0, v217
	v_fmaak_f32 v227, v227, v228, 0x3e0375d0
	v_cmp_nlt_f32_e64 vcc, |v216|, 1.0
	v_fma_f32 v227, |v216|, v227, |v216|
	v_mul_f32_e32 v229, 0.5, v229
	v_cndmask_b32_e32 v217, v227, v217, vcc
	v_bfi_b32 v217, s78, v217, v216
	v_add_f32_e32 v217, 1.0, v217
	v_mul_f32_e32 v229, v229, v217
	v_mul_f32_e32 v229, v161, v229
	v_mul_f32_e32 v207, v165, v229
	ds_write_b64 v198, v[204:205] offset:4096
	ds_write_b64 v198, v[206:207] offset:10240
	s_waitcnt vmcnt(12)
	v_lshlrev_b32_e32 v204, 10, v20
	v_lshlrev_b32_e32 v205, 10, v21
	v_mul_f32_e32 v229, v100, v166
	v_mul_f32_e32 v229, v229, v170
	v_mul_f32_e32 v216, 0x3f3504f3, v229
	v_fma_f32 v217, |v216|, s8, v223
	v_fma_f32 v217, |v216|, v217, s9
	v_fma_f32 v217, |v216|, v217, s13
	v_fma_f32 v217, |v216|, v217, s32
	v_fma_f32 v217, |v216|, v217, s38
	v_fma_f32 v217, |v216|, v217, s49
	v_fma_f32 v217, |v216|, v217, |v216|
	v_mul_f32_e32 v218, 0xbfb8aa3b, v217
	v_fma_f32 v219, v217, s27, -v218
	v_rndne_f32_e32 v226, v218
	v_fmac_f32_e32 v219, 0xb2a5705f, v217
	v_sub_f32_e32 v218, v218, v226
	v_add_f32_e32 v218, v218, v219
	v_cvt_i32_f32_e32 v219, v226
	v_exp_f32_e32 v218, v218
	v_cmp_nlt_f32_e32 vcc, s50, v217
	v_mul_f32_e32 v227, v216, v216
	v_ldexp_f32 v218, v218, v219
	v_fmamk_f32 v228, v227, 0xba1345e1, v212
	v_cndmask_b32_e32 v218, 0, v218, vcc
	v_cmp_ngt_f32_e32 vcc, s51, v217
	v_fmaak_f32 v228, v227, v228, 0xbcdac9b8
	v_fmaak_f32 v228, v227, v228, 0x3de703be
	v_cndmask_b32_e32 v217, v224, v218, vcc
	v_fmaak_f32 v228, v227, v228, 0xbec09330
	v_sub_f32_e32 v217, 1.0, v217
	v_fmaak_f32 v227, v227, v228, 0x3e0375d0
	v_cmp_nlt_f32_e64 vcc, |v216|, 1.0
	v_fma_f32 v227, |v216|, v227, |v216|
	v_mul_f32_e32 v229, 0.5, v229
	v_cndmask_b32_e32 v217, v227, v217, vcc
	v_bfi_b32 v217, s78, v217, v216
	v_add_f32_e32 v217, 1.0, v217
	v_mul_f32_e32 v229, v229, v217
	v_mul_f32_e32 v229, v168, v229
	v_mul_f32_e32 v206, v172, v229
	v_mul_f32_e32 v229, v101, v166
	v_mul_f32_e32 v229, v229, v171
	v_mul_f32_e32 v216, 0x3f3504f3, v229
	v_fma_f32 v217, |v216|, s8, v223
	v_fma_f32 v217, |v216|, v217, s9
	v_fma_f32 v217, |v216|, v217, s13
	v_fma_f32 v217, |v216|, v217, s32
	v_fma_f32 v217, |v216|, v217, s38
	v_fma_f32 v217, |v216|, v217, s49
	v_fma_f32 v217, |v216|, v217, |v216|
	v_mul_f32_e32 v218, 0xbfb8aa3b, v217
	v_fma_f32 v219, v217, s27, -v218
	v_rndne_f32_e32 v226, v218
	v_fmac_f32_e32 v219, 0xb2a5705f, v217
	v_sub_f32_e32 v218, v218, v226
	v_add_f32_e32 v218, v218, v219
	v_cvt_i32_f32_e32 v219, v226
	v_exp_f32_e32 v218, v218
	v_cmp_nlt_f32_e32 vcc, s50, v217
	v_mul_f32_e32 v227, v216, v216
	v_ldexp_f32 v218, v218, v219
	v_fmamk_f32 v228, v227, 0xba1345e1, v212
	v_cndmask_b32_e32 v218, 0, v218, vcc
	v_cmp_ngt_f32_e32 vcc, s51, v217
	v_fmaak_f32 v228, v227, v228, 0xbcdac9b8
	v_fmaak_f32 v228, v227, v228, 0x3de703be
	v_cndmask_b32_e32 v217, v224, v218, vcc
	v_fmaak_f32 v228, v227, v228, 0xbec09330
	v_sub_f32_e32 v217, 1.0, v217
	v_fmaak_f32 v227, v227, v228, 0x3e0375d0
	v_cmp_nlt_f32_e64 vcc, |v216|, 1.0
	v_fma_f32 v227, |v216|, v227, |v216|
	v_mul_f32_e32 v229, 0.5, v229
	v_cndmask_b32_e32 v217, v227, v217, vcc
	v_bfi_b32 v217, s78, v217, v216
	v_add_f32_e32 v217, 1.0, v217
	v_mul_f32_e32 v229, v229, v217
	v_mul_f32_e32 v229, v169, v229
	v_mul_f32_e32 v207, v173, v229
	ds_write_b64 v198, v[204:205] offset:4608
	ds_write_b64 v198, v[206:207] offset:10752
	s_waitcnt vmcnt(6)
	v_lshlrev_b32_e32 v204, 10, v22
	v_lshlrev_b32_e32 v205, 10, v23
	v_mul_f32_e32 v229, v66, v180
	v_mul_f32_e32 v229, v229, v184
	v_mul_f32_e32 v216, 0x3f3504f3, v229
	v_fma_f32 v217, |v216|, s8, v223
	v_fma_f32 v217, |v216|, v217, s9
	v_fma_f32 v217, |v216|, v217, s13
	v_fma_f32 v217, |v216|, v217, s32
	v_fma_f32 v217, |v216|, v217, s38
	v_fma_f32 v217, |v216|, v217, s49
	v_fma_f32 v217, |v216|, v217, |v216|
	v_mul_f32_e32 v218, 0xbfb8aa3b, v217
	v_fma_f32 v219, v217, s27, -v218
	v_rndne_f32_e32 v226, v218
	v_fmac_f32_e32 v219, 0xb2a5705f, v217
	v_sub_f32_e32 v218, v218, v226
	v_add_f32_e32 v218, v218, v219
	v_cvt_i32_f32_e32 v219, v226
	v_exp_f32_e32 v218, v218
	v_cmp_nlt_f32_e32 vcc, s50, v217
	v_mul_f32_e32 v227, v216, v216
	v_ldexp_f32 v218, v218, v219
	v_fmamk_f32 v228, v227, 0xba1345e1, v212
	v_cndmask_b32_e32 v218, 0, v218, vcc
	v_cmp_ngt_f32_e32 vcc, s51, v217
	v_fmaak_f32 v228, v227, v228, 0xbcdac9b8
	v_fmaak_f32 v228, v227, v228, 0x3de703be
	v_cndmask_b32_e32 v217, v224, v218, vcc
	v_fmaak_f32 v228, v227, v228, 0xbec09330
	v_sub_f32_e32 v217, 1.0, v217
	v_fmaak_f32 v227, v227, v228, 0x3e0375d0
	v_cmp_nlt_f32_e64 vcc, |v216|, 1.0
	v_fma_f32 v227, |v216|, v227, |v216|
	v_mul_f32_e32 v229, 0.5, v229
	v_cndmask_b32_e32 v217, v227, v217, vcc
	v_bfi_b32 v217, s78, v217, v216
	v_add_f32_e32 v217, 1.0, v217
	v_mul_f32_e32 v229, v229, v217
	v_mul_f32_e32 v229, v182, v229
	v_mul_f32_e32 v206, v186, v229
	v_mul_f32_e32 v229, v67, v180
	v_mul_f32_e32 v229, v229, v185
	v_mul_f32_e32 v216, 0x3f3504f3, v229
	v_fma_f32 v217, |v216|, s8, v223
	v_fma_f32 v217, |v216|, v217, s9
	v_fma_f32 v217, |v216|, v217, s13
	v_fma_f32 v217, |v216|, v217, s32
	v_fma_f32 v217, |v216|, v217, s38
	v_fma_f32 v217, |v216|, v217, s49
	v_fma_f32 v217, |v216|, v217, |v216|
	v_mul_f32_e32 v218, 0xbfb8aa3b, v217
	v_fma_f32 v219, v217, s27, -v218
	v_rndne_f32_e32 v226, v218
	v_fmac_f32_e32 v219, 0xb2a5705f, v217
	v_sub_f32_e32 v218, v218, v226
	v_add_f32_e32 v218, v218, v219
	v_cvt_i32_f32_e32 v219, v226
	v_exp_f32_e32 v218, v218
	v_cmp_nlt_f32_e32 vcc, s50, v217
	v_mul_f32_e32 v227, v216, v216
	v_ldexp_f32 v218, v218, v219
	v_fmamk_f32 v228, v227, 0xba1345e1, v212
	v_cndmask_b32_e32 v218, 0, v218, vcc
	v_cmp_ngt_f32_e32 vcc, s51, v217
	v_fmaak_f32 v228, v227, v228, 0xbcdac9b8
	v_fmaak_f32 v228, v227, v228, 0x3de703be
	v_cndmask_b32_e32 v217, v224, v218, vcc
	v_fmaak_f32 v228, v227, v228, 0xbec09330
	v_sub_f32_e32 v217, 1.0, v217
	v_fmaak_f32 v227, v227, v228, 0x3e0375d0
	v_cmp_nlt_f32_e64 vcc, |v216|, 1.0
	v_fma_f32 v227, |v216|, v227, |v216|
	v_mul_f32_e32 v229, 0.5, v229
	v_cndmask_b32_e32 v217, v227, v217, vcc
	v_bfi_b32 v217, s78, v217, v216
	v_add_f32_e32 v217, 1.0, v217
	v_mul_f32_e32 v229, v229, v217
	v_mul_f32_e32 v229, v183, v229
	v_mul_f32_e32 v207, v187, v229
	ds_write_b64 v198, v[204:205] offset:5120
	ds_write_b64 v198, v[206:207] offset:11264
	s_waitcnt vmcnt(0)
	v_lshlrev_b32_e32 v204, 10, v24
	v_lshlrev_b32_e32 v205, 10, v25
	v_mul_f32_e32 v229, v68, v188
	v_mul_f32_e32 v229, v229, v192
	v_mul_f32_e32 v216, 0x3f3504f3, v229
	v_fma_f32 v217, |v216|, s8, v223
	v_fma_f32 v217, |v216|, v217, s9
	v_fma_f32 v217, |v216|, v217, s13
	v_fma_f32 v217, |v216|, v217, s32
	v_fma_f32 v217, |v216|, v217, s38
	v_fma_f32 v217, |v216|, v217, s49
	v_fma_f32 v217, |v216|, v217, |v216|
	v_mul_f32_e32 v218, 0xbfb8aa3b, v217
	v_fma_f32 v219, v217, s27, -v218
	v_rndne_f32_e32 v226, v218
	v_fmac_f32_e32 v219, 0xb2a5705f, v217
	v_sub_f32_e32 v218, v218, v226
	v_add_f32_e32 v218, v218, v219
	v_cvt_i32_f32_e32 v219, v226
	v_exp_f32_e32 v218, v218
	v_cmp_nlt_f32_e32 vcc, s50, v217
	v_mul_f32_e32 v227, v216, v216
	v_ldexp_f32 v218, v218, v219
	v_fmamk_f32 v228, v227, 0xba1345e1, v212
	v_cndmask_b32_e32 v218, 0, v218, vcc
	v_cmp_ngt_f32_e32 vcc, s51, v217
	v_fmaak_f32 v228, v227, v228, 0xbcdac9b8
	v_fmaak_f32 v228, v227, v228, 0x3de703be
	v_cndmask_b32_e32 v217, v224, v218, vcc
	v_fmaak_f32 v228, v227, v228, 0xbec09330
	v_sub_f32_e32 v217, 1.0, v217
	v_fmaak_f32 v227, v227, v228, 0x3e0375d0
	v_cmp_nlt_f32_e64 vcc, |v216|, 1.0
	v_fma_f32 v227, |v216|, v227, |v216|
	v_mul_f32_e32 v229, 0.5, v229
	v_cndmask_b32_e32 v217, v227, v217, vcc
	v_bfi_b32 v217, s78, v217, v216
	v_add_f32_e32 v217, 1.0, v217
	v_mul_f32_e32 v229, v229, v217
	v_mul_f32_e32 v229, v190, v229
	v_mul_f32_e32 v206, v194, v229
	v_mul_f32_e32 v229, v69, v188
	v_mul_f32_e32 v229, v229, v193
	v_mul_f32_e32 v216, 0x3f3504f3, v229
	v_fma_f32 v217, |v216|, s8, v223
	v_fma_f32 v217, |v216|, v217, s9
	v_fma_f32 v217, |v216|, v217, s13
	v_fma_f32 v217, |v216|, v217, s32
	v_fma_f32 v217, |v216|, v217, s38
	v_fma_f32 v217, |v216|, v217, s49
	v_fma_f32 v217, |v216|, v217, |v216|
	v_mul_f32_e32 v218, 0xbfb8aa3b, v217
	v_fma_f32 v219, v217, s27, -v218
	v_rndne_f32_e32 v226, v218
	v_fmac_f32_e32 v219, 0xb2a5705f, v217
	v_sub_f32_e32 v218, v218, v226
	v_add_f32_e32 v218, v218, v219
	v_cvt_i32_f32_e32 v219, v226
	v_exp_f32_e32 v218, v218
	v_cmp_nlt_f32_e32 vcc, s50, v217
	v_mul_f32_e32 v227, v216, v216
	v_ldexp_f32 v218, v218, v219
	v_fmamk_f32 v228, v227, 0xba1345e1, v212
	v_cndmask_b32_e32 v218, 0, v218, vcc
	v_cmp_ngt_f32_e32 vcc, s51, v217
	v_fmaak_f32 v228, v227, v228, 0xbcdac9b8
	v_fmaak_f32 v228, v227, v228, 0x3de703be
	v_cndmask_b32_e32 v217, v224, v218, vcc
	v_fmaak_f32 v228, v227, v228, 0xbec09330
	v_sub_f32_e32 v217, 1.0, v217
	v_fmaak_f32 v227, v227, v228, 0x3e0375d0
	v_cmp_nlt_f32_e64 vcc, |v216|, 1.0
	v_fma_f32 v227, |v216|, v227, |v216|
	v_mul_f32_e32 v229, 0.5, v229
	v_cndmask_b32_e32 v217, v227, v217, vcc
	v_bfi_b32 v217, s78, v217, v216
	v_add_f32_e32 v217, 1.0, v217
	v_mul_f32_e32 v229, v229, v217
	v_mul_f32_e32 v229, v191, v229
	v_mul_f32_e32 v207, v195, v229
	ds_write_b64 v198, v[204:205] offset:5632
	ds_write_b64 v198, v[206:207] offset:11776
	s_waitcnt lgkmcnt(0)
.Lv_new:
	v_and_b32_e32 v0, 15, v179
	v_lshlrev_b32_e32 v104, 3, v0
	v_lshrrev_b32_e32 v71, 6, v179
	v_mul_u32_u24_e32 v71, 0x3000, v71
	v_lshl_add_u32 v106, v103, 9, v71
	v_readfirstlane_b32 s50, v80
	v_readfirstlane_b32 s51, v81
	s_mov_b64 s[54:55], s[88:89]
	s_mov_b64 s[56:57], s[36:37]
	s_add_u32 s52, s50, 0x80
	s_addc_u32 s53, s51, 0
	v_mul_lo_u32 v71, v103, s30
	v_add_u32_e32 v71, v70, v71
	s_lshl_b32 s8, s30, 2
	v_lshlrev_b32_e32 v108, 12, v71
	v_lshl_add_u32 v108, v0, 5, v108
	v_add_u32_e32 v93, 0xffffe000, v71
	v_lshrrev_b32_e32 v93, 12, v93
	v_add_u32_e32 v93, 1, v93
	v_cmp_gt_u32_e32 vcc, 0x2000, v71
	s_nop 1
	v_cndmask_b32_e32 v93, v93, v1, vcc
	v_add_u32_e32 v93, s34, v93
	v_mul_u32_u24_e32 v93, 0x1800, v93
	v_add_u32_e32 v93, 0x1400, v93
	v_lshl_add_u32 v93, v0, 3, v93
	v_lshlrev_b32_e32 v114, 2, v93
	v_add_u32_e32 v71, s8, v71
	v_lshlrev_b32_e32 v110, 12, v71
	v_lshl_add_u32 v110, v0, 5, v110
	v_add_u32_e32 v93, 0xffffe000, v71
	v_lshrrev_b32_e32 v93, 12, v93
	v_add_u32_e32 v93, 1, v93
	v_cmp_gt_u32_e32 vcc, 0x2000, v71
	s_nop 1
	v_cndmask_b32_e32 v93, v93, v1, vcc
	v_add_u32_e32 v93, s34, v93
	v_mul_u32_u24_e32 v93, 0x1800, v93
	v_add_u32_e32 v93, 0x1400, v93
	v_lshl_add_u32 v93, v0, 3, v93
	v_lshlrev_b32_e32 v116, 2, v93
	v_add_u32_e32 v71, s8, v71
	v_lshlrev_b32_e32 v112, 12, v71
	v_lshl_add_u32 v112, v0, 5, v112
	v_add_u32_e32 v93, 0xffffe000, v71
	v_lshrrev_b32_e32 v93, 12, v93
	v_add_u32_e32 v93, 1, v93
	v_cmp_gt_u32_e32 vcc, 0x2000, v71
	s_nop 1
	v_cndmask_b32_e32 v93, v93, v1, vcc
	v_add_u32_e32 v93, s34, v93
	v_mul_u32_u24_e32 v93, 0x1800, v93
	v_add_u32_e32 v93, 0x1400, v93
	v_lshl_add_u32 v93, v0, 3, v93
	v_lshlrev_b32_e32 v118, 2, v93
	ds_read_b128 v[226:229], v106 offset:0
	ds_read_b128 v[230:233], v106 offset:16
	ds_read_b128 v[234:237], v106 offset:32
	ds_read_b128 v[238:241], v106 offset:48
	ds_read_b128 v[180:183], v106 offset:6144
	ds_read_b128 v[184:187], v106 offset:6160
	ds_read_b128 v[188:191], v106 offset:6176
	ds_read_b128 v[192:195], v106 offset:6192
	s_waitcnt lgkmcnt(4)
	v_add_u32_e32 v120, v104, v226
	global_load_dwordx2 v[2:3], v120, s[50:51]
	v_add_u32_e32 v122, v104, v227
	global_load_dwordx2 v[4:5], v122, s[50:51]
	v_add_u32_e32 v124, v104, v228
	global_load_dwordx2 v[6:7], v124, s[50:51]
	v_add_u32_e32 v126, v104, v229
	global_load_dwordx2 v[8:9], v126, s[50:51]
	v_add_u32_e32 v120, v104, v230
	global_load_dwordx2 v[10:11], v120, s[50:51]
	v_add_u32_e32 v122, v104, v231
	global_load_dwordx2 v[12:13], v122, s[50:51]
	v_add_u32_e32 v124, v104, v232
	global_load_dwordx2 v[14:15], v124, s[50:51]
	v_add_u32_e32 v126, v104, v233
	global_load_dwordx2 v[16:17], v126, s[50:51]
	v_add_u32_e32 v120, v104, v234
	global_load_dwordx2 v[18:19], v120, s[50:51]
	v_add_u32_e32 v122, v104, v235
	global_load_dwordx2 v[20:21], v122, s[50:51]
	v_add_u32_e32 v124, v104, v236
	global_load_dwordx2 v[22:23], v124, s[50:51]
	v_add_u32_e32 v126, v104, v237
	global_load_dwordx2 v[24:25], v126, s[50:51]
	v_add_u32_e32 v120, v104, v238
	global_load_dwordx2 v[26:27], v120, s[50:51]
	v_add_u32_e32 v122, v104, v239
	global_load_dwordx2 v[28:29], v122, s[50:51]
	v_add_u32_e32 v124, v104, v240
	global_load_dwordx2 v[30:31], v124, s[50:51]
	v_add_u32_e32 v126, v104, v241
	global_load_dwordx2 v[32:33], v126, s[50:51]
	ds_read_b128 v[226:229], v106 offset:64
	ds_read_b128 v[230:233], v106 offset:80
	ds_read_b128 v[234:237], v106 offset:96
	ds_read_b128 v[238:241], v106 offset:112
	s_waitcnt lgkmcnt(0)
	v_add_u32_e32 v120, v104, v226
	global_load_dwordx2 v[34:35], v120, s[50:51]
	v_add_u32_e32 v122, v104, v227
	global_load_dwordx2 v[36:37], v122, s[50:51]
	v_add_u32_e32 v124, v104, v228
	global_load_dwordx2 v[38:39], v124, s[50:51]
	v_add_u32_e32 v126, v104, v229
	global_load_dwordx2 v[40:41], v126, s[50:51]
	v_add_u32_e32 v120, v104, v230
	global_load_dwordx2 v[42:43], v120, s[50:51]
	v_add_u32_e32 v122, v104, v231
	global_load_dwordx2 v[44:45], v122, s[50:51]
	v_add_u32_e32 v124, v104, v232
	global_load_dwordx2 v[46:47], v124, s[50:51]
	v_add_u32_e32 v126, v104, v233
	global_load_dwordx2 v[48:49], v126, s[50:51]
	v_add_u32_e32 v120, v104, v234
	global_load_dwordx2 v[50:51], v120, s[50:51]
	v_add_u32_e32 v122, v104, v235
	global_load_dwordx2 v[52:53], v122, s[50:51]
	v_add_u32_e32 v124, v104, v236
	global_load_dwordx2 v[54:55], v124, s[50:51]
	v_add_u32_e32 v126, v104, v237
	global_load_dwordx2 v[56:57], v126, s[50:51]
	v_add_u32_e32 v120, v104, v238
	global_load_dwordx2 v[58:59], v120, s[50:51]
	v_add_u32_e32 v122, v104, v239
	global_load_dwordx2 v[60:61], v122, s[50:51]
	v_add_u32_e32 v124, v104, v240
	global_load_dwordx2 v[62:63], v124, s[50:51]
	v_add_u32_e32 v126, v104, v241
	global_load_dwordx2 v[64:65], v126, s[50:51]
	ds_read_b128 v[226:229], v106 offset:128
	ds_read_b128 v[230:233], v106 offset:144
	ds_read_b128 v[234:237], v106 offset:160
	ds_read_b128 v[238:241], v106 offset:176
	s_mov_b32 s49, 0
.Lv_cloop:
	global_load_dwordx4 v[94:97], v108, s[54:55]
	global_load_dwordx4 v[98:101], v108, s[54:55] offset:16
	global_load_dwordx4 v[66:69], v114, s[56:57]
	global_load_dwordx4 v[174:177], v114, s[56:57] offset:16
	v_mov_b32_e32 v242, 0
	v_mov_b32_e32 v243, 0
	v_mov_b32_e32 v244, 0
	v_mov_b32_e32 v245, 0
	v_mov_b32_e32 v246, 0
	v_mov_b32_e32 v247, 0
	v_mov_b32_e32 v248, 0
	v_mov_b32_e32 v249, 0
	s_waitcnt lgkmcnt(0)
	v_add_u32_e32 v120, v104, v226
	global_load_dwordx2 v[134:135], v120, s[50:51]
	v_add_u32_e32 v122, v104, v227
	global_load_dwordx2 v[136:137], v122, s[50:51]
	v_add_u32_e32 v124, v104, v228
	global_load_dwordx2 v[138:139], v124, s[50:51]
	v_add_u32_e32 v126, v104, v229
	global_load_dwordx2 v[140:141], v126, s[50:51]
	v_add_u32_e32 v120, v104, v230
	global_load_dwordx2 v[142:143], v120, s[50:51]
	v_add_u32_e32 v122, v104, v231
	global_load_dwordx2 v[144:145], v122, s[50:51]
	v_add_u32_e32 v124, v104, v232
	global_load_dwordx2 v[146:147], v124, s[50:51]
	v_add_u32_e32 v126, v104, v233
	global_load_dwordx2 v[148:149], v126, s[50:51]
	v_add_u32_e32 v120, v104, v234
	global_load_dwordx2 v[150:151], v120, s[50:51]
	v_add_u32_e32 v122, v104, v235
	global_load_dwordx2 v[152:153], v122, s[50:51]
	v_add_u32_e32 v124, v104, v236
	global_load_dwordx2 v[154:155], v124, s[50:51]
	v_add_u32_e32 v126, v104, v237
	global_load_dwordx2 v[156:157], v126, s[50:51]
	v_add_u32_e32 v120, v104, v238
	global_load_dwordx2 v[158:159], v120, s[50:51]
	v_add_u32_e32 v122, v104, v239
	global_load_dwordx2 v[160:161], v122, s[50:51]
	v_add_u32_e32 v124, v104, v240
	global_load_dwordx2 v[162:163], v124, s[50:51]
	v_add_u32_e32 v126, v104, v241
	global_load_dwordx2 v[164:165], v126, s[50:51]
	ds_read_b128 v[226:229], v106 offset:192
	ds_read_b128 v[230:233], v106 offset:208
	ds_read_b128 v[234:237], v106 offset:224
	ds_read_b128 v[238:241], v106 offset:240
	ds_read_b128 v[196:199], v106 offset:6208
	ds_read_b128 v[200:203], v106 offset:6224
	ds_read_b128 v[204:207], v106 offset:6240
	ds_read_b128 v[216:219], v106 offset:6256
	s_waitcnt vmcnt(36)
	v_cvt_pk_f32_fp8_e32 v[166:167], v2
	v_cvt_pk_f32_fp8_sdwa v[168:169], v2 src0_sel:WORD_1
	v_cvt_pk_f32_fp8_e32 v[170:171], v3
	v_cvt_pk_f32_fp8_sdwa v[172:173], v3 src0_sel:WORD_1
	v_pk_fma_f32 v[242:243], v[180:181], v[166:167], v[242:243] op_sel_hi:[0,1,1]
	v_pk_fma_f32 v[244:245], v[180:181], v[168:169], v[244:245] op_sel_hi:[0,1,1]
	v_pk_fma_f32 v[246:247], v[180:181], v[170:171], v[246:247] op_sel_hi:[0,1,1]
	v_pk_fma_f32 v[248:249], v[180:181], v[172:173], v[248:249] op_sel_hi:[0,1,1]
	v_cvt_pk_f32_fp8_e32 v[166:167], v4
	v_cvt_pk_f32_fp8_sdwa v[168:169], v4 src0_sel:WORD_1
	v_cvt_pk_f32_fp8_e32 v[170:171], v5
	v_cvt_pk_f32_fp8_sdwa v[172:173], v5 src0_sel:WORD_1
	v_pk_fma_f32 v[242:243], v[180:181], v[166:167], v[242:243] op_sel:[1,0,0]
	v_pk_fma_f32 v[244:245], v[180:181], v[168:169], v[244:245] op_sel:[1,0,0]
	v_pk_fma_f32 v[246:247], v[180:181], v[170:171], v[246:247] op_sel:[1,0,0]
	v_pk_fma_f32 v[248:249], v[180:181], v[172:173], v[248:249] op_sel:[1,0,0]
	v_cvt_pk_f32_fp8_e32 v[166:167], v6
	v_cvt_pk_f32_fp8_sdwa v[168:169], v6 src0_sel:WORD_1
	v_cvt_pk_f32_fp8_e32 v[170:171], v7
	v_cvt_pk_f32_fp8_sdwa v[172:173], v7 src0_sel:WORD_1
	v_pk_fma_f32 v[242:243], v[182:183], v[166:167], v[242:243] op_sel_hi:[0,1,1]
	v_pk_fma_f32 v[244:245], v[182:183], v[168:169], v[244:245] op_sel_hi:[0,1,1]
	v_pk_fma_f32 v[246:247], v[182:183], v[170:171], v[246:247] op_sel_hi:[0,1,1]
	v_pk_fma_f32 v[248:249], v[182:183], v[172:173], v[248:249] op_sel_hi:[0,1,1]
	v_cvt_pk_f32_fp8_e32 v[166:167], v8
	v_cvt_pk_f32_fp8_sdwa v[168:169], v8 src0_sel:WORD_1
	v_cvt_pk_f32_fp8_e32 v[170:171], v9
	v_cvt_pk_f32_fp8_sdwa v[172:173], v9 src0_sel:WORD_1
	v_pk_fma_f32 v[242:243], v[182:183], v[166:167], v[242:243] op_sel:[1,0,0]
	v_pk_fma_f32 v[244:245], v[182:183], v[168:169], v[244:245] op_sel:[1,0,0]
	v_pk_fma_f32 v[246:247], v[182:183], v[170:171], v[246:247] op_sel:[1,0,0]
	v_pk_fma_f32 v[248:249], v[182:183], v[172:173], v[248:249] op_sel:[1,0,0]
	v_cvt_pk_f32_fp8_e32 v[166:167], v10
	v_cvt_pk_f32_fp8_sdwa v[168:169], v10 src0_sel:WORD_1
	v_cvt_pk_f32_fp8_e32 v[170:171], v11
	v_cvt_pk_f32_fp8_sdwa v[172:173], v11 src0_sel:WORD_1
	v_pk_fma_f32 v[242:243], v[184:185], v[166:167], v[242:243] op_sel_hi:[0,1,1]
	v_pk_fma_f32 v[244:245], v[184:185], v[168:169], v[244:245] op_sel_hi:[0,1,1]
	v_pk_fma_f32 v[246:247], v[184:185], v[170:171], v[246:247] op_sel_hi:[0,1,1]
	v_pk_fma_f32 v[248:249], v[184:185], v[172:173], v[248:249] op_sel_hi:[0,1,1]
	v_cvt_pk_f32_fp8_e32 v[166:167], v12
	v_cvt_pk_f32_fp8_sdwa v[168:169], v12 src0_sel:WORD_1
	v_cvt_pk_f32_fp8_e32 v[170:171], v13
	v_cvt_pk_f32_fp8_sdwa v[172:173], v13 src0_sel:WORD_1
	v_pk_fma_f32 v[242:243], v[184:185], v[166:167], v[242:243] op_sel:[1,0,0]
	v_pk_fma_f32 v[244:245], v[184:185], v[168:169], v[244:245] op_sel:[1,0,0]
	v_pk_fma_f32 v[246:247], v[184:185], v[170:171], v[246:247] op_sel:[1,0,0]
	v_pk_fma_f32 v[248:249], v[184:185], v[172:173], v[248:249] op_sel:[1,0,0]
	v_cvt_pk_f32_fp8_e32 v[166:167], v14
	v_cvt_pk_f32_fp8_sdwa v[168:169], v14 src0_sel:WORD_1
	v_cvt_pk_f32_fp8_e32 v[170:171], v15
	v_cvt_pk_f32_fp8_sdwa v[172:173], v15 src0_sel:WORD_1
	v_pk_fma_f32 v[242:243], v[186:187], v[166:167], v[242:243] op_sel_hi:[0,1,1]
	v_pk_fma_f32 v[244:245], v[186:187], v[168:169], v[244:245] op_sel_hi:[0,1,1]
	v_pk_fma_f32 v[246:247], v[186:187], v[170:171], v[246:247] op_sel_hi:[0,1,1]
	v_pk_fma_f32 v[248:249], v[186:187], v[172:173], v[248:249] op_sel_hi:[0,1,1]
	v_cvt_pk_f32_fp8_e32 v[166:167], v16
	v_cvt_pk_f32_fp8_sdwa v[168:169], v16 src0_sel:WORD_1
	v_cvt_pk_f32_fp8_e32 v[170:171], v17
	v_cvt_pk_f32_fp8_sdwa v[172:173], v17 src0_sel:WORD_1
	v_pk_fma_f32 v[242:243], v[186:187], v[166:167], v[242:243] op_sel:[1,0,0]
	v_pk_fma_f32 v[244:245], v[186:187], v[168:169], v[244:245] op_sel:[1,0,0]
	v_pk_fma_f32 v[246:247], v[186:187], v[170:171], v[246:247] op_sel:[1,0,0]
	v_pk_fma_f32 v[248:249], v[186:187], v[172:173], v[248:249] op_sel:[1,0,0]
	v_cvt_pk_f32_fp8_e32 v[166:167], v18
	v_cvt_pk_f32_fp8_sdwa v[168:169], v18 src0_sel:WORD_1
	v_cvt_pk_f32_fp8_e32 v[170:171], v19
	v_cvt_pk_f32_fp8_sdwa v[172:173], v19 src0_sel:WORD_1
	v_pk_fma_f32 v[242:243], v[188:189], v[166:167], v[242:243] op_sel_hi:[0,1,1]
	v_pk_fma_f32 v[244:245], v[188:189], v[168:169], v[244:245] op_sel_hi:[0,1,1]
	v_pk_fma_f32 v[246:247], v[188:189], v[170:171], v[246:247] op_sel_hi:[0,1,1]
	v_pk_fma_f32 v[248:249], v[188:189], v[172:173], v[248:249] op_sel_hi:[0,1,1]
	v_cvt_pk_f32_fp8_e32 v[166:167], v20
	v_cvt_pk_f32_fp8_sdwa v[168:169], v20 src0_sel:WORD_1
	v_cvt_pk_f32_fp8_e32 v[170:171], v21
	v_cvt_pk_f32_fp8_sdwa v[172:173], v21 src0_sel:WORD_1
	v_pk_fma_f32 v[242:243], v[188:189], v[166:167], v[242:243] op_sel:[1,0,0]
	v_pk_fma_f32 v[244:245], v[188:189], v[168:169], v[244:245] op_sel:[1,0,0]
	v_pk_fma_f32 v[246:247], v[188:189], v[170:171], v[246:247] op_sel:[1,0,0]
	v_pk_fma_f32 v[248:249], v[188:189], v[172:173], v[248:249] op_sel:[1,0,0]
	v_cvt_pk_f32_fp8_e32 v[166:167], v22
	v_cvt_pk_f32_fp8_sdwa v[168:169], v22 src0_sel:WORD_1
	v_cvt_pk_f32_fp8_e32 v[170:171], v23
	v_cvt_pk_f32_fp8_sdwa v[172:173], v23 src0_sel:WORD_1
	v_pk_fma_f32 v[242:243], v[190:191], v[166:167], v[242:243] op_sel_hi:[0,1,1]
	v_pk_fma_f32 v[244:245], v[190:191], v[168:169], v[244:245] op_sel_hi:[0,1,1]
	v_pk_fma_f32 v[246:247], v[190:191], v[170:171], v[246:247] op_sel_hi:[0,1,1]
	v_pk_fma_f32 v[248:249], v[190:191], v[172:173], v[248:249] op_sel_hi:[0,1,1]
	v_cvt_pk_f32_fp8_e32 v[166:167], v24
	v_cvt_pk_f32_fp8_sdwa v[168:169], v24 src0_sel:WORD_1
	v_cvt_pk_f32_fp8_e32 v[170:171], v25
	v_cvt_pk_f32_fp8_sdwa v[172:173], v25 src0_sel:WORD_1
	v_pk_fma_f32 v[242:243], v[190:191], v[166:167], v[242:243] op_sel:[1,0,0]
	v_pk_fma_f32 v[244:245], v[190:191], v[168:169], v[244:245] op_sel:[1,0,0]
	v_pk_fma_f32 v[246:247], v[190:191], v[170:171], v[246:247] op_sel:[1,0,0]
	v_pk_fma_f32 v[248:249], v[190:191], v[172:173], v[248:249] op_sel:[1,0,0]
	v_cvt_pk_f32_fp8_e32 v[166:167], v26
	v_cvt_pk_f32_fp8_sdwa v[168:169], v26 src0_sel:WORD_1
	v_cvt_pk_f32_fp8_e32 v[170:171], v27
	v_cvt_pk_f32_fp8_sdwa v[172:173], v27 src0_sel:WORD_1
	v_pk_fma_f32 v[242:243], v[192:193], v[166:167], v[242:243] op_sel_hi:[0,1,1]
	v_pk_fma_f32 v[244:245], v[192:193], v[168:169], v[244:245] op_sel_hi:[0,1,1]
	v_pk_fma_f32 v[246:247], v[192:193], v[170:171], v[246:247] op_sel_hi:[0,1,1]
	v_pk_fma_f32 v[248:249], v[192:193], v[172:173], v[248:249] op_sel_hi:[0,1,1]
	v_cvt_pk_f32_fp8_e32 v[166:167], v28
	v_cvt_pk_f32_fp8_sdwa v[168:169], v28 src0_sel:WORD_1
	v_cvt_pk_f32_fp8_e32 v[170:171], v29
	v_cvt_pk_f32_fp8_sdwa v[172:173], v29 src0_sel:WORD_1
	v_pk_fma_f32 v[242:243], v[192:193], v[166:167], v[242:243] op_sel:[1,0,0]
	v_pk_fma_f32 v[244:245], v[192:193], v[168:169], v[244:245] op_sel:[1,0,0]
	v_pk_fma_f32 v[246:247], v[192:193], v[170:171], v[246:247] op_sel:[1,0,0]
	v_pk_fma_f32 v[248:249], v[192:193], v[172:173], v[248:249] op_sel:[1,0,0]
	v_cvt_pk_f32_fp8_e32 v[166:167], v30
	v_cvt_pk_f32_fp8_sdwa v[168:169], v30 src0_sel:WORD_1
	v_cvt_pk_f32_fp8_e32 v[170:171], v31
	v_cvt_pk_f32_fp8_sdwa v[172:173], v31 src0_sel:WORD_1
	v_pk_fma_f32 v[242:243], v[194:195], v[166:167], v[242:243] op_sel_hi:[0,1,1]
	v_pk_fma_f32 v[244:245], v[194:195], v[168:169], v[244:245] op_sel_hi:[0,1,1]
	v_pk_fma_f32 v[246:247], v[194:195], v[170:171], v[246:247] op_sel_hi:[0,1,1]
	v_pk_fma_f32 v[248:249], v[194:195], v[172:173], v[248:249] op_sel_hi:[0,1,1]
	v_cvt_pk_f32_fp8_e32 v[166:167], v32
	v_cvt_pk_f32_fp8_sdwa v[168:169], v32 src0_sel:WORD_1
	v_cvt_pk_f32_fp8_e32 v[170:171], v33
	v_cvt_pk_f32_fp8_sdwa v[172:173], v33 src0_sel:WORD_1
	v_pk_fma_f32 v[242:243], v[194:195], v[166:167], v[242:243] op_sel:[1,0,0]
	v_pk_fma_f32 v[244:245], v[194:195], v[168:169], v[244:245] op_sel:[1,0,0]
	v_pk_fma_f32 v[246:247], v[194:195], v[170:171], v[246:247] op_sel:[1,0,0]
	v_pk_fma_f32 v[248:249], v[194:195], v[172:173], v[248:249] op_sel:[1,0,0]
	s_waitcnt lgkmcnt(0)
	v_add_u32_e32 v120, v104, v226
	global_load_dwordx2 v[2:3], v120, s[50:51]
	v_add_u32_e32 v122, v104, v227
	global_load_dwordx2 v[4:5], v122, s[50:51]
	v_add_u32_e32 v124, v104, v228
	global_load_dwordx2 v[6:7], v124, s[50:51]
	v_add_u32_e32 v126, v104, v229
	global_load_dwordx2 v[8:9], v126, s[50:51]
	v_add_u32_e32 v120, v104, v230
	global_load_dwordx2 v[10:11], v120, s[50:51]
	v_add_u32_e32 v122, v104, v231
	global_load_dwordx2 v[12:13], v122, s[50:51]
	v_add_u32_e32 v124, v104, v232
	global_load_dwordx2 v[14:15], v124, s[50:51]
	v_add_u32_e32 v126, v104, v233
	global_load_dwordx2 v[16:17], v126, s[50:51]
	v_add_u32_e32 v120, v104, v234
	global_load_dwordx2 v[18:19], v120, s[50:51]
	v_add_u32_e32 v122, v104, v235
	global_load_dwordx2 v[20:21], v122, s[50:51]
	v_add_u32_e32 v124, v104, v236
	global_load_dwordx2 v[22:23], v124, s[50:51]
	v_add_u32_e32 v126, v104, v237
	global_load_dwordx2 v[24:25], v126, s[50:51]
	v_add_u32_e32 v120, v104, v238
	global_load_dwordx2 v[26:27], v120, s[50:51]
	v_add_u32_e32 v122, v104, v239
	global_load_dwordx2 v[28:29], v122, s[50:51]
	v_add_u32_e32 v124, v104, v240
	global_load_dwordx2 v[30:31], v124, s[50:51]
	v_add_u32_e32 v126, v104, v241
	global_load_dwordx2 v[32:33], v126, s[50:51]
	ds_read_b128 v[226:229], v106 offset:256
	ds_read_b128 v[230:233], v106 offset:272
	ds_read_b128 v[234:237], v106 offset:288
	ds_read_b128 v[238:241], v106 offset:304
	ds_read_b128 v[180:183], v106 offset:6272
	ds_read_b128 v[184:187], v106 offset:6288
	ds_read_b128 v[188:191], v106 offset:6304
	ds_read_b128 v[192:195], v106 offset:6320
	s_waitcnt vmcnt(36)
	v_cvt_pk_f32_fp8_e32 v[166:167], v34
	v_cvt_pk_f32_fp8_sdwa v[168:169], v34 src0_sel:WORD_1
	v_cvt_pk_f32_fp8_e32 v[170:171], v35
	v_cvt_pk_f32_fp8_sdwa v[172:173], v35 src0_sel:WORD_1
	v_pk_fma_f32 v[242:243], v[196:197], v[166:167], v[242:243] op_sel_hi:[0,1,1]
	v_pk_fma_f32 v[244:245], v[196:197], v[168:169], v[244:245] op_sel_hi:[0,1,1]
	v_pk_fma_f32 v[246:247], v[196:197], v[170:171], v[246:247] op_sel_hi:[0,1,1]
	v_pk_fma_f32 v[248:249], v[196:197], v[172:173], v[248:249] op_sel_hi:[0,1,1]
	v_cvt_pk_f32_fp8_e32 v[166:167], v36
	v_cvt_pk_f32_fp8_sdwa v[168:169], v36 src0_sel:WORD_1
	v_cvt_pk_f32_fp8_e32 v[170:171], v37
	v_cvt_pk_f32_fp8_sdwa v[172:173], v37 src0_sel:WORD_1
	v_pk_fma_f32 v[242:243], v[196:197], v[166:167], v[242:243] op_sel:[1,0,0]
	v_pk_fma_f32 v[244:245], v[196:197], v[168:169], v[244:245] op_sel:[1,0,0]
	v_pk_fma_f32 v[246:247], v[196:197], v[170:171], v[246:247] op_sel:[1,0,0]
	v_pk_fma_f32 v[248:249], v[196:197], v[172:173], v[248:249] op_sel:[1,0,0]
	v_cvt_pk_f32_fp8_e32 v[166:167], v38
	v_cvt_pk_f32_fp8_sdwa v[168:169], v38 src0_sel:WORD_1
	v_cvt_pk_f32_fp8_e32 v[170:171], v39
	v_cvt_pk_f32_fp8_sdwa v[172:173], v39 src0_sel:WORD_1
	v_pk_fma_f32 v[242:243], v[198:199], v[166:167], v[242:243] op_sel_hi:[0,1,1]
	v_pk_fma_f32 v[244:245], v[198:199], v[168:169], v[244:245] op_sel_hi:[0,1,1]
	v_pk_fma_f32 v[246:247], v[198:199], v[170:171], v[246:247] op_sel_hi:[0,1,1]
	v_pk_fma_f32 v[248:249], v[198:199], v[172:173], v[248:249] op_sel_hi:[0,1,1]
	v_cvt_pk_f32_fp8_e32 v[166:167], v40
	v_cvt_pk_f32_fp8_sdwa v[168:169], v40 src0_sel:WORD_1
	v_cvt_pk_f32_fp8_e32 v[170:171], v41
	v_cvt_pk_f32_fp8_sdwa v[172:173], v41 src0_sel:WORD_1
	v_pk_fma_f32 v[242:243], v[198:199], v[166:167], v[242:243] op_sel:[1,0,0]
	v_pk_fma_f32 v[244:245], v[198:199], v[168:169], v[244:245] op_sel:[1,0,0]
	v_pk_fma_f32 v[246:247], v[198:199], v[170:171], v[246:247] op_sel:[1,0,0]
	v_pk_fma_f32 v[248:249], v[198:199], v[172:173], v[248:249] op_sel:[1,0,0]
	v_cvt_pk_f32_fp8_e32 v[166:167], v42
	v_cvt_pk_f32_fp8_sdwa v[168:169], v42 src0_sel:WORD_1
	v_cvt_pk_f32_fp8_e32 v[170:171], v43
	v_cvt_pk_f32_fp8_sdwa v[172:173], v43 src0_sel:WORD_1
	v_pk_fma_f32 v[242:243], v[200:201], v[166:167], v[242:243] op_sel_hi:[0,1,1]
	v_pk_fma_f32 v[244:245], v[200:201], v[168:169], v[244:245] op_sel_hi:[0,1,1]
	v_pk_fma_f32 v[246:247], v[200:201], v[170:171], v[246:247] op_sel_hi:[0,1,1]
	v_pk_fma_f32 v[248:249], v[200:201], v[172:173], v[248:249] op_sel_hi:[0,1,1]
	v_cvt_pk_f32_fp8_e32 v[166:167], v44
	v_cvt_pk_f32_fp8_sdwa v[168:169], v44 src0_sel:WORD_1
	v_cvt_pk_f32_fp8_e32 v[170:171], v45
	v_cvt_pk_f32_fp8_sdwa v[172:173], v45 src0_sel:WORD_1
	v_pk_fma_f32 v[242:243], v[200:201], v[166:167], v[242:243] op_sel:[1,0,0]
	v_pk_fma_f32 v[244:245], v[200:201], v[168:169], v[244:245] op_sel:[1,0,0]
	v_pk_fma_f32 v[246:247], v[200:201], v[170:171], v[246:247] op_sel:[1,0,0]
	v_pk_fma_f32 v[248:249], v[200:201], v[172:173], v[248:249] op_sel:[1,0,0]
	v_cvt_pk_f32_fp8_e32 v[166:167], v46
	v_cvt_pk_f32_fp8_sdwa v[168:169], v46 src0_sel:WORD_1
	v_cvt_pk_f32_fp8_e32 v[170:171], v47
	v_cvt_pk_f32_fp8_sdwa v[172:173], v47 src0_sel:WORD_1
	v_pk_fma_f32 v[242:243], v[202:203], v[166:167], v[242:243] op_sel_hi:[0,1,1]
	v_pk_fma_f32 v[244:245], v[202:203], v[168:169], v[244:245] op_sel_hi:[0,1,1]
	v_pk_fma_f32 v[246:247], v[202:203], v[170:171], v[246:247] op_sel_hi:[0,1,1]
	v_pk_fma_f32 v[248:249], v[202:203], v[172:173], v[248:249] op_sel_hi:[0,1,1]
	v_cvt_pk_f32_fp8_e32 v[166:167], v48
	v_cvt_pk_f32_fp8_sdwa v[168:169], v48 src0_sel:WORD_1
	v_cvt_pk_f32_fp8_e32 v[170:171], v49
	v_cvt_pk_f32_fp8_sdwa v[172:173], v49 src0_sel:WORD_1
	v_pk_fma_f32 v[242:243], v[202:203], v[166:167], v[242:243] op_sel:[1,0,0]
	v_pk_fma_f32 v[244:245], v[202:203], v[168:169], v[244:245] op_sel:[1,0,0]
	v_pk_fma_f32 v[246:247], v[202:203], v[170:171], v[246:247] op_sel:[1,0,0]
	v_pk_fma_f32 v[248:249], v[202:203], v[172:173], v[248:249] op_sel:[1,0,0]
	v_cvt_pk_f32_fp8_e32 v[166:167], v50
	v_cvt_pk_f32_fp8_sdwa v[168:169], v50 src0_sel:WORD_1
	v_cvt_pk_f32_fp8_e32 v[170:171], v51
	v_cvt_pk_f32_fp8_sdwa v[172:173], v51 src0_sel:WORD_1
	v_pk_fma_f32 v[242:243], v[204:205], v[166:167], v[242:243] op_sel_hi:[0,1,1]
	v_pk_fma_f32 v[244:245], v[204:205], v[168:169], v[244:245] op_sel_hi:[0,1,1]
	v_pk_fma_f32 v[246:247], v[204:205], v[170:171], v[246:247] op_sel_hi:[0,1,1]
	v_pk_fma_f32 v[248:249], v[204:205], v[172:173], v[248:249] op_sel_hi:[0,1,1]
	v_cvt_pk_f32_fp8_e32 v[166:167], v52
	v_cvt_pk_f32_fp8_sdwa v[168:169], v52 src0_sel:WORD_1
	v_cvt_pk_f32_fp8_e32 v[170:171], v53
	v_cvt_pk_f32_fp8_sdwa v[172:173], v53 src0_sel:WORD_1
	v_pk_fma_f32 v[242:243], v[204:205], v[166:167], v[242:243] op_sel:[1,0,0]
	v_pk_fma_f32 v[244:245], v[204:205], v[168:169], v[244:245] op_sel:[1,0,0]
	v_pk_fma_f32 v[246:247], v[204:205], v[170:171], v[246:247] op_sel:[1,0,0]
	v_pk_fma_f32 v[248:249], v[204:205], v[172:173], v[248:249] op_sel:[1,0,0]
	v_cvt_pk_f32_fp8_e32 v[166:167], v54
	v_cvt_pk_f32_fp8_sdwa v[168:169], v54 src0_sel:WORD_1
	v_cvt_pk_f32_fp8_e32 v[170:171], v55
	v_cvt_pk_f32_fp8_sdwa v[172:173], v55 src0_sel:WORD_1
	v_pk_fma_f32 v[242:243], v[206:207], v[166:167], v[242:243] op_sel_hi:[0,1,1]
	v_pk_fma_f32 v[244:245], v[206:207], v[168:169], v[244:245] op_sel_hi:[0,1,1]
	v_pk_fma_f32 v[246:247], v[206:207], v[170:171], v[246:247] op_sel_hi:[0,1,1]
	v_pk_fma_f32 v[248:249], v[206:207], v[172:173], v[248:249] op_sel_hi:[0,1,1]
	v_cvt_pk_f32_fp8_e32 v[166:167], v56
	v_cvt_pk_f32_fp8_sdwa v[168:169], v56 src0_sel:WORD_1
	v_cvt_pk_f32_fp8_e32 v[170:171], v57
	v_cvt_pk_f32_fp8_sdwa v[172:173], v57 src0_sel:WORD_1
	v_pk_fma_f32 v[242:243], v[206:207], v[166:167], v[242:243] op_sel:[1,0,0]
	v_pk_fma_f32 v[244:245], v[206:207], v[168:169], v[244:245] op_sel:[1,0,0]
	v_pk_fma_f32 v[246:247], v[206:207], v[170:171], v[246:247] op_sel:[1,0,0]
	v_pk_fma_f32 v[248:249], v[206:207], v[172:173], v[248:249] op_sel:[1,0,0]
	v_cvt_pk_f32_fp8_e32 v[166:167], v58
	v_cvt_pk_f32_fp8_sdwa v[168:169], v58 src0_sel:WORD_1
	v_cvt_pk_f32_fp8_e32 v[170:171], v59
	v_cvt_pk_f32_fp8_sdwa v[172:173], v59 src0_sel:WORD_1
	v_pk_fma_f32 v[242:243], v[216:217], v[166:167], v[242:243] op_sel_hi:[0,1,1]
	v_pk_fma_f32 v[244:245], v[216:217], v[168:169], v[244:245] op_sel_hi:[0,1,1]
	v_pk_fma_f32 v[246:247], v[216:217], v[170:171], v[246:247] op_sel_hi:[0,1,1]
	v_pk_fma_f32 v[248:249], v[216:217], v[172:173], v[248:249] op_sel_hi:[0,1,1]
	v_cvt_pk_f32_fp8_e32 v[166:167], v60
	v_cvt_pk_f32_fp8_sdwa v[168:169], v60 src0_sel:WORD_1
	v_cvt_pk_f32_fp8_e32 v[170:171], v61
	v_cvt_pk_f32_fp8_sdwa v[172:173], v61 src0_sel:WORD_1
	v_pk_fma_f32 v[242:243], v[216:217], v[166:167], v[242:243] op_sel:[1,0,0]
	v_pk_fma_f32 v[244:245], v[216:217], v[168:169], v[244:245] op_sel:[1,0,0]
	v_pk_fma_f32 v[246:247], v[216:217], v[170:171], v[246:247] op_sel:[1,0,0]
	v_pk_fma_f32 v[248:249], v[216:217], v[172:173], v[248:249] op_sel:[1,0,0]
	v_cvt_pk_f32_fp8_e32 v[166:167], v62
	v_cvt_pk_f32_fp8_sdwa v[168:169], v62 src0_sel:WORD_1
	v_cvt_pk_f32_fp8_e32 v[170:171], v63
	v_cvt_pk_f32_fp8_sdwa v[172:173], v63 src0_sel:WORD_1
	v_pk_fma_f32 v[242:243], v[218:219], v[166:167], v[242:243] op_sel_hi:[0,1,1]
	v_pk_fma_f32 v[244:245], v[218:219], v[168:169], v[244:245] op_sel_hi:[0,1,1]
	v_pk_fma_f32 v[246:247], v[218:219], v[170:171], v[246:247] op_sel_hi:[0,1,1]
	v_pk_fma_f32 v[248:249], v[218:219], v[172:173], v[248:249] op_sel_hi:[0,1,1]
	v_cvt_pk_f32_fp8_e32 v[166:167], v64
	v_cvt_pk_f32_fp8_sdwa v[168:169], v64 src0_sel:WORD_1
	v_cvt_pk_f32_fp8_e32 v[170:171], v65
	v_cvt_pk_f32_fp8_sdwa v[172:173], v65 src0_sel:WORD_1
	v_pk_fma_f32 v[242:243], v[218:219], v[166:167], v[242:243] op_sel:[1,0,0]
	v_pk_fma_f32 v[244:245], v[218:219], v[168:169], v[244:245] op_sel:[1,0,0]
	v_pk_fma_f32 v[246:247], v[218:219], v[170:171], v[246:247] op_sel:[1,0,0]
	v_pk_fma_f32 v[248:249], v[218:219], v[172:173], v[248:249] op_sel:[1,0,0]
	s_waitcnt lgkmcnt(0)
	v_add_u32_e32 v120, v104, v226
	global_load_dwordx2 v[34:35], v120, s[50:51]
	v_add_u32_e32 v122, v104, v227
	global_load_dwordx2 v[36:37], v122, s[50:51]
	v_add_u32_e32 v124, v104, v228
	global_load_dwordx2 v[38:39], v124, s[50:51]
	v_add_u32_e32 v126, v104, v229
	global_load_dwordx2 v[40:41], v126, s[50:51]
	v_add_u32_e32 v120, v104, v230
	global_load_dwordx2 v[42:43], v120, s[50:51]
	v_add_u32_e32 v122, v104, v231
	global_load_dwordx2 v[44:45], v122, s[50:51]
	v_add_u32_e32 v124, v104, v232
	global_load_dwordx2 v[46:47], v124, s[50:51]
	v_add_u32_e32 v126, v104, v233
	global_load_dwordx2 v[48:49], v126, s[50:51]
	v_add_u32_e32 v120, v104, v234
	global_load_dwordx2 v[50:51], v120, s[50:51]
	v_add_u32_e32 v122, v104, v235
	global_load_dwordx2 v[52:53], v122, s[50:51]
	v_add_u32_e32 v124, v104, v236
	global_load_dwordx2 v[54:55], v124, s[50:51]
	v_add_u32_e32 v126, v104, v237
	global_load_dwordx2 v[56:57], v126, s[50:51]
	v_add_u32_e32 v120, v104, v238
	global_load_dwordx2 v[58:59], v120, s[50:51]
	v_add_u32_e32 v122, v104, v239
	global_load_dwordx2 v[60:61], v122, s[50:51]
	v_add_u32_e32 v124, v104, v240
	global_load_dwordx2 v[62:63], v124, s[50:51]
	v_add_u32_e32 v126, v104, v241
	global_load_dwordx2 v[64:65], v126, s[50:51]
	ds_read_b128 v[226:229], v106 offset:320
	ds_read_b128 v[230:233], v106 offset:336
	ds_read_b128 v[234:237], v106 offset:352
	ds_read_b128 v[238:241], v106 offset:368
	ds_read_b128 v[196:199], v106 offset:6336
	ds_read_b128 v[200:203], v106 offset:6352
	ds_read_b128 v[204:207], v106 offset:6368
	ds_read_b128 v[216:219], v106 offset:6384
	s_waitcnt vmcnt(32)
	v_cvt_pk_f32_fp8_e32 v[166:167], v134
	v_cvt_pk_f32_fp8_sdwa v[168:169], v134 src0_sel:WORD_1
	v_cvt_pk_f32_fp8_e32 v[170:171], v135
	v_cvt_pk_f32_fp8_sdwa v[172:173], v135 src0_sel:WORD_1
	v_pk_fma_f32 v[242:243], v[180:181], v[166:167], v[242:243] op_sel_hi:[0,1,1]
	v_pk_fma_f32 v[244:245], v[180:181], v[168:169], v[244:245] op_sel_hi:[0,1,1]
	v_pk_fma_f32 v[246:247], v[180:181], v[170:171], v[246:247] op_sel_hi:[0,1,1]
	v_pk_fma_f32 v[248:249], v[180:181], v[172:173], v[248:249] op_sel_hi:[0,1,1]
	v_cvt_pk_f32_fp8_e32 v[166:167], v136
	v_cvt_pk_f32_fp8_sdwa v[168:169], v136 src0_sel:WORD_1
	v_cvt_pk_f32_fp8_e32 v[170:171], v137
	v_cvt_pk_f32_fp8_sdwa v[172:173], v137 src0_sel:WORD_1
	v_pk_fma_f32 v[242:243], v[180:181], v[166:167], v[242:243] op_sel:[1,0,0]
	v_pk_fma_f32 v[244:245], v[180:181], v[168:169], v[244:245] op_sel:[1,0,0]
	v_pk_fma_f32 v[246:247], v[180:181], v[170:171], v[246:247] op_sel:[1,0,0]
	v_pk_fma_f32 v[248:249], v[180:181], v[172:173], v[248:249] op_sel:[1,0,0]
	v_cvt_pk_f32_fp8_e32 v[166:167], v138
	v_cvt_pk_f32_fp8_sdwa v[168:169], v138 src0_sel:WORD_1
	v_cvt_pk_f32_fp8_e32 v[170:171], v139
	v_cvt_pk_f32_fp8_sdwa v[172:173], v139 src0_sel:WORD_1
	v_pk_fma_f32 v[242:243], v[182:183], v[166:167], v[242:243] op_sel_hi:[0,1,1]
	v_pk_fma_f32 v[244:245], v[182:183], v[168:169], v[244:245] op_sel_hi:[0,1,1]
	v_pk_fma_f32 v[246:247], v[182:183], v[170:171], v[246:247] op_sel_hi:[0,1,1]
	v_pk_fma_f32 v[248:249], v[182:183], v[172:173], v[248:249] op_sel_hi:[0,1,1]
	v_cvt_pk_f32_fp8_e32 v[166:167], v140
	v_cvt_pk_f32_fp8_sdwa v[168:169], v140 src0_sel:WORD_1
	v_cvt_pk_f32_fp8_e32 v[170:171], v141
	v_cvt_pk_f32_fp8_sdwa v[172:173], v141 src0_sel:WORD_1
	v_pk_fma_f32 v[242:243], v[182:183], v[166:167], v[242:243] op_sel:[1,0,0]
	v_pk_fma_f32 v[244:245], v[182:183], v[168:169], v[244:245] op_sel:[1,0,0]
	v_pk_fma_f32 v[246:247], v[182:183], v[170:171], v[246:247] op_sel:[1,0,0]
	v_pk_fma_f32 v[248:249], v[182:183], v[172:173], v[248:249] op_sel:[1,0,0]
	v_cvt_pk_f32_fp8_e32 v[166:167], v142
	v_cvt_pk_f32_fp8_sdwa v[168:169], v142 src0_sel:WORD_1
	v_cvt_pk_f32_fp8_e32 v[170:171], v143
	v_cvt_pk_f32_fp8_sdwa v[172:173], v143 src0_sel:WORD_1
	v_pk_fma_f32 v[242:243], v[184:185], v[166:167], v[242:243] op_sel_hi:[0,1,1]
	v_pk_fma_f32 v[244:245], v[184:185], v[168:169], v[244:245] op_sel_hi:[0,1,1]
	v_pk_fma_f32 v[246:247], v[184:185], v[170:171], v[246:247] op_sel_hi:[0,1,1]
	v_pk_fma_f32 v[248:249], v[184:185], v[172:173], v[248:249] op_sel_hi:[0,1,1]
	v_cvt_pk_f32_fp8_e32 v[166:167], v144
	v_cvt_pk_f32_fp8_sdwa v[168:169], v144 src0_sel:WORD_1
	v_cvt_pk_f32_fp8_e32 v[170:171], v145
	v_cvt_pk_f32_fp8_sdwa v[172:173], v145 src0_sel:WORD_1
	v_pk_fma_f32 v[242:243], v[184:185], v[166:167], v[242:243] op_sel:[1,0,0]
	v_pk_fma_f32 v[244:245], v[184:185], v[168:169], v[244:245] op_sel:[1,0,0]
	v_pk_fma_f32 v[246:247], v[184:185], v[170:171], v[246:247] op_sel:[1,0,0]
	v_pk_fma_f32 v[248:249], v[184:185], v[172:173], v[248:249] op_sel:[1,0,0]
	v_cvt_pk_f32_fp8_e32 v[166:167], v146
	v_cvt_pk_f32_fp8_sdwa v[168:169], v146 src0_sel:WORD_1
	v_cvt_pk_f32_fp8_e32 v[170:171], v147
	v_cvt_pk_f32_fp8_sdwa v[172:173], v147 src0_sel:WORD_1
	v_pk_fma_f32 v[242:243], v[186:187], v[166:167], v[242:243] op_sel_hi:[0,1,1]
	v_pk_fma_f32 v[244:245], v[186:187], v[168:169], v[244:245] op_sel_hi:[0,1,1]
	v_pk_fma_f32 v[246:247], v[186:187], v[170:171], v[246:247] op_sel_hi:[0,1,1]
	v_pk_fma_f32 v[248:249], v[186:187], v[172:173], v[248:249] op_sel_hi:[0,1,1]
	v_cvt_pk_f32_fp8_e32 v[166:167], v148
	v_cvt_pk_f32_fp8_sdwa v[168:169], v148 src0_sel:WORD_1
	v_cvt_pk_f32_fp8_e32 v[170:171], v149
	v_cvt_pk_f32_fp8_sdwa v[172:173], v149 src0_sel:WORD_1
	v_pk_fma_f32 v[242:243], v[186:187], v[166:167], v[242:243] op_sel:[1,0,0]
	v_pk_fma_f32 v[244:245], v[186:187], v[168:169], v[244:245] op_sel:[1,0,0]
	v_pk_fma_f32 v[246:247], v[186:187], v[170:171], v[246:247] op_sel:[1,0,0]
	v_pk_fma_f32 v[248:249], v[186:187], v[172:173], v[248:249] op_sel:[1,0,0]
	v_cvt_pk_f32_fp8_e32 v[166:167], v150
	v_cvt_pk_f32_fp8_sdwa v[168:169], v150 src0_sel:WORD_1
	v_cvt_pk_f32_fp8_e32 v[170:171], v151
	v_cvt_pk_f32_fp8_sdwa v[172:173], v151 src0_sel:WORD_1
	v_pk_fma_f32 v[242:243], v[188:189], v[166:167], v[242:243] op_sel_hi:[0,1,1]
	v_pk_fma_f32 v[244:245], v[188:189], v[168:169], v[244:245] op_sel_hi:[0,1,1]
	v_pk_fma_f32 v[246:247], v[188:189], v[170:171], v[246:247] op_sel_hi:[0,1,1]
	v_pk_fma_f32 v[248:249], v[188:189], v[172:173], v[248:249] op_sel_hi:[0,1,1]
	v_cvt_pk_f32_fp8_e32 v[166:167], v152
	v_cvt_pk_f32_fp8_sdwa v[168:169], v152 src0_sel:WORD_1
	v_cvt_pk_f32_fp8_e32 v[170:171], v153
	v_cvt_pk_f32_fp8_sdwa v[172:173], v153 src0_sel:WORD_1
	v_pk_fma_f32 v[242:243], v[188:189], v[166:167], v[242:243] op_sel:[1,0,0]
	v_pk_fma_f32 v[244:245], v[188:189], v[168:169], v[244:245] op_sel:[1,0,0]
	v_pk_fma_f32 v[246:247], v[188:189], v[170:171], v[246:247] op_sel:[1,0,0]
	v_pk_fma_f32 v[248:249], v[188:189], v[172:173], v[248:249] op_sel:[1,0,0]
	v_cvt_pk_f32_fp8_e32 v[166:167], v154
	v_cvt_pk_f32_fp8_sdwa v[168:169], v154 src0_sel:WORD_1
	v_cvt_pk_f32_fp8_e32 v[170:171], v155
	v_cvt_pk_f32_fp8_sdwa v[172:173], v155 src0_sel:WORD_1
	v_pk_fma_f32 v[242:243], v[190:191], v[166:167], v[242:243] op_sel_hi:[0,1,1]
	v_pk_fma_f32 v[244:245], v[190:191], v[168:169], v[244:245] op_sel_hi:[0,1,1]
	v_pk_fma_f32 v[246:247], v[190:191], v[170:171], v[246:247] op_sel_hi:[0,1,1]
	v_pk_fma_f32 v[248:249], v[190:191], v[172:173], v[248:249] op_sel_hi:[0,1,1]
	v_cvt_pk_f32_fp8_e32 v[166:167], v156
	v_cvt_pk_f32_fp8_sdwa v[168:169], v156 src0_sel:WORD_1
	v_cvt_pk_f32_fp8_e32 v[170:171], v157
	v_cvt_pk_f32_fp8_sdwa v[172:173], v157 src0_sel:WORD_1
	v_pk_fma_f32 v[242:243], v[190:191], v[166:167], v[242:243] op_sel:[1,0,0]
	v_pk_fma_f32 v[244:245], v[190:191], v[168:169], v[244:245] op_sel:[1,0,0]
	v_pk_fma_f32 v[246:247], v[190:191], v[170:171], v[246:247] op_sel:[1,0,0]
	v_pk_fma_f32 v[248:249], v[190:191], v[172:173], v[248:249] op_sel:[1,0,0]
	v_cvt_pk_f32_fp8_e32 v[166:167], v158
	v_cvt_pk_f32_fp8_sdwa v[168:169], v158 src0_sel:WORD_1
	v_cvt_pk_f32_fp8_e32 v[170:171], v159
	v_cvt_pk_f32_fp8_sdwa v[172:173], v159 src0_sel:WORD_1
	v_pk_fma_f32 v[242:243], v[192:193], v[166:167], v[242:243] op_sel_hi:[0,1,1]
	v_pk_fma_f32 v[244:245], v[192:193], v[168:169], v[244:245] op_sel_hi:[0,1,1]
	v_pk_fma_f32 v[246:247], v[192:193], v[170:171], v[246:247] op_sel_hi:[0,1,1]
	v_pk_fma_f32 v[248:249], v[192:193], v[172:173], v[248:249] op_sel_hi:[0,1,1]
	v_cvt_pk_f32_fp8_e32 v[166:167], v160
	v_cvt_pk_f32_fp8_sdwa v[168:169], v160 src0_sel:WORD_1
	v_cvt_pk_f32_fp8_e32 v[170:171], v161
	v_cvt_pk_f32_fp8_sdwa v[172:173], v161 src0_sel:WORD_1
	v_pk_fma_f32 v[242:243], v[192:193], v[166:167], v[242:243] op_sel:[1,0,0]
	v_pk_fma_f32 v[244:245], v[192:193], v[168:169], v[244:245] op_sel:[1,0,0]
	v_pk_fma_f32 v[246:247], v[192:193], v[170:171], v[246:247] op_sel:[1,0,0]
	v_pk_fma_f32 v[248:249], v[192:193], v[172:173], v[248:249] op_sel:[1,0,0]
	v_cvt_pk_f32_fp8_e32 v[166:167], v162
	v_cvt_pk_f32_fp8_sdwa v[168:169], v162 src0_sel:WORD_1
	v_cvt_pk_f32_fp8_e32 v[170:171], v163
	v_cvt_pk_f32_fp8_sdwa v[172:173], v163 src0_sel:WORD_1
	v_pk_fma_f32 v[242:243], v[194:195], v[166:167], v[242:243] op_sel_hi:[0,1,1]
	v_pk_fma_f32 v[244:245], v[194:195], v[168:169], v[244:245] op_sel_hi:[0,1,1]
	v_pk_fma_f32 v[246:247], v[194:195], v[170:171], v[246:247] op_sel_hi:[0,1,1]
	v_pk_fma_f32 v[248:249], v[194:195], v[172:173], v[248:249] op_sel_hi:[0,1,1]
	v_cvt_pk_f32_fp8_e32 v[166:167], v164
	v_cvt_pk_f32_fp8_sdwa v[168:169], v164 src0_sel:WORD_1
	v_cvt_pk_f32_fp8_e32 v[170:171], v165
	v_cvt_pk_f32_fp8_sdwa v[172:173], v165 src0_sel:WORD_1
	v_pk_fma_f32 v[242:243], v[194:195], v[166:167], v[242:243] op_sel:[1,0,0]
	v_pk_fma_f32 v[244:245], v[194:195], v[168:169], v[244:245] op_sel:[1,0,0]
	v_pk_fma_f32 v[246:247], v[194:195], v[170:171], v[246:247] op_sel:[1,0,0]
	v_pk_fma_f32 v[248:249], v[194:195], v[172:173], v[248:249] op_sel:[1,0,0]
	s_waitcnt lgkmcnt(0)
	v_add_u32_e32 v120, v104, v226
	global_load_dwordx2 v[134:135], v120, s[50:51]
	v_add_u32_e32 v122, v104, v227
	global_load_dwordx2 v[136:137], v122, s[50:51]
	v_add_u32_e32 v124, v104, v228
	global_load_dwordx2 v[138:139], v124, s[50:51]
	v_add_u32_e32 v126, v104, v229
	global_load_dwordx2 v[140:141], v126, s[50:51]
	v_add_u32_e32 v120, v104, v230
	global_load_dwordx2 v[142:143], v120, s[50:51]
	v_add_u32_e32 v122, v104, v231
	global_load_dwordx2 v[144:145], v122, s[50:51]
	v_add_u32_e32 v124, v104, v232
	global_load_dwordx2 v[146:147], v124, s[50:51]
	v_add_u32_e32 v126, v104, v233
	global_load_dwordx2 v[148:149], v126, s[50:51]
	v_add_u32_e32 v120, v104, v234
	global_load_dwordx2 v[150:151], v120, s[50:51]
	v_add_u32_e32 v122, v104, v235
	global_load_dwordx2 v[152:153], v122, s[50:51]
	v_add_u32_e32 v124, v104, v236
	global_load_dwordx2 v[154:155], v124, s[50:51]
	v_add_u32_e32 v126, v104, v237
	global_load_dwordx2 v[156:157], v126, s[50:51]
	v_add_u32_e32 v120, v104, v238
	global_load_dwordx2 v[158:159], v120, s[50:51]
	v_add_u32_e32 v122, v104, v239
	global_load_dwordx2 v[160:161], v122, s[50:51]
	v_add_u32_e32 v124, v104, v240
	global_load_dwordx2 v[162:163], v124, s[50:51]
	v_add_u32_e32 v126, v104, v241
	global_load_dwordx2 v[164:165], v126, s[50:51]
	ds_read_b128 v[226:229], v106 offset:384
	ds_read_b128 v[230:233], v106 offset:400
	ds_read_b128 v[234:237], v106 offset:416
	ds_read_b128 v[238:241], v106 offset:432
	ds_read_b128 v[180:183], v106 offset:6400
	ds_read_b128 v[184:187], v106 offset:6416
	ds_read_b128 v[188:191], v106 offset:6432
	ds_read_b128 v[192:195], v106 offset:6448
	s_waitcnt vmcnt(32)
	v_cvt_pk_f32_fp8_e32 v[166:167], v2
	v_cvt_pk_f32_fp8_sdwa v[168:169], v2 src0_sel:WORD_1
	v_cvt_pk_f32_fp8_e32 v[170:171], v3
	v_cvt_pk_f32_fp8_sdwa v[172:173], v3 src0_sel:WORD_1
	v_pk_fma_f32 v[242:243], v[196:197], v[166:167], v[242:243] op_sel_hi:[0,1,1]
	v_pk_fma_f32 v[244:245], v[196:197], v[168:169], v[244:245] op_sel_hi:[0,1,1]
	v_pk_fma_f32 v[246:247], v[196:197], v[170:171], v[246:247] op_sel_hi:[0,1,1]
	v_pk_fma_f32 v[248:249], v[196:197], v[172:173], v[248:249] op_sel_hi:[0,1,1]
	v_cvt_pk_f32_fp8_e32 v[166:167], v4
	v_cvt_pk_f32_fp8_sdwa v[168:169], v4 src0_sel:WORD_1
	v_cvt_pk_f32_fp8_e32 v[170:171], v5
	v_cvt_pk_f32_fp8_sdwa v[172:173], v5 src0_sel:WORD_1
	v_pk_fma_f32 v[242:243], v[196:197], v[166:167], v[242:243] op_sel:[1,0,0]
	v_pk_fma_f32 v[244:245], v[196:197], v[168:169], v[244:245] op_sel:[1,0,0]
	v_pk_fma_f32 v[246:247], v[196:197], v[170:171], v[246:247] op_sel:[1,0,0]
	v_pk_fma_f32 v[248:249], v[196:197], v[172:173], v[248:249] op_sel:[1,0,0]
	v_cvt_pk_f32_fp8_e32 v[166:167], v6
	v_cvt_pk_f32_fp8_sdwa v[168:169], v6 src0_sel:WORD_1
	v_cvt_pk_f32_fp8_e32 v[170:171], v7
	v_cvt_pk_f32_fp8_sdwa v[172:173], v7 src0_sel:WORD_1
	v_pk_fma_f32 v[242:243], v[198:199], v[166:167], v[242:243] op_sel_hi:[0,1,1]
	v_pk_fma_f32 v[244:245], v[198:199], v[168:169], v[244:245] op_sel_hi:[0,1,1]
	v_pk_fma_f32 v[246:247], v[198:199], v[170:171], v[246:247] op_sel_hi:[0,1,1]
	v_pk_fma_f32 v[248:249], v[198:199], v[172:173], v[248:249] op_sel_hi:[0,1,1]
	v_cvt_pk_f32_fp8_e32 v[166:167], v8
	v_cvt_pk_f32_fp8_sdwa v[168:169], v8 src0_sel:WORD_1
	v_cvt_pk_f32_fp8_e32 v[170:171], v9
	v_cvt_pk_f32_fp8_sdwa v[172:173], v9 src0_sel:WORD_1
	v_pk_fma_f32 v[242:243], v[198:199], v[166:167], v[242:243] op_sel:[1,0,0]
	v_pk_fma_f32 v[244:245], v[198:199], v[168:169], v[244:245] op_sel:[1,0,0]
	v_pk_fma_f32 v[246:247], v[198:199], v[170:171], v[246:247] op_sel:[1,0,0]
	v_pk_fma_f32 v[248:249], v[198:199], v[172:173], v[248:249] op_sel:[1,0,0]
	v_cvt_pk_f32_fp8_e32 v[166:167], v10
	v_cvt_pk_f32_fp8_sdwa v[168:169], v10 src0_sel:WORD_1
	v_cvt_pk_f32_fp8_e32 v[170:171], v11
	v_cvt_pk_f32_fp8_sdwa v[172:173], v11 src0_sel:WORD_1
	v_pk_fma_f32 v[242:243], v[200:201], v[166:167], v[242:243] op_sel_hi:[0,1,1]
	v_pk_fma_f32 v[244:245], v[200:201], v[168:169], v[244:245] op_sel_hi:[0,1,1]
	v_pk_fma_f32 v[246:247], v[200:201], v[170:171], v[246:247] op_sel_hi:[0,1,1]
	v_pk_fma_f32 v[248:249], v[200:201], v[172:173], v[248:249] op_sel_hi:[0,1,1]
	v_cvt_pk_f32_fp8_e32 v[166:167], v12
	v_cvt_pk_f32_fp8_sdwa v[168:169], v12 src0_sel:WORD_1
	v_cvt_pk_f32_fp8_e32 v[170:171], v13
	v_cvt_pk_f32_fp8_sdwa v[172:173], v13 src0_sel:WORD_1
	v_pk_fma_f32 v[242:243], v[200:201], v[166:167], v[242:243] op_sel:[1,0,0]
	v_pk_fma_f32 v[244:245], v[200:201], v[168:169], v[244:245] op_sel:[1,0,0]
	v_pk_fma_f32 v[246:247], v[200:201], v[170:171], v[246:247] op_sel:[1,0,0]
	v_pk_fma_f32 v[248:249], v[200:201], v[172:173], v[248:249] op_sel:[1,0,0]
	v_cvt_pk_f32_fp8_e32 v[166:167], v14
	v_cvt_pk_f32_fp8_sdwa v[168:169], v14 src0_sel:WORD_1
	v_cvt_pk_f32_fp8_e32 v[170:171], v15
	v_cvt_pk_f32_fp8_sdwa v[172:173], v15 src0_sel:WORD_1
	v_pk_fma_f32 v[242:243], v[202:203], v[166:167], v[242:243] op_sel_hi:[0,1,1]
	v_pk_fma_f32 v[244:245], v[202:203], v[168:169], v[244:245] op_sel_hi:[0,1,1]
	v_pk_fma_f32 v[246:247], v[202:203], v[170:171], v[246:247] op_sel_hi:[0,1,1]
	v_pk_fma_f32 v[248:249], v[202:203], v[172:173], v[248:249] op_sel_hi:[0,1,1]
	v_cvt_pk_f32_fp8_e32 v[166:167], v16
	v_cvt_pk_f32_fp8_sdwa v[168:169], v16 src0_sel:WORD_1
	v_cvt_pk_f32_fp8_e32 v[170:171], v17
	v_cvt_pk_f32_fp8_sdwa v[172:173], v17 src0_sel:WORD_1
	v_pk_fma_f32 v[242:243], v[202:203], v[166:167], v[242:243] op_sel:[1,0,0]
	v_pk_fma_f32 v[244:245], v[202:203], v[168:169], v[244:245] op_sel:[1,0,0]
	v_pk_fma_f32 v[246:247], v[202:203], v[170:171], v[246:247] op_sel:[1,0,0]
	v_pk_fma_f32 v[248:249], v[202:203], v[172:173], v[248:249] op_sel:[1,0,0]
	v_cvt_pk_f32_fp8_e32 v[166:167], v18
	v_cvt_pk_f32_fp8_sdwa v[168:169], v18 src0_sel:WORD_1
	v_cvt_pk_f32_fp8_e32 v[170:171], v19
	v_cvt_pk_f32_fp8_sdwa v[172:173], v19 src0_sel:WORD_1
	v_pk_fma_f32 v[242:243], v[204:205], v[166:167], v[242:243] op_sel_hi:[0,1,1]
	v_pk_fma_f32 v[244:245], v[204:205], v[168:169], v[244:245] op_sel_hi:[0,1,1]
	v_pk_fma_f32 v[246:247], v[204:205], v[170:171], v[246:247] op_sel_hi:[0,1,1]
	v_pk_fma_f32 v[248:249], v[204:205], v[172:173], v[248:249] op_sel_hi:[0,1,1]
	v_cvt_pk_f32_fp8_e32 v[166:167], v20
	v_cvt_pk_f32_fp8_sdwa v[168:169], v20 src0_sel:WORD_1
	v_cvt_pk_f32_fp8_e32 v[170:171], v21
	v_cvt_pk_f32_fp8_sdwa v[172:173], v21 src0_sel:WORD_1
	v_pk_fma_f32 v[242:243], v[204:205], v[166:167], v[242:243] op_sel:[1,0,0]
	v_pk_fma_f32 v[244:245], v[204:205], v[168:169], v[244:245] op_sel:[1,0,0]
	v_pk_fma_f32 v[246:247], v[204:205], v[170:171], v[246:247] op_sel:[1,0,0]
	v_pk_fma_f32 v[248:249], v[204:205], v[172:173], v[248:249] op_sel:[1,0,0]
	v_cvt_pk_f32_fp8_e32 v[166:167], v22
	v_cvt_pk_f32_fp8_sdwa v[168:169], v22 src0_sel:WORD_1
	v_cvt_pk_f32_fp8_e32 v[170:171], v23
	v_cvt_pk_f32_fp8_sdwa v[172:173], v23 src0_sel:WORD_1
	v_pk_fma_f32 v[242:243], v[206:207], v[166:167], v[242:243] op_sel_hi:[0,1,1]
	v_pk_fma_f32 v[244:245], v[206:207], v[168:169], v[244:245] op_sel_hi:[0,1,1]
	v_pk_fma_f32 v[246:247], v[206:207], v[170:171], v[246:247] op_sel_hi:[0,1,1]
	v_pk_fma_f32 v[248:249], v[206:207], v[172:173], v[248:249] op_sel_hi:[0,1,1]
	v_cvt_pk_f32_fp8_e32 v[166:167], v24
	v_cvt_pk_f32_fp8_sdwa v[168:169], v24 src0_sel:WORD_1
	v_cvt_pk_f32_fp8_e32 v[170:171], v25
	v_cvt_pk_f32_fp8_sdwa v[172:173], v25 src0_sel:WORD_1
	v_pk_fma_f32 v[242:243], v[206:207], v[166:167], v[242:243] op_sel:[1,0,0]
	v_pk_fma_f32 v[244:245], v[206:207], v[168:169], v[244:245] op_sel:[1,0,0]
	v_pk_fma_f32 v[246:247], v[206:207], v[170:171], v[246:247] op_sel:[1,0,0]
	v_pk_fma_f32 v[248:249], v[206:207], v[172:173], v[248:249] op_sel:[1,0,0]
	v_cvt_pk_f32_fp8_e32 v[166:167], v26
	v_cvt_pk_f32_fp8_sdwa v[168:169], v26 src0_sel:WORD_1
	v_cvt_pk_f32_fp8_e32 v[170:171], v27
	v_cvt_pk_f32_fp8_sdwa v[172:173], v27 src0_sel:WORD_1
	v_pk_fma_f32 v[242:243], v[216:217], v[166:167], v[242:243] op_sel_hi:[0,1,1]
	v_pk_fma_f32 v[244:245], v[216:217], v[168:169], v[244:245] op_sel_hi:[0,1,1]
	v_pk_fma_f32 v[246:247], v[216:217], v[170:171], v[246:247] op_sel_hi:[0,1,1]
	v_pk_fma_f32 v[248:249], v[216:217], v[172:173], v[248:249] op_sel_hi:[0,1,1]
	v_cvt_pk_f32_fp8_e32 v[166:167], v28
	v_cvt_pk_f32_fp8_sdwa v[168:169], v28 src0_sel:WORD_1
	v_cvt_pk_f32_fp8_e32 v[170:171], v29
	v_cvt_pk_f32_fp8_sdwa v[172:173], v29 src0_sel:WORD_1
	v_pk_fma_f32 v[242:243], v[216:217], v[166:167], v[242:243] op_sel:[1,0,0]
	v_pk_fma_f32 v[244:245], v[216:217], v[168:169], v[244:245] op_sel:[1,0,0]
	v_pk_fma_f32 v[246:247], v[216:217], v[170:171], v[246:247] op_sel:[1,0,0]
	v_pk_fma_f32 v[248:249], v[216:217], v[172:173], v[248:249] op_sel:[1,0,0]
	v_cvt_pk_f32_fp8_e32 v[166:167], v30
	v_cvt_pk_f32_fp8_sdwa v[168:169], v30 src0_sel:WORD_1
	v_cvt_pk_f32_fp8_e32 v[170:171], v31
	v_cvt_pk_f32_fp8_sdwa v[172:173], v31 src0_sel:WORD_1
	v_pk_fma_f32 v[242:243], v[218:219], v[166:167], v[242:243] op_sel_hi:[0,1,1]
	v_pk_fma_f32 v[244:245], v[218:219], v[168:169], v[244:245] op_sel_hi:[0,1,1]
	v_pk_fma_f32 v[246:247], v[218:219], v[170:171], v[246:247] op_sel_hi:[0,1,1]
	v_pk_fma_f32 v[248:249], v[218:219], v[172:173], v[248:249] op_sel_hi:[0,1,1]
	v_cvt_pk_f32_fp8_e32 v[166:167], v32
	v_cvt_pk_f32_fp8_sdwa v[168:169], v32 src0_sel:WORD_1
	v_cvt_pk_f32_fp8_e32 v[170:171], v33
	v_cvt_pk_f32_fp8_sdwa v[172:173], v33 src0_sel:WORD_1
	v_pk_fma_f32 v[242:243], v[218:219], v[166:167], v[242:243] op_sel:[1,0,0]
	v_pk_fma_f32 v[244:245], v[218:219], v[168:169], v[244:245] op_sel:[1,0,0]
	v_pk_fma_f32 v[246:247], v[218:219], v[170:171], v[246:247] op_sel:[1,0,0]
	v_pk_fma_f32 v[248:249], v[218:219], v[172:173], v[248:249] op_sel:[1,0,0]
	s_waitcnt lgkmcnt(0)
	v_add_u32_e32 v120, v104, v226
	global_load_dwordx2 v[2:3], v120, s[50:51]
	v_add_u32_e32 v122, v104, v227
	global_load_dwordx2 v[4:5], v122, s[50:51]
	v_add_u32_e32 v124, v104, v228
	global_load_dwordx2 v[6:7], v124, s[50:51]
	v_add_u32_e32 v126, v104, v229
	global_load_dwordx2 v[8:9], v126, s[50:51]
	v_add_u32_e32 v120, v104, v230
	global_load_dwordx2 v[10:11], v120, s[50:51]
	v_add_u32_e32 v122, v104, v231
	global_load_dwordx2 v[12:13], v122, s[50:51]
	v_add_u32_e32 v124, v104, v232
	global_load_dwordx2 v[14:15], v124, s[50:51]
	v_add_u32_e32 v126, v104, v233
	global_load_dwordx2 v[16:17], v126, s[50:51]
	v_add_u32_e32 v120, v104, v234
	global_load_dwordx2 v[18:19], v120, s[50:51]
	v_add_u32_e32 v122, v104, v235
	global_load_dwordx2 v[20:21], v122, s[50:51]
	v_add_u32_e32 v124, v104, v236
	global_load_dwordx2 v[22:23], v124, s[50:51]
	v_add_u32_e32 v126, v104, v237
	global_load_dwordx2 v[24:25], v126, s[50:51]
	v_add_u32_e32 v120, v104, v238
	global_load_dwordx2 v[26:27], v120, s[50:51]
	v_add_u32_e32 v122, v104, v239
	global_load_dwordx2 v[28:29], v122, s[50:51]
	v_add_u32_e32 v124, v104, v240
	global_load_dwordx2 v[30:31], v124, s[50:51]
	v_add_u32_e32 v126, v104, v241
	global_load_dwordx2 v[32:33], v126, s[50:51]
	ds_read_b128 v[226:229], v106 offset:448
	ds_read_b128 v[230:233], v106 offset:464
	ds_read_b128 v[234:237], v106 offset:480
	ds_read_b128 v[238:241], v106 offset:496
	ds_read_b128 v[196:199], v106 offset:6464
	ds_read_b128 v[200:203], v106 offset:6480
	ds_read_b128 v[204:207], v106 offset:6496
	ds_read_b128 v[216:219], v106 offset:6512
	s_waitcnt vmcnt(32)
	v_cvt_pk_f32_fp8_e32 v[166:167], v34
	v_cvt_pk_f32_fp8_sdwa v[168:169], v34 src0_sel:WORD_1
	v_cvt_pk_f32_fp8_e32 v[170:171], v35
	v_cvt_pk_f32_fp8_sdwa v[172:173], v35 src0_sel:WORD_1
	v_pk_fma_f32 v[242:243], v[180:181], v[166:167], v[242:243] op_sel_hi:[0,1,1]
	v_pk_fma_f32 v[244:245], v[180:181], v[168:169], v[244:245] op_sel_hi:[0,1,1]
	v_pk_fma_f32 v[246:247], v[180:181], v[170:171], v[246:247] op_sel_hi:[0,1,1]
	v_pk_fma_f32 v[248:249], v[180:181], v[172:173], v[248:249] op_sel_hi:[0,1,1]
	v_cvt_pk_f32_fp8_e32 v[166:167], v36
	v_cvt_pk_f32_fp8_sdwa v[168:169], v36 src0_sel:WORD_1
	v_cvt_pk_f32_fp8_e32 v[170:171], v37
	v_cvt_pk_f32_fp8_sdwa v[172:173], v37 src0_sel:WORD_1
	v_pk_fma_f32 v[242:243], v[180:181], v[166:167], v[242:243] op_sel:[1,0,0]
	v_pk_fma_f32 v[244:245], v[180:181], v[168:169], v[244:245] op_sel:[1,0,0]
	v_pk_fma_f32 v[246:247], v[180:181], v[170:171], v[246:247] op_sel:[1,0,0]
	v_pk_fma_f32 v[248:249], v[180:181], v[172:173], v[248:249] op_sel:[1,0,0]
	v_cvt_pk_f32_fp8_e32 v[166:167], v38
	v_cvt_pk_f32_fp8_sdwa v[168:169], v38 src0_sel:WORD_1
	v_cvt_pk_f32_fp8_e32 v[170:171], v39
	v_cvt_pk_f32_fp8_sdwa v[172:173], v39 src0_sel:WORD_1
	v_pk_fma_f32 v[242:243], v[182:183], v[166:167], v[242:243] op_sel_hi:[0,1,1]
	v_pk_fma_f32 v[244:245], v[182:183], v[168:169], v[244:245] op_sel_hi:[0,1,1]
	v_pk_fma_f32 v[246:247], v[182:183], v[170:171], v[246:247] op_sel_hi:[0,1,1]
	v_pk_fma_f32 v[248:249], v[182:183], v[172:173], v[248:249] op_sel_hi:[0,1,1]
	v_cvt_pk_f32_fp8_e32 v[166:167], v40
	v_cvt_pk_f32_fp8_sdwa v[168:169], v40 src0_sel:WORD_1
	v_cvt_pk_f32_fp8_e32 v[170:171], v41
	v_cvt_pk_f32_fp8_sdwa v[172:173], v41 src0_sel:WORD_1
	v_pk_fma_f32 v[242:243], v[182:183], v[166:167], v[242:243] op_sel:[1,0,0]
	v_pk_fma_f32 v[244:245], v[182:183], v[168:169], v[244:245] op_sel:[1,0,0]
	v_pk_fma_f32 v[246:247], v[182:183], v[170:171], v[246:247] op_sel:[1,0,0]
	v_pk_fma_f32 v[248:249], v[182:183], v[172:173], v[248:249] op_sel:[1,0,0]
	v_cvt_pk_f32_fp8_e32 v[166:167], v42
	v_cvt_pk_f32_fp8_sdwa v[168:169], v42 src0_sel:WORD_1
	v_cvt_pk_f32_fp8_e32 v[170:171], v43
	v_cvt_pk_f32_fp8_sdwa v[172:173], v43 src0_sel:WORD_1
	v_pk_fma_f32 v[242:243], v[184:185], v[166:167], v[242:243] op_sel_hi:[0,1,1]
	v_pk_fma_f32 v[244:245], v[184:185], v[168:169], v[244:245] op_sel_hi:[0,1,1]
	v_pk_fma_f32 v[246:247], v[184:185], v[170:171], v[246:247] op_sel_hi:[0,1,1]
	v_pk_fma_f32 v[248:249], v[184:185], v[172:173], v[248:249] op_sel_hi:[0,1,1]
	v_cvt_pk_f32_fp8_e32 v[166:167], v44
	v_cvt_pk_f32_fp8_sdwa v[168:169], v44 src0_sel:WORD_1
	v_cvt_pk_f32_fp8_e32 v[170:171], v45
	v_cvt_pk_f32_fp8_sdwa v[172:173], v45 src0_sel:WORD_1
	v_pk_fma_f32 v[242:243], v[184:185], v[166:167], v[242:243] op_sel:[1,0,0]
	v_pk_fma_f32 v[244:245], v[184:185], v[168:169], v[244:245] op_sel:[1,0,0]
	v_pk_fma_f32 v[246:247], v[184:185], v[170:171], v[246:247] op_sel:[1,0,0]
	v_pk_fma_f32 v[248:249], v[184:185], v[172:173], v[248:249] op_sel:[1,0,0]
	v_cvt_pk_f32_fp8_e32 v[166:167], v46
	v_cvt_pk_f32_fp8_sdwa v[168:169], v46 src0_sel:WORD_1
	v_cvt_pk_f32_fp8_e32 v[170:171], v47
	v_cvt_pk_f32_fp8_sdwa v[172:173], v47 src0_sel:WORD_1
	v_pk_fma_f32 v[242:243], v[186:187], v[166:167], v[242:243] op_sel_hi:[0,1,1]
	v_pk_fma_f32 v[244:245], v[186:187], v[168:169], v[244:245] op_sel_hi:[0,1,1]
	v_pk_fma_f32 v[246:247], v[186:187], v[170:171], v[246:247] op_sel_hi:[0,1,1]
	v_pk_fma_f32 v[248:249], v[186:187], v[172:173], v[248:249] op_sel_hi:[0,1,1]
	v_cvt_pk_f32_fp8_e32 v[166:167], v48
	v_cvt_pk_f32_fp8_sdwa v[168:169], v48 src0_sel:WORD_1
	v_cvt_pk_f32_fp8_e32 v[170:171], v49
	v_cvt_pk_f32_fp8_sdwa v[172:173], v49 src0_sel:WORD_1
	v_pk_fma_f32 v[242:243], v[186:187], v[166:167], v[242:243] op_sel:[1,0,0]
	v_pk_fma_f32 v[244:245], v[186:187], v[168:169], v[244:245] op_sel:[1,0,0]
	v_pk_fma_f32 v[246:247], v[186:187], v[170:171], v[246:247] op_sel:[1,0,0]
	v_pk_fma_f32 v[248:249], v[186:187], v[172:173], v[248:249] op_sel:[1,0,0]
	v_cvt_pk_f32_fp8_e32 v[166:167], v50
	v_cvt_pk_f32_fp8_sdwa v[168:169], v50 src0_sel:WORD_1
	v_cvt_pk_f32_fp8_e32 v[170:171], v51
	v_cvt_pk_f32_fp8_sdwa v[172:173], v51 src0_sel:WORD_1
	v_pk_fma_f32 v[242:243], v[188:189], v[166:167], v[242:243] op_sel_hi:[0,1,1]
	v_pk_fma_f32 v[244:245], v[188:189], v[168:169], v[244:245] op_sel_hi:[0,1,1]
	v_pk_fma_f32 v[246:247], v[188:189], v[170:171], v[246:247] op_sel_hi:[0,1,1]
	v_pk_fma_f32 v[248:249], v[188:189], v[172:173], v[248:249] op_sel_hi:[0,1,1]
	v_cvt_pk_f32_fp8_e32 v[166:167], v52
	v_cvt_pk_f32_fp8_sdwa v[168:169], v52 src0_sel:WORD_1
	v_cvt_pk_f32_fp8_e32 v[170:171], v53
	v_cvt_pk_f32_fp8_sdwa v[172:173], v53 src0_sel:WORD_1
	v_pk_fma_f32 v[242:243], v[188:189], v[166:167], v[242:243] op_sel:[1,0,0]
	v_pk_fma_f32 v[244:245], v[188:189], v[168:169], v[244:245] op_sel:[1,0,0]
	v_pk_fma_f32 v[246:247], v[188:189], v[170:171], v[246:247] op_sel:[1,0,0]
	v_pk_fma_f32 v[248:249], v[188:189], v[172:173], v[248:249] op_sel:[1,0,0]
	v_cvt_pk_f32_fp8_e32 v[166:167], v54
	v_cvt_pk_f32_fp8_sdwa v[168:169], v54 src0_sel:WORD_1
	v_cvt_pk_f32_fp8_e32 v[170:171], v55
	v_cvt_pk_f32_fp8_sdwa v[172:173], v55 src0_sel:WORD_1
	v_pk_fma_f32 v[242:243], v[190:191], v[166:167], v[242:243] op_sel_hi:[0,1,1]
	v_pk_fma_f32 v[244:245], v[190:191], v[168:169], v[244:245] op_sel_hi:[0,1,1]
	v_pk_fma_f32 v[246:247], v[190:191], v[170:171], v[246:247] op_sel_hi:[0,1,1]
	v_pk_fma_f32 v[248:249], v[190:191], v[172:173], v[248:249] op_sel_hi:[0,1,1]
	v_cvt_pk_f32_fp8_e32 v[166:167], v56
	v_cvt_pk_f32_fp8_sdwa v[168:169], v56 src0_sel:WORD_1
	v_cvt_pk_f32_fp8_e32 v[170:171], v57
	v_cvt_pk_f32_fp8_sdwa v[172:173], v57 src0_sel:WORD_1
	v_pk_fma_f32 v[242:243], v[190:191], v[166:167], v[242:243] op_sel:[1,0,0]
	v_pk_fma_f32 v[244:245], v[190:191], v[168:169], v[244:245] op_sel:[1,0,0]
	v_pk_fma_f32 v[246:247], v[190:191], v[170:171], v[246:247] op_sel:[1,0,0]
	v_pk_fma_f32 v[248:249], v[190:191], v[172:173], v[248:249] op_sel:[1,0,0]
	v_cvt_pk_f32_fp8_e32 v[166:167], v58
	v_cvt_pk_f32_fp8_sdwa v[168:169], v58 src0_sel:WORD_1
	v_cvt_pk_f32_fp8_e32 v[170:171], v59
	v_cvt_pk_f32_fp8_sdwa v[172:173], v59 src0_sel:WORD_1
	v_pk_fma_f32 v[242:243], v[192:193], v[166:167], v[242:243] op_sel_hi:[0,1,1]
	v_pk_fma_f32 v[244:245], v[192:193], v[168:169], v[244:245] op_sel_hi:[0,1,1]
	v_pk_fma_f32 v[246:247], v[192:193], v[170:171], v[246:247] op_sel_hi:[0,1,1]
	v_pk_fma_f32 v[248:249], v[192:193], v[172:173], v[248:249] op_sel_hi:[0,1,1]
	v_cvt_pk_f32_fp8_e32 v[166:167], v60
	v_cvt_pk_f32_fp8_sdwa v[168:169], v60 src0_sel:WORD_1
	v_cvt_pk_f32_fp8_e32 v[170:171], v61
	v_cvt_pk_f32_fp8_sdwa v[172:173], v61 src0_sel:WORD_1
	v_pk_fma_f32 v[242:243], v[192:193], v[166:167], v[242:243] op_sel:[1,0,0]
	v_pk_fma_f32 v[244:245], v[192:193], v[168:169], v[244:245] op_sel:[1,0,0]
	v_pk_fma_f32 v[246:247], v[192:193], v[170:171], v[246:247] op_sel:[1,0,0]
	v_pk_fma_f32 v[248:249], v[192:193], v[172:173], v[248:249] op_sel:[1,0,0]
	v_cvt_pk_f32_fp8_e32 v[166:167], v62
	v_cvt_pk_f32_fp8_sdwa v[168:169], v62 src0_sel:WORD_1
	v_cvt_pk_f32_fp8_e32 v[170:171], v63
	v_cvt_pk_f32_fp8_sdwa v[172:173], v63 src0_sel:WORD_1
	v_pk_fma_f32 v[242:243], v[194:195], v[166:167], v[242:243] op_sel_hi:[0,1,1]
	v_pk_fma_f32 v[244:245], v[194:195], v[168:169], v[244:245] op_sel_hi:[0,1,1]
	v_pk_fma_f32 v[246:247], v[194:195], v[170:171], v[246:247] op_sel_hi:[0,1,1]
	v_pk_fma_f32 v[248:249], v[194:195], v[172:173], v[248:249] op_sel_hi:[0,1,1]
	v_cvt_pk_f32_fp8_e32 v[166:167], v64
	v_cvt_pk_f32_fp8_sdwa v[168:169], v64 src0_sel:WORD_1
	v_cvt_pk_f32_fp8_e32 v[170:171], v65
	v_cvt_pk_f32_fp8_sdwa v[172:173], v65 src0_sel:WORD_1
	v_pk_fma_f32 v[242:243], v[194:195], v[166:167], v[242:243] op_sel:[1,0,0]
	v_pk_fma_f32 v[244:245], v[194:195], v[168:169], v[244:245] op_sel:[1,0,0]
	v_pk_fma_f32 v[246:247], v[194:195], v[170:171], v[246:247] op_sel:[1,0,0]
	v_pk_fma_f32 v[248:249], v[194:195], v[172:173], v[248:249] op_sel:[1,0,0]
	s_waitcnt lgkmcnt(0)
	v_add_u32_e32 v120, v104, v226
	global_load_dwordx2 v[34:35], v120, s[50:51]
	v_add_u32_e32 v122, v104, v227
	global_load_dwordx2 v[36:37], v122, s[50:51]
	v_add_u32_e32 v124, v104, v228
	global_load_dwordx2 v[38:39], v124, s[50:51]
	v_add_u32_e32 v126, v104, v229
	global_load_dwordx2 v[40:41], v126, s[50:51]
	v_add_u32_e32 v120, v104, v230
	global_load_dwordx2 v[42:43], v120, s[50:51]
	v_add_u32_e32 v122, v104, v231
	global_load_dwordx2 v[44:45], v122, s[50:51]
	v_add_u32_e32 v124, v104, v232
	global_load_dwordx2 v[46:47], v124, s[50:51]
	v_add_u32_e32 v126, v104, v233
	global_load_dwordx2 v[48:49], v126, s[50:51]
	v_add_u32_e32 v120, v104, v234
	global_load_dwordx2 v[50:51], v120, s[50:51]
	v_add_u32_e32 v122, v104, v235
	global_load_dwordx2 v[52:53], v122, s[50:51]
	v_add_u32_e32 v124, v104, v236
	global_load_dwordx2 v[54:55], v124, s[50:51]
	v_add_u32_e32 v126, v104, v237
	global_load_dwordx2 v[56:57], v126, s[50:51]
	v_add_u32_e32 v120, v104, v238
	global_load_dwordx2 v[58:59], v120, s[50:51]
	v_add_u32_e32 v122, v104, v239
	global_load_dwordx2 v[60:61], v122, s[50:51]
	v_add_u32_e32 v124, v104, v240
	global_load_dwordx2 v[62:63], v124, s[50:51]
	v_add_u32_e32 v126, v104, v241
	global_load_dwordx2 v[64:65], v126, s[50:51]
	ds_read_b128 v[226:229], v106 offset:2048
	ds_read_b128 v[230:233], v106 offset:2064
	ds_read_b128 v[234:237], v106 offset:2080
	ds_read_b128 v[238:241], v106 offset:2096
	ds_read_b128 v[180:183], v106 offset:6528
	ds_read_b128 v[184:187], v106 offset:6544
	ds_read_b128 v[188:191], v106 offset:6560
	ds_read_b128 v[192:195], v106 offset:6576
	s_waitcnt vmcnt(32)
	v_cvt_pk_f32_fp8_e32 v[166:167], v134
	v_cvt_pk_f32_fp8_sdwa v[168:169], v134 src0_sel:WORD_1
	v_cvt_pk_f32_fp8_e32 v[170:171], v135
	v_cvt_pk_f32_fp8_sdwa v[172:173], v135 src0_sel:WORD_1
	v_pk_fma_f32 v[242:243], v[196:197], v[166:167], v[242:243] op_sel_hi:[0,1,1]
	v_pk_fma_f32 v[244:245], v[196:197], v[168:169], v[244:245] op_sel_hi:[0,1,1]
	v_pk_fma_f32 v[246:247], v[196:197], v[170:171], v[246:247] op_sel_hi:[0,1,1]
	v_pk_fma_f32 v[248:249], v[196:197], v[172:173], v[248:249] op_sel_hi:[0,1,1]
	v_cvt_pk_f32_fp8_e32 v[166:167], v136
	v_cvt_pk_f32_fp8_sdwa v[168:169], v136 src0_sel:WORD_1
	v_cvt_pk_f32_fp8_e32 v[170:171], v137
	v_cvt_pk_f32_fp8_sdwa v[172:173], v137 src0_sel:WORD_1
	v_pk_fma_f32 v[242:243], v[196:197], v[166:167], v[242:243] op_sel:[1,0,0]
	v_pk_fma_f32 v[244:245], v[196:197], v[168:169], v[244:245] op_sel:[1,0,0]
	v_pk_fma_f32 v[246:247], v[196:197], v[170:171], v[246:247] op_sel:[1,0,0]
	v_pk_fma_f32 v[248:249], v[196:197], v[172:173], v[248:249] op_sel:[1,0,0]
	v_cvt_pk_f32_fp8_e32 v[166:167], v138
	v_cvt_pk_f32_fp8_sdwa v[168:169], v138 src0_sel:WORD_1
	v_cvt_pk_f32_fp8_e32 v[170:171], v139
	v_cvt_pk_f32_fp8_sdwa v[172:173], v139 src0_sel:WORD_1
	v_pk_fma_f32 v[242:243], v[198:199], v[166:167], v[242:243] op_sel_hi:[0,1,1]
	v_pk_fma_f32 v[244:245], v[198:199], v[168:169], v[244:245] op_sel_hi:[0,1,1]
	v_pk_fma_f32 v[246:247], v[198:199], v[170:171], v[246:247] op_sel_hi:[0,1,1]
	v_pk_fma_f32 v[248:249], v[198:199], v[172:173], v[248:249] op_sel_hi:[0,1,1]
	v_cvt_pk_f32_fp8_e32 v[166:167], v140
	v_cvt_pk_f32_fp8_sdwa v[168:169], v140 src0_sel:WORD_1
	v_cvt_pk_f32_fp8_e32 v[170:171], v141
	v_cvt_pk_f32_fp8_sdwa v[172:173], v141 src0_sel:WORD_1
	v_pk_fma_f32 v[242:243], v[198:199], v[166:167], v[242:243] op_sel:[1,0,0]
	v_pk_fma_f32 v[244:245], v[198:199], v[168:169], v[244:245] op_sel:[1,0,0]
	v_pk_fma_f32 v[246:247], v[198:199], v[170:171], v[246:247] op_sel:[1,0,0]
	v_pk_fma_f32 v[248:249], v[198:199], v[172:173], v[248:249] op_sel:[1,0,0]
	v_cvt_pk_f32_fp8_e32 v[166:167], v142
	v_cvt_pk_f32_fp8_sdwa v[168:169], v142 src0_sel:WORD_1
	v_cvt_pk_f32_fp8_e32 v[170:171], v143
	v_cvt_pk_f32_fp8_sdwa v[172:173], v143 src0_sel:WORD_1
	v_pk_fma_f32 v[242:243], v[200:201], v[166:167], v[242:243] op_sel_hi:[0,1,1]
	v_pk_fma_f32 v[244:245], v[200:201], v[168:169], v[244:245] op_sel_hi:[0,1,1]
	v_pk_fma_f32 v[246:247], v[200:201], v[170:171], v[246:247] op_sel_hi:[0,1,1]
	v_pk_fma_f32 v[248:249], v[200:201], v[172:173], v[248:249] op_sel_hi:[0,1,1]
	v_cvt_pk_f32_fp8_e32 v[166:167], v144
	v_cvt_pk_f32_fp8_sdwa v[168:169], v144 src0_sel:WORD_1
	v_cvt_pk_f32_fp8_e32 v[170:171], v145
	v_cvt_pk_f32_fp8_sdwa v[172:173], v145 src0_sel:WORD_1
	v_pk_fma_f32 v[242:243], v[200:201], v[166:167], v[242:243] op_sel:[1,0,0]
	v_pk_fma_f32 v[244:245], v[200:201], v[168:169], v[244:245] op_sel:[1,0,0]
	v_pk_fma_f32 v[246:247], v[200:201], v[170:171], v[246:247] op_sel:[1,0,0]
	v_pk_fma_f32 v[248:249], v[200:201], v[172:173], v[248:249] op_sel:[1,0,0]
	v_cvt_pk_f32_fp8_e32 v[166:167], v146
	v_cvt_pk_f32_fp8_sdwa v[168:169], v146 src0_sel:WORD_1
	v_cvt_pk_f32_fp8_e32 v[170:171], v147
	v_cvt_pk_f32_fp8_sdwa v[172:173], v147 src0_sel:WORD_1
	v_pk_fma_f32 v[242:243], v[202:203], v[166:167], v[242:243] op_sel_hi:[0,1,1]
	v_pk_fma_f32 v[244:245], v[202:203], v[168:169], v[244:245] op_sel_hi:[0,1,1]
	v_pk_fma_f32 v[246:247], v[202:203], v[170:171], v[246:247] op_sel_hi:[0,1,1]
	v_pk_fma_f32 v[248:249], v[202:203], v[172:173], v[248:249] op_sel_hi:[0,1,1]
	v_cvt_pk_f32_fp8_e32 v[166:167], v148
	v_cvt_pk_f32_fp8_sdwa v[168:169], v148 src0_sel:WORD_1
	v_cvt_pk_f32_fp8_e32 v[170:171], v149
	v_cvt_pk_f32_fp8_sdwa v[172:173], v149 src0_sel:WORD_1
	v_pk_fma_f32 v[242:243], v[202:203], v[166:167], v[242:243] op_sel:[1,0,0]
	v_pk_fma_f32 v[244:245], v[202:203], v[168:169], v[244:245] op_sel:[1,0,0]
	v_pk_fma_f32 v[246:247], v[202:203], v[170:171], v[246:247] op_sel:[1,0,0]
	v_pk_fma_f32 v[248:249], v[202:203], v[172:173], v[248:249] op_sel:[1,0,0]
	v_cvt_pk_f32_fp8_e32 v[166:167], v150
	v_cvt_pk_f32_fp8_sdwa v[168:169], v150 src0_sel:WORD_1
	v_cvt_pk_f32_fp8_e32 v[170:171], v151
	v_cvt_pk_f32_fp8_sdwa v[172:173], v151 src0_sel:WORD_1
	v_pk_fma_f32 v[242:243], v[204:205], v[166:167], v[242:243] op_sel_hi:[0,1,1]
	v_pk_fma_f32 v[244:245], v[204:205], v[168:169], v[244:245] op_sel_hi:[0,1,1]
	v_pk_fma_f32 v[246:247], v[204:205], v[170:171], v[246:247] op_sel_hi:[0,1,1]
	v_pk_fma_f32 v[248:249], v[204:205], v[172:173], v[248:249] op_sel_hi:[0,1,1]
	v_cvt_pk_f32_fp8_e32 v[166:167], v152
	v_cvt_pk_f32_fp8_sdwa v[168:169], v152 src0_sel:WORD_1
	v_cvt_pk_f32_fp8_e32 v[170:171], v153
	v_cvt_pk_f32_fp8_sdwa v[172:173], v153 src0_sel:WORD_1
	v_pk_fma_f32 v[242:243], v[204:205], v[166:167], v[242:243] op_sel:[1,0,0]
	v_pk_fma_f32 v[244:245], v[204:205], v[168:169], v[244:245] op_sel:[1,0,0]
	v_pk_fma_f32 v[246:247], v[204:205], v[170:171], v[246:247] op_sel:[1,0,0]
	v_pk_fma_f32 v[248:249], v[204:205], v[172:173], v[248:249] op_sel:[1,0,0]
	v_cvt_pk_f32_fp8_e32 v[166:167], v154
	v_cvt_pk_f32_fp8_sdwa v[168:169], v154 src0_sel:WORD_1
	v_cvt_pk_f32_fp8_e32 v[170:171], v155
	v_cvt_pk_f32_fp8_sdwa v[172:173], v155 src0_sel:WORD_1
	v_pk_fma_f32 v[242:243], v[206:207], v[166:167], v[242:243] op_sel_hi:[0,1,1]
	v_pk_fma_f32 v[244:245], v[206:207], v[168:169], v[244:245] op_sel_hi:[0,1,1]
	v_pk_fma_f32 v[246:247], v[206:207], v[170:171], v[246:247] op_sel_hi:[0,1,1]
	v_pk_fma_f32 v[248:249], v[206:207], v[172:173], v[248:249] op_sel_hi:[0,1,1]
	v_cvt_pk_f32_fp8_e32 v[166:167], v156
	v_cvt_pk_f32_fp8_sdwa v[168:169], v156 src0_sel:WORD_1
	v_cvt_pk_f32_fp8_e32 v[170:171], v157
	v_cvt_pk_f32_fp8_sdwa v[172:173], v157 src0_sel:WORD_1
	v_pk_fma_f32 v[242:243], v[206:207], v[166:167], v[242:243] op_sel:[1,0,0]
	v_pk_fma_f32 v[244:245], v[206:207], v[168:169], v[244:245] op_sel:[1,0,0]
	v_pk_fma_f32 v[246:247], v[206:207], v[170:171], v[246:247] op_sel:[1,0,0]
	v_pk_fma_f32 v[248:249], v[206:207], v[172:173], v[248:249] op_sel:[1,0,0]
	v_cvt_pk_f32_fp8_e32 v[166:167], v158
	v_cvt_pk_f32_fp8_sdwa v[168:169], v158 src0_sel:WORD_1
	v_cvt_pk_f32_fp8_e32 v[170:171], v159
	v_cvt_pk_f32_fp8_sdwa v[172:173], v159 src0_sel:WORD_1
	v_pk_fma_f32 v[242:243], v[216:217], v[166:167], v[242:243] op_sel_hi:[0,1,1]
	v_pk_fma_f32 v[244:245], v[216:217], v[168:169], v[244:245] op_sel_hi:[0,1,1]
	v_pk_fma_f32 v[246:247], v[216:217], v[170:171], v[246:247] op_sel_hi:[0,1,1]
	v_pk_fma_f32 v[248:249], v[216:217], v[172:173], v[248:249] op_sel_hi:[0,1,1]
	v_cvt_pk_f32_fp8_e32 v[166:167], v160
	v_cvt_pk_f32_fp8_sdwa v[168:169], v160 src0_sel:WORD_1
	v_cvt_pk_f32_fp8_e32 v[170:171], v161
	v_cvt_pk_f32_fp8_sdwa v[172:173], v161 src0_sel:WORD_1
	v_pk_fma_f32 v[242:243], v[216:217], v[166:167], v[242:243] op_sel:[1,0,0]
	v_pk_fma_f32 v[244:245], v[216:217], v[168:169], v[244:245] op_sel:[1,0,0]
	v_pk_fma_f32 v[246:247], v[216:217], v[170:171], v[246:247] op_sel:[1,0,0]
	v_pk_fma_f32 v[248:249], v[216:217], v[172:173], v[248:249] op_sel:[1,0,0]
	v_cvt_pk_f32_fp8_e32 v[166:167], v162
	v_cvt_pk_f32_fp8_sdwa v[168:169], v162 src0_sel:WORD_1
	v_cvt_pk_f32_fp8_e32 v[170:171], v163
	v_cvt_pk_f32_fp8_sdwa v[172:173], v163 src0_sel:WORD_1
	v_pk_fma_f32 v[242:243], v[218:219], v[166:167], v[242:243] op_sel_hi:[0,1,1]
	v_pk_fma_f32 v[244:245], v[218:219], v[168:169], v[244:245] op_sel_hi:[0,1,1]
	v_pk_fma_f32 v[246:247], v[218:219], v[170:171], v[246:247] op_sel_hi:[0,1,1]
	v_pk_fma_f32 v[248:249], v[218:219], v[172:173], v[248:249] op_sel_hi:[0,1,1]
	v_cvt_pk_f32_fp8_e32 v[166:167], v164
	v_cvt_pk_f32_fp8_sdwa v[168:169], v164 src0_sel:WORD_1
	v_cvt_pk_f32_fp8_e32 v[170:171], v165
	v_cvt_pk_f32_fp8_sdwa v[172:173], v165 src0_sel:WORD_1
	v_pk_fma_f32 v[242:243], v[218:219], v[166:167], v[242:243] op_sel:[1,0,0]
	v_pk_fma_f32 v[244:245], v[218:219], v[168:169], v[244:245] op_sel:[1,0,0]
	v_pk_fma_f32 v[246:247], v[218:219], v[170:171], v[246:247] op_sel:[1,0,0]
	v_pk_fma_f32 v[248:249], v[218:219], v[172:173], v[248:249] op_sel:[1,0,0]
	s_waitcnt lgkmcnt(0)
	v_add_u32_e32 v120, v104, v226
	global_load_dwordx2 v[134:135], v120, s[50:51]
	v_add_u32_e32 v122, v104, v227
	global_load_dwordx2 v[136:137], v122, s[50:51]
	v_add_u32_e32 v124, v104, v228
	global_load_dwordx2 v[138:139], v124, s[50:51]
	v_add_u32_e32 v126, v104, v229
	global_load_dwordx2 v[140:141], v126, s[50:51]
	v_add_u32_e32 v120, v104, v230
	global_load_dwordx2 v[142:143], v120, s[50:51]
	v_add_u32_e32 v122, v104, v231
	global_load_dwordx2 v[144:145], v122, s[50:51]
	v_add_u32_e32 v124, v104, v232
	global_load_dwordx2 v[146:147], v124, s[50:51]
	v_add_u32_e32 v126, v104, v233
	global_load_dwordx2 v[148:149], v126, s[50:51]
	v_add_u32_e32 v120, v104, v234
	global_load_dwordx2 v[150:151], v120, s[50:51]
	v_add_u32_e32 v122, v104, v235
	global_load_dwordx2 v[152:153], v122, s[50:51]
	v_add_u32_e32 v124, v104, v236
	global_load_dwordx2 v[154:155], v124, s[50:51]
	v_add_u32_e32 v126, v104, v237
	global_load_dwordx2 v[156:157], v126, s[50:51]
	v_add_u32_e32 v120, v104, v238
	global_load_dwordx2 v[158:159], v120, s[50:51]
	v_add_u32_e32 v122, v104, v239
	global_load_dwordx2 v[160:161], v122, s[50:51]
	v_add_u32_e32 v124, v104, v240
	global_load_dwordx2 v[162:163], v124, s[50:51]
	v_add_u32_e32 v126, v104, v241
	global_load_dwordx2 v[164:165], v126, s[50:51]
	ds_read_b128 v[226:229], v106 offset:2112
	ds_read_b128 v[230:233], v106 offset:2128
	ds_read_b128 v[234:237], v106 offset:2144
	ds_read_b128 v[238:241], v106 offset:2160
	ds_read_b128 v[196:199], v106 offset:6592
	ds_read_b128 v[200:203], v106 offset:6608
	ds_read_b128 v[204:207], v106 offset:6624
	ds_read_b128 v[216:219], v106 offset:6640
	s_waitcnt vmcnt(32)
	v_cvt_pk_f32_fp8_e32 v[166:167], v2
	v_cvt_pk_f32_fp8_sdwa v[168:169], v2 src0_sel:WORD_1
	v_cvt_pk_f32_fp8_e32 v[170:171], v3
	v_cvt_pk_f32_fp8_sdwa v[172:173], v3 src0_sel:WORD_1
	v_pk_fma_f32 v[242:243], v[180:181], v[166:167], v[242:243] op_sel_hi:[0,1,1]
	v_pk_fma_f32 v[244:245], v[180:181], v[168:169], v[244:245] op_sel_hi:[0,1,1]
	v_pk_fma_f32 v[246:247], v[180:181], v[170:171], v[246:247] op_sel_hi:[0,1,1]
	v_pk_fma_f32 v[248:249], v[180:181], v[172:173], v[248:249] op_sel_hi:[0,1,1]
	v_cvt_pk_f32_fp8_e32 v[166:167], v4
	v_cvt_pk_f32_fp8_sdwa v[168:169], v4 src0_sel:WORD_1
	v_cvt_pk_f32_fp8_e32 v[170:171], v5
	v_cvt_pk_f32_fp8_sdwa v[172:173], v5 src0_sel:WORD_1
	v_pk_fma_f32 v[242:243], v[180:181], v[166:167], v[242:243] op_sel:[1,0,0]
	v_pk_fma_f32 v[244:245], v[180:181], v[168:169], v[244:245] op_sel:[1,0,0]
	v_pk_fma_f32 v[246:247], v[180:181], v[170:171], v[246:247] op_sel:[1,0,0]
	v_pk_fma_f32 v[248:249], v[180:181], v[172:173], v[248:249] op_sel:[1,0,0]
	v_cvt_pk_f32_fp8_e32 v[166:167], v6
	v_cvt_pk_f32_fp8_sdwa v[168:169], v6 src0_sel:WORD_1
	v_cvt_pk_f32_fp8_e32 v[170:171], v7
	v_cvt_pk_f32_fp8_sdwa v[172:173], v7 src0_sel:WORD_1
	v_pk_fma_f32 v[242:243], v[182:183], v[166:167], v[242:243] op_sel_hi:[0,1,1]
	v_pk_fma_f32 v[244:245], v[182:183], v[168:169], v[244:245] op_sel_hi:[0,1,1]
	v_pk_fma_f32 v[246:247], v[182:183], v[170:171], v[246:247] op_sel_hi:[0,1,1]
	v_pk_fma_f32 v[248:249], v[182:183], v[172:173], v[248:249] op_sel_hi:[0,1,1]
	v_cvt_pk_f32_fp8_e32 v[166:167], v8
	v_cvt_pk_f32_fp8_sdwa v[168:169], v8 src0_sel:WORD_1
	v_cvt_pk_f32_fp8_e32 v[170:171], v9
	v_cvt_pk_f32_fp8_sdwa v[172:173], v9 src0_sel:WORD_1
	v_pk_fma_f32 v[242:243], v[182:183], v[166:167], v[242:243] op_sel:[1,0,0]
	v_pk_fma_f32 v[244:245], v[182:183], v[168:169], v[244:245] op_sel:[1,0,0]
	v_pk_fma_f32 v[246:247], v[182:183], v[170:171], v[246:247] op_sel:[1,0,0]
	v_pk_fma_f32 v[248:249], v[182:183], v[172:173], v[248:249] op_sel:[1,0,0]
	v_cvt_pk_f32_fp8_e32 v[166:167], v10
	v_cvt_pk_f32_fp8_sdwa v[168:169], v10 src0_sel:WORD_1
	v_cvt_pk_f32_fp8_e32 v[170:171], v11
	v_cvt_pk_f32_fp8_sdwa v[172:173], v11 src0_sel:WORD_1
	v_pk_fma_f32 v[242:243], v[184:185], v[166:167], v[242:243] op_sel_hi:[0,1,1]
	v_pk_fma_f32 v[244:245], v[184:185], v[168:169], v[244:245] op_sel_hi:[0,1,1]
	v_pk_fma_f32 v[246:247], v[184:185], v[170:171], v[246:247] op_sel_hi:[0,1,1]
	v_pk_fma_f32 v[248:249], v[184:185], v[172:173], v[248:249] op_sel_hi:[0,1,1]
	v_cvt_pk_f32_fp8_e32 v[166:167], v12
	v_cvt_pk_f32_fp8_sdwa v[168:169], v12 src0_sel:WORD_1
	v_cvt_pk_f32_fp8_e32 v[170:171], v13
	v_cvt_pk_f32_fp8_sdwa v[172:173], v13 src0_sel:WORD_1
	v_pk_fma_f32 v[242:243], v[184:185], v[166:167], v[242:243] op_sel:[1,0,0]
	v_pk_fma_f32 v[244:245], v[184:185], v[168:169], v[244:245] op_sel:[1,0,0]
	v_pk_fma_f32 v[246:247], v[184:185], v[170:171], v[246:247] op_sel:[1,0,0]
	v_pk_fma_f32 v[248:249], v[184:185], v[172:173], v[248:249] op_sel:[1,0,0]
	v_cvt_pk_f32_fp8_e32 v[166:167], v14
	v_cvt_pk_f32_fp8_sdwa v[168:169], v14 src0_sel:WORD_1
	v_cvt_pk_f32_fp8_e32 v[170:171], v15
	v_cvt_pk_f32_fp8_sdwa v[172:173], v15 src0_sel:WORD_1
	v_pk_fma_f32 v[242:243], v[186:187], v[166:167], v[242:243] op_sel_hi:[0,1,1]
	v_pk_fma_f32 v[244:245], v[186:187], v[168:169], v[244:245] op_sel_hi:[0,1,1]
	v_pk_fma_f32 v[246:247], v[186:187], v[170:171], v[246:247] op_sel_hi:[0,1,1]
	v_pk_fma_f32 v[248:249], v[186:187], v[172:173], v[248:249] op_sel_hi:[0,1,1]
	v_cvt_pk_f32_fp8_e32 v[166:167], v16
	v_cvt_pk_f32_fp8_sdwa v[168:169], v16 src0_sel:WORD_1
	v_cvt_pk_f32_fp8_e32 v[170:171], v17
	v_cvt_pk_f32_fp8_sdwa v[172:173], v17 src0_sel:WORD_1
	v_pk_fma_f32 v[242:243], v[186:187], v[166:167], v[242:243] op_sel:[1,0,0]
	v_pk_fma_f32 v[244:245], v[186:187], v[168:169], v[244:245] op_sel:[1,0,0]
	v_pk_fma_f32 v[246:247], v[186:187], v[170:171], v[246:247] op_sel:[1,0,0]
	v_pk_fma_f32 v[248:249], v[186:187], v[172:173], v[248:249] op_sel:[1,0,0]
	v_cvt_pk_f32_fp8_e32 v[166:167], v18
	v_cvt_pk_f32_fp8_sdwa v[168:169], v18 src0_sel:WORD_1
	v_cvt_pk_f32_fp8_e32 v[170:171], v19
	v_cvt_pk_f32_fp8_sdwa v[172:173], v19 src0_sel:WORD_1
	v_pk_fma_f32 v[242:243], v[188:189], v[166:167], v[242:243] op_sel_hi:[0,1,1]
	v_pk_fma_f32 v[244:245], v[188:189], v[168:169], v[244:245] op_sel_hi:[0,1,1]
	v_pk_fma_f32 v[246:247], v[188:189], v[170:171], v[246:247] op_sel_hi:[0,1,1]
	v_pk_fma_f32 v[248:249], v[188:189], v[172:173], v[248:249] op_sel_hi:[0,1,1]
	v_cvt_pk_f32_fp8_e32 v[166:167], v20
	v_cvt_pk_f32_fp8_sdwa v[168:169], v20 src0_sel:WORD_1
	v_cvt_pk_f32_fp8_e32 v[170:171], v21
	v_cvt_pk_f32_fp8_sdwa v[172:173], v21 src0_sel:WORD_1
	v_pk_fma_f32 v[242:243], v[188:189], v[166:167], v[242:243] op_sel:[1,0,0]
	v_pk_fma_f32 v[244:245], v[188:189], v[168:169], v[244:245] op_sel:[1,0,0]
	v_pk_fma_f32 v[246:247], v[188:189], v[170:171], v[246:247] op_sel:[1,0,0]
	v_pk_fma_f32 v[248:249], v[188:189], v[172:173], v[248:249] op_sel:[1,0,0]
	v_cvt_pk_f32_fp8_e32 v[166:167], v22
	v_cvt_pk_f32_fp8_sdwa v[168:169], v22 src0_sel:WORD_1
	v_cvt_pk_f32_fp8_e32 v[170:171], v23
	v_cvt_pk_f32_fp8_sdwa v[172:173], v23 src0_sel:WORD_1
	v_pk_fma_f32 v[242:243], v[190:191], v[166:167], v[242:243] op_sel_hi:[0,1,1]
	v_pk_fma_f32 v[244:245], v[190:191], v[168:169], v[244:245] op_sel_hi:[0,1,1]
	v_pk_fma_f32 v[246:247], v[190:191], v[170:171], v[246:247] op_sel_hi:[0,1,1]
	v_pk_fma_f32 v[248:249], v[190:191], v[172:173], v[248:249] op_sel_hi:[0,1,1]
	v_cvt_pk_f32_fp8_e32 v[166:167], v24
	v_cvt_pk_f32_fp8_sdwa v[168:169], v24 src0_sel:WORD_1
	v_cvt_pk_f32_fp8_e32 v[170:171], v25
	v_cvt_pk_f32_fp8_sdwa v[172:173], v25 src0_sel:WORD_1
	v_pk_fma_f32 v[242:243], v[190:191], v[166:167], v[242:243] op_sel:[1,0,0]
	v_pk_fma_f32 v[244:245], v[190:191], v[168:169], v[244:245] op_sel:[1,0,0]
	v_pk_fma_f32 v[246:247], v[190:191], v[170:171], v[246:247] op_sel:[1,0,0]
	v_pk_fma_f32 v[248:249], v[190:191], v[172:173], v[248:249] op_sel:[1,0,0]
	v_cvt_pk_f32_fp8_e32 v[166:167], v26
	v_cvt_pk_f32_fp8_sdwa v[168:169], v26 src0_sel:WORD_1
	v_cvt_pk_f32_fp8_e32 v[170:171], v27
	v_cvt_pk_f32_fp8_sdwa v[172:173], v27 src0_sel:WORD_1
	v_pk_fma_f32 v[242:243], v[192:193], v[166:167], v[242:243] op_sel_hi:[0,1,1]
	v_pk_fma_f32 v[244:245], v[192:193], v[168:169], v[244:245] op_sel_hi:[0,1,1]
	v_pk_fma_f32 v[246:247], v[192:193], v[170:171], v[246:247] op_sel_hi:[0,1,1]
	v_pk_fma_f32 v[248:249], v[192:193], v[172:173], v[248:249] op_sel_hi:[0,1,1]
	v_cvt_pk_f32_fp8_e32 v[166:167], v28
	v_cvt_pk_f32_fp8_sdwa v[168:169], v28 src0_sel:WORD_1
	v_cvt_pk_f32_fp8_e32 v[170:171], v29
	v_cvt_pk_f32_fp8_sdwa v[172:173], v29 src0_sel:WORD_1
	v_pk_fma_f32 v[242:243], v[192:193], v[166:167], v[242:243] op_sel:[1,0,0]
	v_pk_fma_f32 v[244:245], v[192:193], v[168:169], v[244:245] op_sel:[1,0,0]
	v_pk_fma_f32 v[246:247], v[192:193], v[170:171], v[246:247] op_sel:[1,0,0]
	v_pk_fma_f32 v[248:249], v[192:193], v[172:173], v[248:249] op_sel:[1,0,0]
	v_cvt_pk_f32_fp8_e32 v[166:167], v30
	v_cvt_pk_f32_fp8_sdwa v[168:169], v30 src0_sel:WORD_1
	v_cvt_pk_f32_fp8_e32 v[170:171], v31
	v_cvt_pk_f32_fp8_sdwa v[172:173], v31 src0_sel:WORD_1
	v_pk_fma_f32 v[242:243], v[194:195], v[166:167], v[242:243] op_sel_hi:[0,1,1]
	v_pk_fma_f32 v[244:245], v[194:195], v[168:169], v[244:245] op_sel_hi:[0,1,1]
	v_pk_fma_f32 v[246:247], v[194:195], v[170:171], v[246:247] op_sel_hi:[0,1,1]
	v_pk_fma_f32 v[248:249], v[194:195], v[172:173], v[248:249] op_sel_hi:[0,1,1]
	v_cvt_pk_f32_fp8_e32 v[166:167], v32
	v_cvt_pk_f32_fp8_sdwa v[168:169], v32 src0_sel:WORD_1
	v_cvt_pk_f32_fp8_e32 v[170:171], v33
	v_cvt_pk_f32_fp8_sdwa v[172:173], v33 src0_sel:WORD_1
	v_pk_fma_f32 v[242:243], v[194:195], v[166:167], v[242:243] op_sel:[1,0,0]
	v_pk_fma_f32 v[244:245], v[194:195], v[168:169], v[244:245] op_sel:[1,0,0]
	v_pk_fma_f32 v[246:247], v[194:195], v[170:171], v[246:247] op_sel:[1,0,0]
	v_pk_fma_f32 v[248:249], v[194:195], v[172:173], v[248:249] op_sel:[1,0,0]
	s_waitcnt lgkmcnt(0)
	v_add_u32_e32 v120, v104, v226
	global_load_dwordx2 v[2:3], v120, s[50:51]
	v_add_u32_e32 v122, v104, v227
	global_load_dwordx2 v[4:5], v122, s[50:51]
	v_add_u32_e32 v124, v104, v228
	global_load_dwordx2 v[6:7], v124, s[50:51]
	v_add_u32_e32 v126, v104, v229
	global_load_dwordx2 v[8:9], v126, s[50:51]
	v_add_u32_e32 v120, v104, v230
	global_load_dwordx2 v[10:11], v120, s[50:51]
	v_add_u32_e32 v122, v104, v231
	global_load_dwordx2 v[12:13], v122, s[50:51]
	v_add_u32_e32 v124, v104, v232
	global_load_dwordx2 v[14:15], v124, s[50:51]
	v_add_u32_e32 v126, v104, v233
	global_load_dwordx2 v[16:17], v126, s[50:51]
	v_add_u32_e32 v120, v104, v234
	global_load_dwordx2 v[18:19], v120, s[50:51]
	v_add_u32_e32 v122, v104, v235
	global_load_dwordx2 v[20:21], v122, s[50:51]
	v_add_u32_e32 v124, v104, v236
	global_load_dwordx2 v[22:23], v124, s[50:51]
	v_add_u32_e32 v126, v104, v237
	global_load_dwordx2 v[24:25], v126, s[50:51]
	v_add_u32_e32 v120, v104, v238
	global_load_dwordx2 v[26:27], v120, s[50:51]
	v_add_u32_e32 v122, v104, v239
	global_load_dwordx2 v[28:29], v122, s[50:51]
	v_add_u32_e32 v124, v104, v240
	global_load_dwordx2 v[30:31], v124, s[50:51]
	v_add_u32_e32 v126, v104, v241
	global_load_dwordx2 v[32:33], v126, s[50:51]
	ds_read_b128 v[226:229], v106 offset:2176
	ds_read_b128 v[230:233], v106 offset:2192
	ds_read_b128 v[234:237], v106 offset:2208
	ds_read_b128 v[238:241], v106 offset:2224
	ds_read_b128 v[180:183], v106 offset:8192
	ds_read_b128 v[184:187], v106 offset:8208
	ds_read_b128 v[188:191], v106 offset:8224
	ds_read_b128 v[192:195], v106 offset:8240
	s_waitcnt vmcnt(32)
	v_cvt_pk_f32_fp8_e32 v[166:167], v34
	v_cvt_pk_f32_fp8_sdwa v[168:169], v34 src0_sel:WORD_1
	v_cvt_pk_f32_fp8_e32 v[170:171], v35
	v_cvt_pk_f32_fp8_sdwa v[172:173], v35 src0_sel:WORD_1
	v_pk_fma_f32 v[242:243], v[196:197], v[166:167], v[242:243] op_sel_hi:[0,1,1]
	v_pk_fma_f32 v[244:245], v[196:197], v[168:169], v[244:245] op_sel_hi:[0,1,1]
	v_pk_fma_f32 v[246:247], v[196:197], v[170:171], v[246:247] op_sel_hi:[0,1,1]
	v_pk_fma_f32 v[248:249], v[196:197], v[172:173], v[248:249] op_sel_hi:[0,1,1]
	v_cvt_pk_f32_fp8_e32 v[166:167], v36
	v_cvt_pk_f32_fp8_sdwa v[168:169], v36 src0_sel:WORD_1
	v_cvt_pk_f32_fp8_e32 v[170:171], v37
	v_cvt_pk_f32_fp8_sdwa v[172:173], v37 src0_sel:WORD_1
	v_pk_fma_f32 v[242:243], v[196:197], v[166:167], v[242:243] op_sel:[1,0,0]
	v_pk_fma_f32 v[244:245], v[196:197], v[168:169], v[244:245] op_sel:[1,0,0]
	v_pk_fma_f32 v[246:247], v[196:197], v[170:171], v[246:247] op_sel:[1,0,0]
	v_pk_fma_f32 v[248:249], v[196:197], v[172:173], v[248:249] op_sel:[1,0,0]
	v_cvt_pk_f32_fp8_e32 v[166:167], v38
	v_cvt_pk_f32_fp8_sdwa v[168:169], v38 src0_sel:WORD_1
	v_cvt_pk_f32_fp8_e32 v[170:171], v39
	v_cvt_pk_f32_fp8_sdwa v[172:173], v39 src0_sel:WORD_1
	v_pk_fma_f32 v[242:243], v[198:199], v[166:167], v[242:243] op_sel_hi:[0,1,1]
	v_pk_fma_f32 v[244:245], v[198:199], v[168:169], v[244:245] op_sel_hi:[0,1,1]
	v_pk_fma_f32 v[246:247], v[198:199], v[170:171], v[246:247] op_sel_hi:[0,1,1]
	v_pk_fma_f32 v[248:249], v[198:199], v[172:173], v[248:249] op_sel_hi:[0,1,1]
	v_cvt_pk_f32_fp8_e32 v[166:167], v40
	v_cvt_pk_f32_fp8_sdwa v[168:169], v40 src0_sel:WORD_1
	v_cvt_pk_f32_fp8_e32 v[170:171], v41
	v_cvt_pk_f32_fp8_sdwa v[172:173], v41 src0_sel:WORD_1
	v_pk_fma_f32 v[242:243], v[198:199], v[166:167], v[242:243] op_sel:[1,0,0]
	v_pk_fma_f32 v[244:245], v[198:199], v[168:169], v[244:245] op_sel:[1,0,0]
	v_pk_fma_f32 v[246:247], v[198:199], v[170:171], v[246:247] op_sel:[1,0,0]
	v_pk_fma_f32 v[248:249], v[198:199], v[172:173], v[248:249] op_sel:[1,0,0]
	v_cvt_pk_f32_fp8_e32 v[166:167], v42
	v_cvt_pk_f32_fp8_sdwa v[168:169], v42 src0_sel:WORD_1
	v_cvt_pk_f32_fp8_e32 v[170:171], v43
	v_cvt_pk_f32_fp8_sdwa v[172:173], v43 src0_sel:WORD_1
	v_pk_fma_f32 v[242:243], v[200:201], v[166:167], v[242:243] op_sel_hi:[0,1,1]
	v_pk_fma_f32 v[244:245], v[200:201], v[168:169], v[244:245] op_sel_hi:[0,1,1]
	v_pk_fma_f32 v[246:247], v[200:201], v[170:171], v[246:247] op_sel_hi:[0,1,1]
	v_pk_fma_f32 v[248:249], v[200:201], v[172:173], v[248:249] op_sel_hi:[0,1,1]
	v_cvt_pk_f32_fp8_e32 v[166:167], v44
	v_cvt_pk_f32_fp8_sdwa v[168:169], v44 src0_sel:WORD_1
	v_cvt_pk_f32_fp8_e32 v[170:171], v45
	v_cvt_pk_f32_fp8_sdwa v[172:173], v45 src0_sel:WORD_1
	v_pk_fma_f32 v[242:243], v[200:201], v[166:167], v[242:243] op_sel:[1,0,0]
	v_pk_fma_f32 v[244:245], v[200:201], v[168:169], v[244:245] op_sel:[1,0,0]
	v_pk_fma_f32 v[246:247], v[200:201], v[170:171], v[246:247] op_sel:[1,0,0]
	v_pk_fma_f32 v[248:249], v[200:201], v[172:173], v[248:249] op_sel:[1,0,0]
	v_cvt_pk_f32_fp8_e32 v[166:167], v46
	v_cvt_pk_f32_fp8_sdwa v[168:169], v46 src0_sel:WORD_1
	v_cvt_pk_f32_fp8_e32 v[170:171], v47
	v_cvt_pk_f32_fp8_sdwa v[172:173], v47 src0_sel:WORD_1
	v_pk_fma_f32 v[242:243], v[202:203], v[166:167], v[242:243] op_sel_hi:[0,1,1]
	v_pk_fma_f32 v[244:245], v[202:203], v[168:169], v[244:245] op_sel_hi:[0,1,1]
	v_pk_fma_f32 v[246:247], v[202:203], v[170:171], v[246:247] op_sel_hi:[0,1,1]
	v_pk_fma_f32 v[248:249], v[202:203], v[172:173], v[248:249] op_sel_hi:[0,1,1]
	v_cvt_pk_f32_fp8_e32 v[166:167], v48
	v_cvt_pk_f32_fp8_sdwa v[168:169], v48 src0_sel:WORD_1
	v_cvt_pk_f32_fp8_e32 v[170:171], v49
	v_cvt_pk_f32_fp8_sdwa v[172:173], v49 src0_sel:WORD_1
	v_pk_fma_f32 v[242:243], v[202:203], v[166:167], v[242:243] op_sel:[1,0,0]
	v_pk_fma_f32 v[244:245], v[202:203], v[168:169], v[244:245] op_sel:[1,0,0]
	v_pk_fma_f32 v[246:247], v[202:203], v[170:171], v[246:247] op_sel:[1,0,0]
	v_pk_fma_f32 v[248:249], v[202:203], v[172:173], v[248:249] op_sel:[1,0,0]
	v_cvt_pk_f32_fp8_e32 v[166:167], v50
	v_cvt_pk_f32_fp8_sdwa v[168:169], v50 src0_sel:WORD_1
	v_cvt_pk_f32_fp8_e32 v[170:171], v51
	v_cvt_pk_f32_fp8_sdwa v[172:173], v51 src0_sel:WORD_1
	v_pk_fma_f32 v[242:243], v[204:205], v[166:167], v[242:243] op_sel_hi:[0,1,1]
	v_pk_fma_f32 v[244:245], v[204:205], v[168:169], v[244:245] op_sel_hi:[0,1,1]
	v_pk_fma_f32 v[246:247], v[204:205], v[170:171], v[246:247] op_sel_hi:[0,1,1]
	v_pk_fma_f32 v[248:249], v[204:205], v[172:173], v[248:249] op_sel_hi:[0,1,1]
	v_cvt_pk_f32_fp8_e32 v[166:167], v52
	v_cvt_pk_f32_fp8_sdwa v[168:169], v52 src0_sel:WORD_1
	v_cvt_pk_f32_fp8_e32 v[170:171], v53
	v_cvt_pk_f32_fp8_sdwa v[172:173], v53 src0_sel:WORD_1
	v_pk_fma_f32 v[242:243], v[204:205], v[166:167], v[242:243] op_sel:[1,0,0]
	v_pk_fma_f32 v[244:245], v[204:205], v[168:169], v[244:245] op_sel:[1,0,0]
	v_pk_fma_f32 v[246:247], v[204:205], v[170:171], v[246:247] op_sel:[1,0,0]
	v_pk_fma_f32 v[248:249], v[204:205], v[172:173], v[248:249] op_sel:[1,0,0]
	v_cvt_pk_f32_fp8_e32 v[166:167], v54
	v_cvt_pk_f32_fp8_sdwa v[168:169], v54 src0_sel:WORD_1
	v_cvt_pk_f32_fp8_e32 v[170:171], v55
	v_cvt_pk_f32_fp8_sdwa v[172:173], v55 src0_sel:WORD_1
	v_pk_fma_f32 v[242:243], v[206:207], v[166:167], v[242:243] op_sel_hi:[0,1,1]
	v_pk_fma_f32 v[244:245], v[206:207], v[168:169], v[244:245] op_sel_hi:[0,1,1]
	v_pk_fma_f32 v[246:247], v[206:207], v[170:171], v[246:247] op_sel_hi:[0,1,1]
	v_pk_fma_f32 v[248:249], v[206:207], v[172:173], v[248:249] op_sel_hi:[0,1,1]
	v_cvt_pk_f32_fp8_e32 v[166:167], v56
	v_cvt_pk_f32_fp8_sdwa v[168:169], v56 src0_sel:WORD_1
	v_cvt_pk_f32_fp8_e32 v[170:171], v57
	v_cvt_pk_f32_fp8_sdwa v[172:173], v57 src0_sel:WORD_1
	v_pk_fma_f32 v[242:243], v[206:207], v[166:167], v[242:243] op_sel:[1,0,0]
	v_pk_fma_f32 v[244:245], v[206:207], v[168:169], v[244:245] op_sel:[1,0,0]
	v_pk_fma_f32 v[246:247], v[206:207], v[170:171], v[246:247] op_sel:[1,0,0]
	v_pk_fma_f32 v[248:249], v[206:207], v[172:173], v[248:249] op_sel:[1,0,0]
	v_cvt_pk_f32_fp8_e32 v[166:167], v58
	v_cvt_pk_f32_fp8_sdwa v[168:169], v58 src0_sel:WORD_1
	v_cvt_pk_f32_fp8_e32 v[170:171], v59
	v_cvt_pk_f32_fp8_sdwa v[172:173], v59 src0_sel:WORD_1
	v_pk_fma_f32 v[242:243], v[216:217], v[166:167], v[242:243] op_sel_hi:[0,1,1]
	v_pk_fma_f32 v[244:245], v[216:217], v[168:169], v[244:245] op_sel_hi:[0,1,1]
	v_pk_fma_f32 v[246:247], v[216:217], v[170:171], v[246:247] op_sel_hi:[0,1,1]
	v_pk_fma_f32 v[248:249], v[216:217], v[172:173], v[248:249] op_sel_hi:[0,1,1]
	v_cvt_pk_f32_fp8_e32 v[166:167], v60
	v_cvt_pk_f32_fp8_sdwa v[168:169], v60 src0_sel:WORD_1
	v_cvt_pk_f32_fp8_e32 v[170:171], v61
	v_cvt_pk_f32_fp8_sdwa v[172:173], v61 src0_sel:WORD_1
	v_pk_fma_f32 v[242:243], v[216:217], v[166:167], v[242:243] op_sel:[1,0,0]
	v_pk_fma_f32 v[244:245], v[216:217], v[168:169], v[244:245] op_sel:[1,0,0]
	v_pk_fma_f32 v[246:247], v[216:217], v[170:171], v[246:247] op_sel:[1,0,0]
	v_pk_fma_f32 v[248:249], v[216:217], v[172:173], v[248:249] op_sel:[1,0,0]
	v_cvt_pk_f32_fp8_e32 v[166:167], v62
	v_cvt_pk_f32_fp8_sdwa v[168:169], v62 src0_sel:WORD_1
	v_cvt_pk_f32_fp8_e32 v[170:171], v63
	v_cvt_pk_f32_fp8_sdwa v[172:173], v63 src0_sel:WORD_1
	v_pk_fma_f32 v[242:243], v[218:219], v[166:167], v[242:243] op_sel_hi:[0,1,1]
	v_pk_fma_f32 v[244:245], v[218:219], v[168:169], v[244:245] op_sel_hi:[0,1,1]
	v_pk_fma_f32 v[246:247], v[218:219], v[170:171], v[246:247] op_sel_hi:[0,1,1]
	v_pk_fma_f32 v[248:249], v[218:219], v[172:173], v[248:249] op_sel_hi:[0,1,1]
	v_cvt_pk_f32_fp8_e32 v[166:167], v64
	v_cvt_pk_f32_fp8_sdwa v[168:169], v64 src0_sel:WORD_1
	v_cvt_pk_f32_fp8_e32 v[170:171], v65
	v_cvt_pk_f32_fp8_sdwa v[172:173], v65 src0_sel:WORD_1
	v_pk_fma_f32 v[242:243], v[218:219], v[166:167], v[242:243] op_sel:[1,0,0]
	v_pk_fma_f32 v[244:245], v[218:219], v[168:169], v[244:245] op_sel:[1,0,0]
	v_pk_fma_f32 v[246:247], v[218:219], v[170:171], v[246:247] op_sel:[1,0,0]
	v_pk_fma_f32 v[248:249], v[218:219], v[172:173], v[248:249] op_sel:[1,0,0]
	v_pk_fma_f32 v[94:95], v[242:243], v[66:67], v[94:95]
	v_pk_fma_f32 v[96:97], v[244:245], v[68:69], v[96:97]
	v_pk_fma_f32 v[98:99], v[246:247], v[174:175], v[98:99]
	v_pk_fma_f32 v[100:101], v[248:249], v[176:177], v[100:101]
	global_store_dwordx4 v108, v[94:97], s[54:55]
	global_store_dwordx4 v108, v[98:101], s[54:55] offset:16
	global_load_dwordx4 v[94:97], v110, s[54:55]
	global_load_dwordx4 v[98:101], v110, s[54:55] offset:16
	global_load_dwordx4 v[66:69], v116, s[56:57]
	global_load_dwordx4 v[174:177], v116, s[56:57] offset:16
	v_mov_b32_e32 v242, 0
	v_mov_b32_e32 v243, 0
	v_mov_b32_e32 v244, 0
	v_mov_b32_e32 v245, 0
	v_mov_b32_e32 v246, 0
	v_mov_b32_e32 v247, 0
	v_mov_b32_e32 v248, 0
	v_mov_b32_e32 v249, 0
	s_waitcnt lgkmcnt(0)
	v_add_u32_e32 v120, v104, v226
	global_load_dwordx2 v[34:35], v120, s[50:51]
	v_add_u32_e32 v122, v104, v227
	global_load_dwordx2 v[36:37], v122, s[50:51]
	v_add_u32_e32 v124, v104, v228
	global_load_dwordx2 v[38:39], v124, s[50:51]
	v_add_u32_e32 v126, v104, v229
	global_load_dwordx2 v[40:41], v126, s[50:51]
	v_add_u32_e32 v120, v104, v230
	global_load_dwordx2 v[42:43], v120, s[50:51]
	v_add_u32_e32 v122, v104, v231
	global_load_dwordx2 v[44:45], v122, s[50:51]
	v_add_u32_e32 v124, v104, v232
	global_load_dwordx2 v[46:47], v124, s[50:51]
	v_add_u32_e32 v126, v104, v233
	global_load_dwordx2 v[48:49], v126, s[50:51]
	v_add_u32_e32 v120, v104, v234
	global_load_dwordx2 v[50:51], v120, s[50:51]
	v_add_u32_e32 v122, v104, v235
	global_load_dwordx2 v[52:53], v122, s[50:51]
	v_add_u32_e32 v124, v104, v236
	global_load_dwordx2 v[54:55], v124, s[50:51]
	v_add_u32_e32 v126, v104, v237
	global_load_dwordx2 v[56:57], v126, s[50:51]
	v_add_u32_e32 v120, v104, v238
	global_load_dwordx2 v[58:59], v120, s[50:51]
	v_add_u32_e32 v122, v104, v239
	global_load_dwordx2 v[60:61], v122, s[50:51]
	v_add_u32_e32 v124, v104, v240
	global_load_dwordx2 v[62:63], v124, s[50:51]
	v_add_u32_e32 v126, v104, v241
	global_load_dwordx2 v[64:65], v126, s[50:51]
	ds_read_b128 v[226:229], v106 offset:2240
	ds_read_b128 v[230:233], v106 offset:2256
	ds_read_b128 v[234:237], v106 offset:2272
	ds_read_b128 v[238:241], v106 offset:2288
	ds_read_b128 v[196:199], v106 offset:8256
	ds_read_b128 v[200:203], v106 offset:8272
	ds_read_b128 v[204:207], v106 offset:8288
	ds_read_b128 v[216:219], v106 offset:8304
	s_waitcnt vmcnt(38)
	v_cvt_pk_f32_fp8_e32 v[166:167], v134
	v_cvt_pk_f32_fp8_sdwa v[168:169], v134 src0_sel:WORD_1
	v_cvt_pk_f32_fp8_e32 v[170:171], v135
	v_cvt_pk_f32_fp8_sdwa v[172:173], v135 src0_sel:WORD_1
	v_pk_fma_f32 v[242:243], v[180:181], v[166:167], v[242:243] op_sel_hi:[0,1,1]
	v_pk_fma_f32 v[244:245], v[180:181], v[168:169], v[244:245] op_sel_hi:[0,1,1]
	v_pk_fma_f32 v[246:247], v[180:181], v[170:171], v[246:247] op_sel_hi:[0,1,1]
	v_pk_fma_f32 v[248:249], v[180:181], v[172:173], v[248:249] op_sel_hi:[0,1,1]
	v_cvt_pk_f32_fp8_e32 v[166:167], v136
	v_cvt_pk_f32_fp8_sdwa v[168:169], v136 src0_sel:WORD_1
	v_cvt_pk_f32_fp8_e32 v[170:171], v137
	v_cvt_pk_f32_fp8_sdwa v[172:173], v137 src0_sel:WORD_1
	v_pk_fma_f32 v[242:243], v[180:181], v[166:167], v[242:243] op_sel:[1,0,0]
	v_pk_fma_f32 v[244:245], v[180:181], v[168:169], v[244:245] op_sel:[1,0,0]
	v_pk_fma_f32 v[246:247], v[180:181], v[170:171], v[246:247] op_sel:[1,0,0]
	v_pk_fma_f32 v[248:249], v[180:181], v[172:173], v[248:249] op_sel:[1,0,0]
	v_cvt_pk_f32_fp8_e32 v[166:167], v138
	v_cvt_pk_f32_fp8_sdwa v[168:169], v138 src0_sel:WORD_1
	v_cvt_pk_f32_fp8_e32 v[170:171], v139
	v_cvt_pk_f32_fp8_sdwa v[172:173], v139 src0_sel:WORD_1
	v_pk_fma_f32 v[242:243], v[182:183], v[166:167], v[242:243] op_sel_hi:[0,1,1]
	v_pk_fma_f32 v[244:245], v[182:183], v[168:169], v[244:245] op_sel_hi:[0,1,1]
	v_pk_fma_f32 v[246:247], v[182:183], v[170:171], v[246:247] op_sel_hi:[0,1,1]
	v_pk_fma_f32 v[248:249], v[182:183], v[172:173], v[248:249] op_sel_hi:[0,1,1]
	v_cvt_pk_f32_fp8_e32 v[166:167], v140
	v_cvt_pk_f32_fp8_sdwa v[168:169], v140 src0_sel:WORD_1
	v_cvt_pk_f32_fp8_e32 v[170:171], v141
	v_cvt_pk_f32_fp8_sdwa v[172:173], v141 src0_sel:WORD_1
	v_pk_fma_f32 v[242:243], v[182:183], v[166:167], v[242:243] op_sel:[1,0,0]
	v_pk_fma_f32 v[244:245], v[182:183], v[168:169], v[244:245] op_sel:[1,0,0]
	v_pk_fma_f32 v[246:247], v[182:183], v[170:171], v[246:247] op_sel:[1,0,0]
	v_pk_fma_f32 v[248:249], v[182:183], v[172:173], v[248:249] op_sel:[1,0,0]
	v_cvt_pk_f32_fp8_e32 v[166:167], v142
	v_cvt_pk_f32_fp8_sdwa v[168:169], v142 src0_sel:WORD_1
	v_cvt_pk_f32_fp8_e32 v[170:171], v143
	v_cvt_pk_f32_fp8_sdwa v[172:173], v143 src0_sel:WORD_1
	v_pk_fma_f32 v[242:243], v[184:185], v[166:167], v[242:243] op_sel_hi:[0,1,1]
	v_pk_fma_f32 v[244:245], v[184:185], v[168:169], v[244:245] op_sel_hi:[0,1,1]
	v_pk_fma_f32 v[246:247], v[184:185], v[170:171], v[246:247] op_sel_hi:[0,1,1]
	v_pk_fma_f32 v[248:249], v[184:185], v[172:173], v[248:249] op_sel_hi:[0,1,1]
	v_cvt_pk_f32_fp8_e32 v[166:167], v144
	v_cvt_pk_f32_fp8_sdwa v[168:169], v144 src0_sel:WORD_1
	v_cvt_pk_f32_fp8_e32 v[170:171], v145
	v_cvt_pk_f32_fp8_sdwa v[172:173], v145 src0_sel:WORD_1
	v_pk_fma_f32 v[242:243], v[184:185], v[166:167], v[242:243] op_sel:[1,0,0]
	v_pk_fma_f32 v[244:245], v[184:185], v[168:169], v[244:245] op_sel:[1,0,0]
	v_pk_fma_f32 v[246:247], v[184:185], v[170:171], v[246:247] op_sel:[1,0,0]
	v_pk_fma_f32 v[248:249], v[184:185], v[172:173], v[248:249] op_sel:[1,0,0]
	v_cvt_pk_f32_fp8_e32 v[166:167], v146
	v_cvt_pk_f32_fp8_sdwa v[168:169], v146 src0_sel:WORD_1
	v_cvt_pk_f32_fp8_e32 v[170:171], v147
	v_cvt_pk_f32_fp8_sdwa v[172:173], v147 src0_sel:WORD_1
	v_pk_fma_f32 v[242:243], v[186:187], v[166:167], v[242:243] op_sel_hi:[0,1,1]
	v_pk_fma_f32 v[244:245], v[186:187], v[168:169], v[244:245] op_sel_hi:[0,1,1]
	v_pk_fma_f32 v[246:247], v[186:187], v[170:171], v[246:247] op_sel_hi:[0,1,1]
	v_pk_fma_f32 v[248:249], v[186:187], v[172:173], v[248:249] op_sel_hi:[0,1,1]
	v_cvt_pk_f32_fp8_e32 v[166:167], v148
	v_cvt_pk_f32_fp8_sdwa v[168:169], v148 src0_sel:WORD_1
	v_cvt_pk_f32_fp8_e32 v[170:171], v149
	v_cvt_pk_f32_fp8_sdwa v[172:173], v149 src0_sel:WORD_1
	v_pk_fma_f32 v[242:243], v[186:187], v[166:167], v[242:243] op_sel:[1,0,0]
	v_pk_fma_f32 v[244:245], v[186:187], v[168:169], v[244:245] op_sel:[1,0,0]
	v_pk_fma_f32 v[246:247], v[186:187], v[170:171], v[246:247] op_sel:[1,0,0]
	v_pk_fma_f32 v[248:249], v[186:187], v[172:173], v[248:249] op_sel:[1,0,0]
	v_cvt_pk_f32_fp8_e32 v[166:167], v150
	v_cvt_pk_f32_fp8_sdwa v[168:169], v150 src0_sel:WORD_1
	v_cvt_pk_f32_fp8_e32 v[170:171], v151
	v_cvt_pk_f32_fp8_sdwa v[172:173], v151 src0_sel:WORD_1
	v_pk_fma_f32 v[242:243], v[188:189], v[166:167], v[242:243] op_sel_hi:[0,1,1]
	v_pk_fma_f32 v[244:245], v[188:189], v[168:169], v[244:245] op_sel_hi:[0,1,1]
	v_pk_fma_f32 v[246:247], v[188:189], v[170:171], v[246:247] op_sel_hi:[0,1,1]
	v_pk_fma_f32 v[248:249], v[188:189], v[172:173], v[248:249] op_sel_hi:[0,1,1]
	v_cvt_pk_f32_fp8_e32 v[166:167], v152
	v_cvt_pk_f32_fp8_sdwa v[168:169], v152 src0_sel:WORD_1
	v_cvt_pk_f32_fp8_e32 v[170:171], v153
	v_cvt_pk_f32_fp8_sdwa v[172:173], v153 src0_sel:WORD_1
	v_pk_fma_f32 v[242:243], v[188:189], v[166:167], v[242:243] op_sel:[1,0,0]
	v_pk_fma_f32 v[244:245], v[188:189], v[168:169], v[244:245] op_sel:[1,0,0]
	v_pk_fma_f32 v[246:247], v[188:189], v[170:171], v[246:247] op_sel:[1,0,0]
	v_pk_fma_f32 v[248:249], v[188:189], v[172:173], v[248:249] op_sel:[1,0,0]
	v_cvt_pk_f32_fp8_e32 v[166:167], v154
	v_cvt_pk_f32_fp8_sdwa v[168:169], v154 src0_sel:WORD_1
	v_cvt_pk_f32_fp8_e32 v[170:171], v155
	v_cvt_pk_f32_fp8_sdwa v[172:173], v155 src0_sel:WORD_1
	v_pk_fma_f32 v[242:243], v[190:191], v[166:167], v[242:243] op_sel_hi:[0,1,1]
	v_pk_fma_f32 v[244:245], v[190:191], v[168:169], v[244:245] op_sel_hi:[0,1,1]
	v_pk_fma_f32 v[246:247], v[190:191], v[170:171], v[246:247] op_sel_hi:[0,1,1]
	v_pk_fma_f32 v[248:249], v[190:191], v[172:173], v[248:249] op_sel_hi:[0,1,1]
	v_cvt_pk_f32_fp8_e32 v[166:167], v156
	v_cvt_pk_f32_fp8_sdwa v[168:169], v156 src0_sel:WORD_1
	v_cvt_pk_f32_fp8_e32 v[170:171], v157
	v_cvt_pk_f32_fp8_sdwa v[172:173], v157 src0_sel:WORD_1
	v_pk_fma_f32 v[242:243], v[190:191], v[166:167], v[242:243] op_sel:[1,0,0]
	v_pk_fma_f32 v[244:245], v[190:191], v[168:169], v[244:245] op_sel:[1,0,0]
	v_pk_fma_f32 v[246:247], v[190:191], v[170:171], v[246:247] op_sel:[1,0,0]
	v_pk_fma_f32 v[248:249], v[190:191], v[172:173], v[248:249] op_sel:[1,0,0]
	v_cvt_pk_f32_fp8_e32 v[166:167], v158
	v_cvt_pk_f32_fp8_sdwa v[168:169], v158 src0_sel:WORD_1
	v_cvt_pk_f32_fp8_e32 v[170:171], v159
	v_cvt_pk_f32_fp8_sdwa v[172:173], v159 src0_sel:WORD_1
	v_pk_fma_f32 v[242:243], v[192:193], v[166:167], v[242:243] op_sel_hi:[0,1,1]
	v_pk_fma_f32 v[244:245], v[192:193], v[168:169], v[244:245] op_sel_hi:[0,1,1]
	v_pk_fma_f32 v[246:247], v[192:193], v[170:171], v[246:247] op_sel_hi:[0,1,1]
	v_pk_fma_f32 v[248:249], v[192:193], v[172:173], v[248:249] op_sel_hi:[0,1,1]
	v_cvt_pk_f32_fp8_e32 v[166:167], v160
	v_cvt_pk_f32_fp8_sdwa v[168:169], v160 src0_sel:WORD_1
	v_cvt_pk_f32_fp8_e32 v[170:171], v161
	v_cvt_pk_f32_fp8_sdwa v[172:173], v161 src0_sel:WORD_1
	v_pk_fma_f32 v[242:243], v[192:193], v[166:167], v[242:243] op_sel:[1,0,0]
	v_pk_fma_f32 v[244:245], v[192:193], v[168:169], v[244:245] op_sel:[1,0,0]
	v_pk_fma_f32 v[246:247], v[192:193], v[170:171], v[246:247] op_sel:[1,0,0]
	v_pk_fma_f32 v[248:249], v[192:193], v[172:173], v[248:249] op_sel:[1,0,0]
	v_cvt_pk_f32_fp8_e32 v[166:167], v162
	v_cvt_pk_f32_fp8_sdwa v[168:169], v162 src0_sel:WORD_1
	v_cvt_pk_f32_fp8_e32 v[170:171], v163
	v_cvt_pk_f32_fp8_sdwa v[172:173], v163 src0_sel:WORD_1
	v_pk_fma_f32 v[242:243], v[194:195], v[166:167], v[242:243] op_sel_hi:[0,1,1]
	v_pk_fma_f32 v[244:245], v[194:195], v[168:169], v[244:245] op_sel_hi:[0,1,1]
	v_pk_fma_f32 v[246:247], v[194:195], v[170:171], v[246:247] op_sel_hi:[0,1,1]
	v_pk_fma_f32 v[248:249], v[194:195], v[172:173], v[248:249] op_sel_hi:[0,1,1]
	v_cvt_pk_f32_fp8_e32 v[166:167], v164
	v_cvt_pk_f32_fp8_sdwa v[168:169], v164 src0_sel:WORD_1
	v_cvt_pk_f32_fp8_e32 v[170:171], v165
	v_cvt_pk_f32_fp8_sdwa v[172:173], v165 src0_sel:WORD_1
	v_pk_fma_f32 v[242:243], v[194:195], v[166:167], v[242:243] op_sel:[1,0,0]
	v_pk_fma_f32 v[244:245], v[194:195], v[168:169], v[244:245] op_sel:[1,0,0]
	v_pk_fma_f32 v[246:247], v[194:195], v[170:171], v[246:247] op_sel:[1,0,0]
	v_pk_fma_f32 v[248:249], v[194:195], v[172:173], v[248:249] op_sel:[1,0,0]
	s_waitcnt lgkmcnt(0)
	v_add_u32_e32 v120, v104, v226
	global_load_dwordx2 v[134:135], v120, s[50:51]
	v_add_u32_e32 v122, v104, v227
	global_load_dwordx2 v[136:137], v122, s[50:51]
	v_add_u32_e32 v124, v104, v228
	global_load_dwordx2 v[138:139], v124, s[50:51]
	v_add_u32_e32 v126, v104, v229
	global_load_dwordx2 v[140:141], v126, s[50:51]
	v_add_u32_e32 v120, v104, v230
	global_load_dwordx2 v[142:143], v120, s[50:51]
	v_add_u32_e32 v122, v104, v231
	global_load_dwordx2 v[144:145], v122, s[50:51]
	v_add_u32_e32 v124, v104, v232
	global_load_dwordx2 v[146:147], v124, s[50:51]
	v_add_u32_e32 v126, v104, v233
	global_load_dwordx2 v[148:149], v126, s[50:51]
	v_add_u32_e32 v120, v104, v234
	global_load_dwordx2 v[150:151], v120, s[50:51]
	v_add_u32_e32 v122, v104, v235
	global_load_dwordx2 v[152:153], v122, s[50:51]
	v_add_u32_e32 v124, v104, v236
	global_load_dwordx2 v[154:155], v124, s[50:51]
	v_add_u32_e32 v126, v104, v237
	global_load_dwordx2 v[156:157], v126, s[50:51]
	v_add_u32_e32 v120, v104, v238
	global_load_dwordx2 v[158:159], v120, s[50:51]
	v_add_u32_e32 v122, v104, v239
	global_load_dwordx2 v[160:161], v122, s[50:51]
	v_add_u32_e32 v124, v104, v240
	global_load_dwordx2 v[162:163], v124, s[50:51]
	v_add_u32_e32 v126, v104, v241
	global_load_dwordx2 v[164:165], v126, s[50:51]
	ds_read_b128 v[226:229], v106 offset:2304
	ds_read_b128 v[230:233], v106 offset:2320
	ds_read_b128 v[234:237], v106 offset:2336
	ds_read_b128 v[238:241], v106 offset:2352
	ds_read_b128 v[180:183], v106 offset:8320
	ds_read_b128 v[184:187], v106 offset:8336
	ds_read_b128 v[188:191], v106 offset:8352
	ds_read_b128 v[192:195], v106 offset:8368
	s_waitcnt vmcnt(38)
	v_cvt_pk_f32_fp8_e32 v[166:167], v2
	v_cvt_pk_f32_fp8_sdwa v[168:169], v2 src0_sel:WORD_1
	v_cvt_pk_f32_fp8_e32 v[170:171], v3
	v_cvt_pk_f32_fp8_sdwa v[172:173], v3 src0_sel:WORD_1
	v_pk_fma_f32 v[242:243], v[196:197], v[166:167], v[242:243] op_sel_hi:[0,1,1]
	v_pk_fma_f32 v[244:245], v[196:197], v[168:169], v[244:245] op_sel_hi:[0,1,1]
	v_pk_fma_f32 v[246:247], v[196:197], v[170:171], v[246:247] op_sel_hi:[0,1,1]
	v_pk_fma_f32 v[248:249], v[196:197], v[172:173], v[248:249] op_sel_hi:[0,1,1]
	v_cvt_pk_f32_fp8_e32 v[166:167], v4
	v_cvt_pk_f32_fp8_sdwa v[168:169], v4 src0_sel:WORD_1
	v_cvt_pk_f32_fp8_e32 v[170:171], v5
	v_cvt_pk_f32_fp8_sdwa v[172:173], v5 src0_sel:WORD_1
	v_pk_fma_f32 v[242:243], v[196:197], v[166:167], v[242:243] op_sel:[1,0,0]
	v_pk_fma_f32 v[244:245], v[196:197], v[168:169], v[244:245] op_sel:[1,0,0]
	v_pk_fma_f32 v[246:247], v[196:197], v[170:171], v[246:247] op_sel:[1,0,0]
	v_pk_fma_f32 v[248:249], v[196:197], v[172:173], v[248:249] op_sel:[1,0,0]
	v_cvt_pk_f32_fp8_e32 v[166:167], v6
	v_cvt_pk_f32_fp8_sdwa v[168:169], v6 src0_sel:WORD_1
	v_cvt_pk_f32_fp8_e32 v[170:171], v7
	v_cvt_pk_f32_fp8_sdwa v[172:173], v7 src0_sel:WORD_1
	v_pk_fma_f32 v[242:243], v[198:199], v[166:167], v[242:243] op_sel_hi:[0,1,1]
	v_pk_fma_f32 v[244:245], v[198:199], v[168:169], v[244:245] op_sel_hi:[0,1,1]
	v_pk_fma_f32 v[246:247], v[198:199], v[170:171], v[246:247] op_sel_hi:[0,1,1]
	v_pk_fma_f32 v[248:249], v[198:199], v[172:173], v[248:249] op_sel_hi:[0,1,1]
	v_cvt_pk_f32_fp8_e32 v[166:167], v8
	v_cvt_pk_f32_fp8_sdwa v[168:169], v8 src0_sel:WORD_1
	v_cvt_pk_f32_fp8_e32 v[170:171], v9
	v_cvt_pk_f32_fp8_sdwa v[172:173], v9 src0_sel:WORD_1
	v_pk_fma_f32 v[242:243], v[198:199], v[166:167], v[242:243] op_sel:[1,0,0]
	v_pk_fma_f32 v[244:245], v[198:199], v[168:169], v[244:245] op_sel:[1,0,0]
	v_pk_fma_f32 v[246:247], v[198:199], v[170:171], v[246:247] op_sel:[1,0,0]
	v_pk_fma_f32 v[248:249], v[198:199], v[172:173], v[248:249] op_sel:[1,0,0]
	v_cvt_pk_f32_fp8_e32 v[166:167], v10
	v_cvt_pk_f32_fp8_sdwa v[168:169], v10 src0_sel:WORD_1
	v_cvt_pk_f32_fp8_e32 v[170:171], v11
	v_cvt_pk_f32_fp8_sdwa v[172:173], v11 src0_sel:WORD_1
	v_pk_fma_f32 v[242:243], v[200:201], v[166:167], v[242:243] op_sel_hi:[0,1,1]
	v_pk_fma_f32 v[244:245], v[200:201], v[168:169], v[244:245] op_sel_hi:[0,1,1]
	v_pk_fma_f32 v[246:247], v[200:201], v[170:171], v[246:247] op_sel_hi:[0,1,1]
	v_pk_fma_f32 v[248:249], v[200:201], v[172:173], v[248:249] op_sel_hi:[0,1,1]
	v_cvt_pk_f32_fp8_e32 v[166:167], v12
	v_cvt_pk_f32_fp8_sdwa v[168:169], v12 src0_sel:WORD_1
	v_cvt_pk_f32_fp8_e32 v[170:171], v13
	v_cvt_pk_f32_fp8_sdwa v[172:173], v13 src0_sel:WORD_1
	v_pk_fma_f32 v[242:243], v[200:201], v[166:167], v[242:243] op_sel:[1,0,0]
	v_pk_fma_f32 v[244:245], v[200:201], v[168:169], v[244:245] op_sel:[1,0,0]
	v_pk_fma_f32 v[246:247], v[200:201], v[170:171], v[246:247] op_sel:[1,0,0]
	v_pk_fma_f32 v[248:249], v[200:201], v[172:173], v[248:249] op_sel:[1,0,0]
	v_cvt_pk_f32_fp8_e32 v[166:167], v14
	v_cvt_pk_f32_fp8_sdwa v[168:169], v14 src0_sel:WORD_1
	v_cvt_pk_f32_fp8_e32 v[170:171], v15
	v_cvt_pk_f32_fp8_sdwa v[172:173], v15 src0_sel:WORD_1
	v_pk_fma_f32 v[242:243], v[202:203], v[166:167], v[242:243] op_sel_hi:[0,1,1]
	v_pk_fma_f32 v[244:245], v[202:203], v[168:169], v[244:245] op_sel_hi:[0,1,1]
	v_pk_fma_f32 v[246:247], v[202:203], v[170:171], v[246:247] op_sel_hi:[0,1,1]
	v_pk_fma_f32 v[248:249], v[202:203], v[172:173], v[248:249] op_sel_hi:[0,1,1]
	v_cvt_pk_f32_fp8_e32 v[166:167], v16
	v_cvt_pk_f32_fp8_sdwa v[168:169], v16 src0_sel:WORD_1
	v_cvt_pk_f32_fp8_e32 v[170:171], v17
	v_cvt_pk_f32_fp8_sdwa v[172:173], v17 src0_sel:WORD_1
	v_pk_fma_f32 v[242:243], v[202:203], v[166:167], v[242:243] op_sel:[1,0,0]
	v_pk_fma_f32 v[244:245], v[202:203], v[168:169], v[244:245] op_sel:[1,0,0]
	v_pk_fma_f32 v[246:247], v[202:203], v[170:171], v[246:247] op_sel:[1,0,0]
	v_pk_fma_f32 v[248:249], v[202:203], v[172:173], v[248:249] op_sel:[1,0,0]
	v_cvt_pk_f32_fp8_e32 v[166:167], v18
	v_cvt_pk_f32_fp8_sdwa v[168:169], v18 src0_sel:WORD_1
	v_cvt_pk_f32_fp8_e32 v[170:171], v19
	v_cvt_pk_f32_fp8_sdwa v[172:173], v19 src0_sel:WORD_1
	v_pk_fma_f32 v[242:243], v[204:205], v[166:167], v[242:243] op_sel_hi:[0,1,1]
	v_pk_fma_f32 v[244:245], v[204:205], v[168:169], v[244:245] op_sel_hi:[0,1,1]
	v_pk_fma_f32 v[246:247], v[204:205], v[170:171], v[246:247] op_sel_hi:[0,1,1]
	v_pk_fma_f32 v[248:249], v[204:205], v[172:173], v[248:249] op_sel_hi:[0,1,1]
	v_cvt_pk_f32_fp8_e32 v[166:167], v20
	v_cvt_pk_f32_fp8_sdwa v[168:169], v20 src0_sel:WORD_1
	v_cvt_pk_f32_fp8_e32 v[170:171], v21
	v_cvt_pk_f32_fp8_sdwa v[172:173], v21 src0_sel:WORD_1
	v_pk_fma_f32 v[242:243], v[204:205], v[166:167], v[242:243] op_sel:[1,0,0]
	v_pk_fma_f32 v[244:245], v[204:205], v[168:169], v[244:245] op_sel:[1,0,0]
	v_pk_fma_f32 v[246:247], v[204:205], v[170:171], v[246:247] op_sel:[1,0,0]
	v_pk_fma_f32 v[248:249], v[204:205], v[172:173], v[248:249] op_sel:[1,0,0]
	v_cvt_pk_f32_fp8_e32 v[166:167], v22
	v_cvt_pk_f32_fp8_sdwa v[168:169], v22 src0_sel:WORD_1
	v_cvt_pk_f32_fp8_e32 v[170:171], v23
	v_cvt_pk_f32_fp8_sdwa v[172:173], v23 src0_sel:WORD_1
	v_pk_fma_f32 v[242:243], v[206:207], v[166:167], v[242:243] op_sel_hi:[0,1,1]
	v_pk_fma_f32 v[244:245], v[206:207], v[168:169], v[244:245] op_sel_hi:[0,1,1]
	v_pk_fma_f32 v[246:247], v[206:207], v[170:171], v[246:247] op_sel_hi:[0,1,1]
	v_pk_fma_f32 v[248:249], v[206:207], v[172:173], v[248:249] op_sel_hi:[0,1,1]
	v_cvt_pk_f32_fp8_e32 v[166:167], v24
	v_cvt_pk_f32_fp8_sdwa v[168:169], v24 src0_sel:WORD_1
	v_cvt_pk_f32_fp8_e32 v[170:171], v25
	v_cvt_pk_f32_fp8_sdwa v[172:173], v25 src0_sel:WORD_1
	v_pk_fma_f32 v[242:243], v[206:207], v[166:167], v[242:243] op_sel:[1,0,0]
	v_pk_fma_f32 v[244:245], v[206:207], v[168:169], v[244:245] op_sel:[1,0,0]
	v_pk_fma_f32 v[246:247], v[206:207], v[170:171], v[246:247] op_sel:[1,0,0]
	v_pk_fma_f32 v[248:249], v[206:207], v[172:173], v[248:249] op_sel:[1,0,0]
	v_cvt_pk_f32_fp8_e32 v[166:167], v26
	v_cvt_pk_f32_fp8_sdwa v[168:169], v26 src0_sel:WORD_1
	v_cvt_pk_f32_fp8_e32 v[170:171], v27
	v_cvt_pk_f32_fp8_sdwa v[172:173], v27 src0_sel:WORD_1
	v_pk_fma_f32 v[242:243], v[216:217], v[166:167], v[242:243] op_sel_hi:[0,1,1]
	v_pk_fma_f32 v[244:245], v[216:217], v[168:169], v[244:245] op_sel_hi:[0,1,1]
	v_pk_fma_f32 v[246:247], v[216:217], v[170:171], v[246:247] op_sel_hi:[0,1,1]
	v_pk_fma_f32 v[248:249], v[216:217], v[172:173], v[248:249] op_sel_hi:[0,1,1]
	v_cvt_pk_f32_fp8_e32 v[166:167], v28
	v_cvt_pk_f32_fp8_sdwa v[168:169], v28 src0_sel:WORD_1
	v_cvt_pk_f32_fp8_e32 v[170:171], v29
	v_cvt_pk_f32_fp8_sdwa v[172:173], v29 src0_sel:WORD_1
	v_pk_fma_f32 v[242:243], v[216:217], v[166:167], v[242:243] op_sel:[1,0,0]
	v_pk_fma_f32 v[244:245], v[216:217], v[168:169], v[244:245] op_sel:[1,0,0]
	v_pk_fma_f32 v[246:247], v[216:217], v[170:171], v[246:247] op_sel:[1,0,0]
	v_pk_fma_f32 v[248:249], v[216:217], v[172:173], v[248:249] op_sel:[1,0,0]
	v_cvt_pk_f32_fp8_e32 v[166:167], v30
	v_cvt_pk_f32_fp8_sdwa v[168:169], v30 src0_sel:WORD_1
	v_cvt_pk_f32_fp8_e32 v[170:171], v31
	v_cvt_pk_f32_fp8_sdwa v[172:173], v31 src0_sel:WORD_1
	v_pk_fma_f32 v[242:243], v[218:219], v[166:167], v[242:243] op_sel_hi:[0,1,1]
	v_pk_fma_f32 v[244:245], v[218:219], v[168:169], v[244:245] op_sel_hi:[0,1,1]
	v_pk_fma_f32 v[246:247], v[218:219], v[170:171], v[246:247] op_sel_hi:[0,1,1]
	v_pk_fma_f32 v[248:249], v[218:219], v[172:173], v[248:249] op_sel_hi:[0,1,1]
	v_cvt_pk_f32_fp8_e32 v[166:167], v32
	v_cvt_pk_f32_fp8_sdwa v[168:169], v32 src0_sel:WORD_1
	v_cvt_pk_f32_fp8_e32 v[170:171], v33
	v_cvt_pk_f32_fp8_sdwa v[172:173], v33 src0_sel:WORD_1
	v_pk_fma_f32 v[242:243], v[218:219], v[166:167], v[242:243] op_sel:[1,0,0]
	v_pk_fma_f32 v[244:245], v[218:219], v[168:169], v[244:245] op_sel:[1,0,0]
	v_pk_fma_f32 v[246:247], v[218:219], v[170:171], v[246:247] op_sel:[1,0,0]
	v_pk_fma_f32 v[248:249], v[218:219], v[172:173], v[248:249] op_sel:[1,0,0]
	s_waitcnt lgkmcnt(0)
	v_add_u32_e32 v120, v104, v226
	global_load_dwordx2 v[2:3], v120, s[50:51]
	v_add_u32_e32 v122, v104, v227
	global_load_dwordx2 v[4:5], v122, s[50:51]
	v_add_u32_e32 v124, v104, v228
	global_load_dwordx2 v[6:7], v124, s[50:51]
	v_add_u32_e32 v126, v104, v229
	global_load_dwordx2 v[8:9], v126, s[50:51]
	v_add_u32_e32 v120, v104, v230
	global_load_dwordx2 v[10:11], v120, s[50:51]
	v_add_u32_e32 v122, v104, v231
	global_load_dwordx2 v[12:13], v122, s[50:51]
	v_add_u32_e32 v124, v104, v232
	global_load_dwordx2 v[14:15], v124, s[50:51]
	v_add_u32_e32 v126, v104, v233
	global_load_dwordx2 v[16:17], v126, s[50:51]
	v_add_u32_e32 v120, v104, v234
	global_load_dwordx2 v[18:19], v120, s[50:51]
	v_add_u32_e32 v122, v104, v235
	global_load_dwordx2 v[20:21], v122, s[50:51]
	v_add_u32_e32 v124, v104, v236
	global_load_dwordx2 v[22:23], v124, s[50:51]
	v_add_u32_e32 v126, v104, v237
	global_load_dwordx2 v[24:25], v126, s[50:51]
	v_add_u32_e32 v120, v104, v238
	global_load_dwordx2 v[26:27], v120, s[50:51]
	v_add_u32_e32 v122, v104, v239
	global_load_dwordx2 v[28:29], v122, s[50:51]
	v_add_u32_e32 v124, v104, v240
	global_load_dwordx2 v[30:31], v124, s[50:51]
	v_add_u32_e32 v126, v104, v241
	global_load_dwordx2 v[32:33], v126, s[50:51]
	ds_read_b128 v[226:229], v106 offset:2368
	ds_read_b128 v[230:233], v106 offset:2384
	ds_read_b128 v[234:237], v106 offset:2400
	ds_read_b128 v[238:241], v106 offset:2416
	ds_read_b128 v[196:199], v106 offset:8384
	ds_read_b128 v[200:203], v106 offset:8400
	ds_read_b128 v[204:207], v106 offset:8416
	ds_read_b128 v[216:219], v106 offset:8432
	s_waitcnt vmcnt(32)
	v_cvt_pk_f32_fp8_e32 v[166:167], v34
	v_cvt_pk_f32_fp8_sdwa v[168:169], v34 src0_sel:WORD_1
	v_cvt_pk_f32_fp8_e32 v[170:171], v35
	v_cvt_pk_f32_fp8_sdwa v[172:173], v35 src0_sel:WORD_1
	v_pk_fma_f32 v[242:243], v[180:181], v[166:167], v[242:243] op_sel_hi:[0,1,1]
	v_pk_fma_f32 v[244:245], v[180:181], v[168:169], v[244:245] op_sel_hi:[0,1,1]
	v_pk_fma_f32 v[246:247], v[180:181], v[170:171], v[246:247] op_sel_hi:[0,1,1]
	v_pk_fma_f32 v[248:249], v[180:181], v[172:173], v[248:249] op_sel_hi:[0,1,1]
	v_cvt_pk_f32_fp8_e32 v[166:167], v36
	v_cvt_pk_f32_fp8_sdwa v[168:169], v36 src0_sel:WORD_1
	v_cvt_pk_f32_fp8_e32 v[170:171], v37
	v_cvt_pk_f32_fp8_sdwa v[172:173], v37 src0_sel:WORD_1
	v_pk_fma_f32 v[242:243], v[180:181], v[166:167], v[242:243] op_sel:[1,0,0]
	v_pk_fma_f32 v[244:245], v[180:181], v[168:169], v[244:245] op_sel:[1,0,0]
	v_pk_fma_f32 v[246:247], v[180:181], v[170:171], v[246:247] op_sel:[1,0,0]
	v_pk_fma_f32 v[248:249], v[180:181], v[172:173], v[248:249] op_sel:[1,0,0]
	v_cvt_pk_f32_fp8_e32 v[166:167], v38
	v_cvt_pk_f32_fp8_sdwa v[168:169], v38 src0_sel:WORD_1
	v_cvt_pk_f32_fp8_e32 v[170:171], v39
	v_cvt_pk_f32_fp8_sdwa v[172:173], v39 src0_sel:WORD_1
	v_pk_fma_f32 v[242:243], v[182:183], v[166:167], v[242:243] op_sel_hi:[0,1,1]
	v_pk_fma_f32 v[244:245], v[182:183], v[168:169], v[244:245] op_sel_hi:[0,1,1]
	v_pk_fma_f32 v[246:247], v[182:183], v[170:171], v[246:247] op_sel_hi:[0,1,1]
	v_pk_fma_f32 v[248:249], v[182:183], v[172:173], v[248:249] op_sel_hi:[0,1,1]
	v_cvt_pk_f32_fp8_e32 v[166:167], v40
	v_cvt_pk_f32_fp8_sdwa v[168:169], v40 src0_sel:WORD_1
	v_cvt_pk_f32_fp8_e32 v[170:171], v41
	v_cvt_pk_f32_fp8_sdwa v[172:173], v41 src0_sel:WORD_1
	v_pk_fma_f32 v[242:243], v[182:183], v[166:167], v[242:243] op_sel:[1,0,0]
	v_pk_fma_f32 v[244:245], v[182:183], v[168:169], v[244:245] op_sel:[1,0,0]
	v_pk_fma_f32 v[246:247], v[182:183], v[170:171], v[246:247] op_sel:[1,0,0]
	v_pk_fma_f32 v[248:249], v[182:183], v[172:173], v[248:249] op_sel:[1,0,0]
	v_cvt_pk_f32_fp8_e32 v[166:167], v42
	v_cvt_pk_f32_fp8_sdwa v[168:169], v42 src0_sel:WORD_1
	v_cvt_pk_f32_fp8_e32 v[170:171], v43
	v_cvt_pk_f32_fp8_sdwa v[172:173], v43 src0_sel:WORD_1
	v_pk_fma_f32 v[242:243], v[184:185], v[166:167], v[242:243] op_sel_hi:[0,1,1]
	v_pk_fma_f32 v[244:245], v[184:185], v[168:169], v[244:245] op_sel_hi:[0,1,1]
	v_pk_fma_f32 v[246:247], v[184:185], v[170:171], v[246:247] op_sel_hi:[0,1,1]
	v_pk_fma_f32 v[248:249], v[184:185], v[172:173], v[248:249] op_sel_hi:[0,1,1]
	v_cvt_pk_f32_fp8_e32 v[166:167], v44
	v_cvt_pk_f32_fp8_sdwa v[168:169], v44 src0_sel:WORD_1
	v_cvt_pk_f32_fp8_e32 v[170:171], v45
	v_cvt_pk_f32_fp8_sdwa v[172:173], v45 src0_sel:WORD_1
	v_pk_fma_f32 v[242:243], v[184:185], v[166:167], v[242:243] op_sel:[1,0,0]
	v_pk_fma_f32 v[244:245], v[184:185], v[168:169], v[244:245] op_sel:[1,0,0]
	v_pk_fma_f32 v[246:247], v[184:185], v[170:171], v[246:247] op_sel:[1,0,0]
	v_pk_fma_f32 v[248:249], v[184:185], v[172:173], v[248:249] op_sel:[1,0,0]
	v_cvt_pk_f32_fp8_e32 v[166:167], v46
	v_cvt_pk_f32_fp8_sdwa v[168:169], v46 src0_sel:WORD_1
	v_cvt_pk_f32_fp8_e32 v[170:171], v47
	v_cvt_pk_f32_fp8_sdwa v[172:173], v47 src0_sel:WORD_1
	v_pk_fma_f32 v[242:243], v[186:187], v[166:167], v[242:243] op_sel_hi:[0,1,1]
	v_pk_fma_f32 v[244:245], v[186:187], v[168:169], v[244:245] op_sel_hi:[0,1,1]
	v_pk_fma_f32 v[246:247], v[186:187], v[170:171], v[246:247] op_sel_hi:[0,1,1]
	v_pk_fma_f32 v[248:249], v[186:187], v[172:173], v[248:249] op_sel_hi:[0,1,1]
	v_cvt_pk_f32_fp8_e32 v[166:167], v48
	v_cvt_pk_f32_fp8_sdwa v[168:169], v48 src0_sel:WORD_1
	v_cvt_pk_f32_fp8_e32 v[170:171], v49
	v_cvt_pk_f32_fp8_sdwa v[172:173], v49 src0_sel:WORD_1
	v_pk_fma_f32 v[242:243], v[186:187], v[166:167], v[242:243] op_sel:[1,0,0]
	v_pk_fma_f32 v[244:245], v[186:187], v[168:169], v[244:245] op_sel:[1,0,0]
	v_pk_fma_f32 v[246:247], v[186:187], v[170:171], v[246:247] op_sel:[1,0,0]
	v_pk_fma_f32 v[248:249], v[186:187], v[172:173], v[248:249] op_sel:[1,0,0]
	v_cvt_pk_f32_fp8_e32 v[166:167], v50
	v_cvt_pk_f32_fp8_sdwa v[168:169], v50 src0_sel:WORD_1
	v_cvt_pk_f32_fp8_e32 v[170:171], v51
	v_cvt_pk_f32_fp8_sdwa v[172:173], v51 src0_sel:WORD_1
	v_pk_fma_f32 v[242:243], v[188:189], v[166:167], v[242:243] op_sel_hi:[0,1,1]
	v_pk_fma_f32 v[244:245], v[188:189], v[168:169], v[244:245] op_sel_hi:[0,1,1]
	v_pk_fma_f32 v[246:247], v[188:189], v[170:171], v[246:247] op_sel_hi:[0,1,1]
	v_pk_fma_f32 v[248:249], v[188:189], v[172:173], v[248:249] op_sel_hi:[0,1,1]
	v_cvt_pk_f32_fp8_e32 v[166:167], v52
	v_cvt_pk_f32_fp8_sdwa v[168:169], v52 src0_sel:WORD_1
	v_cvt_pk_f32_fp8_e32 v[170:171], v53
	v_cvt_pk_f32_fp8_sdwa v[172:173], v53 src0_sel:WORD_1
	v_pk_fma_f32 v[242:243], v[188:189], v[166:167], v[242:243] op_sel:[1,0,0]
	v_pk_fma_f32 v[244:245], v[188:189], v[168:169], v[244:245] op_sel:[1,0,0]
	v_pk_fma_f32 v[246:247], v[188:189], v[170:171], v[246:247] op_sel:[1,0,0]
	v_pk_fma_f32 v[248:249], v[188:189], v[172:173], v[248:249] op_sel:[1,0,0]
	v_cvt_pk_f32_fp8_e32 v[166:167], v54
	v_cvt_pk_f32_fp8_sdwa v[168:169], v54 src0_sel:WORD_1
	v_cvt_pk_f32_fp8_e32 v[170:171], v55
	v_cvt_pk_f32_fp8_sdwa v[172:173], v55 src0_sel:WORD_1
	v_pk_fma_f32 v[242:243], v[190:191], v[166:167], v[242:243] op_sel_hi:[0,1,1]
	v_pk_fma_f32 v[244:245], v[190:191], v[168:169], v[244:245] op_sel_hi:[0,1,1]
	v_pk_fma_f32 v[246:247], v[190:191], v[170:171], v[246:247] op_sel_hi:[0,1,1]
	v_pk_fma_f32 v[248:249], v[190:191], v[172:173], v[248:249] op_sel_hi:[0,1,1]
	v_cvt_pk_f32_fp8_e32 v[166:167], v56
	v_cvt_pk_f32_fp8_sdwa v[168:169], v56 src0_sel:WORD_1
	v_cvt_pk_f32_fp8_e32 v[170:171], v57
	v_cvt_pk_f32_fp8_sdwa v[172:173], v57 src0_sel:WORD_1
	v_pk_fma_f32 v[242:243], v[190:191], v[166:167], v[242:243] op_sel:[1,0,0]
	v_pk_fma_f32 v[244:245], v[190:191], v[168:169], v[244:245] op_sel:[1,0,0]
	v_pk_fma_f32 v[246:247], v[190:191], v[170:171], v[246:247] op_sel:[1,0,0]
	v_pk_fma_f32 v[248:249], v[190:191], v[172:173], v[248:249] op_sel:[1,0,0]
	v_cvt_pk_f32_fp8_e32 v[166:167], v58
	v_cvt_pk_f32_fp8_sdwa v[168:169], v58 src0_sel:WORD_1
	v_cvt_pk_f32_fp8_e32 v[170:171], v59
	v_cvt_pk_f32_fp8_sdwa v[172:173], v59 src0_sel:WORD_1
	v_pk_fma_f32 v[242:243], v[192:193], v[166:167], v[242:243] op_sel_hi:[0,1,1]
	v_pk_fma_f32 v[244:245], v[192:193], v[168:169], v[244:245] op_sel_hi:[0,1,1]
	v_pk_fma_f32 v[246:247], v[192:193], v[170:171], v[246:247] op_sel_hi:[0,1,1]
	v_pk_fma_f32 v[248:249], v[192:193], v[172:173], v[248:249] op_sel_hi:[0,1,1]
	v_cvt_pk_f32_fp8_e32 v[166:167], v60
	v_cvt_pk_f32_fp8_sdwa v[168:169], v60 src0_sel:WORD_1
	v_cvt_pk_f32_fp8_e32 v[170:171], v61
	v_cvt_pk_f32_fp8_sdwa v[172:173], v61 src0_sel:WORD_1
	v_pk_fma_f32 v[242:243], v[192:193], v[166:167], v[242:243] op_sel:[1,0,0]
	v_pk_fma_f32 v[244:245], v[192:193], v[168:169], v[244:245] op_sel:[1,0,0]
	v_pk_fma_f32 v[246:247], v[192:193], v[170:171], v[246:247] op_sel:[1,0,0]
	v_pk_fma_f32 v[248:249], v[192:193], v[172:173], v[248:249] op_sel:[1,0,0]
	v_cvt_pk_f32_fp8_e32 v[166:167], v62
	v_cvt_pk_f32_fp8_sdwa v[168:169], v62 src0_sel:WORD_1
	v_cvt_pk_f32_fp8_e32 v[170:171], v63
	v_cvt_pk_f32_fp8_sdwa v[172:173], v63 src0_sel:WORD_1
	v_pk_fma_f32 v[242:243], v[194:195], v[166:167], v[242:243] op_sel_hi:[0,1,1]
	v_pk_fma_f32 v[244:245], v[194:195], v[168:169], v[244:245] op_sel_hi:[0,1,1]
	v_pk_fma_f32 v[246:247], v[194:195], v[170:171], v[246:247] op_sel_hi:[0,1,1]
	v_pk_fma_f32 v[248:249], v[194:195], v[172:173], v[248:249] op_sel_hi:[0,1,1]
	v_cvt_pk_f32_fp8_e32 v[166:167], v64
	v_cvt_pk_f32_fp8_sdwa v[168:169], v64 src0_sel:WORD_1
	v_cvt_pk_f32_fp8_e32 v[170:171], v65
	v_cvt_pk_f32_fp8_sdwa v[172:173], v65 src0_sel:WORD_1
	v_pk_fma_f32 v[242:243], v[194:195], v[166:167], v[242:243] op_sel:[1,0,0]
	v_pk_fma_f32 v[244:245], v[194:195], v[168:169], v[244:245] op_sel:[1,0,0]
	v_pk_fma_f32 v[246:247], v[194:195], v[170:171], v[246:247] op_sel:[1,0,0]
	v_pk_fma_f32 v[248:249], v[194:195], v[172:173], v[248:249] op_sel:[1,0,0]
	s_waitcnt lgkmcnt(0)
	v_add_u32_e32 v120, v104, v226
	global_load_dwordx2 v[34:35], v120, s[50:51]
	v_add_u32_e32 v122, v104, v227
	global_load_dwordx2 v[36:37], v122, s[50:51]
	v_add_u32_e32 v124, v104, v228
	global_load_dwordx2 v[38:39], v124, s[50:51]
	v_add_u32_e32 v126, v104, v229
	global_load_dwordx2 v[40:41], v126, s[50:51]
	v_add_u32_e32 v120, v104, v230
	global_load_dwordx2 v[42:43], v120, s[50:51]
	v_add_u32_e32 v122, v104, v231
	global_load_dwordx2 v[44:45], v122, s[50:51]
	v_add_u32_e32 v124, v104, v232
	global_load_dwordx2 v[46:47], v124, s[50:51]
	v_add_u32_e32 v126, v104, v233
	global_load_dwordx2 v[48:49], v126, s[50:51]
	v_add_u32_e32 v120, v104, v234
	global_load_dwordx2 v[50:51], v120, s[50:51]
	v_add_u32_e32 v122, v104, v235
	global_load_dwordx2 v[52:53], v122, s[50:51]
	v_add_u32_e32 v124, v104, v236
	global_load_dwordx2 v[54:55], v124, s[50:51]
	v_add_u32_e32 v126, v104, v237
	global_load_dwordx2 v[56:57], v126, s[50:51]
	v_add_u32_e32 v120, v104, v238
	global_load_dwordx2 v[58:59], v120, s[50:51]
	v_add_u32_e32 v122, v104, v239
	global_load_dwordx2 v[60:61], v122, s[50:51]
	v_add_u32_e32 v124, v104, v240
	global_load_dwordx2 v[62:63], v124, s[50:51]
	v_add_u32_e32 v126, v104, v241
	global_load_dwordx2 v[64:65], v126, s[50:51]
	ds_read_b128 v[226:229], v106 offset:2432
	ds_read_b128 v[230:233], v106 offset:2448
	ds_read_b128 v[234:237], v106 offset:2464
	ds_read_b128 v[238:241], v106 offset:2480
	ds_read_b128 v[180:183], v106 offset:8448
	ds_read_b128 v[184:187], v106 offset:8464
	ds_read_b128 v[188:191], v106 offset:8480
	ds_read_b128 v[192:195], v106 offset:8496
	s_waitcnt vmcnt(32)
	v_cvt_pk_f32_fp8_e32 v[166:167], v134
	v_cvt_pk_f32_fp8_sdwa v[168:169], v134 src0_sel:WORD_1
	v_cvt_pk_f32_fp8_e32 v[170:171], v135
	v_cvt_pk_f32_fp8_sdwa v[172:173], v135 src0_sel:WORD_1
	v_pk_fma_f32 v[242:243], v[196:197], v[166:167], v[242:243] op_sel_hi:[0,1,1]
	v_pk_fma_f32 v[244:245], v[196:197], v[168:169], v[244:245] op_sel_hi:[0,1,1]
	v_pk_fma_f32 v[246:247], v[196:197], v[170:171], v[246:247] op_sel_hi:[0,1,1]
	v_pk_fma_f32 v[248:249], v[196:197], v[172:173], v[248:249] op_sel_hi:[0,1,1]
	v_cvt_pk_f32_fp8_e32 v[166:167], v136
	v_cvt_pk_f32_fp8_sdwa v[168:169], v136 src0_sel:WORD_1
	v_cvt_pk_f32_fp8_e32 v[170:171], v137
	v_cvt_pk_f32_fp8_sdwa v[172:173], v137 src0_sel:WORD_1
	v_pk_fma_f32 v[242:243], v[196:197], v[166:167], v[242:243] op_sel:[1,0,0]
	v_pk_fma_f32 v[244:245], v[196:197], v[168:169], v[244:245] op_sel:[1,0,0]
	v_pk_fma_f32 v[246:247], v[196:197], v[170:171], v[246:247] op_sel:[1,0,0]
	v_pk_fma_f32 v[248:249], v[196:197], v[172:173], v[248:249] op_sel:[1,0,0]
	v_cvt_pk_f32_fp8_e32 v[166:167], v138
	v_cvt_pk_f32_fp8_sdwa v[168:169], v138 src0_sel:WORD_1
	v_cvt_pk_f32_fp8_e32 v[170:171], v139
	v_cvt_pk_f32_fp8_sdwa v[172:173], v139 src0_sel:WORD_1
	v_pk_fma_f32 v[242:243], v[198:199], v[166:167], v[242:243] op_sel_hi:[0,1,1]
	v_pk_fma_f32 v[244:245], v[198:199], v[168:169], v[244:245] op_sel_hi:[0,1,1]
	v_pk_fma_f32 v[246:247], v[198:199], v[170:171], v[246:247] op_sel_hi:[0,1,1]
	v_pk_fma_f32 v[248:249], v[198:199], v[172:173], v[248:249] op_sel_hi:[0,1,1]
	v_cvt_pk_f32_fp8_e32 v[166:167], v140
	v_cvt_pk_f32_fp8_sdwa v[168:169], v140 src0_sel:WORD_1
	v_cvt_pk_f32_fp8_e32 v[170:171], v141
	v_cvt_pk_f32_fp8_sdwa v[172:173], v141 src0_sel:WORD_1
	v_pk_fma_f32 v[242:243], v[198:199], v[166:167], v[242:243] op_sel:[1,0,0]
	v_pk_fma_f32 v[244:245], v[198:199], v[168:169], v[244:245] op_sel:[1,0,0]
	v_pk_fma_f32 v[246:247], v[198:199], v[170:171], v[246:247] op_sel:[1,0,0]
	v_pk_fma_f32 v[248:249], v[198:199], v[172:173], v[248:249] op_sel:[1,0,0]
	v_cvt_pk_f32_fp8_e32 v[166:167], v142
	v_cvt_pk_f32_fp8_sdwa v[168:169], v142 src0_sel:WORD_1
	v_cvt_pk_f32_fp8_e32 v[170:171], v143
	v_cvt_pk_f32_fp8_sdwa v[172:173], v143 src0_sel:WORD_1
	v_pk_fma_f32 v[242:243], v[200:201], v[166:167], v[242:243] op_sel_hi:[0,1,1]
	v_pk_fma_f32 v[244:245], v[200:201], v[168:169], v[244:245] op_sel_hi:[0,1,1]
	v_pk_fma_f32 v[246:247], v[200:201], v[170:171], v[246:247] op_sel_hi:[0,1,1]
	v_pk_fma_f32 v[248:249], v[200:201], v[172:173], v[248:249] op_sel_hi:[0,1,1]
	v_cvt_pk_f32_fp8_e32 v[166:167], v144
	v_cvt_pk_f32_fp8_sdwa v[168:169], v144 src0_sel:WORD_1
	v_cvt_pk_f32_fp8_e32 v[170:171], v145
	v_cvt_pk_f32_fp8_sdwa v[172:173], v145 src0_sel:WORD_1
	v_pk_fma_f32 v[242:243], v[200:201], v[166:167], v[242:243] op_sel:[1,0,0]
	v_pk_fma_f32 v[244:245], v[200:201], v[168:169], v[244:245] op_sel:[1,0,0]
	v_pk_fma_f32 v[246:247], v[200:201], v[170:171], v[246:247] op_sel:[1,0,0]
	v_pk_fma_f32 v[248:249], v[200:201], v[172:173], v[248:249] op_sel:[1,0,0]
	v_cvt_pk_f32_fp8_e32 v[166:167], v146
	v_cvt_pk_f32_fp8_sdwa v[168:169], v146 src0_sel:WORD_1
	v_cvt_pk_f32_fp8_e32 v[170:171], v147
	v_cvt_pk_f32_fp8_sdwa v[172:173], v147 src0_sel:WORD_1
	v_pk_fma_f32 v[242:243], v[202:203], v[166:167], v[242:243] op_sel_hi:[0,1,1]
	v_pk_fma_f32 v[244:245], v[202:203], v[168:169], v[244:245] op_sel_hi:[0,1,1]
	v_pk_fma_f32 v[246:247], v[202:203], v[170:171], v[246:247] op_sel_hi:[0,1,1]
	v_pk_fma_f32 v[248:249], v[202:203], v[172:173], v[248:249] op_sel_hi:[0,1,1]
	v_cvt_pk_f32_fp8_e32 v[166:167], v148
	v_cvt_pk_f32_fp8_sdwa v[168:169], v148 src0_sel:WORD_1
	v_cvt_pk_f32_fp8_e32 v[170:171], v149
	v_cvt_pk_f32_fp8_sdwa v[172:173], v149 src0_sel:WORD_1
	v_pk_fma_f32 v[242:243], v[202:203], v[166:167], v[242:243] op_sel:[1,0,0]
	v_pk_fma_f32 v[244:245], v[202:203], v[168:169], v[244:245] op_sel:[1,0,0]
	v_pk_fma_f32 v[246:247], v[202:203], v[170:171], v[246:247] op_sel:[1,0,0]
	v_pk_fma_f32 v[248:249], v[202:203], v[172:173], v[248:249] op_sel:[1,0,0]
	v_cvt_pk_f32_fp8_e32 v[166:167], v150
	v_cvt_pk_f32_fp8_sdwa v[168:169], v150 src0_sel:WORD_1
	v_cvt_pk_f32_fp8_e32 v[170:171], v151
	v_cvt_pk_f32_fp8_sdwa v[172:173], v151 src0_sel:WORD_1
	v_pk_fma_f32 v[242:243], v[204:205], v[166:167], v[242:243] op_sel_hi:[0,1,1]
	v_pk_fma_f32 v[244:245], v[204:205], v[168:169], v[244:245] op_sel_hi:[0,1,1]
	v_pk_fma_f32 v[246:247], v[204:205], v[170:171], v[246:247] op_sel_hi:[0,1,1]
	v_pk_fma_f32 v[248:249], v[204:205], v[172:173], v[248:249] op_sel_hi:[0,1,1]
	v_cvt_pk_f32_fp8_e32 v[166:167], v152
	v_cvt_pk_f32_fp8_sdwa v[168:169], v152 src0_sel:WORD_1
	v_cvt_pk_f32_fp8_e32 v[170:171], v153
	v_cvt_pk_f32_fp8_sdwa v[172:173], v153 src0_sel:WORD_1
	v_pk_fma_f32 v[242:243], v[204:205], v[166:167], v[242:243] op_sel:[1,0,0]
	v_pk_fma_f32 v[244:245], v[204:205], v[168:169], v[244:245] op_sel:[1,0,0]
	v_pk_fma_f32 v[246:247], v[204:205], v[170:171], v[246:247] op_sel:[1,0,0]
	v_pk_fma_f32 v[248:249], v[204:205], v[172:173], v[248:249] op_sel:[1,0,0]
	v_cvt_pk_f32_fp8_e32 v[166:167], v154
	v_cvt_pk_f32_fp8_sdwa v[168:169], v154 src0_sel:WORD_1
	v_cvt_pk_f32_fp8_e32 v[170:171], v155
	v_cvt_pk_f32_fp8_sdwa v[172:173], v155 src0_sel:WORD_1
	v_pk_fma_f32 v[242:243], v[206:207], v[166:167], v[242:243] op_sel_hi:[0,1,1]
	v_pk_fma_f32 v[244:245], v[206:207], v[168:169], v[244:245] op_sel_hi:[0,1,1]
	v_pk_fma_f32 v[246:247], v[206:207], v[170:171], v[246:247] op_sel_hi:[0,1,1]
	v_pk_fma_f32 v[248:249], v[206:207], v[172:173], v[248:249] op_sel_hi:[0,1,1]
	v_cvt_pk_f32_fp8_e32 v[166:167], v156
	v_cvt_pk_f32_fp8_sdwa v[168:169], v156 src0_sel:WORD_1
	v_cvt_pk_f32_fp8_e32 v[170:171], v157
	v_cvt_pk_f32_fp8_sdwa v[172:173], v157 src0_sel:WORD_1
	v_pk_fma_f32 v[242:243], v[206:207], v[166:167], v[242:243] op_sel:[1,0,0]
	v_pk_fma_f32 v[244:245], v[206:207], v[168:169], v[244:245] op_sel:[1,0,0]
	v_pk_fma_f32 v[246:247], v[206:207], v[170:171], v[246:247] op_sel:[1,0,0]
	v_pk_fma_f32 v[248:249], v[206:207], v[172:173], v[248:249] op_sel:[1,0,0]
	v_cvt_pk_f32_fp8_e32 v[166:167], v158
	v_cvt_pk_f32_fp8_sdwa v[168:169], v158 src0_sel:WORD_1
	v_cvt_pk_f32_fp8_e32 v[170:171], v159
	v_cvt_pk_f32_fp8_sdwa v[172:173], v159 src0_sel:WORD_1
	v_pk_fma_f32 v[242:243], v[216:217], v[166:167], v[242:243] op_sel_hi:[0,1,1]
	v_pk_fma_f32 v[244:245], v[216:217], v[168:169], v[244:245] op_sel_hi:[0,1,1]
	v_pk_fma_f32 v[246:247], v[216:217], v[170:171], v[246:247] op_sel_hi:[0,1,1]
	v_pk_fma_f32 v[248:249], v[216:217], v[172:173], v[248:249] op_sel_hi:[0,1,1]
	v_cvt_pk_f32_fp8_e32 v[166:167], v160
	v_cvt_pk_f32_fp8_sdwa v[168:169], v160 src0_sel:WORD_1
	v_cvt_pk_f32_fp8_e32 v[170:171], v161
	v_cvt_pk_f32_fp8_sdwa v[172:173], v161 src0_sel:WORD_1
	v_pk_fma_f32 v[242:243], v[216:217], v[166:167], v[242:243] op_sel:[1,0,0]
	v_pk_fma_f32 v[244:245], v[216:217], v[168:169], v[244:245] op_sel:[1,0,0]
	v_pk_fma_f32 v[246:247], v[216:217], v[170:171], v[246:247] op_sel:[1,0,0]
	v_pk_fma_f32 v[248:249], v[216:217], v[172:173], v[248:249] op_sel:[1,0,0]
	v_cvt_pk_f32_fp8_e32 v[166:167], v162
	v_cvt_pk_f32_fp8_sdwa v[168:169], v162 src0_sel:WORD_1
	v_cvt_pk_f32_fp8_e32 v[170:171], v163
	v_cvt_pk_f32_fp8_sdwa v[172:173], v163 src0_sel:WORD_1
	v_pk_fma_f32 v[242:243], v[218:219], v[166:167], v[242:243] op_sel_hi:[0,1,1]
	v_pk_fma_f32 v[244:245], v[218:219], v[168:169], v[244:245] op_sel_hi:[0,1,1]
	v_pk_fma_f32 v[246:247], v[218:219], v[170:171], v[246:247] op_sel_hi:[0,1,1]
	v_pk_fma_f32 v[248:249], v[218:219], v[172:173], v[248:249] op_sel_hi:[0,1,1]
	v_cvt_pk_f32_fp8_e32 v[166:167], v164
	v_cvt_pk_f32_fp8_sdwa v[168:169], v164 src0_sel:WORD_1
	v_cvt_pk_f32_fp8_e32 v[170:171], v165
	v_cvt_pk_f32_fp8_sdwa v[172:173], v165 src0_sel:WORD_1
	v_pk_fma_f32 v[242:243], v[218:219], v[166:167], v[242:243] op_sel:[1,0,0]
	v_pk_fma_f32 v[244:245], v[218:219], v[168:169], v[244:245] op_sel:[1,0,0]
	v_pk_fma_f32 v[246:247], v[218:219], v[170:171], v[246:247] op_sel:[1,0,0]
	v_pk_fma_f32 v[248:249], v[218:219], v[172:173], v[248:249] op_sel:[1,0,0]
	s_waitcnt lgkmcnt(0)
	v_add_u32_e32 v120, v104, v226
	global_load_dwordx2 v[134:135], v120, s[50:51]
	v_add_u32_e32 v122, v104, v227
	global_load_dwordx2 v[136:137], v122, s[50:51]
	v_add_u32_e32 v124, v104, v228
	global_load_dwordx2 v[138:139], v124, s[50:51]
	v_add_u32_e32 v126, v104, v229
	global_load_dwordx2 v[140:141], v126, s[50:51]
	v_add_u32_e32 v120, v104, v230
	global_load_dwordx2 v[142:143], v120, s[50:51]
	v_add_u32_e32 v122, v104, v231
	global_load_dwordx2 v[144:145], v122, s[50:51]
	v_add_u32_e32 v124, v104, v232
	global_load_dwordx2 v[146:147], v124, s[50:51]
	v_add_u32_e32 v126, v104, v233
	global_load_dwordx2 v[148:149], v126, s[50:51]
	v_add_u32_e32 v120, v104, v234
	global_load_dwordx2 v[150:151], v120, s[50:51]
	v_add_u32_e32 v122, v104, v235
	global_load_dwordx2 v[152:153], v122, s[50:51]
	v_add_u32_e32 v124, v104, v236
	global_load_dwordx2 v[154:155], v124, s[50:51]
	v_add_u32_e32 v126, v104, v237
	global_load_dwordx2 v[156:157], v126, s[50:51]
	v_add_u32_e32 v120, v104, v238
	global_load_dwordx2 v[158:159], v120, s[50:51]
	v_add_u32_e32 v122, v104, v239
	global_load_dwordx2 v[160:161], v122, s[50:51]
	v_add_u32_e32 v124, v104, v240
	global_load_dwordx2 v[162:163], v124, s[50:51]
	v_add_u32_e32 v126, v104, v241
	global_load_dwordx2 v[164:165], v126, s[50:51]
	ds_read_b128 v[226:229], v106 offset:2496
	ds_read_b128 v[230:233], v106 offset:2512
	ds_read_b128 v[234:237], v106 offset:2528
	ds_read_b128 v[238:241], v106 offset:2544
	ds_read_b128 v[196:199], v106 offset:8512
	ds_read_b128 v[200:203], v106 offset:8528
	ds_read_b128 v[204:207], v106 offset:8544
	ds_read_b128 v[216:219], v106 offset:8560
	s_waitcnt vmcnt(32)
	v_cvt_pk_f32_fp8_e32 v[166:167], v2
	v_cvt_pk_f32_fp8_sdwa v[168:169], v2 src0_sel:WORD_1
	v_cvt_pk_f32_fp8_e32 v[170:171], v3
	v_cvt_pk_f32_fp8_sdwa v[172:173], v3 src0_sel:WORD_1
	v_pk_fma_f32 v[242:243], v[180:181], v[166:167], v[242:243] op_sel_hi:[0,1,1]
	v_pk_fma_f32 v[244:245], v[180:181], v[168:169], v[244:245] op_sel_hi:[0,1,1]
	v_pk_fma_f32 v[246:247], v[180:181], v[170:171], v[246:247] op_sel_hi:[0,1,1]
	v_pk_fma_f32 v[248:249], v[180:181], v[172:173], v[248:249] op_sel_hi:[0,1,1]
	v_cvt_pk_f32_fp8_e32 v[166:167], v4
	v_cvt_pk_f32_fp8_sdwa v[168:169], v4 src0_sel:WORD_1
	v_cvt_pk_f32_fp8_e32 v[170:171], v5
	v_cvt_pk_f32_fp8_sdwa v[172:173], v5 src0_sel:WORD_1
	v_pk_fma_f32 v[242:243], v[180:181], v[166:167], v[242:243] op_sel:[1,0,0]
	v_pk_fma_f32 v[244:245], v[180:181], v[168:169], v[244:245] op_sel:[1,0,0]
	v_pk_fma_f32 v[246:247], v[180:181], v[170:171], v[246:247] op_sel:[1,0,0]
	v_pk_fma_f32 v[248:249], v[180:181], v[172:173], v[248:249] op_sel:[1,0,0]
	v_cvt_pk_f32_fp8_e32 v[166:167], v6
	v_cvt_pk_f32_fp8_sdwa v[168:169], v6 src0_sel:WORD_1
	v_cvt_pk_f32_fp8_e32 v[170:171], v7
	v_cvt_pk_f32_fp8_sdwa v[172:173], v7 src0_sel:WORD_1
	v_pk_fma_f32 v[242:243], v[182:183], v[166:167], v[242:243] op_sel_hi:[0,1,1]
	v_pk_fma_f32 v[244:245], v[182:183], v[168:169], v[244:245] op_sel_hi:[0,1,1]
	v_pk_fma_f32 v[246:247], v[182:183], v[170:171], v[246:247] op_sel_hi:[0,1,1]
	v_pk_fma_f32 v[248:249], v[182:183], v[172:173], v[248:249] op_sel_hi:[0,1,1]
	v_cvt_pk_f32_fp8_e32 v[166:167], v8
	v_cvt_pk_f32_fp8_sdwa v[168:169], v8 src0_sel:WORD_1
	v_cvt_pk_f32_fp8_e32 v[170:171], v9
	v_cvt_pk_f32_fp8_sdwa v[172:173], v9 src0_sel:WORD_1
	v_pk_fma_f32 v[242:243], v[182:183], v[166:167], v[242:243] op_sel:[1,0,0]
	v_pk_fma_f32 v[244:245], v[182:183], v[168:169], v[244:245] op_sel:[1,0,0]
	v_pk_fma_f32 v[246:247], v[182:183], v[170:171], v[246:247] op_sel:[1,0,0]
	v_pk_fma_f32 v[248:249], v[182:183], v[172:173], v[248:249] op_sel:[1,0,0]
	v_cvt_pk_f32_fp8_e32 v[166:167], v10
	v_cvt_pk_f32_fp8_sdwa v[168:169], v10 src0_sel:WORD_1
	v_cvt_pk_f32_fp8_e32 v[170:171], v11
	v_cvt_pk_f32_fp8_sdwa v[172:173], v11 src0_sel:WORD_1
	v_pk_fma_f32 v[242:243], v[184:185], v[166:167], v[242:243] op_sel_hi:[0,1,1]
	v_pk_fma_f32 v[244:245], v[184:185], v[168:169], v[244:245] op_sel_hi:[0,1,1]
	v_pk_fma_f32 v[246:247], v[184:185], v[170:171], v[246:247] op_sel_hi:[0,1,1]
	v_pk_fma_f32 v[248:249], v[184:185], v[172:173], v[248:249] op_sel_hi:[0,1,1]
	v_cvt_pk_f32_fp8_e32 v[166:167], v12
	v_cvt_pk_f32_fp8_sdwa v[168:169], v12 src0_sel:WORD_1
	v_cvt_pk_f32_fp8_e32 v[170:171], v13
	v_cvt_pk_f32_fp8_sdwa v[172:173], v13 src0_sel:WORD_1
	v_pk_fma_f32 v[242:243], v[184:185], v[166:167], v[242:243] op_sel:[1,0,0]
	v_pk_fma_f32 v[244:245], v[184:185], v[168:169], v[244:245] op_sel:[1,0,0]
	v_pk_fma_f32 v[246:247], v[184:185], v[170:171], v[246:247] op_sel:[1,0,0]
	v_pk_fma_f32 v[248:249], v[184:185], v[172:173], v[248:249] op_sel:[1,0,0]
	v_cvt_pk_f32_fp8_e32 v[166:167], v14
	v_cvt_pk_f32_fp8_sdwa v[168:169], v14 src0_sel:WORD_1
	v_cvt_pk_f32_fp8_e32 v[170:171], v15
	v_cvt_pk_f32_fp8_sdwa v[172:173], v15 src0_sel:WORD_1
	v_pk_fma_f32 v[242:243], v[186:187], v[166:167], v[242:243] op_sel_hi:[0,1,1]
	v_pk_fma_f32 v[244:245], v[186:187], v[168:169], v[244:245] op_sel_hi:[0,1,1]
	v_pk_fma_f32 v[246:247], v[186:187], v[170:171], v[246:247] op_sel_hi:[0,1,1]
	v_pk_fma_f32 v[248:249], v[186:187], v[172:173], v[248:249] op_sel_hi:[0,1,1]
	v_cvt_pk_f32_fp8_e32 v[166:167], v16
	v_cvt_pk_f32_fp8_sdwa v[168:169], v16 src0_sel:WORD_1
	v_cvt_pk_f32_fp8_e32 v[170:171], v17
	v_cvt_pk_f32_fp8_sdwa v[172:173], v17 src0_sel:WORD_1
	v_pk_fma_f32 v[242:243], v[186:187], v[166:167], v[242:243] op_sel:[1,0,0]
	v_pk_fma_f32 v[244:245], v[186:187], v[168:169], v[244:245] op_sel:[1,0,0]
	v_pk_fma_f32 v[246:247], v[186:187], v[170:171], v[246:247] op_sel:[1,0,0]
	v_pk_fma_f32 v[248:249], v[186:187], v[172:173], v[248:249] op_sel:[1,0,0]
	v_cvt_pk_f32_fp8_e32 v[166:167], v18
	v_cvt_pk_f32_fp8_sdwa v[168:169], v18 src0_sel:WORD_1
	v_cvt_pk_f32_fp8_e32 v[170:171], v19
	v_cvt_pk_f32_fp8_sdwa v[172:173], v19 src0_sel:WORD_1
	v_pk_fma_f32 v[242:243], v[188:189], v[166:167], v[242:243] op_sel_hi:[0,1,1]
	v_pk_fma_f32 v[244:245], v[188:189], v[168:169], v[244:245] op_sel_hi:[0,1,1]
	v_pk_fma_f32 v[246:247], v[188:189], v[170:171], v[246:247] op_sel_hi:[0,1,1]
	v_pk_fma_f32 v[248:249], v[188:189], v[172:173], v[248:249] op_sel_hi:[0,1,1]
	v_cvt_pk_f32_fp8_e32 v[166:167], v20
	v_cvt_pk_f32_fp8_sdwa v[168:169], v20 src0_sel:WORD_1
	v_cvt_pk_f32_fp8_e32 v[170:171], v21
	v_cvt_pk_f32_fp8_sdwa v[172:173], v21 src0_sel:WORD_1
	v_pk_fma_f32 v[242:243], v[188:189], v[166:167], v[242:243] op_sel:[1,0,0]
	v_pk_fma_f32 v[244:245], v[188:189], v[168:169], v[244:245] op_sel:[1,0,0]
	v_pk_fma_f32 v[246:247], v[188:189], v[170:171], v[246:247] op_sel:[1,0,0]
	v_pk_fma_f32 v[248:249], v[188:189], v[172:173], v[248:249] op_sel:[1,0,0]
	v_cvt_pk_f32_fp8_e32 v[166:167], v22
	v_cvt_pk_f32_fp8_sdwa v[168:169], v22 src0_sel:WORD_1
	v_cvt_pk_f32_fp8_e32 v[170:171], v23
	v_cvt_pk_f32_fp8_sdwa v[172:173], v23 src0_sel:WORD_1
	v_pk_fma_f32 v[242:243], v[190:191], v[166:167], v[242:243] op_sel_hi:[0,1,1]
	v_pk_fma_f32 v[244:245], v[190:191], v[168:169], v[244:245] op_sel_hi:[0,1,1]
	v_pk_fma_f32 v[246:247], v[190:191], v[170:171], v[246:247] op_sel_hi:[0,1,1]
	v_pk_fma_f32 v[248:249], v[190:191], v[172:173], v[248:249] op_sel_hi:[0,1,1]
	v_cvt_pk_f32_fp8_e32 v[166:167], v24
	v_cvt_pk_f32_fp8_sdwa v[168:169], v24 src0_sel:WORD_1
	v_cvt_pk_f32_fp8_e32 v[170:171], v25
	v_cvt_pk_f32_fp8_sdwa v[172:173], v25 src0_sel:WORD_1
	v_pk_fma_f32 v[242:243], v[190:191], v[166:167], v[242:243] op_sel:[1,0,0]
	v_pk_fma_f32 v[244:245], v[190:191], v[168:169], v[244:245] op_sel:[1,0,0]
	v_pk_fma_f32 v[246:247], v[190:191], v[170:171], v[246:247] op_sel:[1,0,0]
	v_pk_fma_f32 v[248:249], v[190:191], v[172:173], v[248:249] op_sel:[1,0,0]
	v_cvt_pk_f32_fp8_e32 v[166:167], v26
	v_cvt_pk_f32_fp8_sdwa v[168:169], v26 src0_sel:WORD_1
	v_cvt_pk_f32_fp8_e32 v[170:171], v27
	v_cvt_pk_f32_fp8_sdwa v[172:173], v27 src0_sel:WORD_1
	v_pk_fma_f32 v[242:243], v[192:193], v[166:167], v[242:243] op_sel_hi:[0,1,1]
	v_pk_fma_f32 v[244:245], v[192:193], v[168:169], v[244:245] op_sel_hi:[0,1,1]
	v_pk_fma_f32 v[246:247], v[192:193], v[170:171], v[246:247] op_sel_hi:[0,1,1]
	v_pk_fma_f32 v[248:249], v[192:193], v[172:173], v[248:249] op_sel_hi:[0,1,1]
	v_cvt_pk_f32_fp8_e32 v[166:167], v28
	v_cvt_pk_f32_fp8_sdwa v[168:169], v28 src0_sel:WORD_1
	v_cvt_pk_f32_fp8_e32 v[170:171], v29
	v_cvt_pk_f32_fp8_sdwa v[172:173], v29 src0_sel:WORD_1
	v_pk_fma_f32 v[242:243], v[192:193], v[166:167], v[242:243] op_sel:[1,0,0]
	v_pk_fma_f32 v[244:245], v[192:193], v[168:169], v[244:245] op_sel:[1,0,0]
	v_pk_fma_f32 v[246:247], v[192:193], v[170:171], v[246:247] op_sel:[1,0,0]
	v_pk_fma_f32 v[248:249], v[192:193], v[172:173], v[248:249] op_sel:[1,0,0]
	v_cvt_pk_f32_fp8_e32 v[166:167], v30
	v_cvt_pk_f32_fp8_sdwa v[168:169], v30 src0_sel:WORD_1
	v_cvt_pk_f32_fp8_e32 v[170:171], v31
	v_cvt_pk_f32_fp8_sdwa v[172:173], v31 src0_sel:WORD_1
	v_pk_fma_f32 v[242:243], v[194:195], v[166:167], v[242:243] op_sel_hi:[0,1,1]
	v_pk_fma_f32 v[244:245], v[194:195], v[168:169], v[244:245] op_sel_hi:[0,1,1]
	v_pk_fma_f32 v[246:247], v[194:195], v[170:171], v[246:247] op_sel_hi:[0,1,1]
	v_pk_fma_f32 v[248:249], v[194:195], v[172:173], v[248:249] op_sel_hi:[0,1,1]
	v_cvt_pk_f32_fp8_e32 v[166:167], v32
	v_cvt_pk_f32_fp8_sdwa v[168:169], v32 src0_sel:WORD_1
	v_cvt_pk_f32_fp8_e32 v[170:171], v33
	v_cvt_pk_f32_fp8_sdwa v[172:173], v33 src0_sel:WORD_1
	v_pk_fma_f32 v[242:243], v[194:195], v[166:167], v[242:243] op_sel:[1,0,0]
	v_pk_fma_f32 v[244:245], v[194:195], v[168:169], v[244:245] op_sel:[1,0,0]
	v_pk_fma_f32 v[246:247], v[194:195], v[170:171], v[246:247] op_sel:[1,0,0]
	v_pk_fma_f32 v[248:249], v[194:195], v[172:173], v[248:249] op_sel:[1,0,0]
	s_waitcnt lgkmcnt(0)
	v_add_u32_e32 v120, v104, v226
	global_load_dwordx2 v[2:3], v120, s[50:51]
	v_add_u32_e32 v122, v104, v227
	global_load_dwordx2 v[4:5], v122, s[50:51]
	v_add_u32_e32 v124, v104, v228
	global_load_dwordx2 v[6:7], v124, s[50:51]
	v_add_u32_e32 v126, v104, v229
	global_load_dwordx2 v[8:9], v126, s[50:51]
	v_add_u32_e32 v120, v104, v230
	global_load_dwordx2 v[10:11], v120, s[50:51]
	v_add_u32_e32 v122, v104, v231
	global_load_dwordx2 v[12:13], v122, s[50:51]
	v_add_u32_e32 v124, v104, v232
	global_load_dwordx2 v[14:15], v124, s[50:51]
	v_add_u32_e32 v126, v104, v233
	global_load_dwordx2 v[16:17], v126, s[50:51]
	v_add_u32_e32 v120, v104, v234
	global_load_dwordx2 v[18:19], v120, s[50:51]
	v_add_u32_e32 v122, v104, v235
	global_load_dwordx2 v[20:21], v122, s[50:51]
	v_add_u32_e32 v124, v104, v236
	global_load_dwordx2 v[22:23], v124, s[50:51]
	v_add_u32_e32 v126, v104, v237
	global_load_dwordx2 v[24:25], v126, s[50:51]
	v_add_u32_e32 v120, v104, v238
	global_load_dwordx2 v[26:27], v120, s[50:51]
	v_add_u32_e32 v122, v104, v239
	global_load_dwordx2 v[28:29], v122, s[50:51]
	v_add_u32_e32 v124, v104, v240
	global_load_dwordx2 v[30:31], v124, s[50:51]
	v_add_u32_e32 v126, v104, v241
	global_load_dwordx2 v[32:33], v126, s[50:51]
	ds_read_b128 v[226:229], v106 offset:4096
	ds_read_b128 v[230:233], v106 offset:4112
	ds_read_b128 v[234:237], v106 offset:4128
	ds_read_b128 v[238:241], v106 offset:4144
	ds_read_b128 v[180:183], v106 offset:8576
	ds_read_b128 v[184:187], v106 offset:8592
	ds_read_b128 v[188:191], v106 offset:8608
	ds_read_b128 v[192:195], v106 offset:8624
	s_waitcnt vmcnt(32)
	v_cvt_pk_f32_fp8_e32 v[166:167], v34
	v_cvt_pk_f32_fp8_sdwa v[168:169], v34 src0_sel:WORD_1
	v_cvt_pk_f32_fp8_e32 v[170:171], v35
	v_cvt_pk_f32_fp8_sdwa v[172:173], v35 src0_sel:WORD_1
	v_pk_fma_f32 v[242:243], v[196:197], v[166:167], v[242:243] op_sel_hi:[0,1,1]
	v_pk_fma_f32 v[244:245], v[196:197], v[168:169], v[244:245] op_sel_hi:[0,1,1]
	v_pk_fma_f32 v[246:247], v[196:197], v[170:171], v[246:247] op_sel_hi:[0,1,1]
	v_pk_fma_f32 v[248:249], v[196:197], v[172:173], v[248:249] op_sel_hi:[0,1,1]
	v_cvt_pk_f32_fp8_e32 v[166:167], v36
	v_cvt_pk_f32_fp8_sdwa v[168:169], v36 src0_sel:WORD_1
	v_cvt_pk_f32_fp8_e32 v[170:171], v37
	v_cvt_pk_f32_fp8_sdwa v[172:173], v37 src0_sel:WORD_1
	v_pk_fma_f32 v[242:243], v[196:197], v[166:167], v[242:243] op_sel:[1,0,0]
	v_pk_fma_f32 v[244:245], v[196:197], v[168:169], v[244:245] op_sel:[1,0,0]
	v_pk_fma_f32 v[246:247], v[196:197], v[170:171], v[246:247] op_sel:[1,0,0]
	v_pk_fma_f32 v[248:249], v[196:197], v[172:173], v[248:249] op_sel:[1,0,0]
	v_cvt_pk_f32_fp8_e32 v[166:167], v38
	v_cvt_pk_f32_fp8_sdwa v[168:169], v38 src0_sel:WORD_1
	v_cvt_pk_f32_fp8_e32 v[170:171], v39
	v_cvt_pk_f32_fp8_sdwa v[172:173], v39 src0_sel:WORD_1
	v_pk_fma_f32 v[242:243], v[198:199], v[166:167], v[242:243] op_sel_hi:[0,1,1]
	v_pk_fma_f32 v[244:245], v[198:199], v[168:169], v[244:245] op_sel_hi:[0,1,1]
	v_pk_fma_f32 v[246:247], v[198:199], v[170:171], v[246:247] op_sel_hi:[0,1,1]
	v_pk_fma_f32 v[248:249], v[198:199], v[172:173], v[248:249] op_sel_hi:[0,1,1]
	v_cvt_pk_f32_fp8_e32 v[166:167], v40
	v_cvt_pk_f32_fp8_sdwa v[168:169], v40 src0_sel:WORD_1
	v_cvt_pk_f32_fp8_e32 v[170:171], v41
	v_cvt_pk_f32_fp8_sdwa v[172:173], v41 src0_sel:WORD_1
	v_pk_fma_f32 v[242:243], v[198:199], v[166:167], v[242:243] op_sel:[1,0,0]
	v_pk_fma_f32 v[244:245], v[198:199], v[168:169], v[244:245] op_sel:[1,0,0]
	v_pk_fma_f32 v[246:247], v[198:199], v[170:171], v[246:247] op_sel:[1,0,0]
	v_pk_fma_f32 v[248:249], v[198:199], v[172:173], v[248:249] op_sel:[1,0,0]
	v_cvt_pk_f32_fp8_e32 v[166:167], v42
	v_cvt_pk_f32_fp8_sdwa v[168:169], v42 src0_sel:WORD_1
	v_cvt_pk_f32_fp8_e32 v[170:171], v43
	v_cvt_pk_f32_fp8_sdwa v[172:173], v43 src0_sel:WORD_1
	v_pk_fma_f32 v[242:243], v[200:201], v[166:167], v[242:243] op_sel_hi:[0,1,1]
	v_pk_fma_f32 v[244:245], v[200:201], v[168:169], v[244:245] op_sel_hi:[0,1,1]
	v_pk_fma_f32 v[246:247], v[200:201], v[170:171], v[246:247] op_sel_hi:[0,1,1]
	v_pk_fma_f32 v[248:249], v[200:201], v[172:173], v[248:249] op_sel_hi:[0,1,1]
	v_cvt_pk_f32_fp8_e32 v[166:167], v44
	v_cvt_pk_f32_fp8_sdwa v[168:169], v44 src0_sel:WORD_1
	v_cvt_pk_f32_fp8_e32 v[170:171], v45
	v_cvt_pk_f32_fp8_sdwa v[172:173], v45 src0_sel:WORD_1
	v_pk_fma_f32 v[242:243], v[200:201], v[166:167], v[242:243] op_sel:[1,0,0]
	v_pk_fma_f32 v[244:245], v[200:201], v[168:169], v[244:245] op_sel:[1,0,0]
	v_pk_fma_f32 v[246:247], v[200:201], v[170:171], v[246:247] op_sel:[1,0,0]
	v_pk_fma_f32 v[248:249], v[200:201], v[172:173], v[248:249] op_sel:[1,0,0]
	v_cvt_pk_f32_fp8_e32 v[166:167], v46
	v_cvt_pk_f32_fp8_sdwa v[168:169], v46 src0_sel:WORD_1
	v_cvt_pk_f32_fp8_e32 v[170:171], v47
	v_cvt_pk_f32_fp8_sdwa v[172:173], v47 src0_sel:WORD_1
	v_pk_fma_f32 v[242:243], v[202:203], v[166:167], v[242:243] op_sel_hi:[0,1,1]
	v_pk_fma_f32 v[244:245], v[202:203], v[168:169], v[244:245] op_sel_hi:[0,1,1]
	v_pk_fma_f32 v[246:247], v[202:203], v[170:171], v[246:247] op_sel_hi:[0,1,1]
	v_pk_fma_f32 v[248:249], v[202:203], v[172:173], v[248:249] op_sel_hi:[0,1,1]
	v_cvt_pk_f32_fp8_e32 v[166:167], v48
	v_cvt_pk_f32_fp8_sdwa v[168:169], v48 src0_sel:WORD_1
	v_cvt_pk_f32_fp8_e32 v[170:171], v49
	v_cvt_pk_f32_fp8_sdwa v[172:173], v49 src0_sel:WORD_1
	v_pk_fma_f32 v[242:243], v[202:203], v[166:167], v[242:243] op_sel:[1,0,0]
	v_pk_fma_f32 v[244:245], v[202:203], v[168:169], v[244:245] op_sel:[1,0,0]
	v_pk_fma_f32 v[246:247], v[202:203], v[170:171], v[246:247] op_sel:[1,0,0]
	v_pk_fma_f32 v[248:249], v[202:203], v[172:173], v[248:249] op_sel:[1,0,0]
	v_cvt_pk_f32_fp8_e32 v[166:167], v50
	v_cvt_pk_f32_fp8_sdwa v[168:169], v50 src0_sel:WORD_1
	v_cvt_pk_f32_fp8_e32 v[170:171], v51
	v_cvt_pk_f32_fp8_sdwa v[172:173], v51 src0_sel:WORD_1
	v_pk_fma_f32 v[242:243], v[204:205], v[166:167], v[242:243] op_sel_hi:[0,1,1]
	v_pk_fma_f32 v[244:245], v[204:205], v[168:169], v[244:245] op_sel_hi:[0,1,1]
	v_pk_fma_f32 v[246:247], v[204:205], v[170:171], v[246:247] op_sel_hi:[0,1,1]
	v_pk_fma_f32 v[248:249], v[204:205], v[172:173], v[248:249] op_sel_hi:[0,1,1]
	v_cvt_pk_f32_fp8_e32 v[166:167], v52
	v_cvt_pk_f32_fp8_sdwa v[168:169], v52 src0_sel:WORD_1
	v_cvt_pk_f32_fp8_e32 v[170:171], v53
	v_cvt_pk_f32_fp8_sdwa v[172:173], v53 src0_sel:WORD_1
	v_pk_fma_f32 v[242:243], v[204:205], v[166:167], v[242:243] op_sel:[1,0,0]
	v_pk_fma_f32 v[244:245], v[204:205], v[168:169], v[244:245] op_sel:[1,0,0]
	v_pk_fma_f32 v[246:247], v[204:205], v[170:171], v[246:247] op_sel:[1,0,0]
	v_pk_fma_f32 v[248:249], v[204:205], v[172:173], v[248:249] op_sel:[1,0,0]
	v_cvt_pk_f32_fp8_e32 v[166:167], v54
	v_cvt_pk_f32_fp8_sdwa v[168:169], v54 src0_sel:WORD_1
	v_cvt_pk_f32_fp8_e32 v[170:171], v55
	v_cvt_pk_f32_fp8_sdwa v[172:173], v55 src0_sel:WORD_1
	v_pk_fma_f32 v[242:243], v[206:207], v[166:167], v[242:243] op_sel_hi:[0,1,1]
	v_pk_fma_f32 v[244:245], v[206:207], v[168:169], v[244:245] op_sel_hi:[0,1,1]
	v_pk_fma_f32 v[246:247], v[206:207], v[170:171], v[246:247] op_sel_hi:[0,1,1]
	v_pk_fma_f32 v[248:249], v[206:207], v[172:173], v[248:249] op_sel_hi:[0,1,1]
	v_cvt_pk_f32_fp8_e32 v[166:167], v56
	v_cvt_pk_f32_fp8_sdwa v[168:169], v56 src0_sel:WORD_1
	v_cvt_pk_f32_fp8_e32 v[170:171], v57
	v_cvt_pk_f32_fp8_sdwa v[172:173], v57 src0_sel:WORD_1
	v_pk_fma_f32 v[242:243], v[206:207], v[166:167], v[242:243] op_sel:[1,0,0]
	v_pk_fma_f32 v[244:245], v[206:207], v[168:169], v[244:245] op_sel:[1,0,0]
	v_pk_fma_f32 v[246:247], v[206:207], v[170:171], v[246:247] op_sel:[1,0,0]
	v_pk_fma_f32 v[248:249], v[206:207], v[172:173], v[248:249] op_sel:[1,0,0]
	v_cvt_pk_f32_fp8_e32 v[166:167], v58
	v_cvt_pk_f32_fp8_sdwa v[168:169], v58 src0_sel:WORD_1
	v_cvt_pk_f32_fp8_e32 v[170:171], v59
	v_cvt_pk_f32_fp8_sdwa v[172:173], v59 src0_sel:WORD_1
	v_pk_fma_f32 v[242:243], v[216:217], v[166:167], v[242:243] op_sel_hi:[0,1,1]
	v_pk_fma_f32 v[244:245], v[216:217], v[168:169], v[244:245] op_sel_hi:[0,1,1]
	v_pk_fma_f32 v[246:247], v[216:217], v[170:171], v[246:247] op_sel_hi:[0,1,1]
	v_pk_fma_f32 v[248:249], v[216:217], v[172:173], v[248:249] op_sel_hi:[0,1,1]
	v_cvt_pk_f32_fp8_e32 v[166:167], v60
	v_cvt_pk_f32_fp8_sdwa v[168:169], v60 src0_sel:WORD_1
	v_cvt_pk_f32_fp8_e32 v[170:171], v61
	v_cvt_pk_f32_fp8_sdwa v[172:173], v61 src0_sel:WORD_1
	v_pk_fma_f32 v[242:243], v[216:217], v[166:167], v[242:243] op_sel:[1,0,0]
	v_pk_fma_f32 v[244:245], v[216:217], v[168:169], v[244:245] op_sel:[1,0,0]
	v_pk_fma_f32 v[246:247], v[216:217], v[170:171], v[246:247] op_sel:[1,0,0]
	v_pk_fma_f32 v[248:249], v[216:217], v[172:173], v[248:249] op_sel:[1,0,0]
	v_cvt_pk_f32_fp8_e32 v[166:167], v62
	v_cvt_pk_f32_fp8_sdwa v[168:169], v62 src0_sel:WORD_1
	v_cvt_pk_f32_fp8_e32 v[170:171], v63
	v_cvt_pk_f32_fp8_sdwa v[172:173], v63 src0_sel:WORD_1
	v_pk_fma_f32 v[242:243], v[218:219], v[166:167], v[242:243] op_sel_hi:[0,1,1]
	v_pk_fma_f32 v[244:245], v[218:219], v[168:169], v[244:245] op_sel_hi:[0,1,1]
	v_pk_fma_f32 v[246:247], v[218:219], v[170:171], v[246:247] op_sel_hi:[0,1,1]
	v_pk_fma_f32 v[248:249], v[218:219], v[172:173], v[248:249] op_sel_hi:[0,1,1]
	v_cvt_pk_f32_fp8_e32 v[166:167], v64
	v_cvt_pk_f32_fp8_sdwa v[168:169], v64 src0_sel:WORD_1
	v_cvt_pk_f32_fp8_e32 v[170:171], v65
	v_cvt_pk_f32_fp8_sdwa v[172:173], v65 src0_sel:WORD_1
	v_pk_fma_f32 v[242:243], v[218:219], v[166:167], v[242:243] op_sel:[1,0,0]
	v_pk_fma_f32 v[244:245], v[218:219], v[168:169], v[244:245] op_sel:[1,0,0]
	v_pk_fma_f32 v[246:247], v[218:219], v[170:171], v[246:247] op_sel:[1,0,0]
	v_pk_fma_f32 v[248:249], v[218:219], v[172:173], v[248:249] op_sel:[1,0,0]
	s_waitcnt lgkmcnt(0)
	v_add_u32_e32 v120, v104, v226
	global_load_dwordx2 v[34:35], v120, s[50:51]
	v_add_u32_e32 v122, v104, v227
	global_load_dwordx2 v[36:37], v122, s[50:51]
	v_add_u32_e32 v124, v104, v228
	global_load_dwordx2 v[38:39], v124, s[50:51]
	v_add_u32_e32 v126, v104, v229
	global_load_dwordx2 v[40:41], v126, s[50:51]
	v_add_u32_e32 v120, v104, v230
	global_load_dwordx2 v[42:43], v120, s[50:51]
	v_add_u32_e32 v122, v104, v231
	global_load_dwordx2 v[44:45], v122, s[50:51]
	v_add_u32_e32 v124, v104, v232
	global_load_dwordx2 v[46:47], v124, s[50:51]
	v_add_u32_e32 v126, v104, v233
	global_load_dwordx2 v[48:49], v126, s[50:51]
	v_add_u32_e32 v120, v104, v234
	global_load_dwordx2 v[50:51], v120, s[50:51]
	v_add_u32_e32 v122, v104, v235
	global_load_dwordx2 v[52:53], v122, s[50:51]
	v_add_u32_e32 v124, v104, v236
	global_load_dwordx2 v[54:55], v124, s[50:51]
	v_add_u32_e32 v126, v104, v237
	global_load_dwordx2 v[56:57], v126, s[50:51]
	v_add_u32_e32 v120, v104, v238
	global_load_dwordx2 v[58:59], v120, s[50:51]
	v_add_u32_e32 v122, v104, v239
	global_load_dwordx2 v[60:61], v122, s[50:51]
	v_add_u32_e32 v124, v104, v240
	global_load_dwordx2 v[62:63], v124, s[50:51]
	v_add_u32_e32 v126, v104, v241
	global_load_dwordx2 v[64:65], v126, s[50:51]
	ds_read_b128 v[226:229], v106 offset:4160
	ds_read_b128 v[230:233], v106 offset:4176
	ds_read_b128 v[234:237], v106 offset:4192
	ds_read_b128 v[238:241], v106 offset:4208
	ds_read_b128 v[196:199], v106 offset:8640
	ds_read_b128 v[200:203], v106 offset:8656
	ds_read_b128 v[204:207], v106 offset:8672
	ds_read_b128 v[216:219], v106 offset:8688
	s_waitcnt vmcnt(32)
	v_cvt_pk_f32_fp8_e32 v[166:167], v134
	v_cvt_pk_f32_fp8_sdwa v[168:169], v134 src0_sel:WORD_1
	v_cvt_pk_f32_fp8_e32 v[170:171], v135
	v_cvt_pk_f32_fp8_sdwa v[172:173], v135 src0_sel:WORD_1
	v_pk_fma_f32 v[242:243], v[180:181], v[166:167], v[242:243] op_sel_hi:[0,1,1]
	v_pk_fma_f32 v[244:245], v[180:181], v[168:169], v[244:245] op_sel_hi:[0,1,1]
	v_pk_fma_f32 v[246:247], v[180:181], v[170:171], v[246:247] op_sel_hi:[0,1,1]
	v_pk_fma_f32 v[248:249], v[180:181], v[172:173], v[248:249] op_sel_hi:[0,1,1]
	v_cvt_pk_f32_fp8_e32 v[166:167], v136
	v_cvt_pk_f32_fp8_sdwa v[168:169], v136 src0_sel:WORD_1
	v_cvt_pk_f32_fp8_e32 v[170:171], v137
	v_cvt_pk_f32_fp8_sdwa v[172:173], v137 src0_sel:WORD_1
	v_pk_fma_f32 v[242:243], v[180:181], v[166:167], v[242:243] op_sel:[1,0,0]
	v_pk_fma_f32 v[244:245], v[180:181], v[168:169], v[244:245] op_sel:[1,0,0]
	v_pk_fma_f32 v[246:247], v[180:181], v[170:171], v[246:247] op_sel:[1,0,0]
	v_pk_fma_f32 v[248:249], v[180:181], v[172:173], v[248:249] op_sel:[1,0,0]
	v_cvt_pk_f32_fp8_e32 v[166:167], v138
	v_cvt_pk_f32_fp8_sdwa v[168:169], v138 src0_sel:WORD_1
	v_cvt_pk_f32_fp8_e32 v[170:171], v139
	v_cvt_pk_f32_fp8_sdwa v[172:173], v139 src0_sel:WORD_1
	v_pk_fma_f32 v[242:243], v[182:183], v[166:167], v[242:243] op_sel_hi:[0,1,1]
	v_pk_fma_f32 v[244:245], v[182:183], v[168:169], v[244:245] op_sel_hi:[0,1,1]
	v_pk_fma_f32 v[246:247], v[182:183], v[170:171], v[246:247] op_sel_hi:[0,1,1]
	v_pk_fma_f32 v[248:249], v[182:183], v[172:173], v[248:249] op_sel_hi:[0,1,1]
	v_cvt_pk_f32_fp8_e32 v[166:167], v140
	v_cvt_pk_f32_fp8_sdwa v[168:169], v140 src0_sel:WORD_1
	v_cvt_pk_f32_fp8_e32 v[170:171], v141
	v_cvt_pk_f32_fp8_sdwa v[172:173], v141 src0_sel:WORD_1
	v_pk_fma_f32 v[242:243], v[182:183], v[166:167], v[242:243] op_sel:[1,0,0]
	v_pk_fma_f32 v[244:245], v[182:183], v[168:169], v[244:245] op_sel:[1,0,0]
	v_pk_fma_f32 v[246:247], v[182:183], v[170:171], v[246:247] op_sel:[1,0,0]
	v_pk_fma_f32 v[248:249], v[182:183], v[172:173], v[248:249] op_sel:[1,0,0]
	v_cvt_pk_f32_fp8_e32 v[166:167], v142
	v_cvt_pk_f32_fp8_sdwa v[168:169], v142 src0_sel:WORD_1
	v_cvt_pk_f32_fp8_e32 v[170:171], v143
	v_cvt_pk_f32_fp8_sdwa v[172:173], v143 src0_sel:WORD_1
	v_pk_fma_f32 v[242:243], v[184:185], v[166:167], v[242:243] op_sel_hi:[0,1,1]
	v_pk_fma_f32 v[244:245], v[184:185], v[168:169], v[244:245] op_sel_hi:[0,1,1]
	v_pk_fma_f32 v[246:247], v[184:185], v[170:171], v[246:247] op_sel_hi:[0,1,1]
	v_pk_fma_f32 v[248:249], v[184:185], v[172:173], v[248:249] op_sel_hi:[0,1,1]
	v_cvt_pk_f32_fp8_e32 v[166:167], v144
	v_cvt_pk_f32_fp8_sdwa v[168:169], v144 src0_sel:WORD_1
	v_cvt_pk_f32_fp8_e32 v[170:171], v145
	v_cvt_pk_f32_fp8_sdwa v[172:173], v145 src0_sel:WORD_1
	v_pk_fma_f32 v[242:243], v[184:185], v[166:167], v[242:243] op_sel:[1,0,0]
	v_pk_fma_f32 v[244:245], v[184:185], v[168:169], v[244:245] op_sel:[1,0,0]
	v_pk_fma_f32 v[246:247], v[184:185], v[170:171], v[246:247] op_sel:[1,0,0]
	v_pk_fma_f32 v[248:249], v[184:185], v[172:173], v[248:249] op_sel:[1,0,0]
	v_cvt_pk_f32_fp8_e32 v[166:167], v146
	v_cvt_pk_f32_fp8_sdwa v[168:169], v146 src0_sel:WORD_1
	v_cvt_pk_f32_fp8_e32 v[170:171], v147
	v_cvt_pk_f32_fp8_sdwa v[172:173], v147 src0_sel:WORD_1
	v_pk_fma_f32 v[242:243], v[186:187], v[166:167], v[242:243] op_sel_hi:[0,1,1]
	v_pk_fma_f32 v[244:245], v[186:187], v[168:169], v[244:245] op_sel_hi:[0,1,1]
	v_pk_fma_f32 v[246:247], v[186:187], v[170:171], v[246:247] op_sel_hi:[0,1,1]
	v_pk_fma_f32 v[248:249], v[186:187], v[172:173], v[248:249] op_sel_hi:[0,1,1]
	v_cvt_pk_f32_fp8_e32 v[166:167], v148
	v_cvt_pk_f32_fp8_sdwa v[168:169], v148 src0_sel:WORD_1
	v_cvt_pk_f32_fp8_e32 v[170:171], v149
	v_cvt_pk_f32_fp8_sdwa v[172:173], v149 src0_sel:WORD_1
	v_pk_fma_f32 v[242:243], v[186:187], v[166:167], v[242:243] op_sel:[1,0,0]
	v_pk_fma_f32 v[244:245], v[186:187], v[168:169], v[244:245] op_sel:[1,0,0]
	v_pk_fma_f32 v[246:247], v[186:187], v[170:171], v[246:247] op_sel:[1,0,0]
	v_pk_fma_f32 v[248:249], v[186:187], v[172:173], v[248:249] op_sel:[1,0,0]
	v_cvt_pk_f32_fp8_e32 v[166:167], v150
	v_cvt_pk_f32_fp8_sdwa v[168:169], v150 src0_sel:WORD_1
	v_cvt_pk_f32_fp8_e32 v[170:171], v151
	v_cvt_pk_f32_fp8_sdwa v[172:173], v151 src0_sel:WORD_1
	v_pk_fma_f32 v[242:243], v[188:189], v[166:167], v[242:243] op_sel_hi:[0,1,1]
	v_pk_fma_f32 v[244:245], v[188:189], v[168:169], v[244:245] op_sel_hi:[0,1,1]
	v_pk_fma_f32 v[246:247], v[188:189], v[170:171], v[246:247] op_sel_hi:[0,1,1]
	v_pk_fma_f32 v[248:249], v[188:189], v[172:173], v[248:249] op_sel_hi:[0,1,1]
	v_cvt_pk_f32_fp8_e32 v[166:167], v152
	v_cvt_pk_f32_fp8_sdwa v[168:169], v152 src0_sel:WORD_1
	v_cvt_pk_f32_fp8_e32 v[170:171], v153
	v_cvt_pk_f32_fp8_sdwa v[172:173], v153 src0_sel:WORD_1
	v_pk_fma_f32 v[242:243], v[188:189], v[166:167], v[242:243] op_sel:[1,0,0]
	v_pk_fma_f32 v[244:245], v[188:189], v[168:169], v[244:245] op_sel:[1,0,0]
	v_pk_fma_f32 v[246:247], v[188:189], v[170:171], v[246:247] op_sel:[1,0,0]
	v_pk_fma_f32 v[248:249], v[188:189], v[172:173], v[248:249] op_sel:[1,0,0]
	v_cvt_pk_f32_fp8_e32 v[166:167], v154
	v_cvt_pk_f32_fp8_sdwa v[168:169], v154 src0_sel:WORD_1
	v_cvt_pk_f32_fp8_e32 v[170:171], v155
	v_cvt_pk_f32_fp8_sdwa v[172:173], v155 src0_sel:WORD_1
	v_pk_fma_f32 v[242:243], v[190:191], v[166:167], v[242:243] op_sel_hi:[0,1,1]
	v_pk_fma_f32 v[244:245], v[190:191], v[168:169], v[244:245] op_sel_hi:[0,1,1]
	v_pk_fma_f32 v[246:247], v[190:191], v[170:171], v[246:247] op_sel_hi:[0,1,1]
	v_pk_fma_f32 v[248:249], v[190:191], v[172:173], v[248:249] op_sel_hi:[0,1,1]
	v_cvt_pk_f32_fp8_e32 v[166:167], v156
	v_cvt_pk_f32_fp8_sdwa v[168:169], v156 src0_sel:WORD_1
	v_cvt_pk_f32_fp8_e32 v[170:171], v157
	v_cvt_pk_f32_fp8_sdwa v[172:173], v157 src0_sel:WORD_1
	v_pk_fma_f32 v[242:243], v[190:191], v[166:167], v[242:243] op_sel:[1,0,0]
	v_pk_fma_f32 v[244:245], v[190:191], v[168:169], v[244:245] op_sel:[1,0,0]
	v_pk_fma_f32 v[246:247], v[190:191], v[170:171], v[246:247] op_sel:[1,0,0]
	v_pk_fma_f32 v[248:249], v[190:191], v[172:173], v[248:249] op_sel:[1,0,0]
	v_cvt_pk_f32_fp8_e32 v[166:167], v158
	v_cvt_pk_f32_fp8_sdwa v[168:169], v158 src0_sel:WORD_1
	v_cvt_pk_f32_fp8_e32 v[170:171], v159
	v_cvt_pk_f32_fp8_sdwa v[172:173], v159 src0_sel:WORD_1
	v_pk_fma_f32 v[242:243], v[192:193], v[166:167], v[242:243] op_sel_hi:[0,1,1]
	v_pk_fma_f32 v[244:245], v[192:193], v[168:169], v[244:245] op_sel_hi:[0,1,1]
	v_pk_fma_f32 v[246:247], v[192:193], v[170:171], v[246:247] op_sel_hi:[0,1,1]
	v_pk_fma_f32 v[248:249], v[192:193], v[172:173], v[248:249] op_sel_hi:[0,1,1]
	v_cvt_pk_f32_fp8_e32 v[166:167], v160
	v_cvt_pk_f32_fp8_sdwa v[168:169], v160 src0_sel:WORD_1
	v_cvt_pk_f32_fp8_e32 v[170:171], v161
	v_cvt_pk_f32_fp8_sdwa v[172:173], v161 src0_sel:WORD_1
	v_pk_fma_f32 v[242:243], v[192:193], v[166:167], v[242:243] op_sel:[1,0,0]
	v_pk_fma_f32 v[244:245], v[192:193], v[168:169], v[244:245] op_sel:[1,0,0]
	v_pk_fma_f32 v[246:247], v[192:193], v[170:171], v[246:247] op_sel:[1,0,0]
	v_pk_fma_f32 v[248:249], v[192:193], v[172:173], v[248:249] op_sel:[1,0,0]
	v_cvt_pk_f32_fp8_e32 v[166:167], v162
	v_cvt_pk_f32_fp8_sdwa v[168:169], v162 src0_sel:WORD_1
	v_cvt_pk_f32_fp8_e32 v[170:171], v163
	v_cvt_pk_f32_fp8_sdwa v[172:173], v163 src0_sel:WORD_1
	v_pk_fma_f32 v[242:243], v[194:195], v[166:167], v[242:243] op_sel_hi:[0,1,1]
	v_pk_fma_f32 v[244:245], v[194:195], v[168:169], v[244:245] op_sel_hi:[0,1,1]
	v_pk_fma_f32 v[246:247], v[194:195], v[170:171], v[246:247] op_sel_hi:[0,1,1]
	v_pk_fma_f32 v[248:249], v[194:195], v[172:173], v[248:249] op_sel_hi:[0,1,1]
	v_cvt_pk_f32_fp8_e32 v[166:167], v164
	v_cvt_pk_f32_fp8_sdwa v[168:169], v164 src0_sel:WORD_1
	v_cvt_pk_f32_fp8_e32 v[170:171], v165
	v_cvt_pk_f32_fp8_sdwa v[172:173], v165 src0_sel:WORD_1
	v_pk_fma_f32 v[242:243], v[194:195], v[166:167], v[242:243] op_sel:[1,0,0]
	v_pk_fma_f32 v[244:245], v[194:195], v[168:169], v[244:245] op_sel:[1,0,0]
	v_pk_fma_f32 v[246:247], v[194:195], v[170:171], v[246:247] op_sel:[1,0,0]
	v_pk_fma_f32 v[248:249], v[194:195], v[172:173], v[248:249] op_sel:[1,0,0]
	s_waitcnt lgkmcnt(0)
	v_add_u32_e32 v120, v104, v226
	global_load_dwordx2 v[134:135], v120, s[50:51]
	v_add_u32_e32 v122, v104, v227
	global_load_dwordx2 v[136:137], v122, s[50:51]
	v_add_u32_e32 v124, v104, v228
	global_load_dwordx2 v[138:139], v124, s[50:51]
	v_add_u32_e32 v126, v104, v229
	global_load_dwordx2 v[140:141], v126, s[50:51]
	v_add_u32_e32 v120, v104, v230
	global_load_dwordx2 v[142:143], v120, s[50:51]
	v_add_u32_e32 v122, v104, v231
	global_load_dwordx2 v[144:145], v122, s[50:51]
	v_add_u32_e32 v124, v104, v232
	global_load_dwordx2 v[146:147], v124, s[50:51]
	v_add_u32_e32 v126, v104, v233
	global_load_dwordx2 v[148:149], v126, s[50:51]
	v_add_u32_e32 v120, v104, v234
	global_load_dwordx2 v[150:151], v120, s[50:51]
	v_add_u32_e32 v122, v104, v235
	global_load_dwordx2 v[152:153], v122, s[50:51]
	v_add_u32_e32 v124, v104, v236
	global_load_dwordx2 v[154:155], v124, s[50:51]
	v_add_u32_e32 v126, v104, v237
	global_load_dwordx2 v[156:157], v126, s[50:51]
	v_add_u32_e32 v120, v104, v238
	global_load_dwordx2 v[158:159], v120, s[50:51]
	v_add_u32_e32 v122, v104, v239
	global_load_dwordx2 v[160:161], v122, s[50:51]
	v_add_u32_e32 v124, v104, v240
	global_load_dwordx2 v[162:163], v124, s[50:51]
	v_add_u32_e32 v126, v104, v241
	global_load_dwordx2 v[164:165], v126, s[50:51]
	ds_read_b128 v[226:229], v106 offset:4224
	ds_read_b128 v[230:233], v106 offset:4240
	ds_read_b128 v[234:237], v106 offset:4256
	ds_read_b128 v[238:241], v106 offset:4272
	ds_read_b128 v[180:183], v106 offset:10240
	ds_read_b128 v[184:187], v106 offset:10256
	ds_read_b128 v[188:191], v106 offset:10272
	ds_read_b128 v[192:195], v106 offset:10288
	s_waitcnt vmcnt(32)
	v_cvt_pk_f32_fp8_e32 v[166:167], v2
	v_cvt_pk_f32_fp8_sdwa v[168:169], v2 src0_sel:WORD_1
	v_cvt_pk_f32_fp8_e32 v[170:171], v3
	v_cvt_pk_f32_fp8_sdwa v[172:173], v3 src0_sel:WORD_1
	v_pk_fma_f32 v[242:243], v[196:197], v[166:167], v[242:243] op_sel_hi:[0,1,1]
	v_pk_fma_f32 v[244:245], v[196:197], v[168:169], v[244:245] op_sel_hi:[0,1,1]
	v_pk_fma_f32 v[246:247], v[196:197], v[170:171], v[246:247] op_sel_hi:[0,1,1]
	v_pk_fma_f32 v[248:249], v[196:197], v[172:173], v[248:249] op_sel_hi:[0,1,1]
	v_cvt_pk_f32_fp8_e32 v[166:167], v4
	v_cvt_pk_f32_fp8_sdwa v[168:169], v4 src0_sel:WORD_1
	v_cvt_pk_f32_fp8_e32 v[170:171], v5
	v_cvt_pk_f32_fp8_sdwa v[172:173], v5 src0_sel:WORD_1
	v_pk_fma_f32 v[242:243], v[196:197], v[166:167], v[242:243] op_sel:[1,0,0]
	v_pk_fma_f32 v[244:245], v[196:197], v[168:169], v[244:245] op_sel:[1,0,0]
	v_pk_fma_f32 v[246:247], v[196:197], v[170:171], v[246:247] op_sel:[1,0,0]
	v_pk_fma_f32 v[248:249], v[196:197], v[172:173], v[248:249] op_sel:[1,0,0]
	v_cvt_pk_f32_fp8_e32 v[166:167], v6
	v_cvt_pk_f32_fp8_sdwa v[168:169], v6 src0_sel:WORD_1
	v_cvt_pk_f32_fp8_e32 v[170:171], v7
	v_cvt_pk_f32_fp8_sdwa v[172:173], v7 src0_sel:WORD_1
	v_pk_fma_f32 v[242:243], v[198:199], v[166:167], v[242:243] op_sel_hi:[0,1,1]
	v_pk_fma_f32 v[244:245], v[198:199], v[168:169], v[244:245] op_sel_hi:[0,1,1]
	v_pk_fma_f32 v[246:247], v[198:199], v[170:171], v[246:247] op_sel_hi:[0,1,1]
	v_pk_fma_f32 v[248:249], v[198:199], v[172:173], v[248:249] op_sel_hi:[0,1,1]
	v_cvt_pk_f32_fp8_e32 v[166:167], v8
	v_cvt_pk_f32_fp8_sdwa v[168:169], v8 src0_sel:WORD_1
	v_cvt_pk_f32_fp8_e32 v[170:171], v9
	v_cvt_pk_f32_fp8_sdwa v[172:173], v9 src0_sel:WORD_1
	v_pk_fma_f32 v[242:243], v[198:199], v[166:167], v[242:243] op_sel:[1,0,0]
	v_pk_fma_f32 v[244:245], v[198:199], v[168:169], v[244:245] op_sel:[1,0,0]
	v_pk_fma_f32 v[246:247], v[198:199], v[170:171], v[246:247] op_sel:[1,0,0]
	v_pk_fma_f32 v[248:249], v[198:199], v[172:173], v[248:249] op_sel:[1,0,0]
	v_cvt_pk_f32_fp8_e32 v[166:167], v10
	v_cvt_pk_f32_fp8_sdwa v[168:169], v10 src0_sel:WORD_1
	v_cvt_pk_f32_fp8_e32 v[170:171], v11
	v_cvt_pk_f32_fp8_sdwa v[172:173], v11 src0_sel:WORD_1
	v_pk_fma_f32 v[242:243], v[200:201], v[166:167], v[242:243] op_sel_hi:[0,1,1]
	v_pk_fma_f32 v[244:245], v[200:201], v[168:169], v[244:245] op_sel_hi:[0,1,1]
	v_pk_fma_f32 v[246:247], v[200:201], v[170:171], v[246:247] op_sel_hi:[0,1,1]
	v_pk_fma_f32 v[248:249], v[200:201], v[172:173], v[248:249] op_sel_hi:[0,1,1]
	v_cvt_pk_f32_fp8_e32 v[166:167], v12
	v_cvt_pk_f32_fp8_sdwa v[168:169], v12 src0_sel:WORD_1
	v_cvt_pk_f32_fp8_e32 v[170:171], v13
	v_cvt_pk_f32_fp8_sdwa v[172:173], v13 src0_sel:WORD_1
	v_pk_fma_f32 v[242:243], v[200:201], v[166:167], v[242:243] op_sel:[1,0,0]
	v_pk_fma_f32 v[244:245], v[200:201], v[168:169], v[244:245] op_sel:[1,0,0]
	v_pk_fma_f32 v[246:247], v[200:201], v[170:171], v[246:247] op_sel:[1,0,0]
	v_pk_fma_f32 v[248:249], v[200:201], v[172:173], v[248:249] op_sel:[1,0,0]
	v_cvt_pk_f32_fp8_e32 v[166:167], v14
	v_cvt_pk_f32_fp8_sdwa v[168:169], v14 src0_sel:WORD_1
	v_cvt_pk_f32_fp8_e32 v[170:171], v15
	v_cvt_pk_f32_fp8_sdwa v[172:173], v15 src0_sel:WORD_1
	v_pk_fma_f32 v[242:243], v[202:203], v[166:167], v[242:243] op_sel_hi:[0,1,1]
	v_pk_fma_f32 v[244:245], v[202:203], v[168:169], v[244:245] op_sel_hi:[0,1,1]
	v_pk_fma_f32 v[246:247], v[202:203], v[170:171], v[246:247] op_sel_hi:[0,1,1]
	v_pk_fma_f32 v[248:249], v[202:203], v[172:173], v[248:249] op_sel_hi:[0,1,1]
	v_cvt_pk_f32_fp8_e32 v[166:167], v16
	v_cvt_pk_f32_fp8_sdwa v[168:169], v16 src0_sel:WORD_1
	v_cvt_pk_f32_fp8_e32 v[170:171], v17
	v_cvt_pk_f32_fp8_sdwa v[172:173], v17 src0_sel:WORD_1
	v_pk_fma_f32 v[242:243], v[202:203], v[166:167], v[242:243] op_sel:[1,0,0]
	v_pk_fma_f32 v[244:245], v[202:203], v[168:169], v[244:245] op_sel:[1,0,0]
	v_pk_fma_f32 v[246:247], v[202:203], v[170:171], v[246:247] op_sel:[1,0,0]
	v_pk_fma_f32 v[248:249], v[202:203], v[172:173], v[248:249] op_sel:[1,0,0]
	v_cvt_pk_f32_fp8_e32 v[166:167], v18
	v_cvt_pk_f32_fp8_sdwa v[168:169], v18 src0_sel:WORD_1
	v_cvt_pk_f32_fp8_e32 v[170:171], v19
	v_cvt_pk_f32_fp8_sdwa v[172:173], v19 src0_sel:WORD_1
	v_pk_fma_f32 v[242:243], v[204:205], v[166:167], v[242:243] op_sel_hi:[0,1,1]
	v_pk_fma_f32 v[244:245], v[204:205], v[168:169], v[244:245] op_sel_hi:[0,1,1]
	v_pk_fma_f32 v[246:247], v[204:205], v[170:171], v[246:247] op_sel_hi:[0,1,1]
	v_pk_fma_f32 v[248:249], v[204:205], v[172:173], v[248:249] op_sel_hi:[0,1,1]
	v_cvt_pk_f32_fp8_e32 v[166:167], v20
	v_cvt_pk_f32_fp8_sdwa v[168:169], v20 src0_sel:WORD_1
	v_cvt_pk_f32_fp8_e32 v[170:171], v21
	v_cvt_pk_f32_fp8_sdwa v[172:173], v21 src0_sel:WORD_1
	v_pk_fma_f32 v[242:243], v[204:205], v[166:167], v[242:243] op_sel:[1,0,0]
	v_pk_fma_f32 v[244:245], v[204:205], v[168:169], v[244:245] op_sel:[1,0,0]
	v_pk_fma_f32 v[246:247], v[204:205], v[170:171], v[246:247] op_sel:[1,0,0]
	v_pk_fma_f32 v[248:249], v[204:205], v[172:173], v[248:249] op_sel:[1,0,0]
	v_cvt_pk_f32_fp8_e32 v[166:167], v22
	v_cvt_pk_f32_fp8_sdwa v[168:169], v22 src0_sel:WORD_1
	v_cvt_pk_f32_fp8_e32 v[170:171], v23
	v_cvt_pk_f32_fp8_sdwa v[172:173], v23 src0_sel:WORD_1
	v_pk_fma_f32 v[242:243], v[206:207], v[166:167], v[242:243] op_sel_hi:[0,1,1]
	v_pk_fma_f32 v[244:245], v[206:207], v[168:169], v[244:245] op_sel_hi:[0,1,1]
	v_pk_fma_f32 v[246:247], v[206:207], v[170:171], v[246:247] op_sel_hi:[0,1,1]
	v_pk_fma_f32 v[248:249], v[206:207], v[172:173], v[248:249] op_sel_hi:[0,1,1]
	v_cvt_pk_f32_fp8_e32 v[166:167], v24
	v_cvt_pk_f32_fp8_sdwa v[168:169], v24 src0_sel:WORD_1
	v_cvt_pk_f32_fp8_e32 v[170:171], v25
	v_cvt_pk_f32_fp8_sdwa v[172:173], v25 src0_sel:WORD_1
	v_pk_fma_f32 v[242:243], v[206:207], v[166:167], v[242:243] op_sel:[1,0,0]
	v_pk_fma_f32 v[244:245], v[206:207], v[168:169], v[244:245] op_sel:[1,0,0]
	v_pk_fma_f32 v[246:247], v[206:207], v[170:171], v[246:247] op_sel:[1,0,0]
	v_pk_fma_f32 v[248:249], v[206:207], v[172:173], v[248:249] op_sel:[1,0,0]
	v_cvt_pk_f32_fp8_e32 v[166:167], v26
	v_cvt_pk_f32_fp8_sdwa v[168:169], v26 src0_sel:WORD_1
	v_cvt_pk_f32_fp8_e32 v[170:171], v27
	v_cvt_pk_f32_fp8_sdwa v[172:173], v27 src0_sel:WORD_1
	v_pk_fma_f32 v[242:243], v[216:217], v[166:167], v[242:243] op_sel_hi:[0,1,1]
	v_pk_fma_f32 v[244:245], v[216:217], v[168:169], v[244:245] op_sel_hi:[0,1,1]
	v_pk_fma_f32 v[246:247], v[216:217], v[170:171], v[246:247] op_sel_hi:[0,1,1]
	v_pk_fma_f32 v[248:249], v[216:217], v[172:173], v[248:249] op_sel_hi:[0,1,1]
	v_cvt_pk_f32_fp8_e32 v[166:167], v28
	v_cvt_pk_f32_fp8_sdwa v[168:169], v28 src0_sel:WORD_1
	v_cvt_pk_f32_fp8_e32 v[170:171], v29
	v_cvt_pk_f32_fp8_sdwa v[172:173], v29 src0_sel:WORD_1
	v_pk_fma_f32 v[242:243], v[216:217], v[166:167], v[242:243] op_sel:[1,0,0]
	v_pk_fma_f32 v[244:245], v[216:217], v[168:169], v[244:245] op_sel:[1,0,0]
	v_pk_fma_f32 v[246:247], v[216:217], v[170:171], v[246:247] op_sel:[1,0,0]
	v_pk_fma_f32 v[248:249], v[216:217], v[172:173], v[248:249] op_sel:[1,0,0]
	v_cvt_pk_f32_fp8_e32 v[166:167], v30
	v_cvt_pk_f32_fp8_sdwa v[168:169], v30 src0_sel:WORD_1
	v_cvt_pk_f32_fp8_e32 v[170:171], v31
	v_cvt_pk_f32_fp8_sdwa v[172:173], v31 src0_sel:WORD_1
	v_pk_fma_f32 v[242:243], v[218:219], v[166:167], v[242:243] op_sel_hi:[0,1,1]
	v_pk_fma_f32 v[244:245], v[218:219], v[168:169], v[244:245] op_sel_hi:[0,1,1]
	v_pk_fma_f32 v[246:247], v[218:219], v[170:171], v[246:247] op_sel_hi:[0,1,1]
	v_pk_fma_f32 v[248:249], v[218:219], v[172:173], v[248:249] op_sel_hi:[0,1,1]
	v_cvt_pk_f32_fp8_e32 v[166:167], v32
	v_cvt_pk_f32_fp8_sdwa v[168:169], v32 src0_sel:WORD_1
	v_cvt_pk_f32_fp8_e32 v[170:171], v33
	v_cvt_pk_f32_fp8_sdwa v[172:173], v33 src0_sel:WORD_1
	v_pk_fma_f32 v[242:243], v[218:219], v[166:167], v[242:243] op_sel:[1,0,0]
	v_pk_fma_f32 v[244:245], v[218:219], v[168:169], v[244:245] op_sel:[1,0,0]
	v_pk_fma_f32 v[246:247], v[218:219], v[170:171], v[246:247] op_sel:[1,0,0]
	v_pk_fma_f32 v[248:249], v[218:219], v[172:173], v[248:249] op_sel:[1,0,0]
	v_pk_fma_f32 v[94:95], v[242:243], v[66:67], v[94:95]
	v_pk_fma_f32 v[96:97], v[244:245], v[68:69], v[96:97]
	v_pk_fma_f32 v[98:99], v[246:247], v[174:175], v[98:99]
	v_pk_fma_f32 v[100:101], v[248:249], v[176:177], v[100:101]
	global_store_dwordx4 v110, v[94:97], s[54:55]
	global_store_dwordx4 v110, v[98:101], s[54:55] offset:16
	global_load_dwordx4 v[94:97], v112, s[54:55]
	global_load_dwordx4 v[98:101], v112, s[54:55] offset:16
	global_load_dwordx4 v[66:69], v118, s[56:57]
	global_load_dwordx4 v[174:177], v118, s[56:57] offset:16
	v_mov_b32_e32 v242, 0
	v_mov_b32_e32 v243, 0
	v_mov_b32_e32 v244, 0
	v_mov_b32_e32 v245, 0
	v_mov_b32_e32 v246, 0
	v_mov_b32_e32 v247, 0
	v_mov_b32_e32 v248, 0
	v_mov_b32_e32 v249, 0
	s_waitcnt lgkmcnt(0)
	v_add_u32_e32 v120, v104, v226
	global_load_dwordx2 v[2:3], v120, s[50:51]
	v_add_u32_e32 v122, v104, v227
	global_load_dwordx2 v[4:5], v122, s[50:51]
	v_add_u32_e32 v124, v104, v228
	global_load_dwordx2 v[6:7], v124, s[50:51]
	v_add_u32_e32 v126, v104, v229
	global_load_dwordx2 v[8:9], v126, s[50:51]
	v_add_u32_e32 v120, v104, v230
	global_load_dwordx2 v[10:11], v120, s[50:51]
	v_add_u32_e32 v122, v104, v231
	global_load_dwordx2 v[12:13], v122, s[50:51]
	v_add_u32_e32 v124, v104, v232
	global_load_dwordx2 v[14:15], v124, s[50:51]
	v_add_u32_e32 v126, v104, v233
	global_load_dwordx2 v[16:17], v126, s[50:51]
	v_add_u32_e32 v120, v104, v234
	global_load_dwordx2 v[18:19], v120, s[50:51]
	v_add_u32_e32 v122, v104, v235
	global_load_dwordx2 v[20:21], v122, s[50:51]
	v_add_u32_e32 v124, v104, v236
	global_load_dwordx2 v[22:23], v124, s[50:51]
	v_add_u32_e32 v126, v104, v237
	global_load_dwordx2 v[24:25], v126, s[50:51]
	v_add_u32_e32 v120, v104, v238
	global_load_dwordx2 v[26:27], v120, s[50:51]
	v_add_u32_e32 v122, v104, v239
	global_load_dwordx2 v[28:29], v122, s[50:51]
	v_add_u32_e32 v124, v104, v240
	global_load_dwordx2 v[30:31], v124, s[50:51]
	v_add_u32_e32 v126, v104, v241
	global_load_dwordx2 v[32:33], v126, s[50:51]
	ds_read_b128 v[226:229], v106 offset:4288
	ds_read_b128 v[230:233], v106 offset:4304
	ds_read_b128 v[234:237], v106 offset:4320
	ds_read_b128 v[238:241], v106 offset:4336
	ds_read_b128 v[196:199], v106 offset:10304
	ds_read_b128 v[200:203], v106 offset:10320
	ds_read_b128 v[204:207], v106 offset:10336
	ds_read_b128 v[216:219], v106 offset:10352
	s_waitcnt vmcnt(38)
	v_cvt_pk_f32_fp8_e32 v[166:167], v34
	v_cvt_pk_f32_fp8_sdwa v[168:169], v34 src0_sel:WORD_1
	v_cvt_pk_f32_fp8_e32 v[170:171], v35
	v_cvt_pk_f32_fp8_sdwa v[172:173], v35 src0_sel:WORD_1
	v_pk_fma_f32 v[242:243], v[180:181], v[166:167], v[242:243] op_sel_hi:[0,1,1]
	v_pk_fma_f32 v[244:245], v[180:181], v[168:169], v[244:245] op_sel_hi:[0,1,1]
	v_pk_fma_f32 v[246:247], v[180:181], v[170:171], v[246:247] op_sel_hi:[0,1,1]
	v_pk_fma_f32 v[248:249], v[180:181], v[172:173], v[248:249] op_sel_hi:[0,1,1]
	v_cvt_pk_f32_fp8_e32 v[166:167], v36
	v_cvt_pk_f32_fp8_sdwa v[168:169], v36 src0_sel:WORD_1
	v_cvt_pk_f32_fp8_e32 v[170:171], v37
	v_cvt_pk_f32_fp8_sdwa v[172:173], v37 src0_sel:WORD_1
	v_pk_fma_f32 v[242:243], v[180:181], v[166:167], v[242:243] op_sel:[1,0,0]
	v_pk_fma_f32 v[244:245], v[180:181], v[168:169], v[244:245] op_sel:[1,0,0]
	v_pk_fma_f32 v[246:247], v[180:181], v[170:171], v[246:247] op_sel:[1,0,0]
	v_pk_fma_f32 v[248:249], v[180:181], v[172:173], v[248:249] op_sel:[1,0,0]
	v_cvt_pk_f32_fp8_e32 v[166:167], v38
	v_cvt_pk_f32_fp8_sdwa v[168:169], v38 src0_sel:WORD_1
	v_cvt_pk_f32_fp8_e32 v[170:171], v39
	v_cvt_pk_f32_fp8_sdwa v[172:173], v39 src0_sel:WORD_1
	v_pk_fma_f32 v[242:243], v[182:183], v[166:167], v[242:243] op_sel_hi:[0,1,1]
	v_pk_fma_f32 v[244:245], v[182:183], v[168:169], v[244:245] op_sel_hi:[0,1,1]
	v_pk_fma_f32 v[246:247], v[182:183], v[170:171], v[246:247] op_sel_hi:[0,1,1]
	v_pk_fma_f32 v[248:249], v[182:183], v[172:173], v[248:249] op_sel_hi:[0,1,1]
	v_cvt_pk_f32_fp8_e32 v[166:167], v40
	v_cvt_pk_f32_fp8_sdwa v[168:169], v40 src0_sel:WORD_1
	v_cvt_pk_f32_fp8_e32 v[170:171], v41
	v_cvt_pk_f32_fp8_sdwa v[172:173], v41 src0_sel:WORD_1
	v_pk_fma_f32 v[242:243], v[182:183], v[166:167], v[242:243] op_sel:[1,0,0]
	v_pk_fma_f32 v[244:245], v[182:183], v[168:169], v[244:245] op_sel:[1,0,0]
	v_pk_fma_f32 v[246:247], v[182:183], v[170:171], v[246:247] op_sel:[1,0,0]
	v_pk_fma_f32 v[248:249], v[182:183], v[172:173], v[248:249] op_sel:[1,0,0]
	v_cvt_pk_f32_fp8_e32 v[166:167], v42
	v_cvt_pk_f32_fp8_sdwa v[168:169], v42 src0_sel:WORD_1
	v_cvt_pk_f32_fp8_e32 v[170:171], v43
	v_cvt_pk_f32_fp8_sdwa v[172:173], v43 src0_sel:WORD_1
	v_pk_fma_f32 v[242:243], v[184:185], v[166:167], v[242:243] op_sel_hi:[0,1,1]
	v_pk_fma_f32 v[244:245], v[184:185], v[168:169], v[244:245] op_sel_hi:[0,1,1]
	v_pk_fma_f32 v[246:247], v[184:185], v[170:171], v[246:247] op_sel_hi:[0,1,1]
	v_pk_fma_f32 v[248:249], v[184:185], v[172:173], v[248:249] op_sel_hi:[0,1,1]
	v_cvt_pk_f32_fp8_e32 v[166:167], v44
	v_cvt_pk_f32_fp8_sdwa v[168:169], v44 src0_sel:WORD_1
	v_cvt_pk_f32_fp8_e32 v[170:171], v45
	v_cvt_pk_f32_fp8_sdwa v[172:173], v45 src0_sel:WORD_1
	v_pk_fma_f32 v[242:243], v[184:185], v[166:167], v[242:243] op_sel:[1,0,0]
	v_pk_fma_f32 v[244:245], v[184:185], v[168:169], v[244:245] op_sel:[1,0,0]
	v_pk_fma_f32 v[246:247], v[184:185], v[170:171], v[246:247] op_sel:[1,0,0]
	v_pk_fma_f32 v[248:249], v[184:185], v[172:173], v[248:249] op_sel:[1,0,0]
	v_cvt_pk_f32_fp8_e32 v[166:167], v46
	v_cvt_pk_f32_fp8_sdwa v[168:169], v46 src0_sel:WORD_1
	v_cvt_pk_f32_fp8_e32 v[170:171], v47
	v_cvt_pk_f32_fp8_sdwa v[172:173], v47 src0_sel:WORD_1
	v_pk_fma_f32 v[242:243], v[186:187], v[166:167], v[242:243] op_sel_hi:[0,1,1]
	v_pk_fma_f32 v[244:245], v[186:187], v[168:169], v[244:245] op_sel_hi:[0,1,1]
	v_pk_fma_f32 v[246:247], v[186:187], v[170:171], v[246:247] op_sel_hi:[0,1,1]
	v_pk_fma_f32 v[248:249], v[186:187], v[172:173], v[248:249] op_sel_hi:[0,1,1]
	v_cvt_pk_f32_fp8_e32 v[166:167], v48
	v_cvt_pk_f32_fp8_sdwa v[168:169], v48 src0_sel:WORD_1
	v_cvt_pk_f32_fp8_e32 v[170:171], v49
	v_cvt_pk_f32_fp8_sdwa v[172:173], v49 src0_sel:WORD_1
	v_pk_fma_f32 v[242:243], v[186:187], v[166:167], v[242:243] op_sel:[1,0,0]
	v_pk_fma_f32 v[244:245], v[186:187], v[168:169], v[244:245] op_sel:[1,0,0]
	v_pk_fma_f32 v[246:247], v[186:187], v[170:171], v[246:247] op_sel:[1,0,0]
	v_pk_fma_f32 v[248:249], v[186:187], v[172:173], v[248:249] op_sel:[1,0,0]
	v_cvt_pk_f32_fp8_e32 v[166:167], v50
	v_cvt_pk_f32_fp8_sdwa v[168:169], v50 src0_sel:WORD_1
	v_cvt_pk_f32_fp8_e32 v[170:171], v51
	v_cvt_pk_f32_fp8_sdwa v[172:173], v51 src0_sel:WORD_1
	v_pk_fma_f32 v[242:243], v[188:189], v[166:167], v[242:243] op_sel_hi:[0,1,1]
	v_pk_fma_f32 v[244:245], v[188:189], v[168:169], v[244:245] op_sel_hi:[0,1,1]
	v_pk_fma_f32 v[246:247], v[188:189], v[170:171], v[246:247] op_sel_hi:[0,1,1]
	v_pk_fma_f32 v[248:249], v[188:189], v[172:173], v[248:249] op_sel_hi:[0,1,1]
	v_cvt_pk_f32_fp8_e32 v[166:167], v52
	v_cvt_pk_f32_fp8_sdwa v[168:169], v52 src0_sel:WORD_1
	v_cvt_pk_f32_fp8_e32 v[170:171], v53
	v_cvt_pk_f32_fp8_sdwa v[172:173], v53 src0_sel:WORD_1
	v_pk_fma_f32 v[242:243], v[188:189], v[166:167], v[242:243] op_sel:[1,0,0]
	v_pk_fma_f32 v[244:245], v[188:189], v[168:169], v[244:245] op_sel:[1,0,0]
	v_pk_fma_f32 v[246:247], v[188:189], v[170:171], v[246:247] op_sel:[1,0,0]
	v_pk_fma_f32 v[248:249], v[188:189], v[172:173], v[248:249] op_sel:[1,0,0]
	v_cvt_pk_f32_fp8_e32 v[166:167], v54
	v_cvt_pk_f32_fp8_sdwa v[168:169], v54 src0_sel:WORD_1
	v_cvt_pk_f32_fp8_e32 v[170:171], v55
	v_cvt_pk_f32_fp8_sdwa v[172:173], v55 src0_sel:WORD_1
	v_pk_fma_f32 v[242:243], v[190:191], v[166:167], v[242:243] op_sel_hi:[0,1,1]
	v_pk_fma_f32 v[244:245], v[190:191], v[168:169], v[244:245] op_sel_hi:[0,1,1]
	v_pk_fma_f32 v[246:247], v[190:191], v[170:171], v[246:247] op_sel_hi:[0,1,1]
	v_pk_fma_f32 v[248:249], v[190:191], v[172:173], v[248:249] op_sel_hi:[0,1,1]
	v_cvt_pk_f32_fp8_e32 v[166:167], v56
	v_cvt_pk_f32_fp8_sdwa v[168:169], v56 src0_sel:WORD_1
	v_cvt_pk_f32_fp8_e32 v[170:171], v57
	v_cvt_pk_f32_fp8_sdwa v[172:173], v57 src0_sel:WORD_1
	v_pk_fma_f32 v[242:243], v[190:191], v[166:167], v[242:243] op_sel:[1,0,0]
	v_pk_fma_f32 v[244:245], v[190:191], v[168:169], v[244:245] op_sel:[1,0,0]
	v_pk_fma_f32 v[246:247], v[190:191], v[170:171], v[246:247] op_sel:[1,0,0]
	v_pk_fma_f32 v[248:249], v[190:191], v[172:173], v[248:249] op_sel:[1,0,0]
	v_cvt_pk_f32_fp8_e32 v[166:167], v58
	v_cvt_pk_f32_fp8_sdwa v[168:169], v58 src0_sel:WORD_1
	v_cvt_pk_f32_fp8_e32 v[170:171], v59
	v_cvt_pk_f32_fp8_sdwa v[172:173], v59 src0_sel:WORD_1
	v_pk_fma_f32 v[242:243], v[192:193], v[166:167], v[242:243] op_sel_hi:[0,1,1]
	v_pk_fma_f32 v[244:245], v[192:193], v[168:169], v[244:245] op_sel_hi:[0,1,1]
	v_pk_fma_f32 v[246:247], v[192:193], v[170:171], v[246:247] op_sel_hi:[0,1,1]
	v_pk_fma_f32 v[248:249], v[192:193], v[172:173], v[248:249] op_sel_hi:[0,1,1]
	v_cvt_pk_f32_fp8_e32 v[166:167], v60
	v_cvt_pk_f32_fp8_sdwa v[168:169], v60 src0_sel:WORD_1
	v_cvt_pk_f32_fp8_e32 v[170:171], v61
	v_cvt_pk_f32_fp8_sdwa v[172:173], v61 src0_sel:WORD_1
	v_pk_fma_f32 v[242:243], v[192:193], v[166:167], v[242:243] op_sel:[1,0,0]
	v_pk_fma_f32 v[244:245], v[192:193], v[168:169], v[244:245] op_sel:[1,0,0]
	v_pk_fma_f32 v[246:247], v[192:193], v[170:171], v[246:247] op_sel:[1,0,0]
	v_pk_fma_f32 v[248:249], v[192:193], v[172:173], v[248:249] op_sel:[1,0,0]
	v_cvt_pk_f32_fp8_e32 v[166:167], v62
	v_cvt_pk_f32_fp8_sdwa v[168:169], v62 src0_sel:WORD_1
	v_cvt_pk_f32_fp8_e32 v[170:171], v63
	v_cvt_pk_f32_fp8_sdwa v[172:173], v63 src0_sel:WORD_1
	v_pk_fma_f32 v[242:243], v[194:195], v[166:167], v[242:243] op_sel_hi:[0,1,1]
	v_pk_fma_f32 v[244:245], v[194:195], v[168:169], v[244:245] op_sel_hi:[0,1,1]
	v_pk_fma_f32 v[246:247], v[194:195], v[170:171], v[246:247] op_sel_hi:[0,1,1]
	v_pk_fma_f32 v[248:249], v[194:195], v[172:173], v[248:249] op_sel_hi:[0,1,1]
	v_cvt_pk_f32_fp8_e32 v[166:167], v64
	v_cvt_pk_f32_fp8_sdwa v[168:169], v64 src0_sel:WORD_1
	v_cvt_pk_f32_fp8_e32 v[170:171], v65
	v_cvt_pk_f32_fp8_sdwa v[172:173], v65 src0_sel:WORD_1
	v_pk_fma_f32 v[242:243], v[194:195], v[166:167], v[242:243] op_sel:[1,0,0]
	v_pk_fma_f32 v[244:245], v[194:195], v[168:169], v[244:245] op_sel:[1,0,0]
	v_pk_fma_f32 v[246:247], v[194:195], v[170:171], v[246:247] op_sel:[1,0,0]
	v_pk_fma_f32 v[248:249], v[194:195], v[172:173], v[248:249] op_sel:[1,0,0]
	s_waitcnt lgkmcnt(0)
	v_add_u32_e32 v120, v104, v226
	global_load_dwordx2 v[34:35], v120, s[50:51]
	v_add_u32_e32 v122, v104, v227
	global_load_dwordx2 v[36:37], v122, s[50:51]
	v_add_u32_e32 v124, v104, v228
	global_load_dwordx2 v[38:39], v124, s[50:51]
	v_add_u32_e32 v126, v104, v229
	global_load_dwordx2 v[40:41], v126, s[50:51]
	v_add_u32_e32 v120, v104, v230
	global_load_dwordx2 v[42:43], v120, s[50:51]
	v_add_u32_e32 v122, v104, v231
	global_load_dwordx2 v[44:45], v122, s[50:51]
	v_add_u32_e32 v124, v104, v232
	global_load_dwordx2 v[46:47], v124, s[50:51]
	v_add_u32_e32 v126, v104, v233
	global_load_dwordx2 v[48:49], v126, s[50:51]
	v_add_u32_e32 v120, v104, v234
	global_load_dwordx2 v[50:51], v120, s[50:51]
	v_add_u32_e32 v122, v104, v235
	global_load_dwordx2 v[52:53], v122, s[50:51]
	v_add_u32_e32 v124, v104, v236
	global_load_dwordx2 v[54:55], v124, s[50:51]
	v_add_u32_e32 v126, v104, v237
	global_load_dwordx2 v[56:57], v126, s[50:51]
	v_add_u32_e32 v120, v104, v238
	global_load_dwordx2 v[58:59], v120, s[50:51]
	v_add_u32_e32 v122, v104, v239
	global_load_dwordx2 v[60:61], v122, s[50:51]
	v_add_u32_e32 v124, v104, v240
	global_load_dwordx2 v[62:63], v124, s[50:51]
	v_add_u32_e32 v126, v104, v241
	global_load_dwordx2 v[64:65], v126, s[50:51]
	ds_read_b128 v[226:229], v106 offset:4352
	ds_read_b128 v[230:233], v106 offset:4368
	ds_read_b128 v[234:237], v106 offset:4384
	ds_read_b128 v[238:241], v106 offset:4400
	ds_read_b128 v[180:183], v106 offset:10368
	ds_read_b128 v[184:187], v106 offset:10384
	ds_read_b128 v[188:191], v106 offset:10400
	ds_read_b128 v[192:195], v106 offset:10416
	s_waitcnt vmcnt(38)
	v_cvt_pk_f32_fp8_e32 v[166:167], v134
	v_cvt_pk_f32_fp8_sdwa v[168:169], v134 src0_sel:WORD_1
	v_cvt_pk_f32_fp8_e32 v[170:171], v135
	v_cvt_pk_f32_fp8_sdwa v[172:173], v135 src0_sel:WORD_1
	v_pk_fma_f32 v[242:243], v[196:197], v[166:167], v[242:243] op_sel_hi:[0,1,1]
	v_pk_fma_f32 v[244:245], v[196:197], v[168:169], v[244:245] op_sel_hi:[0,1,1]
	v_pk_fma_f32 v[246:247], v[196:197], v[170:171], v[246:247] op_sel_hi:[0,1,1]
	v_pk_fma_f32 v[248:249], v[196:197], v[172:173], v[248:249] op_sel_hi:[0,1,1]
	v_cvt_pk_f32_fp8_e32 v[166:167], v136
	v_cvt_pk_f32_fp8_sdwa v[168:169], v136 src0_sel:WORD_1
	v_cvt_pk_f32_fp8_e32 v[170:171], v137
	v_cvt_pk_f32_fp8_sdwa v[172:173], v137 src0_sel:WORD_1
	v_pk_fma_f32 v[242:243], v[196:197], v[166:167], v[242:243] op_sel:[1,0,0]
	v_pk_fma_f32 v[244:245], v[196:197], v[168:169], v[244:245] op_sel:[1,0,0]
	v_pk_fma_f32 v[246:247], v[196:197], v[170:171], v[246:247] op_sel:[1,0,0]
	v_pk_fma_f32 v[248:249], v[196:197], v[172:173], v[248:249] op_sel:[1,0,0]
	v_cvt_pk_f32_fp8_e32 v[166:167], v138
	v_cvt_pk_f32_fp8_sdwa v[168:169], v138 src0_sel:WORD_1
	v_cvt_pk_f32_fp8_e32 v[170:171], v139
	v_cvt_pk_f32_fp8_sdwa v[172:173], v139 src0_sel:WORD_1
	v_pk_fma_f32 v[242:243], v[198:199], v[166:167], v[242:243] op_sel_hi:[0,1,1]
	v_pk_fma_f32 v[244:245], v[198:199], v[168:169], v[244:245] op_sel_hi:[0,1,1]
	v_pk_fma_f32 v[246:247], v[198:199], v[170:171], v[246:247] op_sel_hi:[0,1,1]
	v_pk_fma_f32 v[248:249], v[198:199], v[172:173], v[248:249] op_sel_hi:[0,1,1]
	v_cvt_pk_f32_fp8_e32 v[166:167], v140
	v_cvt_pk_f32_fp8_sdwa v[168:169], v140 src0_sel:WORD_1
	v_cvt_pk_f32_fp8_e32 v[170:171], v141
	v_cvt_pk_f32_fp8_sdwa v[172:173], v141 src0_sel:WORD_1
	v_pk_fma_f32 v[242:243], v[198:199], v[166:167], v[242:243] op_sel:[1,0,0]
	v_pk_fma_f32 v[244:245], v[198:199], v[168:169], v[244:245] op_sel:[1,0,0]
	v_pk_fma_f32 v[246:247], v[198:199], v[170:171], v[246:247] op_sel:[1,0,0]
	v_pk_fma_f32 v[248:249], v[198:199], v[172:173], v[248:249] op_sel:[1,0,0]
	v_cvt_pk_f32_fp8_e32 v[166:167], v142
	v_cvt_pk_f32_fp8_sdwa v[168:169], v142 src0_sel:WORD_1
	v_cvt_pk_f32_fp8_e32 v[170:171], v143
	v_cvt_pk_f32_fp8_sdwa v[172:173], v143 src0_sel:WORD_1
	v_pk_fma_f32 v[242:243], v[200:201], v[166:167], v[242:243] op_sel_hi:[0,1,1]
	v_pk_fma_f32 v[244:245], v[200:201], v[168:169], v[244:245] op_sel_hi:[0,1,1]
	v_pk_fma_f32 v[246:247], v[200:201], v[170:171], v[246:247] op_sel_hi:[0,1,1]
	v_pk_fma_f32 v[248:249], v[200:201], v[172:173], v[248:249] op_sel_hi:[0,1,1]
	v_cvt_pk_f32_fp8_e32 v[166:167], v144
	v_cvt_pk_f32_fp8_sdwa v[168:169], v144 src0_sel:WORD_1
	v_cvt_pk_f32_fp8_e32 v[170:171], v145
	v_cvt_pk_f32_fp8_sdwa v[172:173], v145 src0_sel:WORD_1
	v_pk_fma_f32 v[242:243], v[200:201], v[166:167], v[242:243] op_sel:[1,0,0]
	v_pk_fma_f32 v[244:245], v[200:201], v[168:169], v[244:245] op_sel:[1,0,0]
	v_pk_fma_f32 v[246:247], v[200:201], v[170:171], v[246:247] op_sel:[1,0,0]
	v_pk_fma_f32 v[248:249], v[200:201], v[172:173], v[248:249] op_sel:[1,0,0]
	v_cvt_pk_f32_fp8_e32 v[166:167], v146
	v_cvt_pk_f32_fp8_sdwa v[168:169], v146 src0_sel:WORD_1
	v_cvt_pk_f32_fp8_e32 v[170:171], v147
	v_cvt_pk_f32_fp8_sdwa v[172:173], v147 src0_sel:WORD_1
	v_pk_fma_f32 v[242:243], v[202:203], v[166:167], v[242:243] op_sel_hi:[0,1,1]
	v_pk_fma_f32 v[244:245], v[202:203], v[168:169], v[244:245] op_sel_hi:[0,1,1]
	v_pk_fma_f32 v[246:247], v[202:203], v[170:171], v[246:247] op_sel_hi:[0,1,1]
	v_pk_fma_f32 v[248:249], v[202:203], v[172:173], v[248:249] op_sel_hi:[0,1,1]
	v_cvt_pk_f32_fp8_e32 v[166:167], v148
	v_cvt_pk_f32_fp8_sdwa v[168:169], v148 src0_sel:WORD_1
	v_cvt_pk_f32_fp8_e32 v[170:171], v149
	v_cvt_pk_f32_fp8_sdwa v[172:173], v149 src0_sel:WORD_1
	v_pk_fma_f32 v[242:243], v[202:203], v[166:167], v[242:243] op_sel:[1,0,0]
	v_pk_fma_f32 v[244:245], v[202:203], v[168:169], v[244:245] op_sel:[1,0,0]
	v_pk_fma_f32 v[246:247], v[202:203], v[170:171], v[246:247] op_sel:[1,0,0]
	v_pk_fma_f32 v[248:249], v[202:203], v[172:173], v[248:249] op_sel:[1,0,0]
	v_cvt_pk_f32_fp8_e32 v[166:167], v150
	v_cvt_pk_f32_fp8_sdwa v[168:169], v150 src0_sel:WORD_1
	v_cvt_pk_f32_fp8_e32 v[170:171], v151
	v_cvt_pk_f32_fp8_sdwa v[172:173], v151 src0_sel:WORD_1
	v_pk_fma_f32 v[242:243], v[204:205], v[166:167], v[242:243] op_sel_hi:[0,1,1]
	v_pk_fma_f32 v[244:245], v[204:205], v[168:169], v[244:245] op_sel_hi:[0,1,1]
	v_pk_fma_f32 v[246:247], v[204:205], v[170:171], v[246:247] op_sel_hi:[0,1,1]
	v_pk_fma_f32 v[248:249], v[204:205], v[172:173], v[248:249] op_sel_hi:[0,1,1]
	v_cvt_pk_f32_fp8_e32 v[166:167], v152
	v_cvt_pk_f32_fp8_sdwa v[168:169], v152 src0_sel:WORD_1
	v_cvt_pk_f32_fp8_e32 v[170:171], v153
	v_cvt_pk_f32_fp8_sdwa v[172:173], v153 src0_sel:WORD_1
	v_pk_fma_f32 v[242:243], v[204:205], v[166:167], v[242:243] op_sel:[1,0,0]
	v_pk_fma_f32 v[244:245], v[204:205], v[168:169], v[244:245] op_sel:[1,0,0]
	v_pk_fma_f32 v[246:247], v[204:205], v[170:171], v[246:247] op_sel:[1,0,0]
	v_pk_fma_f32 v[248:249], v[204:205], v[172:173], v[248:249] op_sel:[1,0,0]
	v_cvt_pk_f32_fp8_e32 v[166:167], v154
	v_cvt_pk_f32_fp8_sdwa v[168:169], v154 src0_sel:WORD_1
	v_cvt_pk_f32_fp8_e32 v[170:171], v155
	v_cvt_pk_f32_fp8_sdwa v[172:173], v155 src0_sel:WORD_1
	v_pk_fma_f32 v[242:243], v[206:207], v[166:167], v[242:243] op_sel_hi:[0,1,1]
	v_pk_fma_f32 v[244:245], v[206:207], v[168:169], v[244:245] op_sel_hi:[0,1,1]
	v_pk_fma_f32 v[246:247], v[206:207], v[170:171], v[246:247] op_sel_hi:[0,1,1]
	v_pk_fma_f32 v[248:249], v[206:207], v[172:173], v[248:249] op_sel_hi:[0,1,1]
	v_cvt_pk_f32_fp8_e32 v[166:167], v156
	v_cvt_pk_f32_fp8_sdwa v[168:169], v156 src0_sel:WORD_1
	v_cvt_pk_f32_fp8_e32 v[170:171], v157
	v_cvt_pk_f32_fp8_sdwa v[172:173], v157 src0_sel:WORD_1
	v_pk_fma_f32 v[242:243], v[206:207], v[166:167], v[242:243] op_sel:[1,0,0]
	v_pk_fma_f32 v[244:245], v[206:207], v[168:169], v[244:245] op_sel:[1,0,0]
	v_pk_fma_f32 v[246:247], v[206:207], v[170:171], v[246:247] op_sel:[1,0,0]
	v_pk_fma_f32 v[248:249], v[206:207], v[172:173], v[248:249] op_sel:[1,0,0]
	v_cvt_pk_f32_fp8_e32 v[166:167], v158
	v_cvt_pk_f32_fp8_sdwa v[168:169], v158 src0_sel:WORD_1
	v_cvt_pk_f32_fp8_e32 v[170:171], v159
	v_cvt_pk_f32_fp8_sdwa v[172:173], v159 src0_sel:WORD_1
	v_pk_fma_f32 v[242:243], v[216:217], v[166:167], v[242:243] op_sel_hi:[0,1,1]
	v_pk_fma_f32 v[244:245], v[216:217], v[168:169], v[244:245] op_sel_hi:[0,1,1]
	v_pk_fma_f32 v[246:247], v[216:217], v[170:171], v[246:247] op_sel_hi:[0,1,1]
	v_pk_fma_f32 v[248:249], v[216:217], v[172:173], v[248:249] op_sel_hi:[0,1,1]
	v_cvt_pk_f32_fp8_e32 v[166:167], v160
	v_cvt_pk_f32_fp8_sdwa v[168:169], v160 src0_sel:WORD_1
	v_cvt_pk_f32_fp8_e32 v[170:171], v161
	v_cvt_pk_f32_fp8_sdwa v[172:173], v161 src0_sel:WORD_1
	v_pk_fma_f32 v[242:243], v[216:217], v[166:167], v[242:243] op_sel:[1,0,0]
	v_pk_fma_f32 v[244:245], v[216:217], v[168:169], v[244:245] op_sel:[1,0,0]
	v_pk_fma_f32 v[246:247], v[216:217], v[170:171], v[246:247] op_sel:[1,0,0]
	v_pk_fma_f32 v[248:249], v[216:217], v[172:173], v[248:249] op_sel:[1,0,0]
	v_cvt_pk_f32_fp8_e32 v[166:167], v162
	v_cvt_pk_f32_fp8_sdwa v[168:169], v162 src0_sel:WORD_1
	v_cvt_pk_f32_fp8_e32 v[170:171], v163
	v_cvt_pk_f32_fp8_sdwa v[172:173], v163 src0_sel:WORD_1
	v_pk_fma_f32 v[242:243], v[218:219], v[166:167], v[242:243] op_sel_hi:[0,1,1]
	v_pk_fma_f32 v[244:245], v[218:219], v[168:169], v[244:245] op_sel_hi:[0,1,1]
	v_pk_fma_f32 v[246:247], v[218:219], v[170:171], v[246:247] op_sel_hi:[0,1,1]
	v_pk_fma_f32 v[248:249], v[218:219], v[172:173], v[248:249] op_sel_hi:[0,1,1]
	v_cvt_pk_f32_fp8_e32 v[166:167], v164
	v_cvt_pk_f32_fp8_sdwa v[168:169], v164 src0_sel:WORD_1
	v_cvt_pk_f32_fp8_e32 v[170:171], v165
	v_cvt_pk_f32_fp8_sdwa v[172:173], v165 src0_sel:WORD_1
	v_pk_fma_f32 v[242:243], v[218:219], v[166:167], v[242:243] op_sel:[1,0,0]
	v_pk_fma_f32 v[244:245], v[218:219], v[168:169], v[244:245] op_sel:[1,0,0]
	v_pk_fma_f32 v[246:247], v[218:219], v[170:171], v[246:247] op_sel:[1,0,0]
	v_pk_fma_f32 v[248:249], v[218:219], v[172:173], v[248:249] op_sel:[1,0,0]
	s_waitcnt lgkmcnt(0)
	v_add_u32_e32 v120, v104, v226
	global_load_dwordx2 v[134:135], v120, s[50:51]
	v_add_u32_e32 v122, v104, v227
	global_load_dwordx2 v[136:137], v122, s[50:51]
	v_add_u32_e32 v124, v104, v228
	global_load_dwordx2 v[138:139], v124, s[50:51]
	v_add_u32_e32 v126, v104, v229
	global_load_dwordx2 v[140:141], v126, s[50:51]
	v_add_u32_e32 v120, v104, v230
	global_load_dwordx2 v[142:143], v120, s[50:51]
	v_add_u32_e32 v122, v104, v231
	global_load_dwordx2 v[144:145], v122, s[50:51]
	v_add_u32_e32 v124, v104, v232
	global_load_dwordx2 v[146:147], v124, s[50:51]
	v_add_u32_e32 v126, v104, v233
	global_load_dwordx2 v[148:149], v126, s[50:51]
	v_add_u32_e32 v120, v104, v234
	global_load_dwordx2 v[150:151], v120, s[50:51]
	v_add_u32_e32 v122, v104, v235
	global_load_dwordx2 v[152:153], v122, s[50:51]
	v_add_u32_e32 v124, v104, v236
	global_load_dwordx2 v[154:155], v124, s[50:51]
	v_add_u32_e32 v126, v104, v237
	global_load_dwordx2 v[156:157], v126, s[50:51]
	v_add_u32_e32 v120, v104, v238
	global_load_dwordx2 v[158:159], v120, s[50:51]
	v_add_u32_e32 v122, v104, v239
	global_load_dwordx2 v[160:161], v122, s[50:51]
	v_add_u32_e32 v124, v104, v240
	global_load_dwordx2 v[162:163], v124, s[50:51]
	v_add_u32_e32 v126, v104, v241
	global_load_dwordx2 v[164:165], v126, s[50:51]
	ds_read_b128 v[226:229], v106 offset:4416
	ds_read_b128 v[230:233], v106 offset:4432
	ds_read_b128 v[234:237], v106 offset:4448
	ds_read_b128 v[238:241], v106 offset:4464
	ds_read_b128 v[196:199], v106 offset:10432
	ds_read_b128 v[200:203], v106 offset:10448
	ds_read_b128 v[204:207], v106 offset:10464
	ds_read_b128 v[216:219], v106 offset:10480
	s_waitcnt vmcnt(32)
	v_cvt_pk_f32_fp8_e32 v[166:167], v2
	v_cvt_pk_f32_fp8_sdwa v[168:169], v2 src0_sel:WORD_1
	v_cvt_pk_f32_fp8_e32 v[170:171], v3
	v_cvt_pk_f32_fp8_sdwa v[172:173], v3 src0_sel:WORD_1
	v_pk_fma_f32 v[242:243], v[180:181], v[166:167], v[242:243] op_sel_hi:[0,1,1]
	v_pk_fma_f32 v[244:245], v[180:181], v[168:169], v[244:245] op_sel_hi:[0,1,1]
	v_pk_fma_f32 v[246:247], v[180:181], v[170:171], v[246:247] op_sel_hi:[0,1,1]
	v_pk_fma_f32 v[248:249], v[180:181], v[172:173], v[248:249] op_sel_hi:[0,1,1]
	v_cvt_pk_f32_fp8_e32 v[166:167], v4
	v_cvt_pk_f32_fp8_sdwa v[168:169], v4 src0_sel:WORD_1
	v_cvt_pk_f32_fp8_e32 v[170:171], v5
	v_cvt_pk_f32_fp8_sdwa v[172:173], v5 src0_sel:WORD_1
	v_pk_fma_f32 v[242:243], v[180:181], v[166:167], v[242:243] op_sel:[1,0,0]
	v_pk_fma_f32 v[244:245], v[180:181], v[168:169], v[244:245] op_sel:[1,0,0]
	v_pk_fma_f32 v[246:247], v[180:181], v[170:171], v[246:247] op_sel:[1,0,0]
	v_pk_fma_f32 v[248:249], v[180:181], v[172:173], v[248:249] op_sel:[1,0,0]
	v_cvt_pk_f32_fp8_e32 v[166:167], v6
	v_cvt_pk_f32_fp8_sdwa v[168:169], v6 src0_sel:WORD_1
	v_cvt_pk_f32_fp8_e32 v[170:171], v7
	v_cvt_pk_f32_fp8_sdwa v[172:173], v7 src0_sel:WORD_1
	v_pk_fma_f32 v[242:243], v[182:183], v[166:167], v[242:243] op_sel_hi:[0,1,1]
	v_pk_fma_f32 v[244:245], v[182:183], v[168:169], v[244:245] op_sel_hi:[0,1,1]
	v_pk_fma_f32 v[246:247], v[182:183], v[170:171], v[246:247] op_sel_hi:[0,1,1]
	v_pk_fma_f32 v[248:249], v[182:183], v[172:173], v[248:249] op_sel_hi:[0,1,1]
	v_cvt_pk_f32_fp8_e32 v[166:167], v8
	v_cvt_pk_f32_fp8_sdwa v[168:169], v8 src0_sel:WORD_1
	v_cvt_pk_f32_fp8_e32 v[170:171], v9
	v_cvt_pk_f32_fp8_sdwa v[172:173], v9 src0_sel:WORD_1
	v_pk_fma_f32 v[242:243], v[182:183], v[166:167], v[242:243] op_sel:[1,0,0]
	v_pk_fma_f32 v[244:245], v[182:183], v[168:169], v[244:245] op_sel:[1,0,0]
	v_pk_fma_f32 v[246:247], v[182:183], v[170:171], v[246:247] op_sel:[1,0,0]
	v_pk_fma_f32 v[248:249], v[182:183], v[172:173], v[248:249] op_sel:[1,0,0]
	v_cvt_pk_f32_fp8_e32 v[166:167], v10
	v_cvt_pk_f32_fp8_sdwa v[168:169], v10 src0_sel:WORD_1
	v_cvt_pk_f32_fp8_e32 v[170:171], v11
	v_cvt_pk_f32_fp8_sdwa v[172:173], v11 src0_sel:WORD_1
	v_pk_fma_f32 v[242:243], v[184:185], v[166:167], v[242:243] op_sel_hi:[0,1,1]
	v_pk_fma_f32 v[244:245], v[184:185], v[168:169], v[244:245] op_sel_hi:[0,1,1]
	v_pk_fma_f32 v[246:247], v[184:185], v[170:171], v[246:247] op_sel_hi:[0,1,1]
	v_pk_fma_f32 v[248:249], v[184:185], v[172:173], v[248:249] op_sel_hi:[0,1,1]
	v_cvt_pk_f32_fp8_e32 v[166:167], v12
	v_cvt_pk_f32_fp8_sdwa v[168:169], v12 src0_sel:WORD_1
	v_cvt_pk_f32_fp8_e32 v[170:171], v13
	v_cvt_pk_f32_fp8_sdwa v[172:173], v13 src0_sel:WORD_1
	v_pk_fma_f32 v[242:243], v[184:185], v[166:167], v[242:243] op_sel:[1,0,0]
	v_pk_fma_f32 v[244:245], v[184:185], v[168:169], v[244:245] op_sel:[1,0,0]
	v_pk_fma_f32 v[246:247], v[184:185], v[170:171], v[246:247] op_sel:[1,0,0]
	v_pk_fma_f32 v[248:249], v[184:185], v[172:173], v[248:249] op_sel:[1,0,0]
	v_cvt_pk_f32_fp8_e32 v[166:167], v14
	v_cvt_pk_f32_fp8_sdwa v[168:169], v14 src0_sel:WORD_1
	v_cvt_pk_f32_fp8_e32 v[170:171], v15
	v_cvt_pk_f32_fp8_sdwa v[172:173], v15 src0_sel:WORD_1
	v_pk_fma_f32 v[242:243], v[186:187], v[166:167], v[242:243] op_sel_hi:[0,1,1]
	v_pk_fma_f32 v[244:245], v[186:187], v[168:169], v[244:245] op_sel_hi:[0,1,1]
	v_pk_fma_f32 v[246:247], v[186:187], v[170:171], v[246:247] op_sel_hi:[0,1,1]
	v_pk_fma_f32 v[248:249], v[186:187], v[172:173], v[248:249] op_sel_hi:[0,1,1]
	v_cvt_pk_f32_fp8_e32 v[166:167], v16
	v_cvt_pk_f32_fp8_sdwa v[168:169], v16 src0_sel:WORD_1
	v_cvt_pk_f32_fp8_e32 v[170:171], v17
	v_cvt_pk_f32_fp8_sdwa v[172:173], v17 src0_sel:WORD_1
	v_pk_fma_f32 v[242:243], v[186:187], v[166:167], v[242:243] op_sel:[1,0,0]
	v_pk_fma_f32 v[244:245], v[186:187], v[168:169], v[244:245] op_sel:[1,0,0]
	v_pk_fma_f32 v[246:247], v[186:187], v[170:171], v[246:247] op_sel:[1,0,0]
	v_pk_fma_f32 v[248:249], v[186:187], v[172:173], v[248:249] op_sel:[1,0,0]
	v_cvt_pk_f32_fp8_e32 v[166:167], v18
	v_cvt_pk_f32_fp8_sdwa v[168:169], v18 src0_sel:WORD_1
	v_cvt_pk_f32_fp8_e32 v[170:171], v19
	v_cvt_pk_f32_fp8_sdwa v[172:173], v19 src0_sel:WORD_1
	v_pk_fma_f32 v[242:243], v[188:189], v[166:167], v[242:243] op_sel_hi:[0,1,1]
	v_pk_fma_f32 v[244:245], v[188:189], v[168:169], v[244:245] op_sel_hi:[0,1,1]
	v_pk_fma_f32 v[246:247], v[188:189], v[170:171], v[246:247] op_sel_hi:[0,1,1]
	v_pk_fma_f32 v[248:249], v[188:189], v[172:173], v[248:249] op_sel_hi:[0,1,1]
	v_cvt_pk_f32_fp8_e32 v[166:167], v20
	v_cvt_pk_f32_fp8_sdwa v[168:169], v20 src0_sel:WORD_1
	v_cvt_pk_f32_fp8_e32 v[170:171], v21
	v_cvt_pk_f32_fp8_sdwa v[172:173], v21 src0_sel:WORD_1
	v_pk_fma_f32 v[242:243], v[188:189], v[166:167], v[242:243] op_sel:[1,0,0]
	v_pk_fma_f32 v[244:245], v[188:189], v[168:169], v[244:245] op_sel:[1,0,0]
	v_pk_fma_f32 v[246:247], v[188:189], v[170:171], v[246:247] op_sel:[1,0,0]
	v_pk_fma_f32 v[248:249], v[188:189], v[172:173], v[248:249] op_sel:[1,0,0]
	v_cvt_pk_f32_fp8_e32 v[166:167], v22
	v_cvt_pk_f32_fp8_sdwa v[168:169], v22 src0_sel:WORD_1
	v_cvt_pk_f32_fp8_e32 v[170:171], v23
	v_cvt_pk_f32_fp8_sdwa v[172:173], v23 src0_sel:WORD_1
	v_pk_fma_f32 v[242:243], v[190:191], v[166:167], v[242:243] op_sel_hi:[0,1,1]
	v_pk_fma_f32 v[244:245], v[190:191], v[168:169], v[244:245] op_sel_hi:[0,1,1]
	v_pk_fma_f32 v[246:247], v[190:191], v[170:171], v[246:247] op_sel_hi:[0,1,1]
	v_pk_fma_f32 v[248:249], v[190:191], v[172:173], v[248:249] op_sel_hi:[0,1,1]
	v_cvt_pk_f32_fp8_e32 v[166:167], v24
	v_cvt_pk_f32_fp8_sdwa v[168:169], v24 src0_sel:WORD_1
	v_cvt_pk_f32_fp8_e32 v[170:171], v25
	v_cvt_pk_f32_fp8_sdwa v[172:173], v25 src0_sel:WORD_1
	v_pk_fma_f32 v[242:243], v[190:191], v[166:167], v[242:243] op_sel:[1,0,0]
	v_pk_fma_f32 v[244:245], v[190:191], v[168:169], v[244:245] op_sel:[1,0,0]
	v_pk_fma_f32 v[246:247], v[190:191], v[170:171], v[246:247] op_sel:[1,0,0]
	v_pk_fma_f32 v[248:249], v[190:191], v[172:173], v[248:249] op_sel:[1,0,0]
	v_cvt_pk_f32_fp8_e32 v[166:167], v26
	v_cvt_pk_f32_fp8_sdwa v[168:169], v26 src0_sel:WORD_1
	v_cvt_pk_f32_fp8_e32 v[170:171], v27
	v_cvt_pk_f32_fp8_sdwa v[172:173], v27 src0_sel:WORD_1
	v_pk_fma_f32 v[242:243], v[192:193], v[166:167], v[242:243] op_sel_hi:[0,1,1]
	v_pk_fma_f32 v[244:245], v[192:193], v[168:169], v[244:245] op_sel_hi:[0,1,1]
	v_pk_fma_f32 v[246:247], v[192:193], v[170:171], v[246:247] op_sel_hi:[0,1,1]
	v_pk_fma_f32 v[248:249], v[192:193], v[172:173], v[248:249] op_sel_hi:[0,1,1]
	v_cvt_pk_f32_fp8_e32 v[166:167], v28
	v_cvt_pk_f32_fp8_sdwa v[168:169], v28 src0_sel:WORD_1
	v_cvt_pk_f32_fp8_e32 v[170:171], v29
	v_cvt_pk_f32_fp8_sdwa v[172:173], v29 src0_sel:WORD_1
	v_pk_fma_f32 v[242:243], v[192:193], v[166:167], v[242:243] op_sel:[1,0,0]
	v_pk_fma_f32 v[244:245], v[192:193], v[168:169], v[244:245] op_sel:[1,0,0]
	v_pk_fma_f32 v[246:247], v[192:193], v[170:171], v[246:247] op_sel:[1,0,0]
	v_pk_fma_f32 v[248:249], v[192:193], v[172:173], v[248:249] op_sel:[1,0,0]
	v_cvt_pk_f32_fp8_e32 v[166:167], v30
	v_cvt_pk_f32_fp8_sdwa v[168:169], v30 src0_sel:WORD_1
	v_cvt_pk_f32_fp8_e32 v[170:171], v31
	v_cvt_pk_f32_fp8_sdwa v[172:173], v31 src0_sel:WORD_1
	v_pk_fma_f32 v[242:243], v[194:195], v[166:167], v[242:243] op_sel_hi:[0,1,1]
	v_pk_fma_f32 v[244:245], v[194:195], v[168:169], v[244:245] op_sel_hi:[0,1,1]
	v_pk_fma_f32 v[246:247], v[194:195], v[170:171], v[246:247] op_sel_hi:[0,1,1]
	v_pk_fma_f32 v[248:249], v[194:195], v[172:173], v[248:249] op_sel_hi:[0,1,1]
	v_cvt_pk_f32_fp8_e32 v[166:167], v32
	v_cvt_pk_f32_fp8_sdwa v[168:169], v32 src0_sel:WORD_1
	v_cvt_pk_f32_fp8_e32 v[170:171], v33
	v_cvt_pk_f32_fp8_sdwa v[172:173], v33 src0_sel:WORD_1
	v_pk_fma_f32 v[242:243], v[194:195], v[166:167], v[242:243] op_sel:[1,0,0]
	v_pk_fma_f32 v[244:245], v[194:195], v[168:169], v[244:245] op_sel:[1,0,0]
	v_pk_fma_f32 v[246:247], v[194:195], v[170:171], v[246:247] op_sel:[1,0,0]
	v_pk_fma_f32 v[248:249], v[194:195], v[172:173], v[248:249] op_sel:[1,0,0]
	s_waitcnt lgkmcnt(0)
	v_add_u32_e32 v120, v104, v226
	global_load_dwordx2 v[2:3], v120, s[50:51]
	v_add_u32_e32 v122, v104, v227
	global_load_dwordx2 v[4:5], v122, s[50:51]
	v_add_u32_e32 v124, v104, v228
	global_load_dwordx2 v[6:7], v124, s[50:51]
	v_add_u32_e32 v126, v104, v229
	global_load_dwordx2 v[8:9], v126, s[50:51]
	v_add_u32_e32 v120, v104, v230
	global_load_dwordx2 v[10:11], v120, s[50:51]
	v_add_u32_e32 v122, v104, v231
	global_load_dwordx2 v[12:13], v122, s[50:51]
	v_add_u32_e32 v124, v104, v232
	global_load_dwordx2 v[14:15], v124, s[50:51]
	v_add_u32_e32 v126, v104, v233
	global_load_dwordx2 v[16:17], v126, s[50:51]
	v_add_u32_e32 v120, v104, v234
	global_load_dwordx2 v[18:19], v120, s[50:51]
	v_add_u32_e32 v122, v104, v235
	global_load_dwordx2 v[20:21], v122, s[50:51]
	v_add_u32_e32 v124, v104, v236
	global_load_dwordx2 v[22:23], v124, s[50:51]
	v_add_u32_e32 v126, v104, v237
	global_load_dwordx2 v[24:25], v126, s[50:51]
	v_add_u32_e32 v120, v104, v238
	global_load_dwordx2 v[26:27], v120, s[50:51]
	v_add_u32_e32 v122, v104, v239
	global_load_dwordx2 v[28:29], v122, s[50:51]
	v_add_u32_e32 v124, v104, v240
	global_load_dwordx2 v[30:31], v124, s[50:51]
	v_add_u32_e32 v126, v104, v241
	global_load_dwordx2 v[32:33], v126, s[50:51]
	ds_read_b128 v[226:229], v106 offset:4480
	ds_read_b128 v[230:233], v106 offset:4496
	ds_read_b128 v[234:237], v106 offset:4512
	ds_read_b128 v[238:241], v106 offset:4528
	ds_read_b128 v[180:183], v106 offset:10496
	ds_read_b128 v[184:187], v106 offset:10512
	ds_read_b128 v[188:191], v106 offset:10528
	ds_read_b128 v[192:195], v106 offset:10544
	s_waitcnt vmcnt(32)
	v_cvt_pk_f32_fp8_e32 v[166:167], v34
	v_cvt_pk_f32_fp8_sdwa v[168:169], v34 src0_sel:WORD_1
	v_cvt_pk_f32_fp8_e32 v[170:171], v35
	v_cvt_pk_f32_fp8_sdwa v[172:173], v35 src0_sel:WORD_1
	v_pk_fma_f32 v[242:243], v[196:197], v[166:167], v[242:243] op_sel_hi:[0,1,1]
	v_pk_fma_f32 v[244:245], v[196:197], v[168:169], v[244:245] op_sel_hi:[0,1,1]
	v_pk_fma_f32 v[246:247], v[196:197], v[170:171], v[246:247] op_sel_hi:[0,1,1]
	v_pk_fma_f32 v[248:249], v[196:197], v[172:173], v[248:249] op_sel_hi:[0,1,1]
	v_cvt_pk_f32_fp8_e32 v[166:167], v36
	v_cvt_pk_f32_fp8_sdwa v[168:169], v36 src0_sel:WORD_1
	v_cvt_pk_f32_fp8_e32 v[170:171], v37
	v_cvt_pk_f32_fp8_sdwa v[172:173], v37 src0_sel:WORD_1
	v_pk_fma_f32 v[242:243], v[196:197], v[166:167], v[242:243] op_sel:[1,0,0]
	v_pk_fma_f32 v[244:245], v[196:197], v[168:169], v[244:245] op_sel:[1,0,0]
	v_pk_fma_f32 v[246:247], v[196:197], v[170:171], v[246:247] op_sel:[1,0,0]
	v_pk_fma_f32 v[248:249], v[196:197], v[172:173], v[248:249] op_sel:[1,0,0]
	v_cvt_pk_f32_fp8_e32 v[166:167], v38
	v_cvt_pk_f32_fp8_sdwa v[168:169], v38 src0_sel:WORD_1
	v_cvt_pk_f32_fp8_e32 v[170:171], v39
	v_cvt_pk_f32_fp8_sdwa v[172:173], v39 src0_sel:WORD_1
	v_pk_fma_f32 v[242:243], v[198:199], v[166:167], v[242:243] op_sel_hi:[0,1,1]
	v_pk_fma_f32 v[244:245], v[198:199], v[168:169], v[244:245] op_sel_hi:[0,1,1]
	v_pk_fma_f32 v[246:247], v[198:199], v[170:171], v[246:247] op_sel_hi:[0,1,1]
	v_pk_fma_f32 v[248:249], v[198:199], v[172:173], v[248:249] op_sel_hi:[0,1,1]
	v_cvt_pk_f32_fp8_e32 v[166:167], v40
	v_cvt_pk_f32_fp8_sdwa v[168:169], v40 src0_sel:WORD_1
	v_cvt_pk_f32_fp8_e32 v[170:171], v41
	v_cvt_pk_f32_fp8_sdwa v[172:173], v41 src0_sel:WORD_1
	v_pk_fma_f32 v[242:243], v[198:199], v[166:167], v[242:243] op_sel:[1,0,0]
	v_pk_fma_f32 v[244:245], v[198:199], v[168:169], v[244:245] op_sel:[1,0,0]
	v_pk_fma_f32 v[246:247], v[198:199], v[170:171], v[246:247] op_sel:[1,0,0]
	v_pk_fma_f32 v[248:249], v[198:199], v[172:173], v[248:249] op_sel:[1,0,0]
	v_cvt_pk_f32_fp8_e32 v[166:167], v42
	v_cvt_pk_f32_fp8_sdwa v[168:169], v42 src0_sel:WORD_1
	v_cvt_pk_f32_fp8_e32 v[170:171], v43
	v_cvt_pk_f32_fp8_sdwa v[172:173], v43 src0_sel:WORD_1
	v_pk_fma_f32 v[242:243], v[200:201], v[166:167], v[242:243] op_sel_hi:[0,1,1]
	v_pk_fma_f32 v[244:245], v[200:201], v[168:169], v[244:245] op_sel_hi:[0,1,1]
	v_pk_fma_f32 v[246:247], v[200:201], v[170:171], v[246:247] op_sel_hi:[0,1,1]
	v_pk_fma_f32 v[248:249], v[200:201], v[172:173], v[248:249] op_sel_hi:[0,1,1]
	v_cvt_pk_f32_fp8_e32 v[166:167], v44
	v_cvt_pk_f32_fp8_sdwa v[168:169], v44 src0_sel:WORD_1
	v_cvt_pk_f32_fp8_e32 v[170:171], v45
	v_cvt_pk_f32_fp8_sdwa v[172:173], v45 src0_sel:WORD_1
	v_pk_fma_f32 v[242:243], v[200:201], v[166:167], v[242:243] op_sel:[1,0,0]
	v_pk_fma_f32 v[244:245], v[200:201], v[168:169], v[244:245] op_sel:[1,0,0]
	v_pk_fma_f32 v[246:247], v[200:201], v[170:171], v[246:247] op_sel:[1,0,0]
	v_pk_fma_f32 v[248:249], v[200:201], v[172:173], v[248:249] op_sel:[1,0,0]
	v_cvt_pk_f32_fp8_e32 v[166:167], v46
	v_cvt_pk_f32_fp8_sdwa v[168:169], v46 src0_sel:WORD_1
	v_cvt_pk_f32_fp8_e32 v[170:171], v47
	v_cvt_pk_f32_fp8_sdwa v[172:173], v47 src0_sel:WORD_1
	v_pk_fma_f32 v[242:243], v[202:203], v[166:167], v[242:243] op_sel_hi:[0,1,1]
	v_pk_fma_f32 v[244:245], v[202:203], v[168:169], v[244:245] op_sel_hi:[0,1,1]
	v_pk_fma_f32 v[246:247], v[202:203], v[170:171], v[246:247] op_sel_hi:[0,1,1]
	v_pk_fma_f32 v[248:249], v[202:203], v[172:173], v[248:249] op_sel_hi:[0,1,1]
	v_cvt_pk_f32_fp8_e32 v[166:167], v48
	v_cvt_pk_f32_fp8_sdwa v[168:169], v48 src0_sel:WORD_1
	v_cvt_pk_f32_fp8_e32 v[170:171], v49
	v_cvt_pk_f32_fp8_sdwa v[172:173], v49 src0_sel:WORD_1
	v_pk_fma_f32 v[242:243], v[202:203], v[166:167], v[242:243] op_sel:[1,0,0]
	v_pk_fma_f32 v[244:245], v[202:203], v[168:169], v[244:245] op_sel:[1,0,0]
	v_pk_fma_f32 v[246:247], v[202:203], v[170:171], v[246:247] op_sel:[1,0,0]
	v_pk_fma_f32 v[248:249], v[202:203], v[172:173], v[248:249] op_sel:[1,0,0]
	v_cvt_pk_f32_fp8_e32 v[166:167], v50
	v_cvt_pk_f32_fp8_sdwa v[168:169], v50 src0_sel:WORD_1
	v_cvt_pk_f32_fp8_e32 v[170:171], v51
	v_cvt_pk_f32_fp8_sdwa v[172:173], v51 src0_sel:WORD_1
	v_pk_fma_f32 v[242:243], v[204:205], v[166:167], v[242:243] op_sel_hi:[0,1,1]
	v_pk_fma_f32 v[244:245], v[204:205], v[168:169], v[244:245] op_sel_hi:[0,1,1]
	v_pk_fma_f32 v[246:247], v[204:205], v[170:171], v[246:247] op_sel_hi:[0,1,1]
	v_pk_fma_f32 v[248:249], v[204:205], v[172:173], v[248:249] op_sel_hi:[0,1,1]
	v_cvt_pk_f32_fp8_e32 v[166:167], v52
	v_cvt_pk_f32_fp8_sdwa v[168:169], v52 src0_sel:WORD_1
	v_cvt_pk_f32_fp8_e32 v[170:171], v53
	v_cvt_pk_f32_fp8_sdwa v[172:173], v53 src0_sel:WORD_1
	v_pk_fma_f32 v[242:243], v[204:205], v[166:167], v[242:243] op_sel:[1,0,0]
	v_pk_fma_f32 v[244:245], v[204:205], v[168:169], v[244:245] op_sel:[1,0,0]
	v_pk_fma_f32 v[246:247], v[204:205], v[170:171], v[246:247] op_sel:[1,0,0]
	v_pk_fma_f32 v[248:249], v[204:205], v[172:173], v[248:249] op_sel:[1,0,0]
	v_cvt_pk_f32_fp8_e32 v[166:167], v54
	v_cvt_pk_f32_fp8_sdwa v[168:169], v54 src0_sel:WORD_1
	v_cvt_pk_f32_fp8_e32 v[170:171], v55
	v_cvt_pk_f32_fp8_sdwa v[172:173], v55 src0_sel:WORD_1
	v_pk_fma_f32 v[242:243], v[206:207], v[166:167], v[242:243] op_sel_hi:[0,1,1]
	v_pk_fma_f32 v[244:245], v[206:207], v[168:169], v[244:245] op_sel_hi:[0,1,1]
	v_pk_fma_f32 v[246:247], v[206:207], v[170:171], v[246:247] op_sel_hi:[0,1,1]
	v_pk_fma_f32 v[248:249], v[206:207], v[172:173], v[248:249] op_sel_hi:[0,1,1]
	v_cvt_pk_f32_fp8_e32 v[166:167], v56
	v_cvt_pk_f32_fp8_sdwa v[168:169], v56 src0_sel:WORD_1
	v_cvt_pk_f32_fp8_e32 v[170:171], v57
	v_cvt_pk_f32_fp8_sdwa v[172:173], v57 src0_sel:WORD_1
	v_pk_fma_f32 v[242:243], v[206:207], v[166:167], v[242:243] op_sel:[1,0,0]
	v_pk_fma_f32 v[244:245], v[206:207], v[168:169], v[244:245] op_sel:[1,0,0]
	v_pk_fma_f32 v[246:247], v[206:207], v[170:171], v[246:247] op_sel:[1,0,0]
	v_pk_fma_f32 v[248:249], v[206:207], v[172:173], v[248:249] op_sel:[1,0,0]
	v_cvt_pk_f32_fp8_e32 v[166:167], v58
	v_cvt_pk_f32_fp8_sdwa v[168:169], v58 src0_sel:WORD_1
	v_cvt_pk_f32_fp8_e32 v[170:171], v59
	v_cvt_pk_f32_fp8_sdwa v[172:173], v59 src0_sel:WORD_1
	v_pk_fma_f32 v[242:243], v[216:217], v[166:167], v[242:243] op_sel_hi:[0,1,1]
	v_pk_fma_f32 v[244:245], v[216:217], v[168:169], v[244:245] op_sel_hi:[0,1,1]
	v_pk_fma_f32 v[246:247], v[216:217], v[170:171], v[246:247] op_sel_hi:[0,1,1]
	v_pk_fma_f32 v[248:249], v[216:217], v[172:173], v[248:249] op_sel_hi:[0,1,1]
	v_cvt_pk_f32_fp8_e32 v[166:167], v60
	v_cvt_pk_f32_fp8_sdwa v[168:169], v60 src0_sel:WORD_1
	v_cvt_pk_f32_fp8_e32 v[170:171], v61
	v_cvt_pk_f32_fp8_sdwa v[172:173], v61 src0_sel:WORD_1
	v_pk_fma_f32 v[242:243], v[216:217], v[166:167], v[242:243] op_sel:[1,0,0]
	v_pk_fma_f32 v[244:245], v[216:217], v[168:169], v[244:245] op_sel:[1,0,0]
	v_pk_fma_f32 v[246:247], v[216:217], v[170:171], v[246:247] op_sel:[1,0,0]
	v_pk_fma_f32 v[248:249], v[216:217], v[172:173], v[248:249] op_sel:[1,0,0]
	v_cvt_pk_f32_fp8_e32 v[166:167], v62
	v_cvt_pk_f32_fp8_sdwa v[168:169], v62 src0_sel:WORD_1
	v_cvt_pk_f32_fp8_e32 v[170:171], v63
	v_cvt_pk_f32_fp8_sdwa v[172:173], v63 src0_sel:WORD_1
	v_pk_fma_f32 v[242:243], v[218:219], v[166:167], v[242:243] op_sel_hi:[0,1,1]
	v_pk_fma_f32 v[244:245], v[218:219], v[168:169], v[244:245] op_sel_hi:[0,1,1]
	v_pk_fma_f32 v[246:247], v[218:219], v[170:171], v[246:247] op_sel_hi:[0,1,1]
	v_pk_fma_f32 v[248:249], v[218:219], v[172:173], v[248:249] op_sel_hi:[0,1,1]
	v_cvt_pk_f32_fp8_e32 v[166:167], v64
	v_cvt_pk_f32_fp8_sdwa v[168:169], v64 src0_sel:WORD_1
	v_cvt_pk_f32_fp8_e32 v[170:171], v65
	v_cvt_pk_f32_fp8_sdwa v[172:173], v65 src0_sel:WORD_1
	v_pk_fma_f32 v[242:243], v[218:219], v[166:167], v[242:243] op_sel:[1,0,0]
	v_pk_fma_f32 v[244:245], v[218:219], v[168:169], v[244:245] op_sel:[1,0,0]
	v_pk_fma_f32 v[246:247], v[218:219], v[170:171], v[246:247] op_sel:[1,0,0]
	v_pk_fma_f32 v[248:249], v[218:219], v[172:173], v[248:249] op_sel:[1,0,0]
	s_waitcnt lgkmcnt(0)
	v_add_u32_e32 v120, v104, v226
	global_load_dwordx2 v[34:35], v120, s[50:51]
	v_add_u32_e32 v122, v104, v227
	global_load_dwordx2 v[36:37], v122, s[50:51]
	v_add_u32_e32 v124, v104, v228
	global_load_dwordx2 v[38:39], v124, s[50:51]
	v_add_u32_e32 v126, v104, v229
	global_load_dwordx2 v[40:41], v126, s[50:51]
	v_add_u32_e32 v120, v104, v230
	global_load_dwordx2 v[42:43], v120, s[50:51]
	v_add_u32_e32 v122, v104, v231
	global_load_dwordx2 v[44:45], v122, s[50:51]
	v_add_u32_e32 v124, v104, v232
	global_load_dwordx2 v[46:47], v124, s[50:51]
	v_add_u32_e32 v126, v104, v233
	global_load_dwordx2 v[48:49], v126, s[50:51]
	v_add_u32_e32 v120, v104, v234
	global_load_dwordx2 v[50:51], v120, s[50:51]
	v_add_u32_e32 v122, v104, v235
	global_load_dwordx2 v[52:53], v122, s[50:51]
	v_add_u32_e32 v124, v104, v236
	global_load_dwordx2 v[54:55], v124, s[50:51]
	v_add_u32_e32 v126, v104, v237
	global_load_dwordx2 v[56:57], v126, s[50:51]
	v_add_u32_e32 v120, v104, v238
	global_load_dwordx2 v[58:59], v120, s[50:51]
	v_add_u32_e32 v122, v104, v239
	global_load_dwordx2 v[60:61], v122, s[50:51]
	v_add_u32_e32 v124, v104, v240
	global_load_dwordx2 v[62:63], v124, s[50:51]
	v_add_u32_e32 v126, v104, v241
	global_load_dwordx2 v[64:65], v126, s[50:51]
	ds_read_b128 v[226:229], v106 offset:4544
	ds_read_b128 v[230:233], v106 offset:4560
	ds_read_b128 v[234:237], v106 offset:4576
	ds_read_b128 v[238:241], v106 offset:4592
	ds_read_b128 v[196:199], v106 offset:10560
	ds_read_b128 v[200:203], v106 offset:10576
	ds_read_b128 v[204:207], v106 offset:10592
	ds_read_b128 v[216:219], v106 offset:10608
	s_waitcnt vmcnt(32)
	v_cvt_pk_f32_fp8_e32 v[166:167], v134
	v_cvt_pk_f32_fp8_sdwa v[168:169], v134 src0_sel:WORD_1
	v_cvt_pk_f32_fp8_e32 v[170:171], v135
	v_cvt_pk_f32_fp8_sdwa v[172:173], v135 src0_sel:WORD_1
	v_pk_fma_f32 v[242:243], v[180:181], v[166:167], v[242:243] op_sel_hi:[0,1,1]
	v_pk_fma_f32 v[244:245], v[180:181], v[168:169], v[244:245] op_sel_hi:[0,1,1]
	v_pk_fma_f32 v[246:247], v[180:181], v[170:171], v[246:247] op_sel_hi:[0,1,1]
	v_pk_fma_f32 v[248:249], v[180:181], v[172:173], v[248:249] op_sel_hi:[0,1,1]
	v_cvt_pk_f32_fp8_e32 v[166:167], v136
	v_cvt_pk_f32_fp8_sdwa v[168:169], v136 src0_sel:WORD_1
	v_cvt_pk_f32_fp8_e32 v[170:171], v137
	v_cvt_pk_f32_fp8_sdwa v[172:173], v137 src0_sel:WORD_1
	v_pk_fma_f32 v[242:243], v[180:181], v[166:167], v[242:243] op_sel:[1,0,0]
	v_pk_fma_f32 v[244:245], v[180:181], v[168:169], v[244:245] op_sel:[1,0,0]
	v_pk_fma_f32 v[246:247], v[180:181], v[170:171], v[246:247] op_sel:[1,0,0]
	v_pk_fma_f32 v[248:249], v[180:181], v[172:173], v[248:249] op_sel:[1,0,0]
	v_cvt_pk_f32_fp8_e32 v[166:167], v138
	v_cvt_pk_f32_fp8_sdwa v[168:169], v138 src0_sel:WORD_1
	v_cvt_pk_f32_fp8_e32 v[170:171], v139
	v_cvt_pk_f32_fp8_sdwa v[172:173], v139 src0_sel:WORD_1
	v_pk_fma_f32 v[242:243], v[182:183], v[166:167], v[242:243] op_sel_hi:[0,1,1]
	v_pk_fma_f32 v[244:245], v[182:183], v[168:169], v[244:245] op_sel_hi:[0,1,1]
	v_pk_fma_f32 v[246:247], v[182:183], v[170:171], v[246:247] op_sel_hi:[0,1,1]
	v_pk_fma_f32 v[248:249], v[182:183], v[172:173], v[248:249] op_sel_hi:[0,1,1]
	v_cvt_pk_f32_fp8_e32 v[166:167], v140
	v_cvt_pk_f32_fp8_sdwa v[168:169], v140 src0_sel:WORD_1
	v_cvt_pk_f32_fp8_e32 v[170:171], v141
	v_cvt_pk_f32_fp8_sdwa v[172:173], v141 src0_sel:WORD_1
	v_pk_fma_f32 v[242:243], v[182:183], v[166:167], v[242:243] op_sel:[1,0,0]
	v_pk_fma_f32 v[244:245], v[182:183], v[168:169], v[244:245] op_sel:[1,0,0]
	v_pk_fma_f32 v[246:247], v[182:183], v[170:171], v[246:247] op_sel:[1,0,0]
	v_pk_fma_f32 v[248:249], v[182:183], v[172:173], v[248:249] op_sel:[1,0,0]
	v_cvt_pk_f32_fp8_e32 v[166:167], v142
	v_cvt_pk_f32_fp8_sdwa v[168:169], v142 src0_sel:WORD_1
	v_cvt_pk_f32_fp8_e32 v[170:171], v143
	v_cvt_pk_f32_fp8_sdwa v[172:173], v143 src0_sel:WORD_1
	v_pk_fma_f32 v[242:243], v[184:185], v[166:167], v[242:243] op_sel_hi:[0,1,1]
	v_pk_fma_f32 v[244:245], v[184:185], v[168:169], v[244:245] op_sel_hi:[0,1,1]
	v_pk_fma_f32 v[246:247], v[184:185], v[170:171], v[246:247] op_sel_hi:[0,1,1]
	v_pk_fma_f32 v[248:249], v[184:185], v[172:173], v[248:249] op_sel_hi:[0,1,1]
	v_cvt_pk_f32_fp8_e32 v[166:167], v144
	v_cvt_pk_f32_fp8_sdwa v[168:169], v144 src0_sel:WORD_1
	v_cvt_pk_f32_fp8_e32 v[170:171], v145
	v_cvt_pk_f32_fp8_sdwa v[172:173], v145 src0_sel:WORD_1
	v_pk_fma_f32 v[242:243], v[184:185], v[166:167], v[242:243] op_sel:[1,0,0]
	v_pk_fma_f32 v[244:245], v[184:185], v[168:169], v[244:245] op_sel:[1,0,0]
	v_pk_fma_f32 v[246:247], v[184:185], v[170:171], v[246:247] op_sel:[1,0,0]
	v_pk_fma_f32 v[248:249], v[184:185], v[172:173], v[248:249] op_sel:[1,0,0]
	v_cvt_pk_f32_fp8_e32 v[166:167], v146
	v_cvt_pk_f32_fp8_sdwa v[168:169], v146 src0_sel:WORD_1
	v_cvt_pk_f32_fp8_e32 v[170:171], v147
	v_cvt_pk_f32_fp8_sdwa v[172:173], v147 src0_sel:WORD_1
	v_pk_fma_f32 v[242:243], v[186:187], v[166:167], v[242:243] op_sel_hi:[0,1,1]
	v_pk_fma_f32 v[244:245], v[186:187], v[168:169], v[244:245] op_sel_hi:[0,1,1]
	v_pk_fma_f32 v[246:247], v[186:187], v[170:171], v[246:247] op_sel_hi:[0,1,1]
	v_pk_fma_f32 v[248:249], v[186:187], v[172:173], v[248:249] op_sel_hi:[0,1,1]
	v_cvt_pk_f32_fp8_e32 v[166:167], v148
	v_cvt_pk_f32_fp8_sdwa v[168:169], v148 src0_sel:WORD_1
	v_cvt_pk_f32_fp8_e32 v[170:171], v149
	v_cvt_pk_f32_fp8_sdwa v[172:173], v149 src0_sel:WORD_1
	v_pk_fma_f32 v[242:243], v[186:187], v[166:167], v[242:243] op_sel:[1,0,0]
	v_pk_fma_f32 v[244:245], v[186:187], v[168:169], v[244:245] op_sel:[1,0,0]
	v_pk_fma_f32 v[246:247], v[186:187], v[170:171], v[246:247] op_sel:[1,0,0]
	v_pk_fma_f32 v[248:249], v[186:187], v[172:173], v[248:249] op_sel:[1,0,0]
	v_cvt_pk_f32_fp8_e32 v[166:167], v150
	v_cvt_pk_f32_fp8_sdwa v[168:169], v150 src0_sel:WORD_1
	v_cvt_pk_f32_fp8_e32 v[170:171], v151
	v_cvt_pk_f32_fp8_sdwa v[172:173], v151 src0_sel:WORD_1
	v_pk_fma_f32 v[242:243], v[188:189], v[166:167], v[242:243] op_sel_hi:[0,1,1]
	v_pk_fma_f32 v[244:245], v[188:189], v[168:169], v[244:245] op_sel_hi:[0,1,1]
	v_pk_fma_f32 v[246:247], v[188:189], v[170:171], v[246:247] op_sel_hi:[0,1,1]
	v_pk_fma_f32 v[248:249], v[188:189], v[172:173], v[248:249] op_sel_hi:[0,1,1]
	v_cvt_pk_f32_fp8_e32 v[166:167], v152
	v_cvt_pk_f32_fp8_sdwa v[168:169], v152 src0_sel:WORD_1
	v_cvt_pk_f32_fp8_e32 v[170:171], v153
	v_cvt_pk_f32_fp8_sdwa v[172:173], v153 src0_sel:WORD_1
	v_pk_fma_f32 v[242:243], v[188:189], v[166:167], v[242:243] op_sel:[1,0,0]
	v_pk_fma_f32 v[244:245], v[188:189], v[168:169], v[244:245] op_sel:[1,0,0]
	v_pk_fma_f32 v[246:247], v[188:189], v[170:171], v[246:247] op_sel:[1,0,0]
	v_pk_fma_f32 v[248:249], v[188:189], v[172:173], v[248:249] op_sel:[1,0,0]
	v_cvt_pk_f32_fp8_e32 v[166:167], v154
	v_cvt_pk_f32_fp8_sdwa v[168:169], v154 src0_sel:WORD_1
	v_cvt_pk_f32_fp8_e32 v[170:171], v155
	v_cvt_pk_f32_fp8_sdwa v[172:173], v155 src0_sel:WORD_1
	v_pk_fma_f32 v[242:243], v[190:191], v[166:167], v[242:243] op_sel_hi:[0,1,1]
	v_pk_fma_f32 v[244:245], v[190:191], v[168:169], v[244:245] op_sel_hi:[0,1,1]
	v_pk_fma_f32 v[246:247], v[190:191], v[170:171], v[246:247] op_sel_hi:[0,1,1]
	v_pk_fma_f32 v[248:249], v[190:191], v[172:173], v[248:249] op_sel_hi:[0,1,1]
	v_cvt_pk_f32_fp8_e32 v[166:167], v156
	v_cvt_pk_f32_fp8_sdwa v[168:169], v156 src0_sel:WORD_1
	v_cvt_pk_f32_fp8_e32 v[170:171], v157
	v_cvt_pk_f32_fp8_sdwa v[172:173], v157 src0_sel:WORD_1
	v_pk_fma_f32 v[242:243], v[190:191], v[166:167], v[242:243] op_sel:[1,0,0]
	v_pk_fma_f32 v[244:245], v[190:191], v[168:169], v[244:245] op_sel:[1,0,0]
	v_pk_fma_f32 v[246:247], v[190:191], v[170:171], v[246:247] op_sel:[1,0,0]
	v_pk_fma_f32 v[248:249], v[190:191], v[172:173], v[248:249] op_sel:[1,0,0]
	v_cvt_pk_f32_fp8_e32 v[166:167], v158
	v_cvt_pk_f32_fp8_sdwa v[168:169], v158 src0_sel:WORD_1
	v_cvt_pk_f32_fp8_e32 v[170:171], v159
	v_cvt_pk_f32_fp8_sdwa v[172:173], v159 src0_sel:WORD_1
	v_pk_fma_f32 v[242:243], v[192:193], v[166:167], v[242:243] op_sel_hi:[0,1,1]
	v_pk_fma_f32 v[244:245], v[192:193], v[168:169], v[244:245] op_sel_hi:[0,1,1]
	v_pk_fma_f32 v[246:247], v[192:193], v[170:171], v[246:247] op_sel_hi:[0,1,1]
	v_pk_fma_f32 v[248:249], v[192:193], v[172:173], v[248:249] op_sel_hi:[0,1,1]
	v_cvt_pk_f32_fp8_e32 v[166:167], v160
	v_cvt_pk_f32_fp8_sdwa v[168:169], v160 src0_sel:WORD_1
	v_cvt_pk_f32_fp8_e32 v[170:171], v161
	v_cvt_pk_f32_fp8_sdwa v[172:173], v161 src0_sel:WORD_1
	v_pk_fma_f32 v[242:243], v[192:193], v[166:167], v[242:243] op_sel:[1,0,0]
	v_pk_fma_f32 v[244:245], v[192:193], v[168:169], v[244:245] op_sel:[1,0,0]
	v_pk_fma_f32 v[246:247], v[192:193], v[170:171], v[246:247] op_sel:[1,0,0]
	v_pk_fma_f32 v[248:249], v[192:193], v[172:173], v[248:249] op_sel:[1,0,0]
	v_cvt_pk_f32_fp8_e32 v[166:167], v162
	v_cvt_pk_f32_fp8_sdwa v[168:169], v162 src0_sel:WORD_1
	v_cvt_pk_f32_fp8_e32 v[170:171], v163
	v_cvt_pk_f32_fp8_sdwa v[172:173], v163 src0_sel:WORD_1
	v_pk_fma_f32 v[242:243], v[194:195], v[166:167], v[242:243] op_sel_hi:[0,1,1]
	v_pk_fma_f32 v[244:245], v[194:195], v[168:169], v[244:245] op_sel_hi:[0,1,1]
	v_pk_fma_f32 v[246:247], v[194:195], v[170:171], v[246:247] op_sel_hi:[0,1,1]
	v_pk_fma_f32 v[248:249], v[194:195], v[172:173], v[248:249] op_sel_hi:[0,1,1]
	v_cvt_pk_f32_fp8_e32 v[166:167], v164
	v_cvt_pk_f32_fp8_sdwa v[168:169], v164 src0_sel:WORD_1
	v_cvt_pk_f32_fp8_e32 v[170:171], v165
	v_cvt_pk_f32_fp8_sdwa v[172:173], v165 src0_sel:WORD_1
	v_pk_fma_f32 v[242:243], v[194:195], v[166:167], v[242:243] op_sel:[1,0,0]
	v_pk_fma_f32 v[244:245], v[194:195], v[168:169], v[244:245] op_sel:[1,0,0]
	v_pk_fma_f32 v[246:247], v[194:195], v[170:171], v[246:247] op_sel:[1,0,0]
	v_pk_fma_f32 v[248:249], v[194:195], v[172:173], v[248:249] op_sel:[1,0,0]
	s_waitcnt lgkmcnt(0)
	v_add_u32_e32 v120, v104, v226
	global_load_dwordx2 v[134:135], v120, s[50:51]
	v_add_u32_e32 v122, v104, v227
	global_load_dwordx2 v[136:137], v122, s[50:51]
	v_add_u32_e32 v124, v104, v228
	global_load_dwordx2 v[138:139], v124, s[50:51]
	v_add_u32_e32 v126, v104, v229
	global_load_dwordx2 v[140:141], v126, s[50:51]
	v_add_u32_e32 v120, v104, v230
	global_load_dwordx2 v[142:143], v120, s[50:51]
	v_add_u32_e32 v122, v104, v231
	global_load_dwordx2 v[144:145], v122, s[50:51]
	v_add_u32_e32 v124, v104, v232
	global_load_dwordx2 v[146:147], v124, s[50:51]
	v_add_u32_e32 v126, v104, v233
	global_load_dwordx2 v[148:149], v126, s[50:51]
	v_add_u32_e32 v120, v104, v234
	global_load_dwordx2 v[150:151], v120, s[50:51]
	v_add_u32_e32 v122, v104, v235
	global_load_dwordx2 v[152:153], v122, s[50:51]
	v_add_u32_e32 v124, v104, v236
	global_load_dwordx2 v[154:155], v124, s[50:51]
	v_add_u32_e32 v126, v104, v237
	global_load_dwordx2 v[156:157], v126, s[50:51]
	v_add_u32_e32 v120, v104, v238
	global_load_dwordx2 v[158:159], v120, s[50:51]
	v_add_u32_e32 v122, v104, v239
	global_load_dwordx2 v[160:161], v122, s[50:51]
	v_add_u32_e32 v124, v104, v240
	global_load_dwordx2 v[162:163], v124, s[50:51]
	v_add_u32_e32 v126, v104, v241
	global_load_dwordx2 v[164:165], v126, s[50:51]
	ds_read_b128 v[226:229], v106 offset:0
	ds_read_b128 v[230:233], v106 offset:16
	ds_read_b128 v[234:237], v106 offset:32
	ds_read_b128 v[238:241], v106 offset:48
	ds_read_b128 v[180:183], v106 offset:10624
	ds_read_b128 v[184:187], v106 offset:10640
	ds_read_b128 v[188:191], v106 offset:10656
	ds_read_b128 v[192:195], v106 offset:10672
	s_waitcnt vmcnt(32)
	v_cvt_pk_f32_fp8_e32 v[166:167], v2
	v_cvt_pk_f32_fp8_sdwa v[168:169], v2 src0_sel:WORD_1
	v_cvt_pk_f32_fp8_e32 v[170:171], v3
	v_cvt_pk_f32_fp8_sdwa v[172:173], v3 src0_sel:WORD_1
	v_pk_fma_f32 v[242:243], v[196:197], v[166:167], v[242:243] op_sel_hi:[0,1,1]
	v_pk_fma_f32 v[244:245], v[196:197], v[168:169], v[244:245] op_sel_hi:[0,1,1]
	v_pk_fma_f32 v[246:247], v[196:197], v[170:171], v[246:247] op_sel_hi:[0,1,1]
	v_pk_fma_f32 v[248:249], v[196:197], v[172:173], v[248:249] op_sel_hi:[0,1,1]
	v_cvt_pk_f32_fp8_e32 v[166:167], v4
	v_cvt_pk_f32_fp8_sdwa v[168:169], v4 src0_sel:WORD_1
	v_cvt_pk_f32_fp8_e32 v[170:171], v5
	v_cvt_pk_f32_fp8_sdwa v[172:173], v5 src0_sel:WORD_1
	v_pk_fma_f32 v[242:243], v[196:197], v[166:167], v[242:243] op_sel:[1,0,0]
	v_pk_fma_f32 v[244:245], v[196:197], v[168:169], v[244:245] op_sel:[1,0,0]
	v_pk_fma_f32 v[246:247], v[196:197], v[170:171], v[246:247] op_sel:[1,0,0]
	v_pk_fma_f32 v[248:249], v[196:197], v[172:173], v[248:249] op_sel:[1,0,0]
	v_cvt_pk_f32_fp8_e32 v[166:167], v6
	v_cvt_pk_f32_fp8_sdwa v[168:169], v6 src0_sel:WORD_1
	v_cvt_pk_f32_fp8_e32 v[170:171], v7
	v_cvt_pk_f32_fp8_sdwa v[172:173], v7 src0_sel:WORD_1
	v_pk_fma_f32 v[242:243], v[198:199], v[166:167], v[242:243] op_sel_hi:[0,1,1]
	v_pk_fma_f32 v[244:245], v[198:199], v[168:169], v[244:245] op_sel_hi:[0,1,1]
	v_pk_fma_f32 v[246:247], v[198:199], v[170:171], v[246:247] op_sel_hi:[0,1,1]
	v_pk_fma_f32 v[248:249], v[198:199], v[172:173], v[248:249] op_sel_hi:[0,1,1]
	v_cvt_pk_f32_fp8_e32 v[166:167], v8
	v_cvt_pk_f32_fp8_sdwa v[168:169], v8 src0_sel:WORD_1
	v_cvt_pk_f32_fp8_e32 v[170:171], v9
	v_cvt_pk_f32_fp8_sdwa v[172:173], v9 src0_sel:WORD_1
	v_pk_fma_f32 v[242:243], v[198:199], v[166:167], v[242:243] op_sel:[1,0,0]
	v_pk_fma_f32 v[244:245], v[198:199], v[168:169], v[244:245] op_sel:[1,0,0]
	v_pk_fma_f32 v[246:247], v[198:199], v[170:171], v[246:247] op_sel:[1,0,0]
	v_pk_fma_f32 v[248:249], v[198:199], v[172:173], v[248:249] op_sel:[1,0,0]
	v_cvt_pk_f32_fp8_e32 v[166:167], v10
	v_cvt_pk_f32_fp8_sdwa v[168:169], v10 src0_sel:WORD_1
	v_cvt_pk_f32_fp8_e32 v[170:171], v11
	v_cvt_pk_f32_fp8_sdwa v[172:173], v11 src0_sel:WORD_1
	v_pk_fma_f32 v[242:243], v[200:201], v[166:167], v[242:243] op_sel_hi:[0,1,1]
	v_pk_fma_f32 v[244:245], v[200:201], v[168:169], v[244:245] op_sel_hi:[0,1,1]
	v_pk_fma_f32 v[246:247], v[200:201], v[170:171], v[246:247] op_sel_hi:[0,1,1]
	v_pk_fma_f32 v[248:249], v[200:201], v[172:173], v[248:249] op_sel_hi:[0,1,1]
	v_cvt_pk_f32_fp8_e32 v[166:167], v12
	v_cvt_pk_f32_fp8_sdwa v[168:169], v12 src0_sel:WORD_1
	v_cvt_pk_f32_fp8_e32 v[170:171], v13
	v_cvt_pk_f32_fp8_sdwa v[172:173], v13 src0_sel:WORD_1
	v_pk_fma_f32 v[242:243], v[200:201], v[166:167], v[242:243] op_sel:[1,0,0]
	v_pk_fma_f32 v[244:245], v[200:201], v[168:169], v[244:245] op_sel:[1,0,0]
	v_pk_fma_f32 v[246:247], v[200:201], v[170:171], v[246:247] op_sel:[1,0,0]
	v_pk_fma_f32 v[248:249], v[200:201], v[172:173], v[248:249] op_sel:[1,0,0]
	v_cvt_pk_f32_fp8_e32 v[166:167], v14
	v_cvt_pk_f32_fp8_sdwa v[168:169], v14 src0_sel:WORD_1
	v_cvt_pk_f32_fp8_e32 v[170:171], v15
	v_cvt_pk_f32_fp8_sdwa v[172:173], v15 src0_sel:WORD_1
	v_pk_fma_f32 v[242:243], v[202:203], v[166:167], v[242:243] op_sel_hi:[0,1,1]
	v_pk_fma_f32 v[244:245], v[202:203], v[168:169], v[244:245] op_sel_hi:[0,1,1]
	v_pk_fma_f32 v[246:247], v[202:203], v[170:171], v[246:247] op_sel_hi:[0,1,1]
	v_pk_fma_f32 v[248:249], v[202:203], v[172:173], v[248:249] op_sel_hi:[0,1,1]
	v_cvt_pk_f32_fp8_e32 v[166:167], v16
	v_cvt_pk_f32_fp8_sdwa v[168:169], v16 src0_sel:WORD_1
	v_cvt_pk_f32_fp8_e32 v[170:171], v17
	v_cvt_pk_f32_fp8_sdwa v[172:173], v17 src0_sel:WORD_1
	v_pk_fma_f32 v[242:243], v[202:203], v[166:167], v[242:243] op_sel:[1,0,0]
	v_pk_fma_f32 v[244:245], v[202:203], v[168:169], v[244:245] op_sel:[1,0,0]
	v_pk_fma_f32 v[246:247], v[202:203], v[170:171], v[246:247] op_sel:[1,0,0]
	v_pk_fma_f32 v[248:249], v[202:203], v[172:173], v[248:249] op_sel:[1,0,0]
	v_cvt_pk_f32_fp8_e32 v[166:167], v18
	v_cvt_pk_f32_fp8_sdwa v[168:169], v18 src0_sel:WORD_1
	v_cvt_pk_f32_fp8_e32 v[170:171], v19
	v_cvt_pk_f32_fp8_sdwa v[172:173], v19 src0_sel:WORD_1
	v_pk_fma_f32 v[242:243], v[204:205], v[166:167], v[242:243] op_sel_hi:[0,1,1]
	v_pk_fma_f32 v[244:245], v[204:205], v[168:169], v[244:245] op_sel_hi:[0,1,1]
	v_pk_fma_f32 v[246:247], v[204:205], v[170:171], v[246:247] op_sel_hi:[0,1,1]
	v_pk_fma_f32 v[248:249], v[204:205], v[172:173], v[248:249] op_sel_hi:[0,1,1]
	v_cvt_pk_f32_fp8_e32 v[166:167], v20
	v_cvt_pk_f32_fp8_sdwa v[168:169], v20 src0_sel:WORD_1
	v_cvt_pk_f32_fp8_e32 v[170:171], v21
	v_cvt_pk_f32_fp8_sdwa v[172:173], v21 src0_sel:WORD_1
	v_pk_fma_f32 v[242:243], v[204:205], v[166:167], v[242:243] op_sel:[1,0,0]
	v_pk_fma_f32 v[244:245], v[204:205], v[168:169], v[244:245] op_sel:[1,0,0]
	v_pk_fma_f32 v[246:247], v[204:205], v[170:171], v[246:247] op_sel:[1,0,0]
	v_pk_fma_f32 v[248:249], v[204:205], v[172:173], v[248:249] op_sel:[1,0,0]
	v_cvt_pk_f32_fp8_e32 v[166:167], v22
	v_cvt_pk_f32_fp8_sdwa v[168:169], v22 src0_sel:WORD_1
	v_cvt_pk_f32_fp8_e32 v[170:171], v23
	v_cvt_pk_f32_fp8_sdwa v[172:173], v23 src0_sel:WORD_1
	v_pk_fma_f32 v[242:243], v[206:207], v[166:167], v[242:243] op_sel_hi:[0,1,1]
	v_pk_fma_f32 v[244:245], v[206:207], v[168:169], v[244:245] op_sel_hi:[0,1,1]
	v_pk_fma_f32 v[246:247], v[206:207], v[170:171], v[246:247] op_sel_hi:[0,1,1]
	v_pk_fma_f32 v[248:249], v[206:207], v[172:173], v[248:249] op_sel_hi:[0,1,1]
	v_cvt_pk_f32_fp8_e32 v[166:167], v24
	v_cvt_pk_f32_fp8_sdwa v[168:169], v24 src0_sel:WORD_1
	v_cvt_pk_f32_fp8_e32 v[170:171], v25
	v_cvt_pk_f32_fp8_sdwa v[172:173], v25 src0_sel:WORD_1
	v_pk_fma_f32 v[242:243], v[206:207], v[166:167], v[242:243] op_sel:[1,0,0]
	v_pk_fma_f32 v[244:245], v[206:207], v[168:169], v[244:245] op_sel:[1,0,0]
	v_pk_fma_f32 v[246:247], v[206:207], v[170:171], v[246:247] op_sel:[1,0,0]
	v_pk_fma_f32 v[248:249], v[206:207], v[172:173], v[248:249] op_sel:[1,0,0]
	v_cvt_pk_f32_fp8_e32 v[166:167], v26
	v_cvt_pk_f32_fp8_sdwa v[168:169], v26 src0_sel:WORD_1
	v_cvt_pk_f32_fp8_e32 v[170:171], v27
	v_cvt_pk_f32_fp8_sdwa v[172:173], v27 src0_sel:WORD_1
	v_pk_fma_f32 v[242:243], v[216:217], v[166:167], v[242:243] op_sel_hi:[0,1,1]
	v_pk_fma_f32 v[244:245], v[216:217], v[168:169], v[244:245] op_sel_hi:[0,1,1]
	v_pk_fma_f32 v[246:247], v[216:217], v[170:171], v[246:247] op_sel_hi:[0,1,1]
	v_pk_fma_f32 v[248:249], v[216:217], v[172:173], v[248:249] op_sel_hi:[0,1,1]
	v_cvt_pk_f32_fp8_e32 v[166:167], v28
	v_cvt_pk_f32_fp8_sdwa v[168:169], v28 src0_sel:WORD_1
	v_cvt_pk_f32_fp8_e32 v[170:171], v29
	v_cvt_pk_f32_fp8_sdwa v[172:173], v29 src0_sel:WORD_1
	v_pk_fma_f32 v[242:243], v[216:217], v[166:167], v[242:243] op_sel:[1,0,0]
	v_pk_fma_f32 v[244:245], v[216:217], v[168:169], v[244:245] op_sel:[1,0,0]
	v_pk_fma_f32 v[246:247], v[216:217], v[170:171], v[246:247] op_sel:[1,0,0]
	v_pk_fma_f32 v[248:249], v[216:217], v[172:173], v[248:249] op_sel:[1,0,0]
	v_cvt_pk_f32_fp8_e32 v[166:167], v30
	v_cvt_pk_f32_fp8_sdwa v[168:169], v30 src0_sel:WORD_1
	v_cvt_pk_f32_fp8_e32 v[170:171], v31
	v_cvt_pk_f32_fp8_sdwa v[172:173], v31 src0_sel:WORD_1
	v_pk_fma_f32 v[242:243], v[218:219], v[166:167], v[242:243] op_sel_hi:[0,1,1]
	v_pk_fma_f32 v[244:245], v[218:219], v[168:169], v[244:245] op_sel_hi:[0,1,1]
	v_pk_fma_f32 v[246:247], v[218:219], v[170:171], v[246:247] op_sel_hi:[0,1,1]
	v_pk_fma_f32 v[248:249], v[218:219], v[172:173], v[248:249] op_sel_hi:[0,1,1]
	v_cvt_pk_f32_fp8_e32 v[166:167], v32
	v_cvt_pk_f32_fp8_sdwa v[168:169], v32 src0_sel:WORD_1
	v_cvt_pk_f32_fp8_e32 v[170:171], v33
	v_cvt_pk_f32_fp8_sdwa v[172:173], v33 src0_sel:WORD_1
	v_pk_fma_f32 v[242:243], v[218:219], v[166:167], v[242:243] op_sel:[1,0,0]
	v_pk_fma_f32 v[244:245], v[218:219], v[168:169], v[244:245] op_sel:[1,0,0]
	v_pk_fma_f32 v[246:247], v[218:219], v[170:171], v[246:247] op_sel:[1,0,0]
	v_pk_fma_f32 v[248:249], v[218:219], v[172:173], v[248:249] op_sel:[1,0,0]
	s_waitcnt lgkmcnt(0)
	v_add_u32_e32 v120, v104, v226
	global_load_dwordx2 v[2:3], v120, s[52:53]
	v_add_u32_e32 v122, v104, v227
	global_load_dwordx2 v[4:5], v122, s[52:53]
	v_add_u32_e32 v124, v104, v228
	global_load_dwordx2 v[6:7], v124, s[52:53]
	v_add_u32_e32 v126, v104, v229
	global_load_dwordx2 v[8:9], v126, s[52:53]
	v_add_u32_e32 v120, v104, v230
	global_load_dwordx2 v[10:11], v120, s[52:53]
	v_add_u32_e32 v122, v104, v231
	global_load_dwordx2 v[12:13], v122, s[52:53]
	v_add_u32_e32 v124, v104, v232
	global_load_dwordx2 v[14:15], v124, s[52:53]
	v_add_u32_e32 v126, v104, v233
	global_load_dwordx2 v[16:17], v126, s[52:53]
	v_add_u32_e32 v120, v104, v234
	global_load_dwordx2 v[18:19], v120, s[52:53]
	v_add_u32_e32 v122, v104, v235
	global_load_dwordx2 v[20:21], v122, s[52:53]
	v_add_u32_e32 v124, v104, v236
	global_load_dwordx2 v[22:23], v124, s[52:53]
	v_add_u32_e32 v126, v104, v237
	global_load_dwordx2 v[24:25], v126, s[52:53]
	v_add_u32_e32 v120, v104, v238
	global_load_dwordx2 v[26:27], v120, s[52:53]
	v_add_u32_e32 v122, v104, v239
	global_load_dwordx2 v[28:29], v122, s[52:53]
	v_add_u32_e32 v124, v104, v240
	global_load_dwordx2 v[30:31], v124, s[52:53]
	v_add_u32_e32 v126, v104, v241
	global_load_dwordx2 v[32:33], v126, s[52:53]
	ds_read_b128 v[226:229], v106 offset:64
	ds_read_b128 v[230:233], v106 offset:80
	ds_read_b128 v[234:237], v106 offset:96
	ds_read_b128 v[238:241], v106 offset:112
	ds_read_b128 v[196:199], v106 offset:10688
	ds_read_b128 v[200:203], v106 offset:10704
	ds_read_b128 v[204:207], v106 offset:10720
	ds_read_b128 v[216:219], v106 offset:10736
	s_waitcnt vmcnt(32)
	v_cvt_pk_f32_fp8_e32 v[166:167], v34
	v_cvt_pk_f32_fp8_sdwa v[168:169], v34 src0_sel:WORD_1
	v_cvt_pk_f32_fp8_e32 v[170:171], v35
	v_cvt_pk_f32_fp8_sdwa v[172:173], v35 src0_sel:WORD_1
	v_pk_fma_f32 v[242:243], v[180:181], v[166:167], v[242:243] op_sel_hi:[0,1,1]
	v_pk_fma_f32 v[244:245], v[180:181], v[168:169], v[244:245] op_sel_hi:[0,1,1]
	v_pk_fma_f32 v[246:247], v[180:181], v[170:171], v[246:247] op_sel_hi:[0,1,1]
	v_pk_fma_f32 v[248:249], v[180:181], v[172:173], v[248:249] op_sel_hi:[0,1,1]
	v_cvt_pk_f32_fp8_e32 v[166:167], v36
	v_cvt_pk_f32_fp8_sdwa v[168:169], v36 src0_sel:WORD_1
	v_cvt_pk_f32_fp8_e32 v[170:171], v37
	v_cvt_pk_f32_fp8_sdwa v[172:173], v37 src0_sel:WORD_1
	v_pk_fma_f32 v[242:243], v[180:181], v[166:167], v[242:243] op_sel:[1,0,0]
	v_pk_fma_f32 v[244:245], v[180:181], v[168:169], v[244:245] op_sel:[1,0,0]
	v_pk_fma_f32 v[246:247], v[180:181], v[170:171], v[246:247] op_sel:[1,0,0]
	v_pk_fma_f32 v[248:249], v[180:181], v[172:173], v[248:249] op_sel:[1,0,0]
	v_cvt_pk_f32_fp8_e32 v[166:167], v38
	v_cvt_pk_f32_fp8_sdwa v[168:169], v38 src0_sel:WORD_1
	v_cvt_pk_f32_fp8_e32 v[170:171], v39
	v_cvt_pk_f32_fp8_sdwa v[172:173], v39 src0_sel:WORD_1
	v_pk_fma_f32 v[242:243], v[182:183], v[166:167], v[242:243] op_sel_hi:[0,1,1]
	v_pk_fma_f32 v[244:245], v[182:183], v[168:169], v[244:245] op_sel_hi:[0,1,1]
	v_pk_fma_f32 v[246:247], v[182:183], v[170:171], v[246:247] op_sel_hi:[0,1,1]
	v_pk_fma_f32 v[248:249], v[182:183], v[172:173], v[248:249] op_sel_hi:[0,1,1]
	v_cvt_pk_f32_fp8_e32 v[166:167], v40
	v_cvt_pk_f32_fp8_sdwa v[168:169], v40 src0_sel:WORD_1
	v_cvt_pk_f32_fp8_e32 v[170:171], v41
	v_cvt_pk_f32_fp8_sdwa v[172:173], v41 src0_sel:WORD_1
	v_pk_fma_f32 v[242:243], v[182:183], v[166:167], v[242:243] op_sel:[1,0,0]
	v_pk_fma_f32 v[244:245], v[182:183], v[168:169], v[244:245] op_sel:[1,0,0]
	v_pk_fma_f32 v[246:247], v[182:183], v[170:171], v[246:247] op_sel:[1,0,0]
	v_pk_fma_f32 v[248:249], v[182:183], v[172:173], v[248:249] op_sel:[1,0,0]
	v_cvt_pk_f32_fp8_e32 v[166:167], v42
	v_cvt_pk_f32_fp8_sdwa v[168:169], v42 src0_sel:WORD_1
	v_cvt_pk_f32_fp8_e32 v[170:171], v43
	v_cvt_pk_f32_fp8_sdwa v[172:173], v43 src0_sel:WORD_1
	v_pk_fma_f32 v[242:243], v[184:185], v[166:167], v[242:243] op_sel_hi:[0,1,1]
	v_pk_fma_f32 v[244:245], v[184:185], v[168:169], v[244:245] op_sel_hi:[0,1,1]
	v_pk_fma_f32 v[246:247], v[184:185], v[170:171], v[246:247] op_sel_hi:[0,1,1]
	v_pk_fma_f32 v[248:249], v[184:185], v[172:173], v[248:249] op_sel_hi:[0,1,1]
	v_cvt_pk_f32_fp8_e32 v[166:167], v44
	v_cvt_pk_f32_fp8_sdwa v[168:169], v44 src0_sel:WORD_1
	v_cvt_pk_f32_fp8_e32 v[170:171], v45
	v_cvt_pk_f32_fp8_sdwa v[172:173], v45 src0_sel:WORD_1
	v_pk_fma_f32 v[242:243], v[184:185], v[166:167], v[242:243] op_sel:[1,0,0]
	v_pk_fma_f32 v[244:245], v[184:185], v[168:169], v[244:245] op_sel:[1,0,0]
	v_pk_fma_f32 v[246:247], v[184:185], v[170:171], v[246:247] op_sel:[1,0,0]
	v_pk_fma_f32 v[248:249], v[184:185], v[172:173], v[248:249] op_sel:[1,0,0]
	v_cvt_pk_f32_fp8_e32 v[166:167], v46
	v_cvt_pk_f32_fp8_sdwa v[168:169], v46 src0_sel:WORD_1
	v_cvt_pk_f32_fp8_e32 v[170:171], v47
	v_cvt_pk_f32_fp8_sdwa v[172:173], v47 src0_sel:WORD_1
	v_pk_fma_f32 v[242:243], v[186:187], v[166:167], v[242:243] op_sel_hi:[0,1,1]
	v_pk_fma_f32 v[244:245], v[186:187], v[168:169], v[244:245] op_sel_hi:[0,1,1]
	v_pk_fma_f32 v[246:247], v[186:187], v[170:171], v[246:247] op_sel_hi:[0,1,1]
	v_pk_fma_f32 v[248:249], v[186:187], v[172:173], v[248:249] op_sel_hi:[0,1,1]
	v_cvt_pk_f32_fp8_e32 v[166:167], v48
	v_cvt_pk_f32_fp8_sdwa v[168:169], v48 src0_sel:WORD_1
	v_cvt_pk_f32_fp8_e32 v[170:171], v49
	v_cvt_pk_f32_fp8_sdwa v[172:173], v49 src0_sel:WORD_1
	v_pk_fma_f32 v[242:243], v[186:187], v[166:167], v[242:243] op_sel:[1,0,0]
	v_pk_fma_f32 v[244:245], v[186:187], v[168:169], v[244:245] op_sel:[1,0,0]
	v_pk_fma_f32 v[246:247], v[186:187], v[170:171], v[246:247] op_sel:[1,0,0]
	v_pk_fma_f32 v[248:249], v[186:187], v[172:173], v[248:249] op_sel:[1,0,0]
	v_cvt_pk_f32_fp8_e32 v[166:167], v50
	v_cvt_pk_f32_fp8_sdwa v[168:169], v50 src0_sel:WORD_1
	v_cvt_pk_f32_fp8_e32 v[170:171], v51
	v_cvt_pk_f32_fp8_sdwa v[172:173], v51 src0_sel:WORD_1
	v_pk_fma_f32 v[242:243], v[188:189], v[166:167], v[242:243] op_sel_hi:[0,1,1]
	v_pk_fma_f32 v[244:245], v[188:189], v[168:169], v[244:245] op_sel_hi:[0,1,1]
	v_pk_fma_f32 v[246:247], v[188:189], v[170:171], v[246:247] op_sel_hi:[0,1,1]
	v_pk_fma_f32 v[248:249], v[188:189], v[172:173], v[248:249] op_sel_hi:[0,1,1]
	v_cvt_pk_f32_fp8_e32 v[166:167], v52
	v_cvt_pk_f32_fp8_sdwa v[168:169], v52 src0_sel:WORD_1
	v_cvt_pk_f32_fp8_e32 v[170:171], v53
	v_cvt_pk_f32_fp8_sdwa v[172:173], v53 src0_sel:WORD_1
	v_pk_fma_f32 v[242:243], v[188:189], v[166:167], v[242:243] op_sel:[1,0,0]
	v_pk_fma_f32 v[244:245], v[188:189], v[168:169], v[244:245] op_sel:[1,0,0]
	v_pk_fma_f32 v[246:247], v[188:189], v[170:171], v[246:247] op_sel:[1,0,0]
	v_pk_fma_f32 v[248:249], v[188:189], v[172:173], v[248:249] op_sel:[1,0,0]
	v_cvt_pk_f32_fp8_e32 v[166:167], v54
	v_cvt_pk_f32_fp8_sdwa v[168:169], v54 src0_sel:WORD_1
	v_cvt_pk_f32_fp8_e32 v[170:171], v55
	v_cvt_pk_f32_fp8_sdwa v[172:173], v55 src0_sel:WORD_1
	v_pk_fma_f32 v[242:243], v[190:191], v[166:167], v[242:243] op_sel_hi:[0,1,1]
	v_pk_fma_f32 v[244:245], v[190:191], v[168:169], v[244:245] op_sel_hi:[0,1,1]
	v_pk_fma_f32 v[246:247], v[190:191], v[170:171], v[246:247] op_sel_hi:[0,1,1]
	v_pk_fma_f32 v[248:249], v[190:191], v[172:173], v[248:249] op_sel_hi:[0,1,1]
	v_cvt_pk_f32_fp8_e32 v[166:167], v56
	v_cvt_pk_f32_fp8_sdwa v[168:169], v56 src0_sel:WORD_1
	v_cvt_pk_f32_fp8_e32 v[170:171], v57
	v_cvt_pk_f32_fp8_sdwa v[172:173], v57 src0_sel:WORD_1
	v_pk_fma_f32 v[242:243], v[190:191], v[166:167], v[242:243] op_sel:[1,0,0]
	v_pk_fma_f32 v[244:245], v[190:191], v[168:169], v[244:245] op_sel:[1,0,0]
	v_pk_fma_f32 v[246:247], v[190:191], v[170:171], v[246:247] op_sel:[1,0,0]
	v_pk_fma_f32 v[248:249], v[190:191], v[172:173], v[248:249] op_sel:[1,0,0]
	v_cvt_pk_f32_fp8_e32 v[166:167], v58
	v_cvt_pk_f32_fp8_sdwa v[168:169], v58 src0_sel:WORD_1
	v_cvt_pk_f32_fp8_e32 v[170:171], v59
	v_cvt_pk_f32_fp8_sdwa v[172:173], v59 src0_sel:WORD_1
	v_pk_fma_f32 v[242:243], v[192:193], v[166:167], v[242:243] op_sel_hi:[0,1,1]
	v_pk_fma_f32 v[244:245], v[192:193], v[168:169], v[244:245] op_sel_hi:[0,1,1]
	v_pk_fma_f32 v[246:247], v[192:193], v[170:171], v[246:247] op_sel_hi:[0,1,1]
	v_pk_fma_f32 v[248:249], v[192:193], v[172:173], v[248:249] op_sel_hi:[0,1,1]
	v_cvt_pk_f32_fp8_e32 v[166:167], v60
	v_cvt_pk_f32_fp8_sdwa v[168:169], v60 src0_sel:WORD_1
	v_cvt_pk_f32_fp8_e32 v[170:171], v61
	v_cvt_pk_f32_fp8_sdwa v[172:173], v61 src0_sel:WORD_1
	v_pk_fma_f32 v[242:243], v[192:193], v[166:167], v[242:243] op_sel:[1,0,0]
	v_pk_fma_f32 v[244:245], v[192:193], v[168:169], v[244:245] op_sel:[1,0,0]
	v_pk_fma_f32 v[246:247], v[192:193], v[170:171], v[246:247] op_sel:[1,0,0]
	v_pk_fma_f32 v[248:249], v[192:193], v[172:173], v[248:249] op_sel:[1,0,0]
	v_cvt_pk_f32_fp8_e32 v[166:167], v62
	v_cvt_pk_f32_fp8_sdwa v[168:169], v62 src0_sel:WORD_1
	v_cvt_pk_f32_fp8_e32 v[170:171], v63
	v_cvt_pk_f32_fp8_sdwa v[172:173], v63 src0_sel:WORD_1
	v_pk_fma_f32 v[242:243], v[194:195], v[166:167], v[242:243] op_sel_hi:[0,1,1]
	v_pk_fma_f32 v[244:245], v[194:195], v[168:169], v[244:245] op_sel_hi:[0,1,1]
	v_pk_fma_f32 v[246:247], v[194:195], v[170:171], v[246:247] op_sel_hi:[0,1,1]
	v_pk_fma_f32 v[248:249], v[194:195], v[172:173], v[248:249] op_sel_hi:[0,1,1]
	v_cvt_pk_f32_fp8_e32 v[166:167], v64
	v_cvt_pk_f32_fp8_sdwa v[168:169], v64 src0_sel:WORD_1
	v_cvt_pk_f32_fp8_e32 v[170:171], v65
	v_cvt_pk_f32_fp8_sdwa v[172:173], v65 src0_sel:WORD_1
	v_pk_fma_f32 v[242:243], v[194:195], v[166:167], v[242:243] op_sel:[1,0,0]
	v_pk_fma_f32 v[244:245], v[194:195], v[168:169], v[244:245] op_sel:[1,0,0]
	v_pk_fma_f32 v[246:247], v[194:195], v[170:171], v[246:247] op_sel:[1,0,0]
	v_pk_fma_f32 v[248:249], v[194:195], v[172:173], v[248:249] op_sel:[1,0,0]
	s_waitcnt lgkmcnt(0)
	v_add_u32_e32 v120, v104, v226
	global_load_dwordx2 v[34:35], v120, s[52:53]
	v_add_u32_e32 v122, v104, v227
	global_load_dwordx2 v[36:37], v122, s[52:53]
	v_add_u32_e32 v124, v104, v228
	global_load_dwordx2 v[38:39], v124, s[52:53]
	v_add_u32_e32 v126, v104, v229
	global_load_dwordx2 v[40:41], v126, s[52:53]
	v_add_u32_e32 v120, v104, v230
	global_load_dwordx2 v[42:43], v120, s[52:53]
	v_add_u32_e32 v122, v104, v231
	global_load_dwordx2 v[44:45], v122, s[52:53]
	v_add_u32_e32 v124, v104, v232
	global_load_dwordx2 v[46:47], v124, s[52:53]
	v_add_u32_e32 v126, v104, v233
	global_load_dwordx2 v[48:49], v126, s[52:53]
	v_add_u32_e32 v120, v104, v234
	global_load_dwordx2 v[50:51], v120, s[52:53]
	v_add_u32_e32 v122, v104, v235
	global_load_dwordx2 v[52:53], v122, s[52:53]
	v_add_u32_e32 v124, v104, v236
	global_load_dwordx2 v[54:55], v124, s[52:53]
	v_add_u32_e32 v126, v104, v237
	global_load_dwordx2 v[56:57], v126, s[52:53]
	v_add_u32_e32 v120, v104, v238
	global_load_dwordx2 v[58:59], v120, s[52:53]
	v_add_u32_e32 v122, v104, v239
	global_load_dwordx2 v[60:61], v122, s[52:53]
	v_add_u32_e32 v124, v104, v240
	global_load_dwordx2 v[62:63], v124, s[52:53]
	v_add_u32_e32 v126, v104, v241
	global_load_dwordx2 v[64:65], v126, s[52:53]
	ds_read_b128 v[226:229], v106 offset:128
	ds_read_b128 v[230:233], v106 offset:144
	ds_read_b128 v[234:237], v106 offset:160
	ds_read_b128 v[238:241], v106 offset:176
	ds_read_b128 v[180:183], v106 offset:6144
	ds_read_b128 v[184:187], v106 offset:6160
	ds_read_b128 v[188:191], v106 offset:6176
	ds_read_b128 v[192:195], v106 offset:6192
	s_waitcnt vmcnt(32)
	v_cvt_pk_f32_fp8_e32 v[166:167], v134
	v_cvt_pk_f32_fp8_sdwa v[168:169], v134 src0_sel:WORD_1
	v_cvt_pk_f32_fp8_e32 v[170:171], v135
	v_cvt_pk_f32_fp8_sdwa v[172:173], v135 src0_sel:WORD_1
	v_pk_fma_f32 v[242:243], v[196:197], v[166:167], v[242:243] op_sel_hi:[0,1,1]
	v_pk_fma_f32 v[244:245], v[196:197], v[168:169], v[244:245] op_sel_hi:[0,1,1]
	v_pk_fma_f32 v[246:247], v[196:197], v[170:171], v[246:247] op_sel_hi:[0,1,1]
	v_pk_fma_f32 v[248:249], v[196:197], v[172:173], v[248:249] op_sel_hi:[0,1,1]
	v_cvt_pk_f32_fp8_e32 v[166:167], v136
	v_cvt_pk_f32_fp8_sdwa v[168:169], v136 src0_sel:WORD_1
	v_cvt_pk_f32_fp8_e32 v[170:171], v137
	v_cvt_pk_f32_fp8_sdwa v[172:173], v137 src0_sel:WORD_1
	v_pk_fma_f32 v[242:243], v[196:197], v[166:167], v[242:243] op_sel:[1,0,0]
	v_pk_fma_f32 v[244:245], v[196:197], v[168:169], v[244:245] op_sel:[1,0,0]
	v_pk_fma_f32 v[246:247], v[196:197], v[170:171], v[246:247] op_sel:[1,0,0]
	v_pk_fma_f32 v[248:249], v[196:197], v[172:173], v[248:249] op_sel:[1,0,0]
	v_cvt_pk_f32_fp8_e32 v[166:167], v138
	v_cvt_pk_f32_fp8_sdwa v[168:169], v138 src0_sel:WORD_1
	v_cvt_pk_f32_fp8_e32 v[170:171], v139
	v_cvt_pk_f32_fp8_sdwa v[172:173], v139 src0_sel:WORD_1
	v_pk_fma_f32 v[242:243], v[198:199], v[166:167], v[242:243] op_sel_hi:[0,1,1]
	v_pk_fma_f32 v[244:245], v[198:199], v[168:169], v[244:245] op_sel_hi:[0,1,1]
	v_pk_fma_f32 v[246:247], v[198:199], v[170:171], v[246:247] op_sel_hi:[0,1,1]
	v_pk_fma_f32 v[248:249], v[198:199], v[172:173], v[248:249] op_sel_hi:[0,1,1]
	v_cvt_pk_f32_fp8_e32 v[166:167], v140
	v_cvt_pk_f32_fp8_sdwa v[168:169], v140 src0_sel:WORD_1
	v_cvt_pk_f32_fp8_e32 v[170:171], v141
	v_cvt_pk_f32_fp8_sdwa v[172:173], v141 src0_sel:WORD_1
	v_pk_fma_f32 v[242:243], v[198:199], v[166:167], v[242:243] op_sel:[1,0,0]
	v_pk_fma_f32 v[244:245], v[198:199], v[168:169], v[244:245] op_sel:[1,0,0]
	v_pk_fma_f32 v[246:247], v[198:199], v[170:171], v[246:247] op_sel:[1,0,0]
	v_pk_fma_f32 v[248:249], v[198:199], v[172:173], v[248:249] op_sel:[1,0,0]
	v_cvt_pk_f32_fp8_e32 v[166:167], v142
	v_cvt_pk_f32_fp8_sdwa v[168:169], v142 src0_sel:WORD_1
	v_cvt_pk_f32_fp8_e32 v[170:171], v143
	v_cvt_pk_f32_fp8_sdwa v[172:173], v143 src0_sel:WORD_1
	v_pk_fma_f32 v[242:243], v[200:201], v[166:167], v[242:243] op_sel_hi:[0,1,1]
	v_pk_fma_f32 v[244:245], v[200:201], v[168:169], v[244:245] op_sel_hi:[0,1,1]
	v_pk_fma_f32 v[246:247], v[200:201], v[170:171], v[246:247] op_sel_hi:[0,1,1]
	v_pk_fma_f32 v[248:249], v[200:201], v[172:173], v[248:249] op_sel_hi:[0,1,1]
	v_cvt_pk_f32_fp8_e32 v[166:167], v144
	v_cvt_pk_f32_fp8_sdwa v[168:169], v144 src0_sel:WORD_1
	v_cvt_pk_f32_fp8_e32 v[170:171], v145
	v_cvt_pk_f32_fp8_sdwa v[172:173], v145 src0_sel:WORD_1
	v_pk_fma_f32 v[242:243], v[200:201], v[166:167], v[242:243] op_sel:[1,0,0]
	v_pk_fma_f32 v[244:245], v[200:201], v[168:169], v[244:245] op_sel:[1,0,0]
	v_pk_fma_f32 v[246:247], v[200:201], v[170:171], v[246:247] op_sel:[1,0,0]
	v_pk_fma_f32 v[248:249], v[200:201], v[172:173], v[248:249] op_sel:[1,0,0]
	v_cvt_pk_f32_fp8_e32 v[166:167], v146
	v_cvt_pk_f32_fp8_sdwa v[168:169], v146 src0_sel:WORD_1
	v_cvt_pk_f32_fp8_e32 v[170:171], v147
	v_cvt_pk_f32_fp8_sdwa v[172:173], v147 src0_sel:WORD_1
	v_pk_fma_f32 v[242:243], v[202:203], v[166:167], v[242:243] op_sel_hi:[0,1,1]
	v_pk_fma_f32 v[244:245], v[202:203], v[168:169], v[244:245] op_sel_hi:[0,1,1]
	v_pk_fma_f32 v[246:247], v[202:203], v[170:171], v[246:247] op_sel_hi:[0,1,1]
	v_pk_fma_f32 v[248:249], v[202:203], v[172:173], v[248:249] op_sel_hi:[0,1,1]
	v_cvt_pk_f32_fp8_e32 v[166:167], v148
	v_cvt_pk_f32_fp8_sdwa v[168:169], v148 src0_sel:WORD_1
	v_cvt_pk_f32_fp8_e32 v[170:171], v149
	v_cvt_pk_f32_fp8_sdwa v[172:173], v149 src0_sel:WORD_1
	v_pk_fma_f32 v[242:243], v[202:203], v[166:167], v[242:243] op_sel:[1,0,0]
	v_pk_fma_f32 v[244:245], v[202:203], v[168:169], v[244:245] op_sel:[1,0,0]
	v_pk_fma_f32 v[246:247], v[202:203], v[170:171], v[246:247] op_sel:[1,0,0]
	v_pk_fma_f32 v[248:249], v[202:203], v[172:173], v[248:249] op_sel:[1,0,0]
	v_cvt_pk_f32_fp8_e32 v[166:167], v150
	v_cvt_pk_f32_fp8_sdwa v[168:169], v150 src0_sel:WORD_1
	v_cvt_pk_f32_fp8_e32 v[170:171], v151
	v_cvt_pk_f32_fp8_sdwa v[172:173], v151 src0_sel:WORD_1
	v_pk_fma_f32 v[242:243], v[204:205], v[166:167], v[242:243] op_sel_hi:[0,1,1]
	v_pk_fma_f32 v[244:245], v[204:205], v[168:169], v[244:245] op_sel_hi:[0,1,1]
	v_pk_fma_f32 v[246:247], v[204:205], v[170:171], v[246:247] op_sel_hi:[0,1,1]
	v_pk_fma_f32 v[248:249], v[204:205], v[172:173], v[248:249] op_sel_hi:[0,1,1]
	v_cvt_pk_f32_fp8_e32 v[166:167], v152
	v_cvt_pk_f32_fp8_sdwa v[168:169], v152 src0_sel:WORD_1
	v_cvt_pk_f32_fp8_e32 v[170:171], v153
	v_cvt_pk_f32_fp8_sdwa v[172:173], v153 src0_sel:WORD_1
	v_pk_fma_f32 v[242:243], v[204:205], v[166:167], v[242:243] op_sel:[1,0,0]
	v_pk_fma_f32 v[244:245], v[204:205], v[168:169], v[244:245] op_sel:[1,0,0]
	v_pk_fma_f32 v[246:247], v[204:205], v[170:171], v[246:247] op_sel:[1,0,0]
	v_pk_fma_f32 v[248:249], v[204:205], v[172:173], v[248:249] op_sel:[1,0,0]
	v_cvt_pk_f32_fp8_e32 v[166:167], v154
	v_cvt_pk_f32_fp8_sdwa v[168:169], v154 src0_sel:WORD_1
	v_cvt_pk_f32_fp8_e32 v[170:171], v155
	v_cvt_pk_f32_fp8_sdwa v[172:173], v155 src0_sel:WORD_1
	v_pk_fma_f32 v[242:243], v[206:207], v[166:167], v[242:243] op_sel_hi:[0,1,1]
	v_pk_fma_f32 v[244:245], v[206:207], v[168:169], v[244:245] op_sel_hi:[0,1,1]
	v_pk_fma_f32 v[246:247], v[206:207], v[170:171], v[246:247] op_sel_hi:[0,1,1]
	v_pk_fma_f32 v[248:249], v[206:207], v[172:173], v[248:249] op_sel_hi:[0,1,1]
	v_cvt_pk_f32_fp8_e32 v[166:167], v156
	v_cvt_pk_f32_fp8_sdwa v[168:169], v156 src0_sel:WORD_1
	v_cvt_pk_f32_fp8_e32 v[170:171], v157
	v_cvt_pk_f32_fp8_sdwa v[172:173], v157 src0_sel:WORD_1
	v_pk_fma_f32 v[242:243], v[206:207], v[166:167], v[242:243] op_sel:[1,0,0]
	v_pk_fma_f32 v[244:245], v[206:207], v[168:169], v[244:245] op_sel:[1,0,0]
	v_pk_fma_f32 v[246:247], v[206:207], v[170:171], v[246:247] op_sel:[1,0,0]
	v_pk_fma_f32 v[248:249], v[206:207], v[172:173], v[248:249] op_sel:[1,0,0]
	v_cvt_pk_f32_fp8_e32 v[166:167], v158
	v_cvt_pk_f32_fp8_sdwa v[168:169], v158 src0_sel:WORD_1
	v_cvt_pk_f32_fp8_e32 v[170:171], v159
	v_cvt_pk_f32_fp8_sdwa v[172:173], v159 src0_sel:WORD_1
	v_pk_fma_f32 v[242:243], v[216:217], v[166:167], v[242:243] op_sel_hi:[0,1,1]
	v_pk_fma_f32 v[244:245], v[216:217], v[168:169], v[244:245] op_sel_hi:[0,1,1]
	v_pk_fma_f32 v[246:247], v[216:217], v[170:171], v[246:247] op_sel_hi:[0,1,1]
	v_pk_fma_f32 v[248:249], v[216:217], v[172:173], v[248:249] op_sel_hi:[0,1,1]
	v_cvt_pk_f32_fp8_e32 v[166:167], v160
	v_cvt_pk_f32_fp8_sdwa v[168:169], v160 src0_sel:WORD_1
	v_cvt_pk_f32_fp8_e32 v[170:171], v161
	v_cvt_pk_f32_fp8_sdwa v[172:173], v161 src0_sel:WORD_1
	v_pk_fma_f32 v[242:243], v[216:217], v[166:167], v[242:243] op_sel:[1,0,0]
	v_pk_fma_f32 v[244:245], v[216:217], v[168:169], v[244:245] op_sel:[1,0,0]
	v_pk_fma_f32 v[246:247], v[216:217], v[170:171], v[246:247] op_sel:[1,0,0]
	v_pk_fma_f32 v[248:249], v[216:217], v[172:173], v[248:249] op_sel:[1,0,0]
	v_cvt_pk_f32_fp8_e32 v[166:167], v162
	v_cvt_pk_f32_fp8_sdwa v[168:169], v162 src0_sel:WORD_1
	v_cvt_pk_f32_fp8_e32 v[170:171], v163
	v_cvt_pk_f32_fp8_sdwa v[172:173], v163 src0_sel:WORD_1
	v_pk_fma_f32 v[242:243], v[218:219], v[166:167], v[242:243] op_sel_hi:[0,1,1]
	v_pk_fma_f32 v[244:245], v[218:219], v[168:169], v[244:245] op_sel_hi:[0,1,1]
	v_pk_fma_f32 v[246:247], v[218:219], v[170:171], v[246:247] op_sel_hi:[0,1,1]
	v_pk_fma_f32 v[248:249], v[218:219], v[172:173], v[248:249] op_sel_hi:[0,1,1]
	v_cvt_pk_f32_fp8_e32 v[166:167], v164
	v_cvt_pk_f32_fp8_sdwa v[168:169], v164 src0_sel:WORD_1
	v_cvt_pk_f32_fp8_e32 v[170:171], v165
	v_cvt_pk_f32_fp8_sdwa v[172:173], v165 src0_sel:WORD_1
	v_pk_fma_f32 v[242:243], v[218:219], v[166:167], v[242:243] op_sel:[1,0,0]
	v_pk_fma_f32 v[244:245], v[218:219], v[168:169], v[244:245] op_sel:[1,0,0]
	v_pk_fma_f32 v[246:247], v[218:219], v[170:171], v[246:247] op_sel:[1,0,0]
	v_pk_fma_f32 v[248:249], v[218:219], v[172:173], v[248:249] op_sel:[1,0,0]
	v_pk_fma_f32 v[94:95], v[242:243], v[66:67], v[94:95]
	v_pk_fma_f32 v[96:97], v[244:245], v[68:69], v[96:97]
	v_pk_fma_f32 v[98:99], v[246:247], v[174:175], v[98:99]
	v_pk_fma_f32 v[100:101], v[248:249], v[176:177], v[100:101]
	global_store_dwordx4 v112, v[94:97], s[54:55]
	global_store_dwordx4 v112, v[98:101], s[54:55] offset:16
	s_mov_b64 s[50:51], s[52:53]
	s_add_u32 s52, s52, 0x80
	s_addc_u32 s53, s53, 0
	s_add_u32 s54, s54, 0x200
	s_addc_u32 s55, s55, 0
	s_add_u32 s56, s56, 0x200
	s_addc_u32 s57, s57, 0
	s_add_i32 s49, s49, 1
	s_cmp_lt_u32 s49, 8
	s_cbranch_scc1 .Lv_cloop
	s_waitcnt vmcnt(0) lgkmcnt(0)
	s_branch .LBB0_2141
